# plus f32->bf16 integer bit-trick (bfe/add3/perm) replaced by v_cvt_pk_bf16_f32 at 533 sites
# speedup vs baseline: 1.0252x; 1.0089x over previous
.LBB0_234:
	v_fma_f32 v46, v72, s17, -v133
	v_exp_f32_e32 v46, v46
	v_fma_f32 v47, v73, s17, -v133
	v_exp_f32_e32 v47, v47
	v_fma_f32 v48, v74, s17, -v133
	v_fma_f32 v49, v75, s17, -v133
	v_exp_f32_e32 v48, v48
	v_exp_f32_e32 v49, v49
	v_add_f32_e32 v50, 0, v46
	v_add_f32_e32 v50, v47, v50
	v_add_f32_e32 v50, v48, v50
	v_cvt_pk_bf16_f32 v46, v46, v47
	v_cvt_pk_bf16_f32 v47, v48, v49
	v_fma_f32 v48, v68, s17, -v133
	v_add_f32_e32 v50, v49, v50
	v_exp_f32_e32 v48, v48
	v_fma_f32 v49, v69, s17, -v133
	v_exp_f32_e32 v49, v49
	v_fma_f32 v51, v70, s17, -v133
	v_fma_f32 v68, v71, s17, -v133
	v_exp_f32_e32 v51, v51
	v_exp_f32_e32 v68, v68
	v_add_f32_e32 v50, v48, v50
	v_add_f32_e32 v50, v49, v50
	v_add_f32_e32 v50, v51, v50
	v_cvt_pk_bf16_f32 v48, v48, v49
	v_cvt_pk_bf16_f32 v49, v51, v68
	v_fma_f32 v51, v64, s17, -v133
	v_exp_f32_e32 v51, v51
	v_fma_f32 v64, v65, s17, -v133
	v_exp_f32_e32 v64, v64
	v_fma_f32 v65, v66, s17, -v133
	v_exp_f32_e32 v65, v65
	v_fma_f32 v66, v67, s17, -v133
	v_add_f32_e32 v50, v68, v50
	v_exp_f32_e32 v66, v66
	v_fma_f32 v40, v40, s17, -v133
	v_add_f32_e32 v50, v51, v50
	v_exp_f32_e32 v40, v40
	v_fma_f32 v41, v41, s17, -v133
	v_add_f32_e32 v50, v64, v50
	v_exp_f32_e32 v41, v41
	v_fma_f32 v42, v42, s17, -v133
	v_add_f32_e32 v50, v65, v50
	v_exp_f32_e32 v42, v42
	v_fma_f32 v43, v43, s17, -v133
	v_add_f32_e32 v50, v66, v50
	v_exp_f32_e32 v43, v43
	v_add_f32_e32 v50, v40, v50
	v_cvt_pk_bf16_f32 v65, v65, v66
	v_add_f32_e32 v50, v41, v50
	v_cvt_pk_bf16_f32 v66, v40, v41
	v_fma_f32 v40, v60, s17, -v3
	v_add_f32_e32 v50, v42, v50
	v_exp_f32_e32 v40, v40
	v_fma_f32 v41, v61, s17, -v3
	v_add_f32_e32 v50, v43, v50
	v_cvt_pk_bf16_f32 v67, v42, v43
	v_exp_f32_e32 v41, v41
	v_fma_f32 v42, v62, s17, -v3
	v_fma_f32 v43, v63, s17, -v3
	v_exp_f32_e32 v42, v42
	v_exp_f32_e32 v43, v43
	v_add_f32_e32 v72, v130, v50
	v_add_f32_e32 v50, 0, v40
	v_add_f32_e32 v50, v41, v50
	v_add_f32_e32 v50, v42, v50
	v_cvt_pk_bf16_f32 v40, v40, v41
	v_cvt_pk_bf16_f32 v41, v42, v43
	v_fma_f32 v42, v56, s17, -v3
	v_add_f32_e32 v50, v43, v50
	v_exp_f32_e32 v42, v42
	v_fma_f32 v43, v57, s17, -v3
	v_cvt_pk_bf16_f32 v64, v51, v64
	v_exp_f32_e32 v43, v43
	v_fma_f32 v51, v58, s17, -v3
	v_fma_f32 v56, v59, s17, -v3
	v_exp_f32_e32 v51, v51
	v_exp_f32_e32 v56, v56
	v_add_f32_e32 v50, v42, v50
	v_add_f32_e32 v50, v43, v50
	v_add_f32_e32 v50, v51, v50
	v_cvt_pk_bf16_f32 v42, v42, v43
	v_cvt_pk_bf16_f32 v43, v51, v56
	v_fma_f32 v51, v52, s17, -v3
	v_exp_f32_e32 v51, v51
	v_fma_f32 v52, v53, s17, -v3
	v_exp_f32_e32 v52, v52
	v_fma_f32 v53, v54, s17, -v3
	v_exp_f32_e32 v53, v53
	v_fma_f32 v54, v55, s17, -v3
	v_add_f32_e32 v50, v56, v50
	v_exp_f32_e32 v54, v54
	v_add_f32_e32 v50, v51, v50
	v_add_f32_e32 v50, v52, v50
	v_add_f32_e32 v50, v53, v50
	v_fma_f32 v36, v36, s17, -v3
	v_add_f32_e32 v55, v54, v50
	v_cvt_pk_bf16_f32 v50, v51, v52
	v_exp_f32_e32 v52, v36
	v_fma_f32 v36, v37, s17, -v3
	v_exp_f32_e32 v62, v36
	v_fma_f32 v36, v38, s17, -v3
	v_exp_f32_e32 v63, v36
	v_add_f32_e32 v36, v52, v55
	v_add_f32_e32 v36, v62, v36
	v_cvt_pk_bf16_f32 v51, v53, v54
	v_add_f32_e32 v53, v63, v36
	v_mul_u32_u24_e32 v36, 0x48, v124
	v_lshl_add_u32 v73, v36, 1, v127
	v_fma_f32 v3, v39, s17, -v3
	ds_read_b64_tr_b16 v[38:39], v73 offset:20736
	ds_read_b64_tr_b16 v[36:37], v73 offset:18432
	ds_read_b64_tr_b16 v[56:57], v73 offset:20768
	ds_read_b64_tr_b16 v[54:55], v73 offset:18464
	ds_read_b64_tr_b16 v[58:59], v73 offset:23040
	ds_read_b64_tr_b16 v[60:61], v73 offset:25344
	ds_read_b64_tr_b16 v[70:71], v73 offset:25376
	ds_read_b64_tr_b16 v[68:69], v73 offset:23072
	v_exp_f32_e32 v3, v3
	v_cvt_pk_bf16_f32 v52, v52, v62
	v_add_f32_e32 v74, v3, v53
	v_cvt_pk_bf16_f32 v53, v63, v3
	v_add_f32_e32 v62, v2, v74
	s_waitcnt lgkmcnt(6)
	v_mfma_f32_16x16x32_bf16 v[28:31], v[36:39], v[46:49], v[28:31]
	v_mfma_f32_16x16x32_bf16 v[32:35], v[36:39], v[40:43], v[32:35]
	s_waitcnt lgkmcnt(4)
	v_mfma_f32_16x16x32_bf16 v[20:23], v[54:57], v[46:49], v[20:23]
	v_mfma_f32_16x16x32_bf16 v[24:27], v[54:57], v[40:43], v[24:27]
	s_waitcnt lgkmcnt(2)
	v_mfma_f32_16x16x32_bf16 v[28:31], v[58:61], v[64:67], v[28:31]
	v_mfma_f32_16x16x32_bf16 v[32:35], v[58:61], v[50:53], v[32:35]
	s_waitcnt lgkmcnt(0)
	v_mfma_f32_16x16x32_bf16 v[20:23], v[68:71], v[64:67], v[20:23]
	v_mfma_f32_16x16x32_bf16 v[24:27], v[68:71], v[50:53], v[24:27]
	ds_read_b64_tr_b16 v[38:39], v73 offset:20800
	ds_read_b64_tr_b16 v[36:37], v73 offset:18496
	ds_read_b64_tr_b16 v[56:57], v73 offset:20832
	ds_read_b64_tr_b16 v[54:55], v73 offset:18528
	ds_read_b64_tr_b16 v[58:59], v73 offset:23104
	ds_read_b64_tr_b16 v[60:61], v73 offset:25408
	ds_read_b64_tr_b16 v[70:71], v73 offset:25440
	ds_read_b64_tr_b16 v[68:69], v73 offset:23136
	s_waitcnt lgkmcnt(6)
	v_mfma_f32_16x16x32_bf16 v[12:15], v[36:39], v[46:49], v[12:15]
	v_mfma_f32_16x16x32_bf16 v[16:19], v[36:39], v[40:43], v[16:19]
	s_waitcnt lgkmcnt(4)
	v_mfma_f32_16x16x32_bf16 v[2:5], v[54:57], v[46:49], v[4:7]
	v_mfma_f32_16x16x32_bf16 v[6:9], v[54:57], v[40:43], v[8:11]
	s_waitcnt lgkmcnt(2)
	v_mfma_f32_16x16x32_bf16 v[12:15], v[58:61], v[64:67], v[12:15]
	v_mfma_f32_16x16x32_bf16 v[16:19], v[58:61], v[50:53], v[16:19]
	s_waitcnt lgkmcnt(0)
	v_mfma_f32_16x16x32_bf16 v[2:5], v[68:71], v[64:67], v[2:5]
	v_mfma_f32_16x16x32_bf16 v[6:9], v[68:71], v[50:53], v[6:9]
	ds_bpermute_b32 v10, v44, v72
	v_readlane_b32 s40, v254, 55
	v_readlane_b32 s46, v254, 61
	v_readlane_b32 s47, v254, 62
	s_waitcnt lgkmcnt(0)
	v_add_f32_e32 v10, v72, v10
	ds_bpermute_b32 v11, v45, v10
	s_barrier
	s_waitcnt lgkmcnt(0)
	v_readlane_b32 s41, v254, 56
	v_readlane_b32 s42, v254, 57
	v_add_f32_e32 v36, v10, v11
	v_div_scale_f32 v37, s[2:3], v36, v36, 1.0
	v_rcp_f32_e32 v38, v37
	v_div_scale_f32 v39, vcc, 1.0, v36, 1.0
	v_lshlrev_b64 v[10:11], 11, v[118:119]
	v_fma_f32 v40, -v37, v38, 1.0
	v_fmac_f32_e32 v38, v40, v38
	v_mul_f32_e32 v40, v39, v38
	v_fma_f32 v41, -v37, v40, v39
	v_fmac_f32_e32 v40, v41, v38
	v_fma_f32 v37, -v37, v40, v39
	v_div_fmas_f32 v37, v37, v38, v40
	v_div_fixup_f32 v36, v37, v36, 1.0
	v_pk_mul_f32 v[30:31], v[30:31], v[36:37] op_sel_hi:[1,0]
	v_pk_mul_f32 v[28:29], v[28:29], v[36:37] op_sel_hi:[1,0]
	v_bfe_u32 v39, v29, 16, 1
	v_bfe_u32 v40, v28, 16, 1
	v_lshl_add_u64 v[10:11], s[46:47], 0, v[10:11]
	v_add3_u32 v28, v28, v40, s0
	v_add3_u32 v37, v29, v39, s0
	v_cvt_pk_bf16_f32 v29, v30, v31
	v_lshl_add_u64 v[10:11], v[10:11], 0, v[0:1]
	v_lshlrev_b32_e32 v30, 1, v123
	v_mov_b32_e32 v31, v1
	v_perm_b32 v28, v37, v28, s19
	v_lshl_add_u64 v[10:11], v[10:11], 0, v[30:31]
	v_pk_mul_f32 v[20:21], v[20:21], v[36:37] op_sel_hi:[1,0]
	v_pk_mul_f32 v[22:23], v[22:23], v[36:37] op_sel_hi:[1,0]
	global_store_dwordx2 v[10:11], v[28:29], off
	v_mov_b32_e32 v28, v21
	v_cvt_pk_bf16_f32 v21, v22, v23
	v_cvt_pk_bf16_f32 v20, v20, v28
	v_pk_mul_f32 v[12:13], v[12:13], v[36:37] op_sel_hi:[1,0]
	v_pk_mul_f32 v[14:15], v[14:15], v[36:37] op_sel_hi:[1,0]
	global_store_dwordx2 v[10:11], v[20:21], off offset:32
	v_mov_b32_e32 v20, v13
	v_cvt_pk_bf16_f32 v13, v14, v15
	v_cvt_pk_bf16_f32 v12, v12, v20
	global_store_dwordx2 v[10:11], v[12:13], off offset:64
	ds_bpermute_b32 v12, v44, v62
	v_pk_mul_f32 v[4:5], v[4:5], v[36:37] op_sel_hi:[1,0]
	v_pk_mul_f32 v[2:3], v[2:3], v[36:37] op_sel_hi:[1,0]
	s_waitcnt lgkmcnt(0)
	v_add_f32_e32 v12, v62, v12
	ds_bpermute_b32 v21, v45, v12
	v_mov_b32_e32 v13, v3
	s_waitcnt lgkmcnt(0)
	v_add_f32_e32 v12, v12, v21
	v_div_scale_f32 v14, s[2:3], v12, v12, 1.0
	v_rcp_f32_e32 v15, v14
	v_cvt_pk_bf16_f32 v3, v4, v5
	v_cvt_pk_bf16_f32 v2, v2, v13
	global_store_dwordx2 v[10:11], v[2:3], off offset:96
	v_fma_f32 v2, -v14, v15, 1.0
	v_fmac_f32_e32 v15, v2, v15
	v_div_scale_f32 v2, vcc, 1.0, v12, 1.0
	v_mul_f32_e32 v3, v2, v15
	v_fma_f32 v4, -v14, v3, v2
	v_fmac_f32_e32 v3, v4, v15
	v_fma_f32 v2, -v14, v3, v2
	v_div_fmas_f32 v2, v2, v15, v3
	v_div_fixup_f32 v2, v2, v12, 1.0
	v_lshlrev_b64 v[4:5], 11, v[116:117]
	v_pk_mul_f32 v[10:11], v[32:33], v[2:3] op_sel_hi:[1,0]
	v_pk_mul_f32 v[12:13], v[34:35], v[2:3] op_sel_hi:[1,0]
	v_bfe_u32 v3, v13, 16, 1
	v_bfe_u32 v14, v12, 16, 1
	v_lshl_add_u64 v[4:5], s[46:47], 0, v[4:5]
	v_add3_u32 v12, v12, v14, s0
	v_add3_u32 v3, v13, v3, s0
	v_mov_b32_e32 v13, v11
	v_lshl_add_u64 v[4:5], v[4:5], 0, v[0:1]
	v_perm_b32 v11, v3, v12, s19
	v_cvt_pk_bf16_f32 v10, v10, v13
	v_lshl_add_u64 v[4:5], v[4:5], 0, v[30:31]
	global_store_dwordx2 v[4:5], v[10:11], off
	v_pk_mul_f32 v[10:11], v[24:25], v[2:3] op_sel_hi:[1,0]
	v_pk_mul_f32 v[12:13], v[26:27], v[2:3] op_sel_hi:[1,0]
	v_bfe_u32 v0, v13, 16, 1
	v_bfe_u32 v3, v12, 16, 1
	v_add3_u32 v3, v12, v3, s0
	v_add3_u32 v0, v13, v0, s0
	v_mov_b32_e32 v12, v11
	v_perm_b32 v11, v0, v3, s19
	v_cvt_pk_bf16_f32 v10, v10, v12
	global_store_dwordx2 v[4:5], v[10:11], off offset:32
	v_pk_mul_f32 v[10:11], v[16:17], v[2:3] op_sel_hi:[1,0]
	v_pk_mul_f32 v[12:13], v[18:19], v[2:3] op_sel_hi:[1,0]
	v_bfe_u32 v0, v13, 16, 1
	v_bfe_u32 v3, v12, 16, 1
	v_add3_u32 v3, v12, v3, s0
	v_add3_u32 v0, v13, v0, s0
	v_mov_b32_e32 v12, v11
	v_perm_b32 v11, v0, v3, s19
	v_cvt_pk_bf16_f32 v10, v10, v12
	v_pk_mul_f32 v[6:7], v[6:7], v[2:3] op_sel_hi:[1,0]
	v_pk_mul_f32 v[2:3], v[8:9], v[2:3] op_sel_hi:[1,0]
	global_store_dwordx2 v[4:5], v[10:11], off offset:64
	v_cvt_pk_bf16_f32 v3, v2, v3
	v_cvt_pk_bf16_f32 v2, v6, v7
	v_readlane_b32 s43, v254, 58
	v_readlane_b32 s44, v254, 59
	v_readlane_b32 s45, v254, 60
	v_readlane_b32 s48, v254, 63
	v_readlane_b32 s49, v255, 0
	v_readlane_b32 s50, v255, 1
	v_readlane_b32 s51, v255, 2
	v_readlane_b32 s52, v255, 3
	v_readlane_b32 s53, v255, 4
	v_readlane_b32 s54, v255, 5
	v_readlane_b32 s55, v255, 6
	global_store_dwordx2 v[4:5], v[2:3], off offset:96

.LBB0_332:
	v_fma_f32 v0, v70, s17, -v144
	v_exp_f32_e32 v0, v0
	v_fma_f32 v44, v71, s17, -v144
	v_exp_f32_e32 v44, v44
	v_fma_f32 v45, v72, s17, -v144
	v_exp_f32_e32 v45, v45
	v_fma_f32 v46, v73, s17, -v144
	v_exp_f32_e32 v46, v46
	v_add_f32_e32 v47, 0, v0
	v_add_f32_e32 v47, v44, v47
	v_add_f32_e32 v47, v45, v47
	v_cvt_pk_bf16_f32 v44, v0, v44
	v_fma_f32 v0, v66, s17, -v144
	v_add_f32_e32 v47, v46, v47
	v_cvt_pk_bf16_f32 v45, v45, v46
	v_exp_f32_e32 v0, v0
	v_fma_f32 v46, v67, s17, -v144
	v_exp_f32_e32 v46, v46
	v_fma_f32 v48, v68, s17, -v144
	v_exp_f32_e32 v48, v48
	v_fma_f32 v49, v69, s17, -v144
	v_exp_f32_e32 v49, v49
	v_add_f32_e32 v47, v0, v47
	v_add_f32_e32 v47, v46, v47
	v_add_f32_e32 v47, v48, v47
	v_cvt_pk_bf16_f32 v46, v0, v46
	v_fma_f32 v0, v62, s17, -v144
	v_add_f32_e32 v66, v49, v47
	v_cvt_pk_bf16_f32 v47, v48, v49
	v_exp_f32_e32 v0, v0
	v_fma_f32 v48, v63, s17, -v144
	v_exp_f32_e32 v48, v48
	v_fma_f32 v49, v64, s17, -v144
	v_exp_f32_e32 v49, v49
	v_fma_f32 v62, v65, s17, -v144
	v_exp_f32_e32 v63, v62
	v_add_f32_e32 v62, v0, v66
	v_add_f32_e32 v62, v48, v62
	v_add_f32_e32 v62, v49, v62
	v_add_f32_e32 v64, v63, v62
	v_cvt_pk_bf16_f32 v62, v0, v48
	v_fma_f32 v0, v38, s17, -v144
	v_exp_f32_e32 v0, v0
	v_fma_f32 v38, v39, s17, -v144
	v_exp_f32_e32 v38, v38
	v_fma_f32 v39, v40, s17, -v144
	v_exp_f32_e32 v39, v39
	v_fma_f32 v40, v41, s17, -v144
	v_exp_f32_e32 v40, v40
	v_add_f32_e32 v41, v0, v64
	v_add_f32_e32 v41, v38, v41
	v_add_f32_e32 v41, v39, v41
	v_cvt_pk_bf16_f32 v64, v0, v38
	v_fma_f32 v38, v58, s17, -v142
	v_add_f32_e32 v41, v40, v41
	v_cvt_pk_bf16_f32 v65, v39, v40
	v_exp_f32_e32 v38, v38
	v_fma_f32 v39, v59, s17, -v142
	v_add_f32_e32 v0, v140, v41
	v_exp_f32_e32 v39, v39
	v_fma_f32 v40, v60, s17, -v142
	v_fma_f32 v41, v61, s17, -v142
	v_exp_f32_e32 v40, v40
	v_exp_f32_e32 v41, v41
	v_add_f32_e32 v48, 0, v38
	v_add_f32_e32 v48, v39, v48
	v_add_f32_e32 v48, v40, v48
	v_cvt_pk_bf16_f32 v38, v38, v39
	v_cvt_pk_bf16_f32 v39, v40, v41
	v_fma_f32 v40, v54, s17, -v142
	v_add_f32_e32 v48, v41, v48
	v_exp_f32_e32 v40, v40
	v_fma_f32 v41, v55, s17, -v142
	v_cvt_pk_bf16_f32 v63, v49, v63
	v_exp_f32_e32 v41, v41
	v_fma_f32 v49, v56, s17, -v142
	v_fma_f32 v54, v57, s17, -v142
	v_exp_f32_e32 v49, v49
	v_exp_f32_e32 v54, v54
	v_add_f32_e32 v48, v40, v48
	v_add_f32_e32 v48, v41, v48
	v_add_f32_e32 v48, v49, v48
	v_cvt_pk_bf16_f32 v40, v40, v41
	v_cvt_pk_bf16_f32 v41, v49, v54
	v_fma_f32 v49, v50, s17, -v142
	v_exp_f32_e32 v49, v49
	v_fma_f32 v50, v51, s17, -v142
	v_exp_f32_e32 v50, v50
	v_fma_f32 v51, v52, s17, -v142
	v_exp_f32_e32 v51, v51
	v_fma_f32 v52, v53, s17, -v142
	v_add_f32_e32 v48, v54, v48
	v_exp_f32_e32 v52, v52
	v_add_f32_e32 v48, v49, v48
	v_add_f32_e32 v48, v50, v48
	v_add_f32_e32 v48, v51, v48
	v_fma_f32 v34, v34, s17, -v142
	v_add_f32_e32 v53, v52, v48
	v_cvt_pk_bf16_f32 v48, v49, v50
	v_exp_f32_e32 v50, v34
	v_fma_f32 v34, v35, s17, -v142
	v_exp_f32_e32 v60, v34
	v_fma_f32 v34, v36, s17, -v142
	v_exp_f32_e32 v61, v34
	v_add_f32_e32 v34, v50, v53
	v_add_f32_e32 v34, v60, v34
	v_cvt_pk_bf16_f32 v49, v51, v52
	v_add_f32_e32 v51, v61, v34
	v_fma_f32 v34, v37, s17, -v142
	v_exp_f32_e32 v70, v34
	v_mul_u32_u24_e32 v34, 0x48, v135
	v_lshl_add_u32 v71, v34, 1, v136
	ds_read_b64_tr_b16 v[36:37], v71 offset:20736
	ds_read_b64_tr_b16 v[34:35], v71 offset:18432
	ds_read_b64_tr_b16 v[54:55], v71 offset:20768
	ds_read_b64_tr_b16 v[52:53], v71 offset:18464
	ds_read_b64_tr_b16 v[56:57], v71 offset:23040
	ds_read_b64_tr_b16 v[58:59], v71 offset:25344
	ds_read_b64_tr_b16 v[68:69], v71 offset:25376
	ds_read_b64_tr_b16 v[66:67], v71 offset:23072
	v_add_f32_e32 v72, v70, v51
	v_cvt_pk_bf16_f32 v50, v50, v60
	v_cvt_pk_bf16_f32 v51, v61, v70
	v_add_f32_e32 v60, v137, v72
	s_waitcnt lgkmcnt(6)
	v_mfma_f32_16x16x32_bf16 v[18:21], v[34:37], v[44:47], v[18:21]
	v_mfma_f32_16x16x32_bf16 v[30:33], v[34:37], v[38:41], v[30:33]
	s_waitcnt lgkmcnt(4)
	v_mfma_f32_16x16x32_bf16 v[22:25], v[52:55], v[44:47], v[22:25]
	v_mfma_f32_16x16x32_bf16 v[26:29], v[52:55], v[38:41], v[26:29]
	s_waitcnt lgkmcnt(2)
	v_mfma_f32_16x16x32_bf16 v[18:21], v[56:59], v[62:65], v[18:21]
	v_mfma_f32_16x16x32_bf16 v[30:33], v[56:59], v[48:51], v[30:33]
	s_waitcnt lgkmcnt(0)
	v_mfma_f32_16x16x32_bf16 v[22:25], v[66:69], v[62:65], v[22:25]
	v_mfma_f32_16x16x32_bf16 v[26:29], v[66:69], v[48:51], v[26:29]
	ds_read_b64_tr_b16 v[36:37], v71 offset:20800
	ds_read_b64_tr_b16 v[34:35], v71 offset:18496
	ds_read_b64_tr_b16 v[54:55], v71 offset:20832
	ds_read_b64_tr_b16 v[52:53], v71 offset:18528
	ds_read_b64_tr_b16 v[56:57], v71 offset:23104
	ds_read_b64_tr_b16 v[58:59], v71 offset:25408
	ds_read_b64_tr_b16 v[68:69], v71 offset:25440
	ds_read_b64_tr_b16 v[66:67], v71 offset:23136
	s_waitcnt lgkmcnt(6)
	v_mfma_f32_16x16x32_bf16 v[10:13], v[34:37], v[44:47], v[10:13]
	v_mfma_f32_16x16x32_bf16 v[14:17], v[34:37], v[38:41], v[14:17]
	s_waitcnt lgkmcnt(4)
	v_mfma_f32_16x16x32_bf16 v[2:5], v[52:55], v[44:47], v[2:5]
	v_mfma_f32_16x16x32_bf16 v[6:9], v[52:55], v[38:41], v[6:9]
	s_waitcnt lgkmcnt(2)
	v_mfma_f32_16x16x32_bf16 v[10:13], v[56:59], v[62:65], v[10:13]
	v_mfma_f32_16x16x32_bf16 v[14:17], v[56:59], v[48:51], v[14:17]
	s_waitcnt lgkmcnt(0)
	v_mfma_f32_16x16x32_bf16 v[2:5], v[66:69], v[62:65], v[2:5]
	v_mfma_f32_16x16x32_bf16 v[6:9], v[66:69], v[48:51], v[6:9]
	ds_bpermute_b32 v34, v42, v0
	s_waitcnt lgkmcnt(0)
	s_barrier
	s_add_i32 s34, s34, 1
	v_add_f32_e32 v0, v0, v34
	ds_bpermute_b32 v34, v43, v0
	s_cmp_eq_u32 s34, 8
	s_waitcnt lgkmcnt(0)
	v_add_f32_e32 v0, v0, v34
	v_div_scale_f32 v36, s[2:3], v0, v0, 1.0
	v_rcp_f32_e32 v37, v36
	v_div_scale_f32 v38, vcc, 1.0, v0, 1.0
	v_lshlrev_b64 v[34:35], 11, v[122:123]
	v_fma_f32 v39, -v36, v37, 1.0
	v_fmac_f32_e32 v37, v39, v37
	v_mul_f32_e32 v39, v38, v37
	v_fma_f32 v40, -v36, v39, v38
	v_fmac_f32_e32 v39, v40, v37
	v_fma_f32 v36, -v36, v39, v38
	v_div_fmas_f32 v36, v36, v37, v39
	v_div_fixup_f32 v36, v36, v0, 1.0
	v_pk_mul_f32 v[18:19], v[18:19], v[36:37] op_sel_hi:[1,0]
	v_pk_mul_f32 v[20:21], v[20:21], v[36:37] op_sel_hi:[1,0]
	v_mov_b32_e32 v0, v21
	v_mov_b32_e32 v21, v19
	v_cvt_pk_bf16_f32 v19, v20, v0
	v_cvt_pk_bf16_f32 v18, v18, v21
	v_lshl_add_u64 v[20:21], v[118:119], 0, v[34:35]
	v_lshlrev_b32_e32 v0, 1, v134
	v_lshl_add_u64 v[20:21], v[20:21], 0, v[0:1]
	global_store_dwordx2 v[20:21], v[18:19], off
	v_pk_mul_f32 v[18:19], v[22:23], v[36:37] op_sel_hi:[1,0]
	v_pk_mul_f32 v[22:23], v[24:25], v[36:37] op_sel_hi:[1,0]
	v_mov_b32_e32 v24, v19
	v_cvt_pk_bf16_f32 v19, v22, v23
	v_cvt_pk_bf16_f32 v18, v18, v24
	v_pk_mul_f32 v[10:11], v[10:11], v[36:37] op_sel_hi:[1,0]
	v_pk_mul_f32 v[12:13], v[12:13], v[36:37] op_sel_hi:[1,0]
	global_store_dwordx2 v[20:21], v[18:19], off offset:32
	v_mov_b32_e32 v18, v11
	v_cvt_pk_bf16_f32 v11, v12, v13
	v_cvt_pk_bf16_f32 v10, v10, v18
	global_store_dwordx2 v[20:21], v[10:11], off offset:64
	ds_bpermute_b32 v10, v42, v60
	v_pk_mul_f32 v[4:5], v[4:5], v[36:37] op_sel_hi:[1,0]
	v_pk_mul_f32 v[2:3], v[2:3], v[36:37] op_sel_hi:[1,0]
	s_waitcnt lgkmcnt(0)
	v_add_f32_e32 v10, v60, v10
	ds_bpermute_b32 v19, v43, v10
	v_mov_b32_e32 v11, v3
	s_waitcnt lgkmcnt(0)
	v_add_f32_e32 v10, v10, v19
	v_div_scale_f32 v12, s[2:3], v10, v10, 1.0
	v_rcp_f32_e32 v13, v12
	v_cvt_pk_bf16_f32 v3, v4, v5
	v_cvt_pk_bf16_f32 v2, v2, v11
	global_store_dwordx2 v[20:21], v[2:3], off offset:96
	v_fma_f32 v2, -v12, v13, 1.0
	v_fmac_f32_e32 v13, v2, v13
	v_div_scale_f32 v2, vcc, 1.0, v10, 1.0
	v_mul_f32_e32 v3, v2, v13
	v_fma_f32 v4, -v12, v3, v2
	v_fmac_f32_e32 v3, v4, v13
	v_fma_f32 v2, -v12, v3, v2
	v_div_fmas_f32 v2, v2, v13, v3
	v_div_fixup_f32 v2, v2, v10, 1.0
	v_pk_mul_f32 v[10:11], v[30:31], v[2:3] op_sel_hi:[1,0]
	v_pk_mul_f32 v[12:13], v[32:33], v[2:3] op_sel_hi:[1,0]
	v_lshlrev_b64 v[4:5], 11, v[120:121]
	v_bfe_u32 v3, v13, 16, 1
	v_bfe_u32 v18, v12, 16, 1
	v_add3_u32 v12, v12, v18, s0
	v_add3_u32 v3, v13, v3, s0
	v_mov_b32_e32 v13, v11
	v_lshl_add_u64 v[4:5], v[118:119], 0, v[4:5]
	v_perm_b32 v11, v3, v12, s19
	v_cvt_pk_bf16_f32 v10, v10, v13
	v_lshl_add_u64 v[4:5], v[4:5], 0, v[0:1]
	global_store_dwordx2 v[4:5], v[10:11], off
	v_pk_mul_f32 v[10:11], v[26:27], v[2:3] op_sel_hi:[1,0]
	v_pk_mul_f32 v[12:13], v[28:29], v[2:3] op_sel_hi:[1,0]
	v_bfe_u32 v0, v13, 16, 1
	v_bfe_u32 v3, v12, 16, 1
	v_add3_u32 v3, v12, v3, s0
	v_add3_u32 v0, v13, v0, s0
	v_mov_b32_e32 v12, v11
	v_perm_b32 v11, v0, v3, s19
	v_cvt_pk_bf16_f32 v10, v10, v12
	global_store_dwordx2 v[4:5], v[10:11], off offset:32
	v_pk_mul_f32 v[10:11], v[14:15], v[2:3] op_sel_hi:[1,0]
	v_pk_mul_f32 v[12:13], v[16:17], v[2:3] op_sel_hi:[1,0]
	v_bfe_u32 v0, v13, 16, 1
	v_bfe_u32 v3, v12, 16, 1
	v_add3_u32 v3, v12, v3, s0
	v_add3_u32 v0, v13, v0, s0
	v_mov_b32_e32 v12, v11
	v_perm_b32 v11, v0, v3, s19
	v_cvt_pk_bf16_f32 v10, v10, v12
	v_pk_mul_f32 v[6:7], v[6:7], v[2:3] op_sel_hi:[1,0]
	v_pk_mul_f32 v[2:3], v[8:9], v[2:3] op_sel_hi:[1,0]
	global_store_dwordx2 v[4:5], v[10:11], off offset:64
	v_cvt_pk_bf16_f32 v3, v2, v3
	v_cvt_pk_bf16_f32 v2, v6, v7
	global_store_dwordx2 v[4:5], v[2:3], off offset:96
	s_cbranch_scc1 .LBB0_423

.LBB0_428:
	v_ashrrev_i32_e32 v3, 31, v2
	s_waitcnt vmcnt(0)
	v_lshlrev_b64 v[20:21], 11, v[2:3]
	v_lshl_or_b32 v20, v4, 1, v20
	v_lshl_add_u64 v[24:25], s[10:11], 0, v[20:21]
	v_lshl_add_u64 v[28:29], s[38:39], 0, v[20:21]
	s_waitcnt lgkmcnt(0)
	global_load_dwordx4 v[12:15], v[24:25], off offset:16
	global_load_dwordx4 v[16:19], v[28:29], off offset:16
	v_lshl_add_u64 v[32:33], s[8:9], 0, v[20:21]
	global_load_dwordx4 v[20:23], v[32:33], off offset:16
	s_nop 0
	global_load_dwordx4 v[24:27], v[24:25], off
	s_nop 0
	global_load_dwordx4 v[28:31], v[28:29], off
	s_nop 0
	global_load_dwordx4 v[32:35], v[32:33], off
	s_nop 0
	global_load_dwordx4 v[36:39], v[6:7], off offset:48
	global_load_dwordx4 v[40:43], v[6:7], off offset:32
	global_load_dwordx4 v[44:47], v[6:7], off offset:16
	global_load_dwordx4 v[48:51], v[6:7], off
	s_movk_i32 s2, 0x43ff
	s_waitcnt vmcnt(7)
	v_and_b32_e32 v57, 0xffff0000, v20
	s_waitcnt vmcnt(6)
	v_and_b32_e32 v67, 0xffff0000, v25
	s_waitcnt vmcnt(5)
	v_and_b32_e32 v65, 0xffff0000, v28
	v_lshlrev_b32_e32 v64, 16, v28
	v_and_b32_e32 v53, 0xffff0000, v12
	v_lshlrev_b32_e32 v52, 16, v12
	v_and_b32_e32 v55, 0xffff0000, v16
	v_lshlrev_b32_e32 v54, 16, v16
	v_and_b32_e32 v59, 0xffff0000, v13
	v_lshlrev_b32_e32 v58, 16, v13
	v_and_b32_e32 v13, 0xffff0000, v17
	v_lshlrev_b32_e32 v12, 16, v17
	v_and_b32_e32 v17, 0xffff0000, v14
	v_lshlrev_b32_e32 v16, 16, v14
	v_and_b32_e32 v61, 0xffff0000, v18
	v_lshlrev_b32_e32 v60, 16, v18
	v_and_b32_e32 v63, 0xffff0000, v15
	v_lshlrev_b32_e32 v62, 16, v15
	v_and_b32_e32 v15, 0xffff0000, v19
	v_lshlrev_b32_e32 v14, 16, v19
	v_and_b32_e32 v19, 0xffff0000, v24
	v_lshlrev_b32_e32 v18, 16, v24
	v_lshlrev_b32_e32 v66, 16, v25
	v_and_b32_e32 v25, 0xffff0000, v29
	v_lshlrev_b32_e32 v24, 16, v29
	v_pk_add_f32 v[18:19], v[18:19], v[64:65]
	v_pk_add_f32 v[14:15], v[62:63], v[14:15]
	v_pk_add_f32 v[24:25], v[66:67], v[24:25]
	v_pk_mul_f32 v[62:63], v[18:19], v[18:19]
	v_and_b32_e32 v29, 0xffff0000, v26
	v_lshlrev_b32_e32 v28, 16, v26
	v_and_b32_e32 v69, 0xffff0000, v30
	v_lshlrev_b32_e32 v68, 16, v30
	v_pk_mul_f32 v[64:65], v[24:25], v[24:25]
	v_add_f32_e32 v0, v62, v63
	v_pk_add_f32 v[28:29], v[28:29], v[68:69]
	v_add_f32_e32 v0, v64, v0
	v_and_b32_e32 v71, 0xffff0000, v27
	v_lshlrev_b32_e32 v70, 16, v27
	v_and_b32_e32 v27, 0xffff0000, v31
	v_lshlrev_b32_e32 v26, 16, v31
	v_pk_mul_f32 v[66:67], v[28:29], v[28:29]
	v_add_f32_e32 v0, v65, v0
	v_pk_add_f32 v[26:27], v[70:71], v[26:27]
	v_add_f32_e32 v0, v66, v0
	v_pk_mul_f32 v[68:69], v[26:27], v[26:27]
	v_add_f32_e32 v0, v67, v0
	v_pk_add_f32 v[30:31], v[52:53], v[54:55]
	v_add_f32_e32 v0, v68, v0
	v_pk_mul_f32 v[52:53], v[30:31], v[30:31]
	v_add_f32_e32 v0, v69, v0
	v_pk_add_f32 v[12:13], v[58:59], v[12:13]
	v_add_f32_e32 v0, v52, v0
	v_pk_mul_f32 v[54:55], v[12:13], v[12:13]
	v_add_f32_e32 v0, v53, v0
	v_pk_add_f32 v[16:17], v[16:17], v[60:61]
	v_add_f32_e32 v0, v54, v0
	v_pk_mul_f32 v[58:59], v[16:17], v[16:17]
	v_add_f32_e32 v0, v55, v0
	v_add_f32_e32 v0, v58, v0
	v_pk_mul_f32 v[60:61], v[14:15], v[14:15]
	v_add_f32_e32 v0, v59, v0
	v_add_f32_e32 v0, v60, v0
	v_add_f32_e32 v0, v61, v0
	ds_bpermute_b32 v54, v5, v0
	v_lshlrev_b32_e32 v56, 16, v20
	v_and_b32_e32 v53, 0xffff0000, v21
	v_lshlrev_b32_e32 v52, 16, v21
	v_and_b32_e32 v21, 0xffff0000, v22
	s_waitcnt lgkmcnt(0)
	v_add_f32_e32 v0, v0, v54
	ds_bpermute_b32 v58, v10, v0
	v_lshlrev_b32_e32 v20, 16, v22
	s_waitcnt vmcnt(4)
	v_and_b32_e32 v55, 0xffff0000, v32
	v_lshlrev_b32_e32 v54, 16, v32
	v_and_b32_e32 v59, 0xffff0000, v33
	s_waitcnt lgkmcnt(0)
	v_add_f32_e32 v0, v0, v58
	ds_bpermute_b32 v22, v11, v0
	v_lshlrev_b32_e32 v58, 16, v33
	v_and_b32_e32 v33, 0xffff0000, v34
	v_lshlrev_b32_e32 v32, 16, v34
	v_and_b32_e32 v61, 0xffff0000, v23
	s_waitcnt lgkmcnt(0)
	v_add_f32_e32 v0, v0, v22
	v_fmamk_f32 v0, v0, 0x3c000000, v162
	v_mul_f32_e32 v22, 0x4b800000, v0
	v_cmp_gt_f32_e32 vcc, s15, v0
	v_lshlrev_b32_e32 v60, 16, v23
	v_and_b32_e32 v23, 0xffff0000, v35
	v_cndmask_b32_e32 v0, v0, v22, vcc
	v_rsq_f32_e32 v0, v0
	v_lshlrev_b32_e32 v22, 16, v35
	v_mul_f32_e32 v34, 0x45800000, v0
	v_cndmask_b32_e32 v0, v0, v34, vcc
	v_pk_mul_f32 v[18:19], v[18:19], v[0:1] op_sel_hi:[1,0]
	v_pk_mul_f32 v[24:25], v[24:25], v[0:1] op_sel_hi:[1,0]
	v_pk_mul_f32 v[12:13], v[12:13], v[0:1] op_sel_hi:[1,0]
	v_pk_mul_f32 v[28:29], v[28:29], v[0:1] op_sel_hi:[1,0]
	v_pk_mul_f32 v[16:17], v[16:17], v[0:1] op_sel_hi:[1,0]
	v_pk_mul_f32 v[26:27], v[26:27], v[0:1] op_sel_hi:[1,0]
	v_pk_mul_f32 v[14:15], v[14:15], v[0:1] op_sel_hi:[1,0]
	s_waitcnt vmcnt(0)
	v_pk_mul_f32 v[18:19], v[48:49], v[18:19]
	v_pk_mul_f32 v[24:25], v[50:51], v[24:25]
	v_pk_mul_f32 v[12:13], v[42:43], v[12:13]
	v_pk_mul_f32 v[28:29], v[44:45], v[28:29]
	v_pk_mul_f32 v[16:17], v[36:37], v[16:17]
	v_pk_mul_f32 v[26:27], v[46:47], v[26:27]
	v_pk_mul_f32 v[14:15], v[38:39], v[14:15]
	v_pk_mul_f32 v[18:19], v[18:19], v[54:55]
	v_pk_mul_f32 v[24:25], v[24:25], v[58:59]
	v_pk_mul_f32 v[34:35], v[12:13], v[52:53]
	v_pk_mul_f32 v[12:13], v[28:29], v[32:33]
	v_pk_mul_f32 v[16:17], v[16:17], v[20:21]
	v_pk_mul_f32 v[20:21], v[26:27], v[22:23]
	v_pk_mul_f32 v[30:31], v[30:31], v[0:1] op_sel_hi:[1,0]
	v_pk_mul_f32 v[22:23], v[14:15], v[60:61]
	v_pk_mul_f32 v[30:31], v[40:41], v[30:31]
	v_cvt_pk_bf16_f32 v15, v20, v21
	v_cvt_pk_bf16_f32 v14, v12, v13
	v_cvt_pk_bf16_f32 v13, v24, v25
	v_cvt_pk_bf16_f32 v12, v18, v19
	v_pk_mul_f32 v[30:31], v[30:31], v[56:57]
	v_cvt_pk_bf16_f32 v19, v22, v23
	v_cvt_pk_bf16_f32 v18, v16, v17
	v_cvt_pk_bf16_f32 v17, v34, v35
	v_lshl_add_u64 v[20:21], s[56:57], 0, v[2:3]
	v_add_u32_e32 v2, s14, v2
	v_lshlrev_b64 v[20:21], 11, v[20:21]
	v_cmp_lt_i32_e32 vcc, s2, v2
	v_cvt_pk_bf16_f32 v16, v30, v31
	v_lshl_add_u64 v[20:21], v[8:9], 0, v[20:21]
	s_or_b64 s[6:7], vcc, s[6:7]
	global_store_dwordx4 v[20:21], v[12:15], off
	global_store_dwordx4 v[20:21], v[16:19], off offset:16
	s_andn2_b64 exec, exec, s[6:7]
	s_cbranch_execnz .LBB0_428

.LBB0_466:
	s_or_b64 exec, exec, s[4:5]
	s_waitcnt lgkmcnt(0)
	ds_read_u16 v68, v43
	v_mul_f32_e32 v67, v64, v102
	v_rcp_f32_e32 v66, v67
	v_pk_add_f32 v[64:65], v[64:65], 1.0 op_sel_hi:[1,0] neg_lo:[1,0] neg_hi:[1,0]
	v_pk_add_f32 v[62:63], v[62:63], 1.0 op_sel_hi:[1,0] neg_lo:[1,0] neg_hi:[1,0]
	s_waitcnt lgkmcnt(0)
	v_lshlrev_b32_e32 v68, 16, v68
	v_mul_f32_e32 v67, v67, v68
	v_bfe_u32 v68, v67, 16, 1
	v_add3_u32 v67, v67, v68, s0
	v_mul_f32_e32 v68, v116, v102
	ds_write_b16_d16_hi v43, v67
	v_rcp_f32_e32 v67, v68
	v_pk_add_f32 v[60:61], v[60:61], 1.0 op_sel_hi:[1,0] neg_lo:[1,0] neg_hi:[1,0]
	v_pk_add_f32 v[58:59], v[58:59], 1.0 op_sel_hi:[1,0] neg_lo:[1,0] neg_hi:[1,0]
	v_pk_add_f32 v[56:57], v[56:57], 1.0 op_sel_hi:[1,0] neg_lo:[1,0] neg_hi:[1,0]
	v_pk_mul_f32 v[64:65], v[64:65], v[66:67]
	v_pk_add_f32 v[54:55], v[54:55], 1.0 op_sel_hi:[1,0] neg_lo:[1,0] neg_hi:[1,0]
	v_and_b32_sdwa v67, v64, v190 dst_sel:DWORD dst_unused:UNUSED_PAD src0_sel:WORD_1 src1_sel:DWORD
	v_add3_u32 v67, v64, v67, s0
	v_lshrrev_b32_e32 v64, 16, v67
	ds_write_b16 v43, v64 offset:17408
	ds_read_u16 v64, v45
	v_and_b32_sdwa v66, v65, v190 dst_sel:DWORD dst_unused:UNUSED_PAD src0_sel:WORD_1 src1_sel:DWORD
	v_add3_u32 v66, v65, v66, s0
	v_lshrrev_b32_e32 v65, 16, v66
	v_pk_add_f32 v[52:53], v[52:53], 1.0 op_sel_hi:[1,0] neg_lo:[1,0] neg_hi:[1,0]
	s_waitcnt lgkmcnt(0)
	v_lshlrev_b32_e32 v64, 16, v64
	v_mul_f32_e32 v64, v68, v64
	v_bfe_u32 v68, v64, 16, 1
	v_add3_u32 v64, v64, v68, s0
	ds_write_b16_d16_hi v45, v64
	ds_write_b16 v45, v65 offset:17408
	ds_read_u16 v68, v76
	v_mul_f32_e32 v65, v115, v102
	v_rcp_f32_e32 v64, v65
	v_pk_add_f32 v[50:51], v[50:51], 1.0 op_sel_hi:[1,0] neg_lo:[1,0] neg_hi:[1,0]
	s_waitcnt lgkmcnt(0)
	v_lshlrev_b32_e32 v68, 16, v68
	v_mul_f32_e32 v65, v65, v68
	v_bfe_u32 v68, v65, 16, 1
	v_add3_u32 v65, v65, v68, s0
	v_mul_f32_e32 v68, v114, v102
	ds_write_b16_d16_hi v76, v65
	v_rcp_f32_e32 v65, v68
	s_nop 0
	v_pk_mul_f32 v[62:63], v[62:63], v[64:65]
	s_nop 0
	v_and_b32_sdwa v65, v62, v190 dst_sel:DWORD dst_unused:UNUSED_PAD src0_sel:WORD_1 src1_sel:DWORD
	v_add3_u32 v65, v62, v65, s0
	v_lshrrev_b32_e32 v62, 16, v65
	ds_write_b16 v76, v62 offset:17408
	ds_read_u16 v62, v77
	v_and_b32_sdwa v64, v63, v190 dst_sel:DWORD dst_unused:UNUSED_PAD src0_sel:WORD_1 src1_sel:DWORD
	v_add3_u32 v64, v63, v64, s0
	v_lshrrev_b32_e32 v63, 16, v64
	s_waitcnt lgkmcnt(0)
	v_lshlrev_b32_e32 v62, 16, v62
	v_mul_f32_e32 v62, v68, v62
	v_bfe_u32 v68, v62, 16, 1
	v_add3_u32 v62, v62, v68, s0
	ds_write_b16_d16_hi v77, v62
	ds_write_b16 v77, v63 offset:17408
	ds_read_u16 v68, v78
	v_mul_f32_e32 v63, v113, v102
	v_rcp_f32_e32 v62, v63
	s_waitcnt lgkmcnt(0)
	v_lshlrev_b32_e32 v68, 16, v68
	v_mul_f32_e32 v63, v63, v68
	v_bfe_u32 v68, v63, 16, 1
	v_add3_u32 v63, v63, v68, s0
	v_mul_f32_e32 v68, v112, v102
	ds_write_b16_d16_hi v78, v63
	v_rcp_f32_e32 v63, v68
	s_nop 0
	v_pk_mul_f32 v[60:61], v[60:61], v[62:63]
	s_nop 0
	v_and_b32_sdwa v63, v60, v190 dst_sel:DWORD dst_unused:UNUSED_PAD src0_sel:WORD_1 src1_sel:DWORD
	v_add3_u32 v63, v60, v63, s0
	v_lshrrev_b32_e32 v60, 16, v63
	ds_write_b16 v78, v60 offset:17408
	ds_read_u16 v60, v79
	v_and_b32_sdwa v62, v61, v190 dst_sel:DWORD dst_unused:UNUSED_PAD src0_sel:WORD_1 src1_sel:DWORD
	v_add3_u32 v62, v61, v62, s0
	v_lshrrev_b32_e32 v61, 16, v62
	s_waitcnt lgkmcnt(0)
	v_lshlrev_b32_e32 v60, 16, v60
	v_mul_f32_e32 v60, v68, v60
	v_bfe_u32 v68, v60, 16, 1
	v_add3_u32 v60, v60, v68, s0
	ds_write_b16_d16_hi v79, v60
	ds_write_b16 v79, v61 offset:17408
	ds_read_u16 v68, v80
	v_mul_f32_e32 v61, v111, v102
	v_rcp_f32_e32 v60, v61
	s_waitcnt lgkmcnt(0)
	v_lshlrev_b32_e32 v68, 16, v68
	v_mul_f32_e32 v61, v61, v68
	v_bfe_u32 v68, v61, 16, 1
	v_add3_u32 v61, v61, v68, s0
	v_mul_f32_e32 v68, v110, v102
	ds_write_b16_d16_hi v80, v61
	v_rcp_f32_e32 v61, v68
	s_nop 0
	v_pk_mul_f32 v[58:59], v[58:59], v[60:61]
	s_nop 0
	v_and_b32_sdwa v61, v58, v190 dst_sel:DWORD dst_unused:UNUSED_PAD src0_sel:WORD_1 src1_sel:DWORD
	v_and_b32_sdwa v60, v59, v190 dst_sel:DWORD dst_unused:UNUSED_PAD src0_sel:WORD_1 src1_sel:DWORD
	v_add3_u32 v58, v58, v61, s0
	v_add3_u32 v59, v59, v60, s0
	v_lshrrev_b32_e32 v60, 16, v58
	ds_write_b16 v80, v60 offset:17408
	ds_read_u16 v60, v81
	v_lshrrev_b32_e32 v61, 16, v59
	s_waitcnt lgkmcnt(0)
	v_lshlrev_b32_e32 v60, 16, v60
	v_mul_f32_e32 v60, v68, v60
	v_bfe_u32 v68, v60, 16, 1
	v_add3_u32 v60, v60, v68, s0
	ds_write_b16_d16_hi v81, v60
	ds_write_b16 v81, v61 offset:17408
	v_perm_b32 v61, v59, v58, s19
	v_perm_b32 v60, v62, v63, s19
	v_perm_b32 v59, v64, v65, s19
	v_perm_b32 v58, v66, v67, s19
	ds_write_b128 v94, v[58:61] offset:34816
	ds_read_u16 v60, v82
	v_mul_f32_e32 v59, v109, v102
	v_rcp_f32_e32 v58, v59
	s_waitcnt lgkmcnt(0)
	v_lshlrev_b32_e32 v60, 16, v60
	v_mul_f32_e32 v59, v59, v60
	v_bfe_u32 v60, v59, 16, 1
	v_add3_u32 v59, v59, v60, s0
	v_mul_f32_e32 v60, v108, v102
	ds_write_b16_d16_hi v82, v59
	v_rcp_f32_e32 v59, v60
	s_nop 0
	v_pk_mul_f32 v[56:57], v[56:57], v[58:59]
	s_nop 0
	v_and_b32_sdwa v59, v56, v190 dst_sel:DWORD dst_unused:UNUSED_PAD src0_sel:WORD_1 src1_sel:DWORD
	v_add3_u32 v59, v56, v59, s0
	v_lshrrev_b32_e32 v56, 16, v59
	ds_write_b16 v82, v56 offset:17408
	ds_read_u16 v56, v43 offset:2448
	v_and_b32_sdwa v58, v57, v190 dst_sel:DWORD dst_unused:UNUSED_PAD src0_sel:WORD_1 src1_sel:DWORD
	v_add3_u32 v58, v57, v58, s0
	v_lshrrev_b32_e32 v57, 16, v58
	s_waitcnt lgkmcnt(0)
	v_lshlrev_b32_e32 v56, 16, v56
	v_mul_f32_e32 v56, v60, v56
	v_bfe_u32 v60, v56, 16, 1
	v_add3_u32 v56, v56, v60, s0
	ds_write_b16_d16_hi v43, v56 offset:2448
	ds_write_b16 v43, v57 offset:19856
	ds_read_u16 v60, v43 offset:2720
	ds_read_u16 v61, v43 offset:2992
	v_mul_f32_e32 v57, v107, v102
	v_rcp_f32_e32 v56, v57
	s_waitcnt lgkmcnt(1)
	v_lshlrev_b32_e32 v60, 16, v60
	v_mul_f32_e32 v57, v57, v60
	v_bfe_u32 v60, v57, 16, 1
	v_add3_u32 v57, v57, v60, s0
	v_mul_f32_e32 v60, v106, v102
	ds_write_b16_d16_hi v43, v57 offset:2720
	v_rcp_f32_e32 v57, v60
	s_waitcnt lgkmcnt(1)
	v_lshlrev_b32_e32 v61, 16, v61
	v_mul_f32_e32 v60, v60, v61
	v_bfe_u32 v61, v60, 16, 1
	v_pk_mul_f32 v[54:55], v[54:55], v[56:57]
	v_add3_u32 v60, v60, v61, s0
	v_and_b32_sdwa v57, v54, v190 dst_sel:DWORD dst_unused:UNUSED_PAD src0_sel:WORD_1 src1_sel:DWORD
	v_and_b32_sdwa v56, v55, v190 dst_sel:DWORD dst_unused:UNUSED_PAD src0_sel:WORD_1 src1_sel:DWORD
	v_add3_u32 v57, v54, v57, s0
	v_add3_u32 v56, v55, v56, s0
	v_lshrrev_b32_e32 v54, 16, v57
	ds_write_b16_d16_hi v43, v60 offset:2992
	v_lshrrev_b32_e32 v55, 16, v56
	ds_write_b16 v43, v54 offset:20128
	ds_write_b16 v43, v55 offset:20400
	ds_read_u16 v60, v43 offset:3264
	ds_read_u16 v61, v43 offset:3536
	v_mul_f32_e32 v55, v105, v102
	v_rcp_f32_e32 v54, v55
	s_waitcnt lgkmcnt(1)
	v_lshlrev_b32_e32 v60, 16, v60
	v_mul_f32_e32 v55, v55, v60
	v_bfe_u32 v60, v55, 16, 1
	v_add3_u32 v55, v55, v60, s0
	v_mul_f32_e32 v60, v104, v102
	ds_write_b16_d16_hi v43, v55 offset:3264
	v_rcp_f32_e32 v55, v60
	s_waitcnt lgkmcnt(1)
	v_lshlrev_b32_e32 v61, 16, v61
	v_mul_f32_e32 v60, v60, v61
	v_bfe_u32 v61, v60, 16, 1
	v_pk_mul_f32 v[52:53], v[52:53], v[54:55]
	v_add3_u32 v60, v60, v61, s0
	v_and_b32_sdwa v55, v52, v190 dst_sel:DWORD dst_unused:UNUSED_PAD src0_sel:WORD_1 src1_sel:DWORD
	v_and_b32_sdwa v54, v53, v190 dst_sel:DWORD dst_unused:UNUSED_PAD src0_sel:WORD_1 src1_sel:DWORD
	v_add3_u32 v55, v52, v55, s0
	v_add3_u32 v54, v53, v54, s0
	v_lshrrev_b32_e32 v52, 16, v55
	ds_write_b16_d16_hi v43, v60 offset:3536
	v_lshrrev_b32_e32 v53, 16, v54
	ds_write_b16 v43, v52 offset:20672
	ds_write_b16 v43, v53 offset:20944
	ds_read_u16 v60, v43 offset:3808
	ds_read_u16 v61, v43 offset:4080
	v_mul_f32_e32 v53, v103, v102
	v_rcp_f32_e32 v52, v53
	s_waitcnt lgkmcnt(1)
	v_lshlrev_b32_e32 v60, 16, v60
	v_mul_f32_e32 v53, v53, v60
	v_bfe_u32 v60, v53, 16, 1
	v_add3_u32 v53, v53, v60, s0
	v_mul_f32_e32 v60, v101, v102
	ds_write_b16_d16_hi v43, v53 offset:3808
	v_rcp_f32_e32 v53, v60
	s_waitcnt lgkmcnt(1)
	v_lshlrev_b32_e32 v61, 16, v61
	v_mul_f32_e32 v60, v60, v61
	v_bfe_u32 v61, v60, 16, 1
	v_pk_mul_f32 v[50:51], v[50:51], v[52:53]
	v_add3_u32 v60, v60, v61, s0
	v_and_b32_sdwa v52, v51, v190 dst_sel:DWORD dst_unused:UNUSED_PAD src0_sel:WORD_1 src1_sel:DWORD
	v_and_b32_sdwa v53, v50, v190 dst_sel:DWORD dst_unused:UNUSED_PAD src0_sel:WORD_1 src1_sel:DWORD
	v_add3_u32 v51, v51, v52, s0
	v_add3_u32 v50, v50, v53, s0
	v_lshrrev_b32_e32 v52, 16, v50
	v_lshrrev_b32_e32 v53, 16, v51
	ds_write_b16_d16_hi v43, v60 offset:4080
	ds_write_b16 v43, v52 offset:21216
	ds_write_b16 v43, v53 offset:21488
	v_perm_b32 v53, v51, v50, s19
	v_perm_b32 v52, v54, v55, s19
	v_perm_b32 v51, v56, v57, s19
	v_perm_b32 v50, v58, v59, s19
	ds_write_b128 v94, v[50:53] offset:34832
	s_waitcnt lgkmcnt(0)
	s_barrier
	s_and_saveexec_b64 s[6:7], s[42:43]
	s_cbranch_execz .LBB0_468
	ds_read_b128 v[50:53], v95
	ds_read_b128 v[54:57], v95 offset:64
	ds_read_b128 v[58:61], v95 offset:128
	ds_read_b128 v[62:65], v95 offset:192
	ds_read_b128 v[66:69], v99 offset:17408
	ds_read_b128 v[102:105], v99 offset:17472
	ds_read_b128 v[106:109], v99 offset:17536
	ds_read_b128 v[110:113], v99 offset:17600
	ds_read_b128 v[114:117], v99 offset:21760
	ds_read_b128 v[118:121], v99 offset:21824
	ds_read_b128 v[126:129], v99 offset:21888
	ds_read_b128 v[130:133], v99 offset:21952
	ds_read_b128 v[134:137], v96 offset:34816
	ds_read_b128 v[138:141], v96 offset:34880
	ds_read_b128 v[142:145], v96 offset:37120
	ds_read_b128 v[146:149], v96 offset:37184
	v_add_u32_e32 v101, v75, v83
	ds_read_b128 v[150:153], v101 offset:53248
	ds_read_b128 v[154:157], v101 offset:53312
	ds_read_b128 v[158:161], v101 offset:55552
	ds_read_b128 v[164:167], v101 offset:55616
	s_waitcnt lgkmcnt(14)
	v_mfma_f32_16x16x32_bf16 v[66:69], v[66:69], v[50:53], 0
	v_mfma_f32_16x16x32_bf16 v[66:69], v[102:105], v[54:57], v[66:69]
	s_waitcnt lgkmcnt(11)
	v_mfma_f32_16x16x32_bf16 v[102:105], v[114:117], v[50:53], 0
	s_waitcnt lgkmcnt(10)
	v_mfma_f32_16x16x32_bf16 v[102:105], v[118:121], v[54:57], v[102:105]
	s_waitcnt lgkmcnt(3)
	v_mfma_f32_16x16x32_bf16 v[22:25], v[134:137], v[150:153], v[22:25]
	s_waitcnt lgkmcnt(1)
	v_mfma_f32_16x16x32_bf16 v[26:29], v[134:137], v[158:161], v[26:29]
	v_mfma_f32_16x16x32_bf16 v[30:33], v[142:145], v[150:153], v[30:33]
	v_mfma_f32_16x16x32_bf16 v[34:37], v[142:145], v[158:161], v[34:37]
	v_mfma_f32_16x16x32_bf16 v[66:69], v[106:109], v[58:61], v[66:69]
	v_mfma_f32_16x16x32_bf16 v[102:105], v[126:129], v[58:61], v[102:105]
	v_mfma_f32_16x16x32_bf16 v[22:25], v[138:141], v[154:157], v[22:25]
	s_waitcnt lgkmcnt(0)
	v_mfma_f32_16x16x32_bf16 v[26:29], v[138:141], v[164:167], v[26:29]
	v_mfma_f32_16x16x32_bf16 v[30:33], v[146:149], v[154:157], v[30:33]
	v_mfma_f32_16x16x32_bf16 v[34:37], v[146:149], v[164:167], v[34:37]
	v_mfma_f32_16x16x32_bf16 v[66:69], v[110:113], v[62:65], v[66:69]
	v_mfma_f32_16x16x32_bf16 v[102:105], v[130:133], v[62:65], v[102:105]
	ds_read_b128 v[106:109], v99 offset:26112
	ds_read_b128 v[110:113], v99 offset:26176
	ds_read_b128 v[114:117], v99 offset:26240
	ds_read_b128 v[118:121], v99 offset:26304
	ds_read_b128 v[126:129], v97 offset:26112
	ds_read_b128 v[130:133], v97 offset:26176
	ds_read_b128 v[134:137], v97 offset:26240
	ds_read_b128 v[138:141], v97 offset:26304
	v_add_u32_e32 v101, 0xd000, v98
	ds_read2_b64 v[142:145], v101 offset1:4
	ds_read2_b64 v[146:149], v101 offset0:8 offset1:12
	ds_read_b128 v[150:153], v99 offset:57856
	ds_read_b128 v[154:157], v99 offset:57920
	ds_read_b128 v[158:161], v99 offset:57984
	ds_read_b128 v[164:167], v99 offset:58048
	v_add_u32_e32 v101, 0xd800, v98
	ds_read2_b64 v[168:171], v101 offset0:32 offset1:36
	ds_read2_b64 v[172:175], v101 offset0:40 offset1:44
	ds_read_b128 v[176:179], v99 offset:62208
	ds_read_b128 v[180:183], v99 offset:62272
	ds_read_b128 v[184:187], v99 offset:62336
	ds_read_b128 v[200:203], v99 offset:62400
	s_waitcnt lgkmcnt(14)
	v_mfma_f32_16x16x32_bf16 v[106:109], v[106:109], v[50:53], 0
	v_cndmask_b32_e64 v101, v66, 0, s[50:51]
	v_cndmask_b32_e64 v122, 0, v67, s[48:49]
	v_cndmask_b32_e64 v123, v68, 0, s[54:55]
	v_cndmask_b32_e64 v124, v69, 0, s[52:53]
	v_mfma_f32_16x16x32_bf16 v[66:69], v[110:113], v[54:57], v[106:109]
	v_cndmask_b32_e64 v223, v102, 0, s[58:59]
	v_mfma_f32_16x16x32_bf16 v[66:69], v[114:117], v[58:61], v[66:69]
	v_cndmask_b32_e64 v106, v103, 0, s[56:57]
	v_cndmask_b32_e64 v107, v104, 0, s[62:63]
	v_cndmask_b32_e64 v108, v105, 0, s[60:61]
	v_mfma_f32_16x16x32_bf16 v[66:69], v[118:121], v[62:65], v[66:69]
	v_mov_b32_e32 v111, v106
	v_mov_b32_e32 v110, v107
	v_mfma_f32_16x16x32_bf16 v[102:105], v[126:129], v[50:53], 0
	v_mov_b32_e32 v116, v108
	s_nop 2
	v_cndmask_b32_e64 v117, v66, 0, s[66:67]
	v_cndmask_b32_e64 v118, v67, 0, s[64:65]
	s_waitcnt lgkmcnt(9)
	v_mfma_f32_16x16x32_bf16 v[106:109], v[150:153], v[50:53], 0
	v_cndmask_b32_e64 v119, v68, 0, s[70:71]
	v_cndmask_b32_e64 v120, v69, 0, s[68:69]
	s_waitcnt lgkmcnt(3)
	v_mfma_f32_16x16x32_bf16 v[50:53], v[176:179], v[50:53], 0
	v_mov_b32_e32 v115, v122
	v_mov_b32_e32 v114, v123
	v_mfma_f32_16x16x32_bf16 v[102:105], v[130:133], v[54:57], v[102:105]
	v_mov_b32_e32 v113, v124
	v_mfma_f32_16x16x32_bf16 v[66:69], v[154:157], v[54:57], v[106:109]
	s_waitcnt lgkmcnt(2)
	v_mfma_f32_16x16x32_bf16 v[50:53], v[180:183], v[54:57], v[50:53]
	v_cvt_pk_bf16_f32 v57, v110, v116
	v_cvt_pk_bf16_f32 v56, v223, v111
	v_cvt_pk_bf16_f32 v55, v114, v113
	v_mfma_f32_16x16x32_bf16 v[102:105], v[134:137], v[58:61], v[102:105]
	v_cvt_pk_bf16_f32 v54, v101, v115
	v_mfma_f32_16x16x32_bf16 v[66:69], v[158:161], v[58:61], v[66:69]
	s_waitcnt lgkmcnt(1)
	v_mfma_f32_16x16x32_bf16 v[50:53], v[184:187], v[58:61], v[50:53]
	v_mfma_f32_16x16x32_bf16 v[102:105], v[138:141], v[62:65], v[102:105]
	v_mfma_f32_16x16x32_bf16 v[66:69], v[164:167], v[62:65], v[66:69]
	s_waitcnt lgkmcnt(0)
	v_mfma_f32_16x16x32_bf16 v[50:53], v[200:203], v[62:65], v[50:53]
	s_nop 4
	v_cndmask_b32_e64 v102, v102, 0, s[74:75]
	v_cndmask_b32_e64 v103, v103, 0, s[72:73]
	v_cndmask_b32_e64 v104, v104, 0, s[78:79]
	v_cndmask_b32_e64 v105, v105, 0, s[76:77]
	v_mfma_f32_16x16x32_bf16 v[58:61], v[142:145], v[54:57], v[66:69]
	v_mfma_f32_16x16x32_bf16 v[50:53], v[168:171], v[54:57], v[50:53]
	v_add_u32_e32 v54, s31, v74
	v_cvt_pk_bf16_f32 v65, v104, v105
	v_cvt_pk_bf16_f32 v64, v102, v103
	v_cvt_pk_bf16_f32 v63, v119, v120
	v_cvt_pk_bf16_f32 v62, v117, v118
	v_cmp_lt_i32_e64 s[4:5], s33, v54
	s_nop 0
	v_mfma_f32_16x16x32_bf16 v[58:61], v[146:149], v[62:65], v[58:61]
	v_cndmask_b32_e64 v55, v205, v206, s[4:5]
	v_add_u32_e32 v55, v55, v0
	v_cndmask_b32_e32 v54, v55, v54, vcc
	v_mfma_f32_16x16x32_bf16 v[50:53], v[172:175], v[62:65], v[50:53]
	v_ashrrev_i32_e32 v55, 31, v54
	v_lshl_add_u64 v[54:55], s[2:3], 0, v[54:55]
	s_nop 1
	v_lshlrev_b64 v[54:55], 11, v[54:55]
	v_lshl_add_u64 v[54:55], v[40:41], 0, v[54:55]
	v_cvt_pk_bf16_f32 v57, v60, v61
	v_cvt_pk_bf16_f32 v56, v58, v59
	global_store_dwordx2 v[54:55], v[56:57], off
	v_mov_b32_e32 v58, v51
	v_mov_b32_e32 v51, v52
	v_cvt_pk_bf16_f32 v51, v51, v53
	v_cvt_pk_bf16_f32 v50, v50, v58
	global_store_dwordx2 v[54:55], v[50:51], off offset:32
.LBB0_468:
	s_or_b64 exec, exec, s[6:7]
	s_barrier
	s_and_saveexec_b64 s[4:5], s[42:43]
	s_cbranch_execz .LBB0_449
	ds_read_b128 v[50:53], v84
	s_waitcnt lgkmcnt(0)
	v_pk_mul_f32 v[22:23], v[22:23], v[50:51]
	v_pk_mul_f32 v[24:25], v[24:25], v[52:53]
	v_pk_mul_f32 v[26:27], v[26:27], v[50:51]
	v_pk_mul_f32 v[28:29], v[28:29], v[52:53]
	v_cvt_pk_bf16_f32 v55, v24, v25
	v_cvt_pk_bf16_f32 v54, v22, v23
	v_cvt_pk_bf16_f32 v51, v28, v29
	v_cvt_pk_bf16_f32 v50, v26, v27
	ds_write_b64 v100, v[54:55] offset:57856
	ds_write_b64 v100, v[50:51] offset:62208
	ds_read_b128 v[50:53], v85
	s_waitcnt lgkmcnt(0)
	v_pk_mul_f32 v[30:31], v[30:31], v[50:51]
	v_pk_mul_f32 v[32:33], v[32:33], v[52:53]
	v_pk_mul_f32 v[34:35], v[34:35], v[50:51]
	v_pk_mul_f32 v[36:37], v[36:37], v[52:53]
	v_cvt_pk_bf16_f32 v55, v32, v33
	v_cvt_pk_bf16_f32 v54, v30, v31
	v_cvt_pk_bf16_f32 v51, v36, v37
	v_cvt_pk_bf16_f32 v50, v34, v35
	ds_write_b64 v100, v[54:55] offset:57888
	ds_write_b64 v100, v[50:51] offset:62240
	s_branch .LBB0_449

.LBB0_472:
	s_or_b64 exec, exec, s[10:11]
	s_brev_b32 s10, -2
	v_bfi_b32 v2, s10, v6, v2
	v_mul_f32_e32 v0, 0.5, v0
	v_add_f32_e32 v2, 1.0, v2
	v_mul_f32_e32 v0, v0, v2
	v_mul_f32_e32 v2, 0.5, v3
	v_bfi_b32 v3, s10, v10, v7
	v_add_f32_e32 v3, 1.0, v3
	v_mul_f32_e32 v2, v2, v3
	v_mul_f32_e32 v3, 0.5, v4
	v_bfi_b32 v4, s10, v11, v8
	v_add_f32_e32 v4, 1.0, v4
	v_mul_f32_e32 v3, v3, v4
	v_mul_f32_e32 v4, 0.5, v5
	v_bfi_b32 v5, s10, v12, v9
	v_readlane_b32 s10, v253, 28
	v_readlane_b32 s11, v253, 29
	v_add_f32_e32 v5, 1.0, v5
	v_mul_f32_e32 v4, v4, v5
	v_lshl_add_u64 v[18:19], v[18:19], 0, s[10:11]
	v_readlane_b32 s10, v254, 44
	v_readlane_b32 s11, v254, 45
	v_lshl_add_u64 v[20:21], v[20:21], 0, s[10:11]
	v_readlane_b32 s10, v254, 46
	v_readlane_b32 s11, v254, 47
	s_add_u32 s4, s4, s10
	s_addc_u32 s5, s5, s11
	s_add_u32 s6, s6, s10
	s_addc_u32 s7, s7, s11
	s_mov_b64 s[10:11], 0x43ffff
	v_cmp_lt_u64_e32 vcc, s[10:11], v[18:19]
	v_readlane_b32 s10, v254, 50
	v_cvt_pk_bf16_f32 v3, v3, v4
	v_cvt_pk_bf16_f32 v2, v0, v2
	v_readlane_b32 s11, v254, 51
	global_store_dwordx2 v[24:25], v[2:3], off
	s_or_b64 s[8:9], vcc, s[8:9]
	v_lshl_add_u64 v[24:25], v[24:25], 0, s[10:11]
	s_andn2_b64 exec, exec, s[8:9]
	s_cbranch_execz .LBB0_489

.LBB0_554:
	ds_bpermute_b32 v0, v124, v141
	v_readlane_b32 s4, v254, 38
	v_readlane_b32 s5, v254, 39
	s_add_i32 s6, s6, 1
	s_cmp_eq_u32 s6, 8
	s_waitcnt lgkmcnt(0)
	v_add_f32_e32 v0, v141, v0
	ds_bpermute_b32 v2, v129, v0
	s_waitcnt lgkmcnt(0)
	v_add_f32_e32 v0, v0, v2
	v_div_scale_f32 v4, s[2:3], v0, v0, 1.0
	v_rcp_f32_e32 v5, v4
	v_div_scale_f32 v6, vcc, 1.0, v0, 1.0
	v_lshlrev_b64 v[2:3], 11, v[112:113]
	v_fma_f32 v7, -v4, v5, 1.0
	v_fmac_f32_e32 v5, v7, v5
	v_mul_f32_e32 v7, v6, v5
	v_fma_f32 v8, -v4, v7, v6
	v_fmac_f32_e32 v7, v8, v5
	v_fma_f32 v4, -v4, v7, v6
	v_div_fmas_f32 v4, v4, v5, v7
	v_div_fixup_f32 v4, v4, v0, 1.0
	v_pk_mul_f32 v[8:9], v[76:77], v[4:5] op_sel_hi:[1,0]
	v_pk_mul_f32 v[6:7], v[74:75], v[4:5] op_sel_hi:[1,0]
	v_bfe_u32 v0, v9, 16, 1
	v_bfe_u32 v5, v8, 16, 1
	v_add3_u32 v5, v8, v5, s0
	v_add3_u32 v0, v9, v0, s0
	v_mov_b32_e32 v10, v7
	v_perm_b32 v7, v0, v5, s19
	v_lshl_add_u64 v[2:3], s[4:5], 0, v[2:3]
	v_lshlrev_b32_e32 v0, 1, v131
	v_cvt_pk_bf16_f32 v6, v6, v10
	v_lshl_add_u64 v[2:3], v[2:3], 0, v[0:1]
	global_store_dwordx2 v[2:3], v[6:7], off
	v_pk_mul_f32 v[6:7], v[70:71], v[4:5] op_sel_hi:[1,0]
	v_pk_mul_f32 v[8:9], v[72:73], v[4:5] op_sel_hi:[1,0]
	v_bfe_u32 v5, v9, 16, 1
	v_bfe_u32 v10, v8, 16, 1
	v_mov_b32_e32 v11, v7
	v_add3_u32 v7, v8, v10, s0
	v_add3_u32 v5, v9, v5, s0
	v_perm_b32 v7, v5, v7, s19
	v_cvt_pk_bf16_f32 v6, v6, v11
	global_store_dwordx2 v[2:3], v[6:7], off offset:32
	v_pk_mul_f32 v[6:7], v[66:67], v[4:5] op_sel_hi:[1,0]
	v_pk_mul_f32 v[8:9], v[68:69], v[4:5] op_sel_hi:[1,0]
	v_bfe_u32 v10, v8, 16, 1
	v_mov_b32_e32 v11, v7
	v_add3_u32 v7, v8, v10, s0
	ds_bpermute_b32 v8, v124, v140
	v_bfe_u32 v5, v9, 16, 1
	v_add3_u32 v5, v9, v5, s0
	s_waitcnt lgkmcnt(0)
	v_add_f32_e32 v8, v140, v8
	ds_bpermute_b32 v13, v129, v8
	v_perm_b32 v7, v5, v7, s19
	v_cvt_pk_bf16_f32 v6, v6, v11
	global_store_dwordx2 v[2:3], v[6:7], off offset:64
	v_pk_mul_f32 v[6:7], v[62:63], v[4:5] op_sel_hi:[1,0]
	v_pk_mul_f32 v[4:5], v[64:65], v[4:5] op_sel_hi:[1,0]
	s_waitcnt lgkmcnt(0)
	v_add_f32_e32 v8, v8, v13
	v_div_scale_f32 v9, s[2:3], v8, v8, 1.0
	v_rcp_f32_e32 v10, v9
	v_cvt_pk_bf16_f32 v5, v4, v5
	v_cvt_pk_bf16_f32 v4, v6, v7
	global_store_dwordx2 v[2:3], v[4:5], off offset:96
	v_fma_f32 v2, -v9, v10, 1.0
	v_fmac_f32_e32 v10, v2, v10
	v_div_scale_f32 v2, vcc, 1.0, v8, 1.0
	v_mul_f32_e32 v3, v2, v10
	v_fma_f32 v4, -v9, v3, v2
	v_fmac_f32_e32 v3, v4, v10
	v_fma_f32 v2, -v9, v3, v2
	v_div_fmas_f32 v2, v2, v10, v3
	v_div_fixup_f32 v2, v2, v8, 1.0
	v_pk_mul_f32 v[6:7], v[58:59], v[2:3] op_sel_hi:[1,0]
	v_pk_mul_f32 v[8:9], v[60:61], v[2:3] op_sel_hi:[1,0]
	v_lshlrev_b64 v[4:5], 11, v[110:111]
	v_bfe_u32 v3, v9, 16, 1
	v_bfe_u32 v10, v8, 16, 1
	v_mov_b32_e32 v11, v7
	v_add3_u32 v7, v8, v10, s0
	v_add3_u32 v3, v9, v3, s0
	v_lshl_add_u64 v[4:5], s[4:5], 0, v[4:5]
	v_perm_b32 v7, v3, v7, s19
	v_cvt_pk_bf16_f32 v6, v6, v11
	v_lshl_add_u64 v[4:5], v[4:5], 0, v[0:1]
	global_store_dwordx2 v[4:5], v[6:7], off
	v_pk_mul_f32 v[6:7], v[54:55], v[2:3] op_sel_hi:[1,0]
	v_pk_mul_f32 v[8:9], v[56:57], v[2:3] op_sel_hi:[1,0]
	v_bfe_u32 v0, v9, 16, 1
	v_bfe_u32 v3, v8, 16, 1
	v_mov_b32_e32 v10, v7
	v_add3_u32 v3, v8, v3, s0
	v_add3_u32 v0, v9, v0, s0
	v_perm_b32 v7, v0, v3, s19
	v_cvt_pk_bf16_f32 v6, v6, v10
	global_store_dwordx2 v[4:5], v[6:7], off offset:32
	v_pk_mul_f32 v[6:7], v[50:51], v[2:3] op_sel_hi:[1,0]
	v_pk_mul_f32 v[8:9], v[52:53], v[2:3] op_sel_hi:[1,0]
	v_bfe_u32 v0, v9, 16, 1
	v_bfe_u32 v3, v8, 16, 1
	v_mov_b32_e32 v10, v7
	v_add3_u32 v3, v8, v3, s0
	v_add3_u32 v0, v9, v0, s0
	v_perm_b32 v7, v0, v3, s19
	v_cvt_pk_bf16_f32 v6, v6, v10
	global_store_dwordx2 v[4:5], v[6:7], off offset:64
	v_pk_mul_f32 v[6:7], v[46:47], v[2:3] op_sel_hi:[1,0]
	v_pk_mul_f32 v[2:3], v[48:49], v[2:3] op_sel_hi:[1,0]
	v_cvt_pk_bf16_f32 v3, v2, v3
	v_cvt_pk_bf16_f32 v2, v6, v7
	global_store_dwordx2 v[4:5], v[2:3], off offset:96
	s_cbranch_scc1 .LBB0_588
.LBB0_555:
	s_lshl_b32 s2, s6, 4
	s_add_i32 s2, s7, s2
	s_ashr_i32 s3, s2, 4
	v_mov_b32_e32 v58, v163
	s_mul_i32 s2, s3, 0x1100
	v_readlane_b32 s4, v253, 36
	s_add_i32 s4, s4, s2
	v_and_b32_e32 v125, 15, v58
	v_ashrrev_i32_e32 v0, 1, v58
	v_bfe_u32 v59, v58, 4, 2
	v_and_b32_e32 v0, 0xffffffe0, v0
	s_waitcnt vmcnt(3)
	v_or_b32_e32 v2, s4, v125
	v_readlane_b32 s4, v254, 16
	v_add_u32_e32 v112, v2, v0
	v_lshlrev_b32_e32 v0, 4, v59
	v_readlane_b32 s5, v254, 17
	s_movk_i32 s8, 0xc00
	s_mulk_i32 s3, 0xef00
	v_lshl_add_u64 v[30:31], s[4:5], 0, v[0:1]
	s_waitcnt vmcnt(2)
	v_mad_i64_i32 v[6:7], s[4:5], v112, s8, v[30:31]
	s_waitcnt lgkmcnt(0)
	global_load_dwordx4 v[10:13], v[6:7], off offset:128
	s_addk_i32 s3, 0xff00
	v_add_u32_e32 v2, s3, v112
	v_ashrrev_i32_e32 v32, 6, v2
	v_and_b32_e32 v2, 47, v112
	v_cmp_gt_u32_e32 vcc, 2, v59
	v_readlane_b32 s40, v254, 55
	v_readlane_b32 s50, v255, 1
	v_cndmask_b32_e32 v2, v2, v32, vcc
	v_lshlrev_b32_e32 v2, 4, v2
	v_ashrrev_i32_e32 v3, 31, v2
	v_readlane_b32 s51, v255, 2
	v_cmp_lt_i32_e64 s[4:5], v198, v196
	v_or_b32_e32 v110, 16, v112
	v_lshl_add_u64 v[2:3], v[2:3], 2, s[50:51]
	global_load_dwordx4 v[14:17], v[2:3], off
	global_load_dwordx4 v[18:21], v[2:3], off offset:16
	global_load_dwordx4 v[22:25], v[2:3], off offset:32
	global_load_dwordx4 v[26:29], v[2:3], off offset:48
	v_cndmask_b32_e64 v2, v195, v198, s[4:5]
	v_mad_i64_i32 v[30:31], s[4:5], v110, s8, v[30:31]
	v_lshlrev_b32_e32 v124, 2, v2
	v_bitop3_b32 v33, v112, 63, 16 bitop3:0xc8
	global_load_dwordx4 v[2:5], v[6:7], off
	s_nop 0
	global_load_dwordx4 v[6:9], v[6:7], off offset:64
	v_cndmask_b32_e32 v32, v33, v32, vcc
	global_load_dwordx4 v[42:45], v[30:31], off offset:128
	v_lshlrev_b32_e32 v32, 4, v32
	v_ashrrev_i32_e32 v33, 31, v32
	v_lshl_add_u64 v[32:33], v[32:33], 2, s[50:51]
	global_load_dwordx4 v[38:41], v[32:33], off offset:48
	global_load_dwordx4 v[46:49], v[32:33], off offset:32
	global_load_dwordx4 v[50:53], v[32:33], off offset:16
	global_load_dwordx4 v[54:57], v[32:33], off
	v_and_b32_e32 v68, 16, v58
	v_cmp_eq_u32_e32 vcc, 0, v68
	v_ashrrev_i32_e32 v126, 3, v58
	v_readlane_b32 s4, v254, 18
	v_readlane_b32 s5, v254, 19
	v_readlane_b32 s8, v254, 36
	v_mov_b32_e32 v115, v1
	v_readlane_b32 s9, v254, 37
	v_ashrrev_i32_e32 v128, 2, v58
	v_readlane_b32 s41, v254, 56
	v_readlane_b32 s42, v254, 57
	v_readlane_b32 s43, v254, 58
	v_readlane_b32 s44, v254, 59
	v_readlane_b32 s45, v254, 60
	v_readlane_b32 s46, v254, 61
	v_readlane_b32 s47, v254, 62
	v_readlane_b32 s48, v254, 63
	v_readlane_b32 s49, v255, 0
	v_readlane_b32 s52, v255, 3
	v_readlane_b32 s53, v255, 4
	v_readlane_b32 s54, v255, 5
	v_readlane_b32 s55, v255, 6
	v_readlane_b32 s40, v252, 16
	v_readlane_b32 s42, v252, 18
	v_readlane_b32 s43, v252, 19
	v_mov_b32_e32 v117, v1
	s_waitcnt vmcnt(12)
	v_lshlrev_b32_e32 v131, 2, v59
	v_ashrrev_i32_e32 v113, 31, v112
	v_ashrrev_i32_e32 v111, 31, v110
	v_mov_b32_e32 v140, 0
	v_mov_b32_e32 v138, 0xf149f2ca
	v_mov_b32_e32 v139, 0xf149f2ca
	v_mov_b32_e32 v141, 0
	v_readlane_b32 s41, v252, 17
	v_readlane_b32 s44, v252, 20
	v_readlane_b32 s45, v252, 21
	v_readlane_b32 s46, v252, 22
	v_readlane_b32 s47, v252, 23
	v_readlane_b32 s48, v252, 24
	v_readlane_b32 s49, v252, 25
	v_readlane_b32 s50, v252, 26
	v_readlane_b32 s51, v252, 27
	v_readlane_b32 s52, v252, 28
	v_readlane_b32 s53, v252, 29
	v_readlane_b32 s54, v252, 30
	v_readlane_b32 s55, v252, 31
	s_waitcnt vmcnt(11)
	v_and_b32_e32 v33, 0xffff0000, v10
	v_lshlrev_b32_e32 v32, 16, v10
	v_and_b32_e32 v35, 0xffff0000, v11
	v_lshlrev_b32_e32 v34, 16, v11
	v_and_b32_e32 v11, 0xffff0000, v12
	v_lshlrev_b32_e32 v10, 16, v12
	v_and_b32_e32 v37, 0xffff0000, v13
	v_lshlrev_b32_e32 v36, 16, v13
	ds_bpermute_b32 v12, v124, v32
	ds_bpermute_b32 v13, v124, v33
	ds_bpermute_b32 v60, v124, v34
	ds_bpermute_b32 v61, v124, v35
	ds_bpermute_b32 v62, v124, v10
	ds_bpermute_b32 v63, v124, v11
	s_waitcnt vmcnt(10)
	v_mov_b32_e32 v67, v16
	v_mov_b32_e32 v16, v15
	s_waitcnt vmcnt(9)
	v_mov_b32_e32 v15, v20
	v_mov_b32_e32 v20, v19
	s_waitcnt vmcnt(8)
	v_mov_b32_e32 v19, v24
	v_mov_b32_e32 v24, v23
	s_waitcnt lgkmcnt(4)
	v_pk_mul_f32 v[12:13], v[16:17], v[12:13]
	s_waitcnt lgkmcnt(2)
	v_pk_mul_f32 v[16:17], v[20:21], v[60:61]
	ds_bpermute_b32 v64, v124, v36
	ds_bpermute_b32 v65, v124, v37
	v_mov_b32_e32 v66, v14
	v_mov_b32_e32 v14, v18
	s_waitcnt lgkmcnt(2)
	v_pk_mul_f32 v[20:21], v[24:25], v[62:63]
	v_cndmask_b32_e64 v17, v17, -v17, vcc
	v_cndmask_b32_e64 v16, v16, -v16, vcc
	v_mov_b32_e32 v18, v22
	v_cndmask_b32_e64 v13, v13, -v13, vcc
	v_cndmask_b32_e64 v12, v12, -v12, vcc
	v_cndmask_b32_e64 v21, v21, -v21, vcc
	v_cndmask_b32_e64 v20, v20, -v20, vcc
	v_pk_fma_f32 v[14:15], v[14:15], v[34:35], v[16:17]
	v_pk_fma_f32 v[12:13], v[66:67], v[32:33], v[12:13]
	v_pk_fma_f32 v[10:11], v[18:19], v[10:11], v[20:21]
	v_add_u32_e32 v60, s2, v126
	v_mov_b32_e32 v75, v15
	v_ashrrev_i32_e32 v61, 31, v60
	v_add_u32_e32 v18, 0x200, v58
	s_waitcnt vmcnt(7)
	v_mov_b32_e32 v23, v28
	v_mov_b32_e32 v28, v27
	v_mov_b32_e32 v72, v12
	v_mov_b32_e32 v74, v14
	v_lshlrev_b64 v[14:15], 11, v[60:61]
	v_lshlrev_b32_e32 v12, 4, v58
	v_ashrrev_i32_e32 v127, 3, v18
	s_waitcnt lgkmcnt(0)
	v_pk_mul_f32 v[24:25], v[28:29], v[64:65]
	v_mov_b32_e32 v76, v10
	v_mov_b32_e32 v77, v11
	v_lshl_add_u64 v[10:11], s[4:5], 0, v[14:15]
	v_and_b32_e32 v114, 0x70, v12
	v_add_u32_e32 v62, s2, v127
	v_mov_b32_e32 v22, v26
	v_cndmask_b32_e64 v25, v25, -v25, vcc
	v_cndmask_b32_e64 v24, v24, -v24, vcc
	v_lshl_add_u64 v[10:11], v[10:11], 0, v[114:115]
	v_lshl_add_u64 v[14:15], s[8:9], 0, v[14:15]
	v_ashrrev_i32_e32 v63, 31, v62
	v_pk_fma_f32 v[26:27], v[22:23], v[36:37], v[24:25]
	v_mov_b32_e32 v73, v13
	global_load_dwordx4 v[10:13], v[10:11], off
	v_lshl_add_u64 v[14:15], v[14:15], 0, v[114:115]
	v_lshlrev_b64 v[22:23], 11, v[62:63]
	v_add_u32_e32 v64, s2, v128
	v_lshlrev_b32_e32 v34, 3, v58
	global_load_dwordx4 v[14:17], v[14:15], off
	v_lshl_add_u64 v[18:19], s[4:5], 0, v[22:23]
	v_ashrrev_i32_e32 v65, 31, v64
	v_lshl_add_u64 v[18:19], v[18:19], 0, v[114:115]
	v_lshl_add_u64 v[22:23], s[8:9], 0, v[22:23]
	v_lshlrev_b64 v[28:29], 6, v[64:65]
	v_and_b32_e32 v130, 24, v34
	global_load_dwordx4 v[18:21], v[18:19], off
	v_lshl_add_u64 v[22:23], v[22:23], 0, v[114:115]
	v_lshl_add_u64 v[28:29], s[42:43], 0, v[28:29]
	v_lshlrev_b32_e32 v116, 1, v130
	global_load_dwordx4 v[22:25], v[22:23], off
	v_lshl_add_u64 v[28:29], v[28:29], 0, v[116:117]
	global_load_dwordx4 v[34:37], v[28:29], off
	v_mov_b32_e32 v61, v26
	v_mov_b32_e32 v63, v27
	global_load_dwordx4 v[26:29], v[30:31], off
	s_nop 0
	global_load_dwordx4 v[30:33], v[30:31], off offset:64
	s_waitcnt vmcnt(11)
	v_and_b32_e32 v67, 0xffff0000, v42
	v_lshlrev_b32_e32 v66, 16, v42
	ds_bpermute_b32 v68, v124, v66
	ds_bpermute_b32 v69, v124, v67
	s_waitcnt vmcnt(7)
	v_mov_b32_e32 v71, v56
	v_mov_b32_e32 v56, v55
	v_mov_b32_e32 v70, v54
	v_lshl_add_u64 v[118:119], s[4:5], 0, v[114:115]
	s_waitcnt lgkmcnt(0)
	v_pk_mul_f32 v[54:55], v[56:57], v[68:69]
	v_and_b32_e32 v57, 0xffff0000, v43
	v_lshlrev_b32_e32 v56, 16, v43
	ds_bpermute_b32 v42, v124, v56
	ds_bpermute_b32 v43, v124, v57
	v_cndmask_b32_e64 v55, v55, -v55, vcc
	v_cndmask_b32_e64 v54, v54, -v54, vcc
	v_pk_fma_f32 v[54:55], v[70:71], v[66:67], v[54:55]
	v_mov_b32_e32 v66, v50
	v_mov_b32_e32 v67, v52
	v_mov_b32_e32 v52, v51
	v_and_b32_e32 v51, 0xffff0000, v44
	v_lshlrev_b32_e32 v50, 16, v44
	s_waitcnt lgkmcnt(0)
	v_pk_mul_f32 v[42:43], v[52:53], v[42:43]
	ds_bpermute_b32 v52, v124, v50
	ds_bpermute_b32 v53, v124, v51
	v_cndmask_b32_e64 v43, v43, -v43, vcc
	v_cndmask_b32_e64 v42, v42, -v42, vcc
	v_pk_fma_f32 v[42:43], v[66:67], v[56:57], v[42:43]
	v_mov_b32_e32 v57, v48
	v_mov_b32_e32 v48, v47
	v_mov_b32_e32 v56, v46
	s_waitcnt lgkmcnt(0)
	v_pk_mul_f32 v[46:47], v[48:49], v[52:53]
	v_and_b32_e32 v49, 0xffff0000, v45
	v_lshlrev_b32_e32 v48, 16, v45
	ds_bpermute_b32 v44, v124, v48
	ds_bpermute_b32 v45, v124, v49
	v_cndmask_b32_e64 v47, v47, -v47, vcc
	v_cndmask_b32_e64 v46, v46, -v46, vcc
	v_pk_fma_f32 v[46:47], v[56:57], v[50:51], v[46:47]
	v_mov_b32_e32 v51, v40
	v_mov_b32_e32 v40, v39
	v_mov_b32_e32 v50, v38
	s_waitcnt lgkmcnt(0)
	v_pk_mul_f32 v[38:39], v[40:41], v[44:45]
	v_cndmask_b32_e64 v39, v39, -v39, vcc
	v_cndmask_b32_e64 v38, v38, -v38, vcc
	v_pk_fma_f32 v[38:39], v[50:51], v[48:49], v[38:39]
	v_mov_b32_e32 v44, v47
	v_mov_b32_e32 v45, v38
	v_mov_b32_e32 v47, v39
	v_mad_u64_u32 v[38:39], s[2:3], v126, s12, v[114:115]
	v_lshlrev_b32_e32 v39, 6, v126
	s_waitcnt vmcnt(6)
	ds_write_b128 v38, v[10:13]
	v_sub_u32_e32 v38, v38, v39
	v_cmp_lt_i32_e32 vcc, v197, v196
	s_waitcnt vmcnt(5)
	ds_write_b128 v38, v[14:17] offset:53248
	v_mad_u64_u32 v[38:39], s[2:3], v127, s12, v[114:115]
	v_lshlrev_b32_e32 v39, 6, v127
	s_waitcnt vmcnt(4)
	ds_write_b128 v38, v[18:21]
	v_sub_u32_e32 v38, v38, v39
	s_waitcnt vmcnt(3)
	ds_write_b128 v38, v[22:25] offset:53248
	v_mad_u64_u32 v[38:39], s[2:3], v128, s12, v[116:117]
	s_waitcnt vmcnt(2)
	ds_write_b128 v38, v[34:37] offset:128
	v_cndmask_b32_e32 v38, v195, v197, vcc
	v_lshlrev_b32_e32 v129, 2, v38
	v_bfe_u32 v38, v58, 2, 2
	v_mov_b32_e32 v48, v1
	v_mov_b32_e32 v49, v1
	v_or_b32_e32 v132, v131, v38
	v_cvt_pk_bf16_f32 v41, v61, v63
	v_cvt_pk_bf16_f32 v40, v76, v77
	v_cvt_pk_bf16_f32 v39, v74, v75
	v_cvt_pk_bf16_f32 v38, v72, v73
	v_cvt_pk_bf16_f32 v45, v45, v47
	v_cvt_pk_bf16_f32 v44, v46, v44
	v_cvt_pk_bf16_f32 v43, v42, v43
	v_cvt_pk_bf16_f32 v42, v54, v55
	v_lshl_add_u64 v[120:121], s[8:9], 0, v[114:115]
	v_lshl_add_u64 v[122:123], s[42:43], 0, v[116:117]
	v_add_u32_e32 v115, 0x80, v64
	v_add_u32_e32 v117, 0x80, v62
	v_add_u32_e32 v137, 0x80, v60
	v_mov_b32_e32 v46, v1
	v_mov_b32_e32 v47, v1
	v_mov_b64_e32 v[64:65], v[48:49]
	v_mov_b64_e32 v[52:53], v[48:49]
	v_mov_b64_e32 v[68:69], v[48:49]
	v_mov_b64_e32 v[56:57], v[48:49]
	v_mov_b64_e32 v[72:73], v[48:49]
	v_mov_b64_e32 v[60:61], v[48:49]
	v_mov_b64_e32 v[76:77], v[48:49]
	v_or_b32_e32 v133, 0xd000, v130
	v_or_b32_e32 v134, 0xd020, v130
	v_or_b32_e32 v135, 0xd040, v130
	v_or_b32_e32 v136, 0xd060, v130
	s_mov_b32 s4, 0
	v_mov_b64_e32 v[62:63], v[46:47]
	v_mov_b64_e32 v[50:51], v[46:47]
	v_mov_b64_e32 v[66:67], v[46:47]
	v_mov_b64_e32 v[54:55], v[46:47]
	v_mov_b64_e32 v[70:71], v[46:47]
	v_mov_b64_e32 v[58:59], v[46:47]
	v_mov_b64_e32 v[74:75], v[46:47]
	s_waitcnt lgkmcnt(0)
	s_barrier
	s_branch .LBB0_557

.LBB0_571:
	ds_bpermute_b32 v0, v124, v141
	v_readlane_b32 s40, v254, 55
	v_readlane_b32 s46, v254, 61
	v_readlane_b32 s47, v254, 62
	s_lshl_b32 s34, s4, 1
	s_waitcnt lgkmcnt(0)
	v_add_f32_e32 v0, v141, v0
	ds_bpermute_b32 v2, v127, v0
	v_readlane_b32 s50, v255, 1
	v_readlane_b32 s51, v255, 2
	v_readlane_b32 s41, v254, 56
	v_readlane_b32 s42, v254, 57
	s_waitcnt lgkmcnt(0)
	v_add_f32_e32 v0, v0, v2
	v_div_scale_f32 v4, s[2:3], v0, v0, 1.0
	v_rcp_f32_e32 v5, v4
	v_div_scale_f32 v6, vcc, 1.0, v0, 1.0
	v_lshlrev_b64 v[2:3], 11, v[112:113]
	v_fma_f32 v7, -v4, v5, 1.0
	v_fmac_f32_e32 v5, v7, v5
	v_mul_f32_e32 v7, v6, v5
	v_fma_f32 v8, -v4, v7, v6
	v_fmac_f32_e32 v7, v8, v5
	v_fma_f32 v4, -v4, v7, v6
	v_div_fmas_f32 v4, v4, v5, v7
	v_div_fixup_f32 v4, v4, v0, 1.0
	v_pk_mul_f32 v[8:9], v[76:77], v[4:5] op_sel_hi:[1,0]
	v_pk_mul_f32 v[6:7], v[74:75], v[4:5] op_sel_hi:[1,0]
	v_bfe_u32 v0, v9, 16, 1
	v_bfe_u32 v5, v8, 16, 1
	v_add3_u32 v5, v8, v5, s0
	v_add3_u32 v0, v9, v0, s0
	v_lshl_add_u64 v[2:3], s[46:47], 0, v[2:3]
	v_mov_b32_e32 v10, v7
	v_perm_b32 v7, v0, v5, s19
	v_lshl_add_u64 v[2:3], v[2:3], 0, s[34:35]
	v_lshlrev_b32_e32 v0, 1, v131
	v_cvt_pk_bf16_f32 v6, v6, v10
	v_lshl_add_u64 v[2:3], v[2:3], 0, v[0:1]
	global_store_dwordx2 v[2:3], v[6:7], off
	v_pk_mul_f32 v[6:7], v[70:71], v[4:5] op_sel_hi:[1,0]
	v_pk_mul_f32 v[8:9], v[72:73], v[4:5] op_sel_hi:[1,0]
	v_bfe_u32 v5, v9, 16, 1
	v_bfe_u32 v10, v8, 16, 1
	v_mov_b32_e32 v11, v7
	v_add3_u32 v7, v8, v10, s0
	v_add3_u32 v5, v9, v5, s0
	v_perm_b32 v7, v5, v7, s19
	v_cvt_pk_bf16_f32 v6, v6, v11
	global_store_dwordx2 v[2:3], v[6:7], off offset:32
	v_pk_mul_f32 v[6:7], v[66:67], v[4:5] op_sel_hi:[1,0]
	v_pk_mul_f32 v[8:9], v[68:69], v[4:5] op_sel_hi:[1,0]
	v_bfe_u32 v10, v8, 16, 1
	v_mov_b32_e32 v11, v7
	v_add3_u32 v7, v8, v10, s0
	ds_bpermute_b32 v8, v124, v140
	v_bfe_u32 v5, v9, 16, 1
	v_add3_u32 v5, v9, v5, s0
	s_waitcnt lgkmcnt(0)
	v_add_f32_e32 v8, v140, v8
	ds_bpermute_b32 v13, v127, v8
	v_perm_b32 v7, v5, v7, s19
	v_cvt_pk_bf16_f32 v6, v6, v11
	global_store_dwordx2 v[2:3], v[6:7], off offset:64
	v_pk_mul_f32 v[6:7], v[62:63], v[4:5] op_sel_hi:[1,0]
	v_pk_mul_f32 v[4:5], v[64:65], v[4:5] op_sel_hi:[1,0]
	s_waitcnt lgkmcnt(0)
	v_add_f32_e32 v8, v8, v13
	v_div_scale_f32 v9, s[2:3], v8, v8, 1.0
	v_rcp_f32_e32 v10, v9
	v_cvt_pk_bf16_f32 v5, v4, v5
	v_cvt_pk_bf16_f32 v4, v6, v7
	global_store_dwordx2 v[2:3], v[4:5], off offset:96
	v_fma_f32 v2, -v9, v10, 1.0
	v_fmac_f32_e32 v10, v2, v10
	v_div_scale_f32 v2, vcc, 1.0, v8, 1.0
	v_mul_f32_e32 v3, v2, v10
	v_fma_f32 v4, -v9, v3, v2
	v_fmac_f32_e32 v3, v4, v10
	v_fma_f32 v2, -v9, v3, v2
	v_div_fmas_f32 v2, v2, v10, v3
	v_div_fixup_f32 v2, v2, v8, 1.0
	v_lshlrev_b64 v[4:5], 11, v[110:111]
	v_pk_mul_f32 v[6:7], v[58:59], v[2:3] op_sel_hi:[1,0]
	v_pk_mul_f32 v[8:9], v[60:61], v[2:3] op_sel_hi:[1,0]
	v_bfe_u32 v3, v9, 16, 1
	v_bfe_u32 v10, v8, 16, 1
	v_lshl_add_u64 v[4:5], s[46:47], 0, v[4:5]
	v_mov_b32_e32 v11, v7
	v_add3_u32 v7, v8, v10, s0
	v_add3_u32 v3, v9, v3, s0
	v_lshl_add_u64 v[4:5], v[4:5], 0, s[34:35]
	v_perm_b32 v7, v3, v7, s19
	v_cvt_pk_bf16_f32 v6, v6, v11
	v_lshl_add_u64 v[4:5], v[4:5], 0, v[0:1]
	global_store_dwordx2 v[4:5], v[6:7], off
	v_pk_mul_f32 v[6:7], v[54:55], v[2:3] op_sel_hi:[1,0]
	v_pk_mul_f32 v[8:9], v[56:57], v[2:3] op_sel_hi:[1,0]
	v_bfe_u32 v0, v9, 16, 1
	v_bfe_u32 v3, v8, 16, 1
	v_mov_b32_e32 v10, v7
	v_add3_u32 v3, v8, v3, s0
	v_add3_u32 v0, v9, v0, s0
	v_perm_b32 v7, v0, v3, s19
	v_cvt_pk_bf16_f32 v6, v6, v10
	global_store_dwordx2 v[4:5], v[6:7], off offset:32
	v_pk_mul_f32 v[6:7], v[50:51], v[2:3] op_sel_hi:[1,0]
	v_pk_mul_f32 v[8:9], v[52:53], v[2:3] op_sel_hi:[1,0]
	v_bfe_u32 v0, v9, 16, 1
	v_bfe_u32 v3, v8, 16, 1
	v_mov_b32_e32 v10, v7
	v_add3_u32 v3, v8, v3, s0
	v_add3_u32 v0, v9, v0, s0
	v_perm_b32 v7, v0, v3, s19
	v_cvt_pk_bf16_f32 v6, v6, v10
	global_store_dwordx2 v[4:5], v[6:7], off offset:64
	v_pk_mul_f32 v[6:7], v[46:47], v[2:3] op_sel_hi:[1,0]
	v_pk_mul_f32 v[2:3], v[48:49], v[2:3] op_sel_hi:[1,0]
	v_readlane_b32 s2, v254, 48
	s_add_i32 s6, s6, s2
	v_cvt_pk_bf16_f32 v3, v2, v3
	v_cvt_pk_bf16_f32 v2, v6, v7
	s_cmpk_lt_i32 s6, 0x800
	v_readlane_b32 s43, v254, 58
	v_readlane_b32 s44, v254, 59
	v_readlane_b32 s45, v254, 60
	v_readlane_b32 s48, v254, 63
	v_readlane_b32 s49, v255, 0
	v_readlane_b32 s52, v255, 3
	v_readlane_b32 s53, v255, 4
	v_readlane_b32 s54, v255, 5
	v_readlane_b32 s55, v255, 6
	v_readlane_b32 s3, v254, 49
	global_store_dwordx2 v[4:5], v[2:3], off offset:96
	s_cbranch_scc0 .LBB0_551
.LBB0_572:
	s_ashr_i32 s7, s6, 8
	s_lshl_b32 s4, s6, 8
	s_mul_i32 s3, s7, 0x1100
	s_and_b32 s4, s4, 0xf00
	v_mov_b32_e32 v50, v163
	s_add_i32 s4, s3, s4
	s_bfe_u32 s2, s6, 0x40004
	v_and_b32_e32 v125, 15, v50
	s_addk_i32 s4, 0x100
	v_readlane_b32 s52, v254, 20
	v_ashrrev_i32_e32 v0, 1, v50
	s_waitcnt vmcnt(3)
	v_or_b32_e32 v2, s4, v125
	s_mul_i32 s4, s2, 0xc0
	v_readlane_b32 s60, v254, 28
	v_bfe_u32 v51, v50, 4, 2
	v_and_b32_e32 v0, 0xffffffe0, v0
	v_readlane_b32 s61, v254, 29
	s_add_u32 s4, s60, s4
	v_add_u32_e32 v112, v2, v0
	s_addc_u32 s5, s61, 0
	v_lshlrev_b32_e32 v0, 4, v51
	v_lshl_add_u64 v[2:3], s[4:5], 0, v[0:1]
	s_movk_i32 s8, 0xc00
	s_waitcnt vmcnt(2)
	v_mad_i64_i32 v[6:7], s[4:5], v112, s8, v[2:3]
	s_mul_i32 s4, s7, 0xffffef00
	s_addk_i32 s4, 0xff00
	global_load_dwordx4 v[14:17], v[6:7], off offset:128
	v_add_u32_e32 v4, s4, v112
	v_ashrrev_i32_e32 v32, 6, v4
	v_and_b32_e32 v4, 47, v112
	v_cmp_gt_u32_e32 vcc, 2, v51
	v_cmp_lt_i32_e64 s[4:5], v198, v196
	v_or_b32_e32 v110, 16, v112
	v_cndmask_b32_e32 v4, v4, v32, vcc
	v_lshlrev_b32_e32 v4, 4, v4
	v_ashrrev_i32_e32 v5, 31, v4
	v_lshl_add_u64 v[4:5], v[4:5], 2, s[50:51]
	global_load_dwordx4 v[18:21], v[4:5], off
	global_load_dwordx4 v[22:25], v[4:5], off offset:16
	global_load_dwordx4 v[26:29], v[4:5], off offset:32
	s_waitcnt lgkmcnt(0)
	global_load_dwordx4 v[10:13], v[4:5], off offset:48
	v_cndmask_b32_e64 v4, v195, v198, s[4:5]
	v_lshlrev_b32_e32 v124, 2, v4
	v_bitop3_b32 v33, v112, 63, 16 bitop3:0xc8
	v_mad_i64_i32 v[30:31], s[4:5], v110, s8, v[2:3]
	global_load_dwordx4 v[2:5], v[6:7], off
	s_nop 0
	global_load_dwordx4 v[6:9], v[6:7], off offset:64
	s_nop 0
	global_load_dwordx4 v[38:41], v[30:31], off offset:128
	v_cndmask_b32_e32 v32, v33, v32, vcc
	v_lshlrev_b32_e32 v32, 4, v32
	v_ashrrev_i32_e32 v33, 31, v32
	v_lshl_add_u64 v[32:33], v[32:33], 2, s[50:51]
	global_load_dwordx4 v[42:45], v[32:33], off offset:16
	global_load_dwordx4 v[46:49], v[32:33], off
	v_and_b32_e32 v62, 16, v50
	v_cmp_eq_u32_e32 vcc, 0, v62
	v_ashrrev_i32_e32 v126, 3, v50
	v_readlane_b32 s62, v254, 30
	v_readlane_b32 s63, v254, 31
	v_readlane_b32 s64, v254, 32
	v_readlane_b32 s65, v254, 33
	s_lshl_b32 s34, s2, 7
	v_mov_b32_e32 v115, v1
	v_ashrrev_i32_e32 v129, 2, v50
	v_readlane_b32 s53, v254, 21
	v_readlane_b32 s54, v254, 22
	v_readlane_b32 s55, v254, 23
	v_add_u32_e32 v64, s3, v129
	v_ashrrev_i32_e32 v65, 31, v64
	v_readlane_b32 s40, v252, 16
	v_readlane_b32 s42, v252, 18
	v_readlane_b32 s43, v252, 19
	v_mov_b32_e32 v117, v1
	s_lshl_b32 s4, s2, 6
	s_waitcnt vmcnt(10)
	v_lshlrev_b32_e32 v131, 2, v51
	s_mov_b32 s7, 0
	v_ashrrev_i32_e32 v113, 31, v112
	v_ashrrev_i32_e32 v111, 31, v110
	v_mov_b32_e32 v140, 0
	v_mov_b32_e32 v138, 0xf149f2ca
	v_mov_b32_e32 v139, 0xf149f2ca
	v_mov_b32_e32 v141, 0
	v_readlane_b32 s56, v254, 24
	v_readlane_b32 s57, v254, 25
	v_readlane_b32 s58, v254, 26
	v_readlane_b32 s59, v254, 27
	v_readlane_b32 s66, v254, 34
	v_readlane_b32 s67, v254, 35
	v_readlane_b32 s41, v252, 17
	v_readlane_b32 s44, v252, 20
	v_readlane_b32 s45, v252, 21
	v_readlane_b32 s46, v252, 22
	v_readlane_b32 s47, v252, 23
	v_readlane_b32 s48, v252, 24
	v_readlane_b32 s49, v252, 25
	v_readlane_b32 s50, v252, 26
	v_readlane_b32 s51, v252, 27
	v_readlane_b32 s52, v252, 28
	v_readlane_b32 s53, v252, 29
	v_readlane_b32 s54, v252, 30
	v_readlane_b32 s55, v252, 31
	s_waitcnt vmcnt(9)
	v_and_b32_e32 v35, 0xffff0000, v14
	v_lshlrev_b32_e32 v34, 16, v14
	v_and_b32_e32 v37, 0xffff0000, v15
	v_lshlrev_b32_e32 v36, 16, v15
	v_and_b32_e32 v15, 0xffff0000, v16
	v_lshlrev_b32_e32 v14, 16, v16
	v_and_b32_e32 v53, 0xffff0000, v17
	v_lshlrev_b32_e32 v52, 16, v17
	ds_bpermute_b32 v16, v124, v34
	ds_bpermute_b32 v17, v124, v35
	ds_bpermute_b32 v56, v124, v14
	ds_bpermute_b32 v57, v124, v15
	ds_bpermute_b32 v54, v124, v36
	ds_bpermute_b32 v55, v124, v37
	ds_bpermute_b32 v58, v124, v52
	ds_bpermute_b32 v59, v124, v53
	s_waitcnt vmcnt(8)
	v_mov_b32_e32 v61, v20
	v_mov_b32_e32 v20, v19
	s_waitcnt vmcnt(7)
	v_mov_b32_e32 v19, v24
	v_mov_b32_e32 v24, v23
	s_waitcnt vmcnt(6)
	v_mov_b32_e32 v23, v28
	v_mov_b32_e32 v28, v27
	v_mov_b32_e32 v60, v18
	v_mov_b32_e32 v18, v22
	v_mov_b32_e32 v22, v26
	s_waitcnt vmcnt(5)
	v_mov_b32_e32 v26, v10
	v_mov_b32_e32 v27, v12
	v_mov_b32_e32 v12, v11
	s_waitcnt lgkmcnt(6)
	v_pk_mul_f32 v[10:11], v[20:21], v[16:17]
	s_waitcnt lgkmcnt(4)
	v_pk_mul_f32 v[20:21], v[28:29], v[56:57]
	s_waitcnt lgkmcnt(2)
	v_pk_mul_f32 v[16:17], v[24:25], v[54:55]
	v_cndmask_b32_e64 v21, v21, -v21, vcc
	v_cndmask_b32_e64 v20, v20, -v20, vcc
	s_waitcnt lgkmcnt(0)
	v_pk_mul_f32 v[12:13], v[12:13], v[58:59]
	v_cndmask_b32_e64 v11, v11, -v11, vcc
	v_cndmask_b32_e64 v10, v10, -v10, vcc
	v_cndmask_b32_e64 v17, v17, -v17, vcc
	v_cndmask_b32_e64 v16, v16, -v16, vcc
	v_pk_fma_f32 v[14:15], v[22:23], v[14:15], v[20:21]
	v_cndmask_b32_e64 v13, v13, -v13, vcc
	v_cndmask_b32_e64 v12, v12, -v12, vcc
	v_pk_fma_f32 v[10:11], v[60:61], v[34:35], v[10:11]
	v_pk_fma_f32 v[16:17], v[18:19], v[36:37], v[16:17]
	v_pk_fma_f32 v[26:27], v[26:27], v[52:53], v[12:13]
	global_load_dwordx4 v[52:55], v[32:33], off offset:48
	global_load_dwordx4 v[56:59], v[32:33], off offset:32
	v_add_u32_e32 v60, s3, v126
	v_mov_b32_e32 v76, v14
	v_ashrrev_i32_e32 v61, 31, v60
	v_add_u32_e32 v18, 0x200, v50
	v_mov_b32_e32 v77, v15
	v_lshlrev_b64 v[14:15], 11, v[60:61]
	v_ashrrev_i32_e32 v128, 3, v18
	v_mov_b32_e32 v72, v10
	v_mov_b32_e32 v73, v11
	v_mov_b32_e32 v78, v26
	v_lshl_add_u64 v[10:11], s[62:63], 0, v[14:15]
	v_lshlrev_b32_e32 v12, 4, v50
	v_add_u32_e32 v62, s3, v128
	v_lshl_add_u64 v[10:11], v[10:11], 0, s[34:35]
	v_and_b32_e32 v114, 0x70, v12
	v_lshl_add_u64 v[14:15], s[64:65], 0, v[14:15]
	v_ashrrev_i32_e32 v63, 31, v62
	v_lshl_add_u64 v[10:11], v[10:11], 0, v[114:115]
	v_lshl_add_u64 v[14:15], v[14:15], 0, s[34:35]
	v_lshlrev_b64 v[22:23], 11, v[62:63]
	v_mov_b32_e32 v75, v17
	global_load_dwordx4 v[10:13], v[10:11], off
	v_lshl_add_u64 v[14:15], v[14:15], 0, v[114:115]
	v_lshl_add_u64 v[18:19], s[62:63], 0, v[22:23]
	v_mov_b32_e32 v74, v16
	global_load_dwordx4 v[14:17], v[14:15], off
	v_lshl_add_u64 v[18:19], v[18:19], 0, s[34:35]
	v_lshl_add_u64 v[22:23], s[64:65], 0, v[22:23]
	v_lshl_add_u64 v[18:19], v[18:19], 0, v[114:115]
	v_lshl_add_u64 v[22:23], v[22:23], 0, s[34:35]
	v_lshlrev_b32_e32 v26, 3, v50
	global_load_dwordx4 v[18:21], v[18:19], off
	v_lshl_add_u64 v[22:23], v[22:23], 0, v[114:115]
	global_load_dwordx4 v[22:25], v[22:23], off
	v_lshlrev_b64 v[28:29], 6, v[64:65]
	v_and_b32_e32 v130, 24, v26
	v_lshl_add_u64 v[28:29], s[42:43], 0, v[28:29]
	v_lshlrev_b32_e32 v116, 1, v130
	v_lshl_add_u64 v[28:29], v[28:29], 0, v[116:117]
	global_load_dwordx4 v[34:37], v[28:29], off
	v_mov_b32_e32 v61, v27
	global_load_dwordx4 v[26:29], v[30:31], off
	s_nop 0
	global_load_dwordx4 v[30:33], v[30:31], off offset:64
	s_waitcnt vmcnt(11)
	v_and_b32_e32 v67, 0xffff0000, v38
	v_lshlrev_b32_e32 v66, 16, v38
	ds_bpermute_b32 v68, v124, v66
	ds_bpermute_b32 v69, v124, v67
	s_waitcnt vmcnt(9)
	v_mov_b32_e32 v71, v48
	v_mov_b32_e32 v48, v47
	v_mov_b32_e32 v70, v46
	v_lshl_add_u64 v[122:123], s[42:43], 0, v[116:117]
	s_waitcnt lgkmcnt(0)
	v_pk_mul_f32 v[46:47], v[48:49], v[68:69]
	v_and_b32_e32 v49, 0xffff0000, v39
	v_lshlrev_b32_e32 v48, 16, v39
	ds_bpermute_b32 v38, v124, v48
	ds_bpermute_b32 v39, v124, v49
	v_cndmask_b32_e64 v47, v47, -v47, vcc
	v_cndmask_b32_e64 v46, v46, -v46, vcc
	v_pk_fma_f32 v[46:47], v[70:71], v[66:67], v[46:47]
	v_mov_b32_e32 v66, v42
	v_mov_b32_e32 v67, v44
	v_mov_b32_e32 v44, v43
	v_and_b32_e32 v43, 0xffff0000, v40
	v_lshlrev_b32_e32 v42, 16, v40
	s_waitcnt lgkmcnt(0)
	v_pk_mul_f32 v[38:39], v[44:45], v[38:39]
	ds_bpermute_b32 v44, v124, v42
	ds_bpermute_b32 v45, v124, v43
	v_cndmask_b32_e64 v39, v39, -v39, vcc
	v_cndmask_b32_e64 v38, v38, -v38, vcc
	v_pk_fma_f32 v[38:39], v[66:67], v[48:49], v[38:39]
	v_add_u32_e32 v137, 0x80, v60
	v_or_b32_e32 v133, 0xd000, v130
	v_or_b32_e32 v134, 0xd020, v130
	s_waitcnt vmcnt(7)
	v_mov_b32_e32 v49, v58
	v_mov_b32_e32 v58, v57
	s_waitcnt lgkmcnt(0)
	v_pk_mul_f32 v[44:45], v[58:59], v[44:45]
	v_mov_b32_e32 v48, v56
	v_cndmask_b32_e64 v45, v45, -v45, vcc
	v_cndmask_b32_e64 v44, v44, -v44, vcc
	v_pk_fma_f32 v[42:43], v[48:49], v[42:43], v[44:45]
	v_mov_b32_e32 v44, v52
	v_mov_b32_e32 v45, v54
	v_mov_b32_e32 v54, v53
	v_and_b32_e32 v57, 0xffff0000, v41
	v_lshlrev_b32_e32 v56, 16, v41
	v_mov_b32_e32 v53, v38
	v_mov_b32_e32 v52, v39
	v_mad_u64_u32 v[38:39], s[2:3], v126, s12, v[114:115]
	ds_bpermute_b32 v40, v124, v56
	ds_bpermute_b32 v41, v124, v57
	v_lshlrev_b32_e32 v39, 6, v126
	s_waitcnt lgkmcnt(0)
	v_pk_mul_f32 v[40:41], v[54:55], v[40:41]
	v_cndmask_b32_e64 v41, v41, -v41, vcc
	v_cndmask_b32_e64 v40, v40, -v40, vcc
	s_waitcnt vmcnt(6)
	ds_write_b128 v38, v[10:13]
	v_sub_u32_e32 v38, v38, v39
	v_pk_fma_f32 v[40:41], v[44:45], v[56:57], v[40:41]
	v_cmp_lt_i32_e32 vcc, v197, v196
	s_waitcnt vmcnt(5)
	ds_write_b128 v38, v[14:17] offset:53248
	v_mad_u64_u32 v[38:39], s[2:3], v128, s12, v[114:115]
	v_lshlrev_b32_e32 v39, 6, v128
	s_waitcnt vmcnt(4)
	ds_write_b128 v38, v[18:21]
	v_sub_u32_e32 v38, v38, v39
	s_waitcnt vmcnt(3)
	ds_write_b128 v38, v[22:25] offset:53248
	v_mad_u64_u32 v[38:39], s[2:3], v129, s12, v[116:117]
	s_add_u32 s2, s62, s34
	s_addc_u32 s3, s63, 0
	s_waitcnt vmcnt(2)
	ds_write_b128 v38, v[34:37] offset:128
	v_cndmask_b32_e32 v38, v195, v197, vcc
	v_lshl_add_u64 v[118:119], s[2:3], 0, v[114:115]
	s_add_u32 s2, s64, s34
	v_mov_b32_e32 v45, v40
	v_mov_b32_e32 v44, v41
	v_lshlrev_b32_e32 v127, 2, v38
	v_bfe_u32 v38, v50, 2, 2
	s_addc_u32 s3, s65, 0
	v_mov_b32_e32 v48, v1
	v_mov_b32_e32 v49, v1
	v_or_b32_e32 v132, v131, v38
	v_cvt_pk_bf16_f32 v41, v78, v61
	v_cvt_pk_bf16_f32 v40, v76, v77
	v_cvt_pk_bf16_f32 v39, v74, v75
	v_cvt_pk_bf16_f32 v38, v72, v73
	v_cvt_pk_bf16_f32 v45, v45, v44
	v_cvt_pk_bf16_f32 v44, v42, v43
	v_cvt_pk_bf16_f32 v43, v53, v52
	v_cvt_pk_bf16_f32 v42, v46, v47
	v_lshl_add_u64 v[120:121], s[2:3], 0, v[114:115]
	v_add_u32_e32 v115, 0x80, v64
	v_add_u32_e32 v117, 0x80, v62
	v_mov_b32_e32 v46, v1
	v_mov_b32_e32 v47, v1
	v_mov_b64_e32 v[64:65], v[48:49]
	v_mov_b64_e32 v[52:53], v[48:49]
	v_mov_b64_e32 v[68:69], v[48:49]
	v_mov_b64_e32 v[56:57], v[48:49]
	v_mov_b64_e32 v[72:73], v[48:49]
	v_mov_b64_e32 v[60:61], v[48:49]
	v_mov_b64_e32 v[76:77], v[48:49]
	v_or_b32_e32 v135, 0xd040, v130
	v_or_b32_e32 v136, 0xd060, v130
	v_mov_b64_e32 v[62:63], v[46:47]
	v_mov_b64_e32 v[50:51], v[46:47]
	v_mov_b64_e32 v[66:67], v[46:47]
	v_mov_b64_e32 v[54:55], v[46:47]
	v_mov_b64_e32 v[70:71], v[46:47]
	v_mov_b64_e32 v[58:59], v[46:47]
	v_mov_b64_e32 v[74:75], v[46:47]
	s_waitcnt lgkmcnt(0)
	s_barrier
	s_branch .LBB0_574

.LBB0_600:
	ds_bpermute_b32 v0, v130, v142
	v_readlane_b32 s40, v254, 55
	v_readlane_b32 s46, v254, 61
	v_readlane_b32 s47, v254, 62
	s_lshl_b32 s34, s7, 1
	s_waitcnt lgkmcnt(0)
	v_add_f32_e32 v0, v142, v0
	ds_bpermute_b32 v2, v115, v0
	v_readlane_b32 s41, v254, 56
	v_readlane_b32 s42, v254, 57
	v_readlane_b32 s43, v254, 58
	v_readlane_b32 s44, v254, 59
	s_waitcnt lgkmcnt(0)
	v_add_f32_e32 v0, v0, v2
	v_div_scale_f32 v4, s[2:3], v0, v0, 1.0
	v_rcp_f32_e32 v5, v4
	v_div_scale_f32 v6, vcc, 1.0, v0, 1.0
	v_lshlrev_b64 v[2:3], 11, v[112:113]
	v_fma_f32 v7, -v4, v5, 1.0
	v_fmac_f32_e32 v5, v7, v5
	v_mul_f32_e32 v7, v6, v5
	v_fma_f32 v8, -v4, v7, v6
	v_fmac_f32_e32 v7, v8, v5
	v_fma_f32 v4, -v4, v7, v6
	v_div_fmas_f32 v4, v4, v5, v7
	v_div_fixup_f32 v4, v4, v0, 1.0
	v_pk_mul_f32 v[8:9], v[76:77], v[4:5] op_sel_hi:[1,0]
	v_pk_mul_f32 v[6:7], v[74:75], v[4:5] op_sel_hi:[1,0]
	v_bfe_u32 v0, v9, 16, 1
	v_bfe_u32 v5, v8, 16, 1
	v_add3_u32 v5, v8, v5, s0
	v_add3_u32 v0, v9, v0, s0
	v_lshl_add_u64 v[2:3], s[46:47], 0, v[2:3]
	v_mov_b32_e32 v10, v7
	v_perm_b32 v7, v0, v5, s19
	v_lshl_add_u64 v[2:3], v[2:3], 0, s[34:35]
	v_lshlrev_b32_e32 v0, 1, v131
	v_cvt_pk_bf16_f32 v6, v6, v10
	v_lshl_add_u64 v[2:3], v[2:3], 0, v[0:1]
	global_store_dwordx2 v[2:3], v[6:7], off
	v_pk_mul_f32 v[6:7], v[70:71], v[4:5] op_sel_hi:[1,0]
	v_pk_mul_f32 v[8:9], v[72:73], v[4:5] op_sel_hi:[1,0]
	v_bfe_u32 v5, v9, 16, 1
	v_bfe_u32 v10, v8, 16, 1
	v_mov_b32_e32 v11, v7
	v_add3_u32 v7, v8, v10, s0
	v_add3_u32 v5, v9, v5, s0
	v_perm_b32 v7, v5, v7, s19
	v_cvt_pk_bf16_f32 v6, v6, v11
	global_store_dwordx2 v[2:3], v[6:7], off offset:32
	v_pk_mul_f32 v[6:7], v[66:67], v[4:5] op_sel_hi:[1,0]
	v_pk_mul_f32 v[8:9], v[68:69], v[4:5] op_sel_hi:[1,0]
	v_bfe_u32 v10, v8, 16, 1
	v_mov_b32_e32 v11, v7
	v_add3_u32 v7, v8, v10, s0
	ds_bpermute_b32 v8, v130, v141
	v_bfe_u32 v5, v9, 16, 1
	v_add3_u32 v5, v9, v5, s0
	s_waitcnt lgkmcnt(0)
	v_add_f32_e32 v8, v141, v8
	ds_bpermute_b32 v13, v115, v8
	v_perm_b32 v7, v5, v7, s19
	v_cvt_pk_bf16_f32 v6, v6, v11
	global_store_dwordx2 v[2:3], v[6:7], off offset:64
	v_pk_mul_f32 v[6:7], v[62:63], v[4:5] op_sel_hi:[1,0]
	v_pk_mul_f32 v[4:5], v[64:65], v[4:5] op_sel_hi:[1,0]
	s_waitcnt lgkmcnt(0)
	v_add_f32_e32 v8, v8, v13
	v_div_scale_f32 v9, s[2:3], v8, v8, 1.0
	v_rcp_f32_e32 v10, v9
	v_cvt_pk_bf16_f32 v5, v4, v5
	v_cvt_pk_bf16_f32 v4, v6, v7
	global_store_dwordx2 v[2:3], v[4:5], off offset:96
	v_fma_f32 v2, -v9, v10, 1.0
	v_fmac_f32_e32 v10, v2, v10
	v_div_scale_f32 v2, vcc, 1.0, v8, 1.0
	v_mul_f32_e32 v3, v2, v10
	v_fma_f32 v4, -v9, v3, v2
	v_fmac_f32_e32 v3, v4, v10
	v_fma_f32 v2, -v9, v3, v2
	v_div_fmas_f32 v2, v2, v10, v3
	v_div_fixup_f32 v2, v2, v8, 1.0
	v_lshlrev_b64 v[4:5], 11, v[110:111]
	v_pk_mul_f32 v[6:7], v[58:59], v[2:3] op_sel_hi:[1,0]
	v_pk_mul_f32 v[8:9], v[60:61], v[2:3] op_sel_hi:[1,0]
	v_bfe_u32 v3, v9, 16, 1
	v_bfe_u32 v10, v8, 16, 1
	v_lshl_add_u64 v[4:5], s[46:47], 0, v[4:5]
	v_mov_b32_e32 v11, v7
	v_add3_u32 v7, v8, v10, s0
	v_add3_u32 v3, v9, v3, s0
	v_lshl_add_u64 v[4:5], v[4:5], 0, s[34:35]
	v_perm_b32 v7, v3, v7, s19
	v_cvt_pk_bf16_f32 v6, v6, v11
	v_lshl_add_u64 v[4:5], v[4:5], 0, v[0:1]
	global_store_dwordx2 v[4:5], v[6:7], off
	v_pk_mul_f32 v[6:7], v[54:55], v[2:3] op_sel_hi:[1,0]
	v_pk_mul_f32 v[8:9], v[56:57], v[2:3] op_sel_hi:[1,0]
	v_bfe_u32 v0, v9, 16, 1
	v_bfe_u32 v3, v8, 16, 1
	v_mov_b32_e32 v10, v7
	v_add3_u32 v3, v8, v3, s0
	v_add3_u32 v0, v9, v0, s0
	v_perm_b32 v7, v0, v3, s19
	v_cvt_pk_bf16_f32 v6, v6, v10
	global_store_dwordx2 v[4:5], v[6:7], off offset:32
	v_pk_mul_f32 v[6:7], v[50:51], v[2:3] op_sel_hi:[1,0]
	v_pk_mul_f32 v[8:9], v[52:53], v[2:3] op_sel_hi:[1,0]
	v_bfe_u32 v0, v9, 16, 1
	v_bfe_u32 v3, v8, 16, 1
	v_mov_b32_e32 v10, v7
	v_add3_u32 v3, v8, v3, s0
	v_add3_u32 v0, v9, v0, s0
	v_perm_b32 v7, v0, v3, s19
	v_cvt_pk_bf16_f32 v6, v6, v10
	global_store_dwordx2 v[4:5], v[6:7], off offset:64
	v_pk_mul_f32 v[6:7], v[46:47], v[2:3] op_sel_hi:[1,0]
	v_pk_mul_f32 v[2:3], v[48:49], v[2:3] op_sel_hi:[1,0]
	v_readlane_b32 s2, v254, 48
	s_add_i32 s6, s6, s2
	v_cvt_pk_bf16_f32 v3, v2, v3
	v_cvt_pk_bf16_f32 v2, v6, v7
	s_cmpk_gt_i32 s6, 0x7f
	v_readlane_b32 s45, v254, 60
	v_readlane_b32 s48, v254, 63
	v_readlane_b32 s49, v255, 0
	v_readlane_b32 s50, v255, 1
	v_readlane_b32 s51, v255, 2
	v_readlane_b32 s52, v255, 3
	v_readlane_b32 s53, v255, 4
	v_readlane_b32 s54, v255, 5
	v_readlane_b32 s55, v255, 6
	v_readlane_b32 s3, v254, 49
	global_store_dwordx2 v[4:5], v[2:3], off offset:96
	s_cbranch_scc1 .LBB0_589

.LBB0_640:
	s_and_b64 s[2:3], s[8:9], exec
	s_waitcnt vmcnt(0)
	v_readlane_b32 s2, v255, 15
	v_readlane_b32 s4, v255, 19
	v_readlane_b32 s3, v255, 16
	v_readlane_b32 s5, v255, 20
	s_cselect_b32 s42, s2, s4
	v_readlane_b32 s2, v255, 17
	s_cselect_b32 s28, s51, 0
	s_cselect_b32 s29, s52, 0
	s_cselect_b32 s43, s3, s5
	s_cselect_b32 s46, s2, 0
	s_cmp_lt_i32 s44, 4
	s_mov_b64 s[2:3], -1
	s_waitcnt vmcnt(0) lgkmcnt(0)
	s_barrier
	s_cbranch_scc1 .LBB0_1047
	s_cmp_lt_i32 s44, 6
	s_cbranch_scc1 .LBB0_1041
	s_cmp_gt_i32 s44, 6
	s_cbranch_scc0 .LBB0_654
	s_movk_i32 s15, 0x210
	v_lshlrev_b32_e32 v0, 3, v223
	v_mul_lo_u32 v132, v225, s15
	v_cvt_pk_bf16_f32 v131, v128, v129
	v_cvt_pk_bf16_f32 v130, v126, v127
	v_add3_u32 v0, v224, v132, v0
	v_cvt_pk_bf16_f32 v133, v124, v125
	v_cvt_pk_bf16_f32 v132, v122, v123
	ds_write2_b64 v0, v[130:131], v[132:133] offset1:4
	v_cvt_pk_bf16_f32 v131, v120, v121
	v_cvt_pk_bf16_f32 v130, v118, v119
	v_cvt_pk_bf16_f32 v133, v116, v117
	v_cvt_pk_bf16_f32 v132, v114, v115
	ds_write2_b64 v0, v[130:131], v[132:133] offset0:32 offset1:36
	v_cvt_pk_bf16_f32 v131, v112, v113
	v_cvt_pk_bf16_f32 v130, v110, v111
	v_cvt_pk_bf16_f32 v133, v108, v109
	v_cvt_pk_bf16_f32 v132, v106, v107
	v_add_u32_e32 v134, 0x2000, v0
	ds_write2_b64 v134, v[130:131], v[132:133] offset0:32 offset1:36
	v_cvt_pk_bf16_f32 v131, v104, v105
	v_cvt_pk_bf16_f32 v130, v102, v103
	v_cvt_pk_bf16_f32 v133, v100, v101
	v_cvt_pk_bf16_f32 v132, v98, v99
	ds_write2_b64 v134, v[130:131], v[132:133] offset0:64 offset1:68
	v_cvt_pk_bf16_f32 v131, v96, v97
	v_cvt_pk_bf16_f32 v130, v94, v95
	v_cvt_pk_bf16_f32 v133, v92, v93
	v_cvt_pk_bf16_f32 v132, v90, v91
	v_add_u32_e32 v134, 0x4000, v0
	ds_write2_b64 v134, v[130:131], v[132:133] offset0:64 offset1:68
	v_cvt_pk_bf16_f32 v131, v88, v89
	v_cvt_pk_bf16_f32 v130, v86, v87
	v_cvt_pk_bf16_f32 v133, v84, v85
	v_cvt_pk_bf16_f32 v132, v82, v83
	ds_write2_b64 v134, v[130:131], v[132:133] offset0:96 offset1:100
	v_cvt_pk_bf16_f32 v131, v80, v81
	v_cvt_pk_bf16_f32 v130, v78, v79
	v_cvt_pk_bf16_f32 v133, v76, v77
	v_cvt_pk_bf16_f32 v132, v74, v75
	v_add_u32_e32 v134, 0x6000, v0
	ds_write2_b64 v134, v[130:131], v[132:133] offset0:96 offset1:100
	v_cvt_pk_bf16_f32 v131, v72, v73
	v_cvt_pk_bf16_f32 v130, v70, v71
	v_cvt_pk_bf16_f32 v133, v68, v69
	v_cvt_pk_bf16_f32 v132, v66, v67
	ds_write2_b64 v134, v[130:131], v[132:133] offset0:128 offset1:132
	v_cvt_pk_bf16_f32 v131, v64, v65
	v_cvt_pk_bf16_f32 v130, v62, v63
	v_cvt_pk_bf16_f32 v133, v60, v61
	v_cvt_pk_bf16_f32 v132, v58, v59
	v_add_u32_e32 v134, 0x8000, v0
	ds_write2_b64 v134, v[130:131], v[132:133] offset0:128 offset1:132
	v_cvt_pk_bf16_f32 v131, v56, v57
	v_cvt_pk_bf16_f32 v130, v54, v55
	v_cvt_pk_bf16_f32 v133, v52, v53
	v_cvt_pk_bf16_f32 v132, v50, v51
	ds_write2_b64 v134, v[130:131], v[132:133] offset0:160 offset1:164
	v_cvt_pk_bf16_f32 v131, v48, v49
	v_cvt_pk_bf16_f32 v130, v46, v47
	v_cvt_pk_bf16_f32 v133, v44, v45
	v_cvt_pk_bf16_f32 v132, v42, v43
	v_add_u32_e32 v134, 0xa000, v0
	ds_write2_b64 v134, v[130:131], v[132:133] offset0:160 offset1:164
	v_cvt_pk_bf16_f32 v131, v36, v37
	v_cvt_pk_bf16_f32 v130, v34, v35
	v_cvt_pk_bf16_f32 v133, v32, v33
	v_cvt_pk_bf16_f32 v132, v30, v31
	ds_write2_b64 v134, v[130:131], v[132:133] offset0:192 offset1:196
	v_cvt_pk_bf16_f32 v131, v40, v41
	v_cvt_pk_bf16_f32 v130, v38, v39
	v_cvt_pk_bf16_f32 v133, v28, v29
	v_cvt_pk_bf16_f32 v132, v26, v27
	v_add_u32_e32 v134, 0xc000, v0
	ds_write2_b64 v134, v[130:131], v[132:133] offset0:192 offset1:196
	v_cvt_pk_bf16_f32 v131, v24, v25
	v_cvt_pk_bf16_f32 v130, v22, v23
	v_cvt_pk_bf16_f32 v133, v20, v21
	v_cvt_pk_bf16_f32 v132, v18, v19
	ds_write2_b64 v134, v[130:131], v[132:133] offset0:224 offset1:228
	v_cvt_pk_bf16_f32 v131, v16, v17
	v_cvt_pk_bf16_f32 v130, v14, v15
	v_cvt_pk_bf16_f32 v133, v12, v13
	v_cvt_pk_bf16_f32 v132, v10, v11
	v_add_u32_e32 v134, 0xe000, v0
	ds_write2_b64 v134, v[130:131], v[132:133] offset0:224 offset1:228
	v_cvt_pk_bf16_f32 v131, v8, v9
	v_cvt_pk_bf16_f32 v130, v6, v7
	v_cvt_pk_bf16_f32 v133, v4, v5
	v_cvt_pk_bf16_f32 v132, v2, v3
	v_add_u32_e32 v0, 0xe800, v0
	ds_write2_b64 v0, v[130:131], v[132:133] offset1:4
	v_lshlrev_b32_e32 v0, 2, v175
	v_and_b32_e32 v0, 0x7c, v0
	s_mul_i32 s2, s28, 0x10800
	v_readlane_b32 s48, v253, 61
	v_lshl_or_b32 v164, s47, 7, v0
	s_mul_hi_u32 s3, s28, 0x10800
	v_readlane_b32 s49, v253, 62
	s_add_u32 s2, s48, s2
	v_ashrrev_i32_e32 v165, 31, v164
	s_addc_u32 s3, s49, s3
	v_lshlrev_b64 v[130:131], 2, v[164:165]
	v_lshl_add_u64 v[150:151], s[2:3], 0, v[130:131]
	s_movk_i32 s2, 0x5000
	v_add_co_u32_e32 v134, vcc, s2, v150
	s_mov_b32 s2, 0xb000
	s_nop 0
	v_addc_co_u32_e32 v135, vcc, 0, v151, vcc
	v_add_co_u32_e32 v138, vcc, s2, v150
	v_readlane_b32 s50, v253, 63
	s_nop 0
	v_addc_co_u32_e32 v139, vcc, 0, v151, vcc
	v_add_co_u32_e32 v142, vcc, s25, v150
	s_mul_i32 s4, s28, 0x5800
	s_nop 0
	v_addc_co_u32_e32 v143, vcc, 0, v151, vcc
	s_mov_b32 s2, 0x8000
	v_readlane_b32 s51, v254, 0
	s_mul_hi_u32 s5, s28, 0x5800
	s_add_u32 s4, s50, s4
	v_add_co_u32_e32 v146, vcc, s2, v150
	s_addc_u32 s5, s51, s5
	s_nop 0
	v_addc_co_u32_e32 v147, vcc, 0, v151, vcc
	s_mov_b32 s2, 0xd000
	s_waitcnt lgkmcnt(0)
	s_barrier
	v_lshl_add_u64 v[158:159], s[4:5], 0, v[130:131]
	global_load_dwordx4 v[130:133], v[150:151], off
	v_add_co_u32_e32 v150, vcc, s2, v150
	global_load_dwordx4 v[134:137], v[134:135], off offset:2048
	s_nop 0
	global_load_dwordx4 v[138:141], v[138:139], off
	v_addc_co_u32_e32 v151, vcc, 0, v151, vcc
	global_load_dwordx4 v[142:145], v[142:143], off offset:3072
	s_nop 0
	global_load_dwordx4 v[146:149], v[146:147], off offset:1024
	s_nop 0
	global_load_dwordx4 v[150:153], v[150:151], off offset:3072
	s_nop 0
	global_load_dwordx4 v[154:157], v[158:159], off
	v_add_co_u32_e32 v158, vcc, 0x2000, v158
	v_ashrrev_i32_e32 v0, 5, v175
	s_nop 0
	v_addc_co_u32_e32 v159, vcc, 0, v159, vcc
	global_load_dwordx4 v[158:161], v[158:159], off offset:3072
	v_readlane_b32 s2, v252, 32
	v_readlane_b32 s3, v252, 33
	v_mul_lo_u32 v166, v0, s15
	v_and_b32_e32 v167, 31, v175
	s_mov_b32 s14, 0
	v_lshl_add_u64 v[164:165], v[164:165], 1, s[2:3]
	v_lshl_add_u32 v166, v167, 3, v166
	v_add_u32_e32 v167, s40, v0
	s_waitcnt vmcnt(0)
	s_branch .LBB0_645

.LBB0_645:
	v_add_u32_e32 v168, s14, v0
	v_add_u32_e32 v169, s14, v167
	v_add_u32_e32 v171, 1, v168
	v_add_u32_e32 v170, 1, v169
	s_mov_b32 s2, 0x8800
	v_cmp_gt_i32_e32 vcc, s33, v171
	v_cmp_gt_i32_e64 s[4:5], s2, v170
	s_and_b64 s[4:5], vcc, s[4:5]
	s_and_saveexec_b64 s[2:3], s[4:5]
	s_cbranch_execz .LBB0_647
	s_mov_b32 s4, 0x78787879
	v_mul_hi_i32 v171, v170, s4
	v_lshrrev_b32_e32 v172, 31, v171
	v_ashrrev_i32_e32 v171, 11, v171
	v_add_u32_e32 v171, v171, v172
	ds_read2_b64 v[176:179], v166 offset0:66 offset1:98
	ds_read2_b64 v[180:183], v166 offset1:32
	v_mul_i32_i24_e32 v171, 0x1100, v171
	ds_read2_b64 v[184:187], v166 offset0:132 offset1:164
	v_sub_u32_e32 v171, v170, v171
	v_and_b32_e32 v172, 0xfffffeff, v171
	v_and_b32_e32 v171, 0xffffefff, v171
	v_cmp_eq_u32_e32 vcc, 0, v172
	s_waitcnt lgkmcnt(2)
	v_and_b32_e32 v229, 0xffff0000, v178
	v_lshlrev_b32_e32 v228, 16, v178
	v_cndmask_b32_e64 v172, 1.0, 0, vcc
	v_cmp_eq_u32_e32 vcc, s33, v171
	s_waitcnt lgkmcnt(1)
	v_and_b32_e32 v231, 0xffff0000, v182
	v_lshlrev_b32_e32 v230, 16, v182
	v_cndmask_b32_e64 v200, 1.0, 0, vcc
	s_waitcnt lgkmcnt(0)
	v_and_b32_e32 v233, 0xffff0000, v186
	v_lshlrev_b32_e32 v232, 16, v186
	v_pk_fma_f32 v[228:229], v[146:147], v[228:229], v[158:159]
	v_pk_mul_f32 v[230:231], v[172:173], v[230:231] op_sel_hi:[0,1]
	v_pk_fma_f32 v[228:229], v[142:143], v[230:231], v[228:229]
	v_pk_mul_f32 v[230:231], v[200:201], v[232:233] op_sel_hi:[0,1]
	v_pk_fma_f32 v[228:229], v[150:151], v[230:231], v[228:229]
	v_and_b32_e32 v227, 0xffff0000, v180
	v_mul_f32_e32 v171, 0xbfb8aa3b, v228
	v_exp_f32_e32 v230, v171
	v_mul_f32_e32 v171, 0xbfb8aa3b, v229
	v_exp_f32_e32 v231, v171
	v_lshlrev_b32_e32 v226, 16, v180
	v_pk_mul_f32 v[226:227], v[172:173], v[226:227] op_sel_hi:[0,1]
	v_and_b32_e32 v203, 0xffff0000, v176
	v_pk_add_f32 v[230:231], v[230:231], 1.0 op_sel_hi:[1,0]
	v_lshlrev_b32_e32 v202, 16, v176
	v_rcp_f32_e32 v173, v231
	v_pk_fma_f32 v[202:203], v[134:135], v[202:203], v[154:155]
	v_lshlrev_b32_e32 v180, 16, v179
	v_pk_fma_f32 v[202:203], v[130:131], v[226:227], v[202:203]
	v_rcp_f32_e32 v178, v230
	v_and_b32_e32 v227, 0xffff0000, v184
	v_lshlrev_b32_e32 v226, 16, v184
	v_pk_mul_f32 v[226:227], v[200:201], v[226:227] op_sel_hi:[0,1]
	v_mul_f32_e32 v171, v229, v173
	v_pk_fma_f32 v[202:203], v[138:139], v[226:227], v[202:203]
	v_mov_b32_e32 v227, v171
	v_mul_f32_e32 v171, v228, v178
	v_mov_b32_e32 v226, v171
	v_pk_mul_f32 v[202:203], v[202:203], v[226:227]
	v_and_b32_e32 v227, 0xffff0000, v177
	v_lshlrev_b32_e32 v226, 16, v177
	v_and_b32_e32 v177, 0xffff0000, v181
	v_lshlrev_b32_e32 v176, 16, v181
	v_and_b32_e32 v181, 0xffff0000, v179
	v_and_b32_e32 v179, 0xffff0000, v183
	v_lshlrev_b32_e32 v178, 16, v183
	v_and_b32_e32 v183, 0xffff0000, v187
	v_lshlrev_b32_e32 v182, 16, v187
	v_pk_fma_f32 v[180:181], v[148:149], v[180:181], v[160:161]
	v_pk_mul_f32 v[178:179], v[172:173], v[178:179] op_sel_hi:[0,1]
	v_pk_fma_f32 v[178:179], v[144:145], v[178:179], v[180:181]
	v_pk_mul_f32 v[180:181], v[200:201], v[182:183] op_sel_hi:[0,1]
	v_pk_fma_f32 v[178:179], v[152:153], v[180:181], v[178:179]
	v_pk_fma_f32 v[182:183], v[136:137], v[226:227], v[156:157]
	v_mul_f32_e32 v171, 0xbfb8aa3b, v178
	v_exp_f32_e32 v180, v171
	v_mul_f32_e32 v171, 0xbfb8aa3b, v179
	v_exp_f32_e32 v181, v171
	v_pk_mul_f32 v[172:173], v[172:173], v[176:177] op_sel_hi:[0,1]
	v_and_b32_e32 v177, 0xffff0000, v185
	v_lshlrev_b32_e32 v176, 16, v185
	v_pk_add_f32 v[180:181], v[180:181], 1.0 op_sel_hi:[1,0]
	v_pk_fma_f32 v[172:173], v[132:133], v[172:173], v[182:183]
	v_rcp_f32_e32 v175, v181
	v_pk_mul_f32 v[176:177], v[200:201], v[176:177] op_sel_hi:[0,1]
	v_pk_fma_f32 v[172:173], v[140:141], v[176:177], v[172:173]
	v_rcp_f32_e32 v182, v180
	v_mul_f32_e32 v171, v179, v175
	v_mov_b32_e32 v177, v171
	s_movk_i32 s4, 0x1600
	v_mul_f32_e32 v171, v178, v182
	v_mov_b32_e32 v176, v171
	v_pk_mul_f32 v[172:173], v[172:173], v[176:177]
	v_cvt_pk_bf16_f32 v173, v172, v173
	v_cvt_pk_bf16_f32 v172, v202, v203
	v_mad_i64_i32 v[170:171], s[4:5], v170, s4, v[164:165]
	global_store_dwordx2 v[170:171], v[172:173], off
.LBB0_647:
	s_or_b64 exec, exec, s[2:3]
	v_add_u32_e32 v171, 17, v168
	v_add_u32_e32 v170, 17, v169
	s_mov_b32 s2, 0x8800
	v_cmp_gt_i32_e32 vcc, s33, v171
	v_cmp_gt_i32_e64 s[4:5], s2, v170
	s_and_b64 s[4:5], vcc, s[4:5]
	s_and_saveexec_b64 s[2:3], s[4:5]
	s_cbranch_execz .LBB0_649
	s_mov_b32 s4, 0x78787879
	v_mul_hi_i32 v171, v170, s4
	v_lshrrev_b32_e32 v172, 31, v171
	v_ashrrev_i32_e32 v171, 11, v171
	v_add_u32_e32 v173, 0x2000, v166
	v_add_u32_e32 v171, v171, v172
	ds_read2_b64 v[176:179], v173 offset0:98 offset1:130
	ds_read2_b64 v[180:183], v173 offset0:32 offset1:64
	v_mul_i32_i24_e32 v171, 0x1100, v171
	ds_read2_b64 v[184:187], v173 offset0:164 offset1:196
	v_sub_u32_e32 v171, v170, v171
	v_and_b32_e32 v172, 0xfffffeff, v171
	v_and_b32_e32 v171, 0xffffefff, v171
	v_cmp_eq_u32_e32 vcc, 0, v172
	s_waitcnt lgkmcnt(2)
	v_and_b32_e32 v229, 0xffff0000, v178
	v_lshlrev_b32_e32 v228, 16, v178
	v_cndmask_b32_e64 v172, 1.0, 0, vcc
	v_cmp_eq_u32_e32 vcc, s33, v171
	s_waitcnt lgkmcnt(1)
	v_and_b32_e32 v231, 0xffff0000, v182
	v_lshlrev_b32_e32 v230, 16, v182
	v_cndmask_b32_e64 v200, 1.0, 0, vcc
	s_waitcnt lgkmcnt(0)
	v_and_b32_e32 v233, 0xffff0000, v186
	v_lshlrev_b32_e32 v232, 16, v186
	v_pk_fma_f32 v[228:229], v[146:147], v[228:229], v[158:159]
	v_pk_mul_f32 v[230:231], v[172:173], v[230:231] op_sel_hi:[0,1]
	v_pk_fma_f32 v[228:229], v[142:143], v[230:231], v[228:229]
	v_pk_mul_f32 v[230:231], v[200:201], v[232:233] op_sel_hi:[0,1]
	v_pk_fma_f32 v[228:229], v[150:151], v[230:231], v[228:229]
	v_and_b32_e32 v227, 0xffff0000, v180
	v_mul_f32_e32 v171, 0xbfb8aa3b, v228
	v_exp_f32_e32 v230, v171
	v_mul_f32_e32 v171, 0xbfb8aa3b, v229
	v_exp_f32_e32 v231, v171
	v_lshlrev_b32_e32 v226, 16, v180
	v_pk_mul_f32 v[226:227], v[172:173], v[226:227] op_sel_hi:[0,1]
	v_and_b32_e32 v203, 0xffff0000, v176
	v_pk_add_f32 v[230:231], v[230:231], 1.0 op_sel_hi:[1,0]
	v_lshlrev_b32_e32 v202, 16, v176
	v_rcp_f32_e32 v173, v231
	v_pk_fma_f32 v[202:203], v[134:135], v[202:203], v[154:155]
	v_lshlrev_b32_e32 v180, 16, v179
	v_pk_fma_f32 v[202:203], v[130:131], v[226:227], v[202:203]
	v_rcp_f32_e32 v178, v230
	v_and_b32_e32 v227, 0xffff0000, v184
	v_lshlrev_b32_e32 v226, 16, v184
	v_pk_mul_f32 v[226:227], v[200:201], v[226:227] op_sel_hi:[0,1]
	v_mul_f32_e32 v171, v229, v173
	v_pk_fma_f32 v[202:203], v[138:139], v[226:227], v[202:203]
	v_mov_b32_e32 v227, v171
	v_mul_f32_e32 v171, v228, v178
	v_mov_b32_e32 v226, v171
	v_pk_mul_f32 v[202:203], v[202:203], v[226:227]
	v_and_b32_e32 v227, 0xffff0000, v177
	v_lshlrev_b32_e32 v226, 16, v177
	v_and_b32_e32 v177, 0xffff0000, v181
	v_lshlrev_b32_e32 v176, 16, v181
	v_and_b32_e32 v181, 0xffff0000, v179
	v_and_b32_e32 v179, 0xffff0000, v183
	v_lshlrev_b32_e32 v178, 16, v183
	v_and_b32_e32 v183, 0xffff0000, v187
	v_lshlrev_b32_e32 v182, 16, v187
	v_pk_fma_f32 v[180:181], v[148:149], v[180:181], v[160:161]
	v_pk_mul_f32 v[178:179], v[172:173], v[178:179] op_sel_hi:[0,1]
	v_pk_fma_f32 v[178:179], v[144:145], v[178:179], v[180:181]
	v_pk_mul_f32 v[180:181], v[200:201], v[182:183] op_sel_hi:[0,1]
	v_pk_fma_f32 v[178:179], v[152:153], v[180:181], v[178:179]
	v_pk_fma_f32 v[182:183], v[136:137], v[226:227], v[156:157]
	v_mul_f32_e32 v171, 0xbfb8aa3b, v178
	v_exp_f32_e32 v180, v171
	v_mul_f32_e32 v171, 0xbfb8aa3b, v179
	v_exp_f32_e32 v181, v171
	v_pk_mul_f32 v[172:173], v[172:173], v[176:177] op_sel_hi:[0,1]
	v_and_b32_e32 v177, 0xffff0000, v185
	v_lshlrev_b32_e32 v176, 16, v185
	v_pk_add_f32 v[180:181], v[180:181], 1.0 op_sel_hi:[1,0]
	v_pk_fma_f32 v[172:173], v[132:133], v[172:173], v[182:183]
	v_rcp_f32_e32 v175, v181
	v_pk_mul_f32 v[176:177], v[200:201], v[176:177] op_sel_hi:[0,1]
	v_pk_fma_f32 v[172:173], v[140:141], v[176:177], v[172:173]
	v_rcp_f32_e32 v182, v180
	v_mul_f32_e32 v171, v179, v175
	v_mov_b32_e32 v177, v171
	s_movk_i32 s4, 0x1600
	v_mul_f32_e32 v171, v178, v182
	v_mov_b32_e32 v176, v171
	v_pk_mul_f32 v[172:173], v[172:173], v[176:177]
	v_cvt_pk_bf16_f32 v173, v172, v173
	v_cvt_pk_bf16_f32 v172, v202, v203
	v_mad_i64_i32 v[170:171], s[4:5], v170, s4, v[164:165]
	global_store_dwordx2 v[170:171], v[172:173], off
.LBB0_649:
	s_or_b64 exec, exec, s[2:3]
	v_add_u32_e32 v171, 33, v168
	v_add_u32_e32 v170, 33, v169
	s_mov_b32 s2, 0x8800
	v_cmp_gt_i32_e32 vcc, s33, v171
	v_cmp_gt_i32_e64 s[4:5], s2, v170
	s_and_b64 s[4:5], vcc, s[4:5]
	s_and_saveexec_b64 s[2:3], s[4:5]
	s_cbranch_execz .LBB0_651
	s_mov_b32 s4, 0x78787879
	v_mul_hi_i32 v171, v170, s4
	v_lshrrev_b32_e32 v172, 31, v171
	v_ashrrev_i32_e32 v171, 11, v171
	v_add_u32_e32 v173, 0x4000, v166
	v_add_u32_e32 v171, v171, v172
	ds_read2_b64 v[176:179], v173 offset0:130 offset1:162
	ds_read2_b64 v[180:183], v173 offset0:64 offset1:96
	v_mul_i32_i24_e32 v171, 0x1100, v171
	ds_read2_b64 v[184:187], v173 offset0:196 offset1:228
	v_sub_u32_e32 v171, v170, v171
	v_and_b32_e32 v172, 0xfffffeff, v171
	v_and_b32_e32 v171, 0xffffefff, v171
	v_cmp_eq_u32_e32 vcc, 0, v172
	s_waitcnt lgkmcnt(2)
	v_and_b32_e32 v229, 0xffff0000, v178
	v_lshlrev_b32_e32 v228, 16, v178
	v_cndmask_b32_e64 v172, 1.0, 0, vcc
	v_cmp_eq_u32_e32 vcc, s33, v171
	s_waitcnt lgkmcnt(1)
	v_and_b32_e32 v231, 0xffff0000, v182
	v_lshlrev_b32_e32 v230, 16, v182
	v_cndmask_b32_e64 v200, 1.0, 0, vcc
	s_waitcnt lgkmcnt(0)
	v_and_b32_e32 v233, 0xffff0000, v186
	v_lshlrev_b32_e32 v232, 16, v186
	v_pk_fma_f32 v[228:229], v[146:147], v[228:229], v[158:159]
	v_pk_mul_f32 v[230:231], v[172:173], v[230:231] op_sel_hi:[0,1]
	v_pk_fma_f32 v[228:229], v[142:143], v[230:231], v[228:229]
	v_pk_mul_f32 v[230:231], v[200:201], v[232:233] op_sel_hi:[0,1]
	v_pk_fma_f32 v[228:229], v[150:151], v[230:231], v[228:229]
	v_and_b32_e32 v227, 0xffff0000, v180
	v_mul_f32_e32 v171, 0xbfb8aa3b, v228
	v_exp_f32_e32 v230, v171
	v_mul_f32_e32 v171, 0xbfb8aa3b, v229
	v_exp_f32_e32 v231, v171
	v_lshlrev_b32_e32 v226, 16, v180
	v_pk_mul_f32 v[226:227], v[172:173], v[226:227] op_sel_hi:[0,1]
	v_and_b32_e32 v203, 0xffff0000, v176
	v_pk_add_f32 v[230:231], v[230:231], 1.0 op_sel_hi:[1,0]
	v_lshlrev_b32_e32 v202, 16, v176
	v_rcp_f32_e32 v173, v231
	v_pk_fma_f32 v[202:203], v[134:135], v[202:203], v[154:155]
	v_lshlrev_b32_e32 v180, 16, v179
	v_pk_fma_f32 v[202:203], v[130:131], v[226:227], v[202:203]
	v_rcp_f32_e32 v178, v230
	v_and_b32_e32 v227, 0xffff0000, v184
	v_lshlrev_b32_e32 v226, 16, v184
	v_pk_mul_f32 v[226:227], v[200:201], v[226:227] op_sel_hi:[0,1]
	v_mul_f32_e32 v171, v229, v173
	v_pk_fma_f32 v[202:203], v[138:139], v[226:227], v[202:203]
	v_mov_b32_e32 v227, v171
	v_mul_f32_e32 v171, v228, v178
	v_mov_b32_e32 v226, v171
	v_pk_mul_f32 v[202:203], v[202:203], v[226:227]
	v_and_b32_e32 v227, 0xffff0000, v177
	v_lshlrev_b32_e32 v226, 16, v177
	v_and_b32_e32 v177, 0xffff0000, v181
	v_lshlrev_b32_e32 v176, 16, v181
	v_and_b32_e32 v181, 0xffff0000, v179
	v_and_b32_e32 v179, 0xffff0000, v183
	v_lshlrev_b32_e32 v178, 16, v183
	v_and_b32_e32 v183, 0xffff0000, v187
	v_lshlrev_b32_e32 v182, 16, v187
	v_pk_fma_f32 v[180:181], v[148:149], v[180:181], v[160:161]
	v_pk_mul_f32 v[178:179], v[172:173], v[178:179] op_sel_hi:[0,1]
	v_pk_fma_f32 v[178:179], v[144:145], v[178:179], v[180:181]
	v_pk_mul_f32 v[180:181], v[200:201], v[182:183] op_sel_hi:[0,1]
	v_pk_fma_f32 v[178:179], v[152:153], v[180:181], v[178:179]
	v_pk_fma_f32 v[182:183], v[136:137], v[226:227], v[156:157]
	v_mul_f32_e32 v171, 0xbfb8aa3b, v178
	v_exp_f32_e32 v180, v171
	v_mul_f32_e32 v171, 0xbfb8aa3b, v179
	v_exp_f32_e32 v181, v171
	v_pk_mul_f32 v[172:173], v[172:173], v[176:177] op_sel_hi:[0,1]
	v_and_b32_e32 v177, 0xffff0000, v185
	v_lshlrev_b32_e32 v176, 16, v185
	v_pk_add_f32 v[180:181], v[180:181], 1.0 op_sel_hi:[1,0]
	v_pk_fma_f32 v[172:173], v[132:133], v[172:173], v[182:183]
	v_rcp_f32_e32 v175, v181
	v_pk_mul_f32 v[176:177], v[200:201], v[176:177] op_sel_hi:[0,1]
	v_pk_fma_f32 v[172:173], v[140:141], v[176:177], v[172:173]
	v_rcp_f32_e32 v182, v180
	v_mul_f32_e32 v171, v179, v175
	v_mov_b32_e32 v177, v171
	s_movk_i32 s4, 0x1600
	v_mul_f32_e32 v171, v178, v182
	v_mov_b32_e32 v176, v171
	v_pk_mul_f32 v[172:173], v[172:173], v[176:177]
	v_cvt_pk_bf16_f32 v173, v172, v173
	v_cvt_pk_bf16_f32 v172, v202, v203
	v_mad_i64_i32 v[170:171], s[4:5], v170, s4, v[164:165]
	global_store_dwordx2 v[170:171], v[172:173], off
.LBB0_651:
	s_or_b64 exec, exec, s[2:3]
	v_add_u32_e32 v170, 49, v168
	v_add_u32_e32 v168, 49, v169
	s_mov_b32 s2, 0x8800
	v_cmp_gt_i32_e32 vcc, s33, v170
	v_cmp_gt_i32_e64 s[4:5], s2, v168
	s_and_b64 s[4:5], vcc, s[4:5]
	s_and_saveexec_b64 s[2:3], s[4:5]
	s_cbranch_execz .LBB0_644
	s_mov_b32 s4, 0x78787879
	v_mul_hi_i32 v169, v168, s4
	v_lshrrev_b32_e32 v170, 31, v169
	v_ashrrev_i32_e32 v169, 11, v169
	v_add_u32_e32 v169, v169, v170
	v_mul_i32_i24_e32 v169, 0x1100, v169
	v_sub_u32_e32 v169, v168, v169
	v_and_b32_e32 v170, 0xfffffeff, v169
	v_and_b32_e32 v169, 0xffffefff, v169
	v_cmp_eq_u32_e32 vcc, 0, v170
	v_add_u32_e32 v175, 0x6000, v166
	ds_read2_b64 v[170:173], v175 offset0:162 offset1:194
	v_cndmask_b32_e64 v184, 1.0, 0, vcc
	v_cmp_eq_u32_e32 vcc, s33, v169
	ds_read2_b64 v[176:179], v175 offset0:96 offset1:128
	v_add_u32_e32 v169, 0x6400, v166
	ds_read2_b64 v[180:183], v169 offset0:100 offset1:132
	s_waitcnt lgkmcnt(2)
	v_and_b32_e32 v227, 0xffff0000, v172
	v_lshlrev_b32_e32 v226, 16, v172
	s_waitcnt lgkmcnt(1)
	v_and_b32_e32 v229, 0xffff0000, v178
	v_lshlrev_b32_e32 v228, 16, v178
	v_cndmask_b32_e64 v186, 1.0, 0, vcc
	s_waitcnt lgkmcnt(0)
	v_and_b32_e32 v231, 0xffff0000, v182
	v_lshlrev_b32_e32 v230, 16, v182
	v_pk_fma_f32 v[226:227], v[146:147], v[226:227], v[158:159]
	v_pk_mul_f32 v[228:229], v[184:185], v[228:229] op_sel_hi:[0,1]
	v_pk_fma_f32 v[226:227], v[142:143], v[228:229], v[226:227]
	v_pk_mul_f32 v[228:229], v[186:187], v[230:231] op_sel_hi:[0,1]
	v_pk_fma_f32 v[226:227], v[150:151], v[228:229], v[226:227]
	v_and_b32_e32 v201, 0xffff0000, v170
	v_mul_f32_e32 v169, 0xbfb8aa3b, v226
	v_exp_f32_e32 v228, v169
	v_mul_f32_e32 v169, 0xbfb8aa3b, v227
	v_exp_f32_e32 v229, v169
	v_lshlrev_b32_e32 v200, 16, v170
	v_and_b32_e32 v203, 0xffff0000, v176
	v_lshlrev_b32_e32 v202, 16, v176
	v_pk_add_f32 v[228:229], v[228:229], 1.0 op_sel_hi:[1,0]
	v_pk_fma_f32 v[200:201], v[134:135], v[200:201], v[154:155]
	v_rcp_f32_e32 v170, v229
	v_pk_mul_f32 v[202:203], v[184:185], v[202:203] op_sel_hi:[0,1]
	v_pk_fma_f32 v[200:201], v[130:131], v[202:203], v[200:201]
	v_and_b32_e32 v203, 0xffff0000, v180
	v_rcp_f32_e32 v176, v228
	v_lshlrev_b32_e32 v202, 16, v180
	v_pk_mul_f32 v[202:203], v[186:187], v[202:203] op_sel_hi:[0,1]
	v_mul_f32_e32 v169, v227, v170
	v_pk_fma_f32 v[200:201], v[138:139], v[202:203], v[200:201]
	v_mov_b32_e32 v203, v169
	v_mul_f32_e32 v169, v226, v176
	v_mov_b32_e32 v202, v169
	v_pk_mul_f32 v[200:201], v[200:201], v[202:203]
	v_and_b32_e32 v203, 0xffff0000, v171
	v_lshlrev_b32_e32 v202, 16, v171
	v_and_b32_e32 v171, 0xffff0000, v177
	v_lshlrev_b32_e32 v170, 16, v177
	v_and_b32_e32 v177, 0xffff0000, v173
	v_lshlrev_b32_e32 v176, 16, v173
	v_and_b32_e32 v173, 0xffff0000, v179
	v_lshlrev_b32_e32 v172, 16, v179
	v_and_b32_e32 v179, 0xffff0000, v183
	v_lshlrev_b32_e32 v178, 16, v183
	v_pk_fma_f32 v[176:177], v[148:149], v[176:177], v[160:161]
	v_pk_mul_f32 v[172:173], v[184:185], v[172:173] op_sel_hi:[0,1]
	v_pk_fma_f32 v[172:173], v[144:145], v[172:173], v[176:177]
	v_pk_mul_f32 v[176:177], v[186:187], v[178:179] op_sel_hi:[0,1]
	v_pk_fma_f32 v[172:173], v[152:153], v[176:177], v[172:173]
	v_pk_fma_f32 v[178:179], v[136:137], v[202:203], v[156:157]
	v_mul_f32_e32 v169, 0xbfb8aa3b, v172
	v_exp_f32_e32 v176, v169
	v_mul_f32_e32 v169, 0xbfb8aa3b, v173
	v_exp_f32_e32 v177, v169
	v_pk_mul_f32 v[170:171], v[184:185], v[170:171] op_sel_hi:[0,1]
	v_pk_fma_f32 v[170:171], v[132:133], v[170:171], v[178:179]
	v_and_b32_e32 v179, 0xffff0000, v181
	v_pk_add_f32 v[176:177], v[176:177], 1.0 op_sel_hi:[1,0]
	v_lshlrev_b32_e32 v178, 16, v181
	v_rcp_f32_e32 v175, v177
	v_pk_mul_f32 v[178:179], v[186:187], v[178:179] op_sel_hi:[0,1]
	v_pk_fma_f32 v[170:171], v[140:141], v[178:179], v[170:171]
	v_rcp_f32_e32 v180, v176
	v_mul_f32_e32 v169, v173, v175
	v_mov_b32_e32 v173, v169
	s_movk_i32 s4, 0x1600
	v_mul_f32_e32 v169, v172, v180
	v_mov_b32_e32 v172, v169
	v_pk_mul_f32 v[170:171], v[170:171], v[172:173]
	v_cvt_pk_bf16_f32 v171, v170, v171
	v_cvt_pk_bf16_f32 v170, v200, v201
	v_mad_i64_i32 v[168:169], s[4:5], v168, s4, v[164:165]
	global_store_dwordx2 v[168:169], v[170:171], off
	s_branch .LBB0_644

.LBB0_654:
	s_and_b64 vcc, exec, s[2:3]
	s_cbranch_vccz .LBB0_1040
	v_lshlrev_b32_e32 v0, 2, v223
	s_and_b32 s2, s6, 0x300
	v_or3_b32 v130, v0, s2, v224
	v_readlane_b32 s48, v254, 55
	v_lshlrev_b32_e32 v130, 2, v130
	v_readlane_b32 s60, v255, 3
	v_readlane_b32 s61, v255, 4
	s_nop 4
	global_load_dwordx4 v[142:145], v130, s[60:61]
	global_load_dwordx4 v[138:141], v130, s[60:61] offset:64
	global_load_dwordx4 v[134:137], v130, s[60:61] offset:128
	s_nop 0
	global_load_dwordx4 v[130:133], v130, s[60:61] offset:192
	s_ashr_i32 s34, s47, 2
	v_add_u32_e32 v146, s45, v225
	s_cmpk_gt_u32 s6, 0x3ff
	v_or3_b32 v148, v224, s2, v0
	v_subrev_u32_e32 v146, s39, v146
	s_cselect_b64 s[2:3], -1, 0
	v_ashrrev_i32_e32 v147, 31, v146
	s_mov_b64 s[4:5], -1
	s_and_b64 vcc, exec, s[2:3]
	v_readlane_b32 s49, v254, 56
	v_readlane_b32 s50, v254, 57
	v_readlane_b32 s51, v254, 58
	v_readlane_b32 s52, v254, 59
	v_readlane_b32 s53, v254, 60
	v_readlane_b32 s54, v254, 61
	v_readlane_b32 s55, v254, 62
	v_readlane_b32 s56, v254, 63
	v_readlane_b32 s57, v255, 0
	v_readlane_b32 s58, v255, 1
	v_readlane_b32 s59, v255, 2
	v_readlane_b32 s62, v255, 5
	v_readlane_b32 s63, v255, 6
	s_cbranch_vccz .LBB0_665
	s_cmp_gt_i32 s34, 2
	s_cbranch_scc0 .LBB0_662
	s_cmp_eq_u32 s34, 3
	s_cbranch_scc1 .LBB0_659
	v_mul_f32_e32 v0, 0xbfb8aa3b, v126
	v_exp_f32_e32 v150, v0
	v_mul_f32_e32 v0, 0xbfb8aa3b, v127
	v_exp_f32_e32 v151, v0
	v_readlane_b32 s48, v253, 4
	v_readlane_b32 s49, v253, 5
	v_readlane_b32 s50, v253, 6
	v_pk_add_f32 v[150:151], v[150:151], 1.0 op_sel_hi:[1,0]
	v_readlane_b32 s51, v253, 7
	v_rcp_f32_e32 v149, v150
	s_nop 0
	v_mul_f32_e32 v0, v126, v149
	v_rcp_f32_e32 v150, v151
	s_nop 0
	v_mul_f32_e32 v149, v127, v150
	v_mul_f32_e32 v150, 0xbfb8aa3b, v128
	v_mul_f32_e32 v151, 0xbfb8aa3b, v129
	v_exp_f32_e32 v150, v150
	v_exp_f32_e32 v151, v151
	s_nop 0
	v_pk_add_f32 v[150:151], v[150:151], 1.0 op_sel_hi:[1,0]
	s_nop 0
	v_rcp_f32_e32 v153, v150
	s_nop 0
	v_mul_f32_e32 v152, v128, v153
	v_mov_b32_e32 v150, v152
	v_rcp_f32_e32 v153, v151
	s_mov_b64 s[4:5], 0
	v_mul_f32_e32 v152, v129, v153
	v_mov_b32_e32 v151, v152
	v_lshlrev_b64 v[152:153], 11, v[146:147]
	v_cvt_pk_bf16_f32 v151, v150, v151
	v_cvt_pk_bf16_f32 v150, v0, v149
	v_lshl_add_u64 v[152:153], s[48:49], 0, v[152:153]
	v_lshlrev_b32_e32 v0, 1, v148
	v_lshl_add_u64 v[152:153], v[152:153], 0, v[0:1]
	global_store_dwordx2 v[152:153], v[150:151], off
.LBB0_659:
	s_andn2_b64 vcc, exec, s[4:5]
	s_cbranch_vccnz .LBB0_661
	v_readlane_b32 s48, v252, 16
	v_cvt_pk_bf16_f32 v150, v126, v127
	v_lshlrev_b64 v[152:153], 11, v[146:147]
	v_readlane_b32 s62, v252, 30
	v_readlane_b32 s63, v252, 31
	v_cvt_pk_bf16_f32 v151, v128, v129
	v_lshlrev_b32_e32 v0, 1, v148
	v_lshl_add_u64 v[152:153], s[62:63], 0, v[152:153]
	v_lshl_add_u64 v[152:153], v[152:153], 0, v[0:1]
	v_readlane_b32 s49, v252, 17
	v_readlane_b32 s50, v252, 18
	v_readlane_b32 s51, v252, 19
	v_readlane_b32 s52, v252, 20
	v_readlane_b32 s53, v252, 21
	v_readlane_b32 s54, v252, 22
	v_readlane_b32 s55, v252, 23
	v_readlane_b32 s56, v252, 24
	v_readlane_b32 s57, v252, 25
	v_readlane_b32 s58, v252, 26
	v_readlane_b32 s59, v252, 27
	v_readlane_b32 s60, v252, 28
	v_readlane_b32 s61, v252, 29
	global_store_dwordx2 v[152:153], v[150:151], off

.LBB0_665:
	v_readlane_b32 s48, v252, 16
	v_lshlrev_b64 v[150:151], 11, v[146:147]
	v_readlane_b32 s58, v252, 26
	v_readlane_b32 s59, v252, 27
	s_andn2_b64 vcc, exec, s[4:5]
	v_lshlrev_b32_e32 v0, 1, v148
	v_lshl_add_u64 v[148:149], s[58:59], 0, v[150:151]
	v_readlane_b32 s49, v252, 17
	v_readlane_b32 s50, v252, 18
	v_readlane_b32 s51, v252, 19
	v_readlane_b32 s52, v252, 20
	v_readlane_b32 s53, v252, 21
	v_readlane_b32 s54, v252, 22
	v_readlane_b32 s55, v252, 23
	v_readlane_b32 s56, v252, 24
	v_readlane_b32 s57, v252, 25
	v_readlane_b32 s60, v252, 28
	v_readlane_b32 s61, v252, 29
	v_readlane_b32 s62, v252, 30
	v_readlane_b32 s63, v252, 31
	s_cbranch_vccnz .LBB0_667
	v_mul_f32_e32 v147, 0xbfb8aa3b, v126
	v_exp_f32_e32 v152, v147
	v_mul_f32_e32 v147, 0xbfb8aa3b, v127
	v_exp_f32_e32 v153, v147
	s_mov_b32 s14, 0x3db504f3
	v_pk_add_f32 v[152:153], v[152:153], 1.0 op_sel_hi:[1,0]
	s_nop 0
	v_rcp_f32_e32 v154, v153
	s_nop 0
	v_mul_f32_e32 v147, v127, v154
	v_mov_b32_e32 v153, v147
	v_rcp_f32_e32 v154, v152
	s_nop 0
	v_mul_f32_e32 v147, v126, v154
	v_mov_b32_e32 v152, v147
	v_mul_f32_e32 v147, 0xbfb8aa3b, v128
	v_exp_f32_e32 v154, v147
	v_mul_f32_e32 v147, 0xbfb8aa3b, v129
	v_exp_f32_e32 v155, v147
	v_pk_mul_f32 v[152:153], v[152:153], s[14:15] op_sel_hi:[1,0]
	v_pk_add_f32 v[154:155], v[154:155], 1.0 op_sel_hi:[1,0]
	s_nop 0
	v_rcp_f32_e32 v156, v155
	s_nop 0
	v_mul_f32_e32 v147, v129, v156
	v_mov_b32_e32 v155, v147
	v_rcp_f32_e32 v156, v154
	s_nop 0
	v_mul_f32_e32 v147, v128, v156
	v_mov_b32_e32 v154, v147
	v_pk_mul_f32 v[154:155], v[154:155], s[14:15] op_sel_hi:[1,0]
	v_mov_b32_e32 v157, v153
	v_cvt_pk_bf16_f32 v153, v154, v155
	v_cvt_pk_bf16_f32 v152, v152, v157
	v_lshl_add_u64 v[154:155], v[148:149], 0, v[0:1]
	global_store_dwordx2 v[154:155], v[152:153], off
.LBB0_667:
	v_cndmask_b32_e64 v147, 0, 1, s[2:3]
	v_cmp_ne_u32_e64 s[40:41], 1, v147
	s_andn2_b64 vcc, exec, s[2:3]
	s_mov_b64 s[2:3], -1
	s_cbranch_vccnz .LBB0_677
	s_cmp_lt_i32 s34, 3
	s_cbranch_scc1 .LBB0_674
	s_cmp_eq_u32 s34, 3
	s_cbranch_scc1 .LBB0_671
	v_mul_f32_e32 v147, 0xbfb8aa3b, v122
	v_exp_f32_e32 v152, v147
	v_mul_f32_e32 v147, 0xbfb8aa3b, v123
	v_exp_f32_e32 v153, v147
	v_readlane_b32 s48, v253, 4
	v_readlane_b32 s49, v253, 5
	v_readlane_b32 s50, v253, 6
	v_pk_add_f32 v[152:153], v[152:153], 1.0 op_sel_hi:[1,0]
	v_readlane_b32 s51, v253, 7
	v_rcp_f32_e32 v154, v152
	s_nop 0
	v_mul_f32_e32 v147, v122, v154
	v_rcp_f32_e32 v154, v153
	s_nop 0
	v_mul_f32_e32 v152, v123, v154
	v_mov_b32_e32 v154, v152
	v_mul_f32_e32 v152, 0xbfb8aa3b, v124
	v_mul_f32_e32 v153, 0xbfb8aa3b, v125
	v_exp_f32_e32 v152, v152
	v_exp_f32_e32 v153, v153
	s_nop 0
	v_pk_add_f32 v[152:153], v[152:153], 1.0 op_sel_hi:[1,0]
	s_nop 0
	v_rcp_f32_e32 v156, v152
	s_nop 0
	v_mul_f32_e32 v155, v124, v156
	v_mov_b32_e32 v152, v155
	v_rcp_f32_e32 v156, v153
	s_mov_b64 s[2:3], 0
	v_mul_f32_e32 v155, v125, v156
	v_mov_b32_e32 v153, v155
	v_cvt_pk_bf16_f32 v153, v152, v153
	v_cvt_pk_bf16_f32 v152, v147, v154
	v_lshl_add_u64 v[154:155], s[48:49], 0, v[150:151]
	v_lshl_add_u64 v[154:155], v[154:155], 0, v[0:1]
	global_store_dwordx2 v[154:155], v[152:153], off offset:32
.LBB0_671:
	s_andn2_b64 vcc, exec, s[2:3]
	s_cbranch_vccnz .LBB0_673
	v_readlane_b32 s48, v252, 16
	v_readlane_b32 s62, v252, 30
	v_readlane_b32 s63, v252, 31
	v_cvt_pk_bf16_f32 v153, v124, v125
	v_cvt_pk_bf16_f32 v152, v122, v123
	v_lshl_add_u64 v[154:155], s[62:63], 0, v[150:151]
	v_lshl_add_u64 v[154:155], v[154:155], 0, v[0:1]
	v_readlane_b32 s49, v252, 17
	v_readlane_b32 s50, v252, 18
	v_readlane_b32 s51, v252, 19
	v_readlane_b32 s52, v252, 20
	v_readlane_b32 s53, v252, 21
	v_readlane_b32 s54, v252, 22
	v_readlane_b32 s55, v252, 23
	v_readlane_b32 s56, v252, 24
	v_readlane_b32 s57, v252, 25
	v_readlane_b32 s58, v252, 26
	v_readlane_b32 s59, v252, 27
	v_readlane_b32 s60, v252, 28
	v_readlane_b32 s61, v252, 29
	global_store_dwordx2 v[154:155], v[152:153], off offset:32

.LBB0_677:
	s_andn2_b64 vcc, exec, s[2:3]
	s_cbranch_vccnz .LBB0_679
	v_mul_f32_e32 v147, 0xbfb8aa3b, v122
	v_exp_f32_e32 v152, v147
	v_mul_f32_e32 v147, 0xbfb8aa3b, v123
	v_exp_f32_e32 v153, v147
	s_mov_b32 s4, 0x3db504f3
	v_pk_add_f32 v[152:153], v[152:153], 1.0 op_sel_hi:[1,0]
	s_nop 0
	v_rcp_f32_e32 v154, v153
	s_nop 0
	v_mul_f32_e32 v147, v123, v154
	v_mov_b32_e32 v153, v147
	v_rcp_f32_e32 v154, v152
	s_nop 0
	v_mul_f32_e32 v147, v122, v154
	v_mov_b32_e32 v152, v147
	v_mul_f32_e32 v147, 0xbfb8aa3b, v124
	v_exp_f32_e32 v154, v147
	v_mul_f32_e32 v147, 0xbfb8aa3b, v125
	v_exp_f32_e32 v155, v147
	v_pk_mul_f32 v[152:153], v[152:153], s[4:5] op_sel_hi:[1,0]
	v_pk_add_f32 v[154:155], v[154:155], 1.0 op_sel_hi:[1,0]
	s_nop 0
	v_rcp_f32_e32 v156, v155
	s_nop 0
	v_mul_f32_e32 v147, v125, v156
	v_mov_b32_e32 v155, v147
	v_rcp_f32_e32 v156, v154
	s_nop 0
	v_mul_f32_e32 v147, v124, v156
	v_mov_b32_e32 v154, v147
	v_pk_mul_f32 v[154:155], v[154:155], s[4:5] op_sel_hi:[1,0]
	v_mov_b32_e32 v157, v153
	v_cvt_pk_bf16_f32 v153, v154, v155
	v_cvt_pk_bf16_f32 v152, v152, v157
	v_lshl_add_u64 v[154:155], v[148:149], 0, v[0:1]
	global_store_dwordx2 v[154:155], v[152:153], off offset:32
.LBB0_679:
	s_and_b64 vcc, exec, s[40:41]
	s_mov_b64 s[2:3], -1
	s_cbranch_vccnz .LBB0_689
	s_cmp_lt_i32 s34, 3
	s_cbranch_scc1 .LBB0_686
	s_cmp_eq_u32 s34, 3
	s_cbranch_scc1 .LBB0_683
	v_mul_f32_e32 v147, 0xbfb8aa3b, v118
	v_exp_f32_e32 v152, v147
	v_mul_f32_e32 v147, 0xbfb8aa3b, v119
	v_exp_f32_e32 v153, v147
	v_readlane_b32 s48, v253, 4
	v_readlane_b32 s49, v253, 5
	v_readlane_b32 s50, v253, 6
	v_pk_add_f32 v[152:153], v[152:153], 1.0 op_sel_hi:[1,0]
	v_readlane_b32 s51, v253, 7
	v_rcp_f32_e32 v154, v152
	s_nop 0
	v_mul_f32_e32 v147, v118, v154
	v_rcp_f32_e32 v154, v153
	s_nop 0
	v_mul_f32_e32 v152, v119, v154
	v_mov_b32_e32 v154, v152
	v_mul_f32_e32 v152, 0xbfb8aa3b, v120
	v_mul_f32_e32 v153, 0xbfb8aa3b, v121
	v_exp_f32_e32 v152, v152
	v_exp_f32_e32 v153, v153
	s_nop 0
	v_pk_add_f32 v[152:153], v[152:153], 1.0 op_sel_hi:[1,0]
	s_nop 0
	v_rcp_f32_e32 v156, v152
	s_nop 0
	v_mul_f32_e32 v155, v120, v156
	v_mov_b32_e32 v152, v155
	v_rcp_f32_e32 v156, v153
	s_mov_b64 s[2:3], 0
	v_mul_f32_e32 v155, v121, v156
	v_mov_b32_e32 v153, v155
	v_cvt_pk_bf16_f32 v153, v152, v153
	v_cvt_pk_bf16_f32 v152, v147, v154
	v_lshl_add_u64 v[154:155], s[48:49], 0, v[150:151]
	v_lshl_add_u64 v[154:155], v[154:155], 0, v[0:1]
	global_store_dwordx2 v[154:155], v[152:153], off offset:64
.LBB0_683:
	s_andn2_b64 vcc, exec, s[2:3]
	s_cbranch_vccnz .LBB0_685
	v_readlane_b32 s48, v252, 16
	v_readlane_b32 s62, v252, 30
	v_readlane_b32 s63, v252, 31
	v_cvt_pk_bf16_f32 v153, v120, v121
	v_cvt_pk_bf16_f32 v152, v118, v119
	v_lshl_add_u64 v[154:155], s[62:63], 0, v[150:151]
	v_lshl_add_u64 v[154:155], v[154:155], 0, v[0:1]
	v_readlane_b32 s49, v252, 17
	v_readlane_b32 s50, v252, 18
	v_readlane_b32 s51, v252, 19
	v_readlane_b32 s52, v252, 20
	v_readlane_b32 s53, v252, 21
	v_readlane_b32 s54, v252, 22
	v_readlane_b32 s55, v252, 23
	v_readlane_b32 s56, v252, 24
	v_readlane_b32 s57, v252, 25
	v_readlane_b32 s58, v252, 26
	v_readlane_b32 s59, v252, 27
	v_readlane_b32 s60, v252, 28
	v_readlane_b32 s61, v252, 29
	global_store_dwordx2 v[154:155], v[152:153], off offset:64

.LBB0_689:
	s_andn2_b64 vcc, exec, s[2:3]
	s_cbranch_vccnz .LBB0_691
	v_mul_f32_e32 v147, 0xbfb8aa3b, v118
	v_exp_f32_e32 v152, v147
	v_mul_f32_e32 v147, 0xbfb8aa3b, v119
	v_exp_f32_e32 v153, v147
	s_mov_b32 s4, 0x3db504f3
	v_pk_add_f32 v[152:153], v[152:153], 1.0 op_sel_hi:[1,0]
	s_nop 0
	v_rcp_f32_e32 v154, v153
	s_nop 0
	v_mul_f32_e32 v147, v119, v154
	v_mov_b32_e32 v153, v147
	v_rcp_f32_e32 v154, v152
	s_nop 0
	v_mul_f32_e32 v147, v118, v154
	v_mov_b32_e32 v152, v147
	v_mul_f32_e32 v147, 0xbfb8aa3b, v120
	v_exp_f32_e32 v154, v147
	v_mul_f32_e32 v147, 0xbfb8aa3b, v121
	v_exp_f32_e32 v155, v147
	v_pk_mul_f32 v[152:153], v[152:153], s[4:5] op_sel_hi:[1,0]
	v_pk_add_f32 v[154:155], v[154:155], 1.0 op_sel_hi:[1,0]
	s_nop 0
	v_rcp_f32_e32 v156, v155
	s_nop 0
	v_mul_f32_e32 v147, v121, v156
	v_mov_b32_e32 v155, v147
	v_rcp_f32_e32 v156, v154
	s_nop 0
	v_mul_f32_e32 v147, v120, v156
	v_mov_b32_e32 v154, v147
	v_pk_mul_f32 v[154:155], v[154:155], s[4:5] op_sel_hi:[1,0]
	v_mov_b32_e32 v157, v153
	v_cvt_pk_bf16_f32 v153, v154, v155
	v_cvt_pk_bf16_f32 v152, v152, v157
	v_lshl_add_u64 v[154:155], v[148:149], 0, v[0:1]
	global_store_dwordx2 v[154:155], v[152:153], off offset:64
.LBB0_691:
	s_and_b64 vcc, exec, s[40:41]
	s_mov_b64 s[2:3], -1
	s_cbranch_vccnz .LBB0_701
	s_cmp_lt_i32 s34, 3
	s_cbranch_scc1 .LBB0_698
	s_cmp_eq_u32 s34, 3
	s_cbranch_scc1 .LBB0_695
	v_mul_f32_e32 v147, 0xbfb8aa3b, v114
	v_exp_f32_e32 v152, v147
	v_mul_f32_e32 v147, 0xbfb8aa3b, v115
	v_exp_f32_e32 v153, v147
	v_readlane_b32 s48, v253, 4
	v_readlane_b32 s49, v253, 5
	v_readlane_b32 s50, v253, 6
	v_pk_add_f32 v[152:153], v[152:153], 1.0 op_sel_hi:[1,0]
	v_readlane_b32 s51, v253, 7
	v_rcp_f32_e32 v154, v152
	s_nop 0
	v_mul_f32_e32 v147, v114, v154
	v_rcp_f32_e32 v154, v153
	s_nop 0
	v_mul_f32_e32 v152, v115, v154
	v_mov_b32_e32 v154, v152
	v_mul_f32_e32 v152, 0xbfb8aa3b, v116
	v_mul_f32_e32 v153, 0xbfb8aa3b, v117
	v_exp_f32_e32 v152, v152
	v_exp_f32_e32 v153, v153
	s_nop 0
	v_pk_add_f32 v[152:153], v[152:153], 1.0 op_sel_hi:[1,0]
	s_nop 0
	v_rcp_f32_e32 v156, v152
	s_nop 0
	v_mul_f32_e32 v155, v116, v156
	v_mov_b32_e32 v152, v155
	v_rcp_f32_e32 v156, v153
	s_mov_b64 s[2:3], 0
	v_mul_f32_e32 v155, v117, v156
	v_mov_b32_e32 v153, v155
	v_cvt_pk_bf16_f32 v153, v152, v153
	v_cvt_pk_bf16_f32 v152, v147, v154
	v_lshl_add_u64 v[154:155], s[48:49], 0, v[150:151]
	v_lshl_add_u64 v[154:155], v[154:155], 0, v[0:1]
	global_store_dwordx2 v[154:155], v[152:153], off offset:96
.LBB0_695:
	s_andn2_b64 vcc, exec, s[2:3]
	s_cbranch_vccnz .LBB0_697
	v_readlane_b32 s48, v252, 16
	v_readlane_b32 s62, v252, 30
	v_readlane_b32 s63, v252, 31
	v_cvt_pk_bf16_f32 v153, v116, v117
	v_cvt_pk_bf16_f32 v152, v114, v115
	v_lshl_add_u64 v[154:155], s[62:63], 0, v[150:151]
	v_lshl_add_u64 v[154:155], v[154:155], 0, v[0:1]
	v_readlane_b32 s49, v252, 17
	v_readlane_b32 s50, v252, 18
	v_readlane_b32 s51, v252, 19
	v_readlane_b32 s52, v252, 20
	v_readlane_b32 s53, v252, 21
	v_readlane_b32 s54, v252, 22
	v_readlane_b32 s55, v252, 23
	v_readlane_b32 s56, v252, 24
	v_readlane_b32 s57, v252, 25
	v_readlane_b32 s58, v252, 26
	v_readlane_b32 s59, v252, 27
	v_readlane_b32 s60, v252, 28
	v_readlane_b32 s61, v252, 29
	global_store_dwordx2 v[154:155], v[152:153], off offset:96

.LBB0_701:
	s_andn2_b64 vcc, exec, s[2:3]
	s_cbranch_vccnz .LBB0_703
	v_mul_f32_e32 v147, 0xbfb8aa3b, v114
	v_exp_f32_e32 v150, v147
	v_mul_f32_e32 v147, 0xbfb8aa3b, v115
	v_exp_f32_e32 v151, v147
	s_mov_b32 s4, 0x3db504f3
	v_lshl_add_u64 v[148:149], v[148:149], 0, v[0:1]
	v_pk_add_f32 v[150:151], v[150:151], 1.0 op_sel_hi:[1,0]
	s_nop 0
	v_rcp_f32_e32 v152, v151
	s_nop 0
	v_mul_f32_e32 v147, v115, v152
	v_mov_b32_e32 v151, v147
	v_rcp_f32_e32 v152, v150
	s_nop 0
	v_mul_f32_e32 v147, v114, v152
	v_mov_b32_e32 v150, v147
	v_mul_f32_e32 v147, 0xbfb8aa3b, v116
	v_exp_f32_e32 v152, v147
	v_mul_f32_e32 v147, 0xbfb8aa3b, v117
	v_exp_f32_e32 v153, v147
	v_pk_mul_f32 v[150:151], v[150:151], s[4:5] op_sel_hi:[1,0]
	v_pk_add_f32 v[152:153], v[152:153], 1.0 op_sel_hi:[1,0]
	s_nop 0
	v_rcp_f32_e32 v154, v153
	s_nop 0
	v_mul_f32_e32 v147, v117, v154
	v_mov_b32_e32 v153, v147
	v_rcp_f32_e32 v154, v152
	s_nop 0
	v_mul_f32_e32 v147, v116, v154
	v_mov_b32_e32 v152, v147
	v_pk_mul_f32 v[152:153], v[152:153], s[4:5] op_sel_hi:[1,0]
	v_mov_b32_e32 v155, v151
	v_cvt_pk_bf16_f32 v151, v152, v153
	v_cvt_pk_bf16_f32 v150, v150, v155
	global_store_dwordx2 v[148:149], v[150:151], off offset:96
.LBB0_703:
	v_or_b32_e32 v148, 16, v146
	v_ashrrev_i32_e32 v149, 31, v148
	s_and_b64 vcc, exec, s[40:41]
	s_mov_b64 s[2:3], -1
	s_cbranch_vccnz .LBB0_713
	s_cmp_lt_i32 s34, 3
	s_cbranch_scc1 .LBB0_710
	s_cmp_eq_u32 s34, 3
	s_cbranch_scc1 .LBB0_707
	v_mul_f32_e32 v147, 0xbfb8aa3b, v110
	v_exp_f32_e32 v150, v147
	v_mul_f32_e32 v147, 0xbfb8aa3b, v111
	v_exp_f32_e32 v151, v147
	v_readlane_b32 s48, v253, 4
	v_readlane_b32 s49, v253, 5
	v_readlane_b32 s50, v253, 6
	v_pk_add_f32 v[150:151], v[150:151], 1.0 op_sel_hi:[1,0]
	v_readlane_b32 s51, v253, 7
	v_rcp_f32_e32 v152, v150
	s_nop 0
	v_mul_f32_e32 v147, v110, v152
	v_rcp_f32_e32 v152, v151
	s_nop 0
	v_mul_f32_e32 v150, v111, v152
	v_mov_b32_e32 v152, v150
	v_mul_f32_e32 v150, 0xbfb8aa3b, v112
	v_mul_f32_e32 v151, 0xbfb8aa3b, v113
	v_exp_f32_e32 v150, v150
	v_exp_f32_e32 v151, v151
	s_nop 0
	v_pk_add_f32 v[150:151], v[150:151], 1.0 op_sel_hi:[1,0]
	s_nop 0
	v_rcp_f32_e32 v154, v150
	s_nop 0
	v_mul_f32_e32 v153, v112, v154
	v_mov_b32_e32 v150, v153
	v_rcp_f32_e32 v154, v151
	s_mov_b64 s[2:3], 0
	v_mul_f32_e32 v153, v113, v154
	v_mov_b32_e32 v151, v153
	v_cvt_pk_bf16_f32 v151, v150, v151
	v_cvt_pk_bf16_f32 v150, v147, v152
	v_lshlrev_b64 v[152:153], 11, v[148:149]
	v_lshl_add_u64 v[152:153], s[48:49], 0, v[152:153]
	v_lshl_add_u64 v[152:153], v[152:153], 0, v[0:1]
	global_store_dwordx2 v[152:153], v[150:151], off
.LBB0_707:
	s_andn2_b64 vcc, exec, s[2:3]
	s_cbranch_vccnz .LBB0_709
	v_readlane_b32 s48, v252, 16
	v_cvt_pk_bf16_f32 v151, v112, v113
	v_cvt_pk_bf16_f32 v150, v110, v111
	v_lshlrev_b64 v[152:153], 11, v[148:149]
	v_readlane_b32 s62, v252, 30
	v_readlane_b32 s63, v252, 31
	v_readlane_b32 s49, v252, 17
	v_readlane_b32 s50, v252, 18
	v_lshl_add_u64 v[152:153], s[62:63], 0, v[152:153]
	v_lshl_add_u64 v[152:153], v[152:153], 0, v[0:1]
	v_readlane_b32 s51, v252, 19
	v_readlane_b32 s52, v252, 20
	v_readlane_b32 s53, v252, 21
	v_readlane_b32 s54, v252, 22
	v_readlane_b32 s55, v252, 23
	v_readlane_b32 s56, v252, 24
	v_readlane_b32 s57, v252, 25
	v_readlane_b32 s58, v252, 26
	v_readlane_b32 s59, v252, 27
	v_readlane_b32 s60, v252, 28
	v_readlane_b32 s61, v252, 29
	global_store_dwordx2 v[152:153], v[150:151], off

.LBB0_713:
	v_readlane_b32 s48, v252, 16
	v_lshlrev_b64 v[150:151], 11, v[148:149]
	v_readlane_b32 s58, v252, 26
	v_readlane_b32 s59, v252, 27
	s_andn2_b64 vcc, exec, s[2:3]
	v_readlane_b32 s49, v252, 17
	v_lshl_add_u64 v[148:149], s[58:59], 0, v[150:151]
	v_readlane_b32 s50, v252, 18
	v_readlane_b32 s51, v252, 19
	v_readlane_b32 s52, v252, 20
	v_readlane_b32 s53, v252, 21
	v_readlane_b32 s54, v252, 22
	v_readlane_b32 s55, v252, 23
	v_readlane_b32 s56, v252, 24
	v_readlane_b32 s57, v252, 25
	v_readlane_b32 s60, v252, 28
	v_readlane_b32 s61, v252, 29
	v_readlane_b32 s62, v252, 30
	v_readlane_b32 s63, v252, 31
	s_cbranch_vccnz .LBB0_715
	v_mul_f32_e32 v147, 0xbfb8aa3b, v110
	v_exp_f32_e32 v152, v147
	v_mul_f32_e32 v147, 0xbfb8aa3b, v111
	v_exp_f32_e32 v153, v147
	s_mov_b32 s4, 0x3db504f3
	v_pk_add_f32 v[152:153], v[152:153], 1.0 op_sel_hi:[1,0]
	s_nop 0
	v_rcp_f32_e32 v154, v153
	s_nop 0
	v_mul_f32_e32 v147, v111, v154
	v_mov_b32_e32 v153, v147
	v_rcp_f32_e32 v154, v152
	s_nop 0
	v_mul_f32_e32 v147, v110, v154
	v_mov_b32_e32 v152, v147
	v_mul_f32_e32 v147, 0xbfb8aa3b, v112
	v_exp_f32_e32 v154, v147
	v_mul_f32_e32 v147, 0xbfb8aa3b, v113
	v_exp_f32_e32 v155, v147
	v_pk_mul_f32 v[152:153], v[152:153], s[4:5] op_sel_hi:[1,0]
	v_pk_add_f32 v[154:155], v[154:155], 1.0 op_sel_hi:[1,0]
	s_nop 0
	v_rcp_f32_e32 v156, v155
	s_nop 0
	v_mul_f32_e32 v147, v113, v156
	v_mov_b32_e32 v155, v147
	v_rcp_f32_e32 v156, v154
	s_nop 0
	v_mul_f32_e32 v147, v112, v156
	v_mov_b32_e32 v154, v147
	v_pk_mul_f32 v[154:155], v[154:155], s[4:5] op_sel_hi:[1,0]
	v_mov_b32_e32 v157, v153
	v_cvt_pk_bf16_f32 v153, v154, v155
	v_cvt_pk_bf16_f32 v152, v152, v157
	v_lshl_add_u64 v[154:155], v[148:149], 0, v[0:1]
	global_store_dwordx2 v[154:155], v[152:153], off
.LBB0_715:
	s_and_b64 vcc, exec, s[40:41]
	s_mov_b64 s[2:3], -1
	s_cbranch_vccnz .LBB0_725
	s_cmp_lt_i32 s34, 3
	s_cbranch_scc1 .LBB0_722
	s_cmp_eq_u32 s34, 3
	s_cbranch_scc1 .LBB0_719
	v_mul_f32_e32 v147, 0xbfb8aa3b, v106
	v_exp_f32_e32 v152, v147
	v_mul_f32_e32 v147, 0xbfb8aa3b, v107
	v_exp_f32_e32 v153, v147
	v_readlane_b32 s48, v253, 4
	v_readlane_b32 s49, v253, 5
	v_readlane_b32 s50, v253, 6
	v_pk_add_f32 v[152:153], v[152:153], 1.0 op_sel_hi:[1,0]
	v_readlane_b32 s51, v253, 7
	v_rcp_f32_e32 v154, v152
	s_nop 0
	v_mul_f32_e32 v147, v106, v154
	v_rcp_f32_e32 v154, v153
	s_nop 0
	v_mul_f32_e32 v152, v107, v154
	v_mov_b32_e32 v154, v152
	v_mul_f32_e32 v152, 0xbfb8aa3b, v108
	v_mul_f32_e32 v153, 0xbfb8aa3b, v109
	v_exp_f32_e32 v152, v152
	v_exp_f32_e32 v153, v153
	s_nop 0
	v_pk_add_f32 v[152:153], v[152:153], 1.0 op_sel_hi:[1,0]
	s_nop 0
	v_rcp_f32_e32 v156, v152
	s_nop 0
	v_mul_f32_e32 v155, v108, v156
	v_mov_b32_e32 v152, v155
	v_rcp_f32_e32 v156, v153
	s_mov_b64 s[2:3], 0
	v_mul_f32_e32 v155, v109, v156
	v_mov_b32_e32 v153, v155
	v_cvt_pk_bf16_f32 v153, v152, v153
	v_cvt_pk_bf16_f32 v152, v147, v154
	v_lshl_add_u64 v[154:155], s[48:49], 0, v[150:151]
	v_lshl_add_u64 v[154:155], v[154:155], 0, v[0:1]
	global_store_dwordx2 v[154:155], v[152:153], off offset:32
.LBB0_719:
	s_andn2_b64 vcc, exec, s[2:3]
	s_cbranch_vccnz .LBB0_721
	v_readlane_b32 s48, v252, 16
	v_readlane_b32 s62, v252, 30
	v_readlane_b32 s63, v252, 31
	v_cvt_pk_bf16_f32 v153, v108, v109
	v_cvt_pk_bf16_f32 v152, v106, v107
	v_lshl_add_u64 v[154:155], s[62:63], 0, v[150:151]
	v_lshl_add_u64 v[154:155], v[154:155], 0, v[0:1]
	v_readlane_b32 s49, v252, 17
	v_readlane_b32 s50, v252, 18
	v_readlane_b32 s51, v252, 19
	v_readlane_b32 s52, v252, 20
	v_readlane_b32 s53, v252, 21
	v_readlane_b32 s54, v252, 22
	v_readlane_b32 s55, v252, 23
	v_readlane_b32 s56, v252, 24
	v_readlane_b32 s57, v252, 25
	v_readlane_b32 s58, v252, 26
	v_readlane_b32 s59, v252, 27
	v_readlane_b32 s60, v252, 28
	v_readlane_b32 s61, v252, 29
	global_store_dwordx2 v[154:155], v[152:153], off offset:32

.LBB0_725:
	s_andn2_b64 vcc, exec, s[2:3]
	s_cbranch_vccnz .LBB0_727
	v_mul_f32_e32 v147, 0xbfb8aa3b, v106
	v_exp_f32_e32 v152, v147
	v_mul_f32_e32 v147, 0xbfb8aa3b, v107
	v_exp_f32_e32 v153, v147
	s_mov_b32 s4, 0x3db504f3
	v_pk_add_f32 v[152:153], v[152:153], 1.0 op_sel_hi:[1,0]
	s_nop 0
	v_rcp_f32_e32 v154, v153
	s_nop 0
	v_mul_f32_e32 v147, v107, v154
	v_mov_b32_e32 v153, v147
	v_rcp_f32_e32 v154, v152
	s_nop 0
	v_mul_f32_e32 v147, v106, v154
	v_mov_b32_e32 v152, v147
	v_mul_f32_e32 v147, 0xbfb8aa3b, v108
	v_exp_f32_e32 v154, v147
	v_mul_f32_e32 v147, 0xbfb8aa3b, v109
	v_exp_f32_e32 v155, v147
	v_pk_mul_f32 v[152:153], v[152:153], s[4:5] op_sel_hi:[1,0]
	v_pk_add_f32 v[154:155], v[154:155], 1.0 op_sel_hi:[1,0]
	s_nop 0
	v_rcp_f32_e32 v156, v155
	s_nop 0
	v_mul_f32_e32 v147, v109, v156
	v_mov_b32_e32 v155, v147
	v_rcp_f32_e32 v156, v154
	s_nop 0
	v_mul_f32_e32 v147, v108, v156
	v_mov_b32_e32 v154, v147
	v_pk_mul_f32 v[154:155], v[154:155], s[4:5] op_sel_hi:[1,0]
	v_mov_b32_e32 v157, v153
	v_cvt_pk_bf16_f32 v153, v154, v155
	v_cvt_pk_bf16_f32 v152, v152, v157
	v_lshl_add_u64 v[154:155], v[148:149], 0, v[0:1]
	global_store_dwordx2 v[154:155], v[152:153], off offset:32
.LBB0_727:
	s_and_b64 vcc, exec, s[40:41]
	s_mov_b64 s[2:3], -1
	s_cbranch_vccnz .LBB0_737
	s_cmp_lt_i32 s34, 3
	s_cbranch_scc1 .LBB0_734
	s_cmp_eq_u32 s34, 3
	s_cbranch_scc1 .LBB0_731
	v_mul_f32_e32 v147, 0xbfb8aa3b, v102
	v_exp_f32_e32 v152, v147
	v_mul_f32_e32 v147, 0xbfb8aa3b, v103
	v_exp_f32_e32 v153, v147
	v_readlane_b32 s48, v253, 4
	v_readlane_b32 s49, v253, 5
	v_readlane_b32 s50, v253, 6
	v_pk_add_f32 v[152:153], v[152:153], 1.0 op_sel_hi:[1,0]
	v_readlane_b32 s51, v253, 7
	v_rcp_f32_e32 v154, v152
	s_nop 0
	v_mul_f32_e32 v147, v102, v154
	v_rcp_f32_e32 v154, v153
	s_nop 0
	v_mul_f32_e32 v152, v103, v154
	v_mov_b32_e32 v154, v152
	v_mul_f32_e32 v152, 0xbfb8aa3b, v104
	v_mul_f32_e32 v153, 0xbfb8aa3b, v105
	v_exp_f32_e32 v152, v152
	v_exp_f32_e32 v153, v153
	s_nop 0
	v_pk_add_f32 v[152:153], v[152:153], 1.0 op_sel_hi:[1,0]
	s_nop 0
	v_rcp_f32_e32 v156, v152
	s_nop 0
	v_mul_f32_e32 v155, v104, v156
	v_mov_b32_e32 v152, v155
	v_rcp_f32_e32 v156, v153
	s_mov_b64 s[2:3], 0
	v_mul_f32_e32 v155, v105, v156
	v_mov_b32_e32 v153, v155
	v_cvt_pk_bf16_f32 v153, v152, v153
	v_cvt_pk_bf16_f32 v152, v147, v154
	v_lshl_add_u64 v[154:155], s[48:49], 0, v[150:151]
	v_lshl_add_u64 v[154:155], v[154:155], 0, v[0:1]
	global_store_dwordx2 v[154:155], v[152:153], off offset:64
.LBB0_731:
	s_andn2_b64 vcc, exec, s[2:3]
	s_cbranch_vccnz .LBB0_733
	v_readlane_b32 s48, v252, 16
	v_readlane_b32 s62, v252, 30
	v_readlane_b32 s63, v252, 31
	v_cvt_pk_bf16_f32 v153, v104, v105
	v_cvt_pk_bf16_f32 v152, v102, v103
	v_lshl_add_u64 v[154:155], s[62:63], 0, v[150:151]
	v_lshl_add_u64 v[154:155], v[154:155], 0, v[0:1]
	v_readlane_b32 s49, v252, 17
	v_readlane_b32 s50, v252, 18
	v_readlane_b32 s51, v252, 19
	v_readlane_b32 s52, v252, 20
	v_readlane_b32 s53, v252, 21
	v_readlane_b32 s54, v252, 22
	v_readlane_b32 s55, v252, 23
	v_readlane_b32 s56, v252, 24
	v_readlane_b32 s57, v252, 25
	v_readlane_b32 s58, v252, 26
	v_readlane_b32 s59, v252, 27
	v_readlane_b32 s60, v252, 28
	v_readlane_b32 s61, v252, 29
	global_store_dwordx2 v[154:155], v[152:153], off offset:64

.LBB0_737:
	s_andn2_b64 vcc, exec, s[2:3]
	s_cbranch_vccnz .LBB0_739
	v_mul_f32_e32 v147, 0xbfb8aa3b, v102
	v_exp_f32_e32 v152, v147
	v_mul_f32_e32 v147, 0xbfb8aa3b, v103
	v_exp_f32_e32 v153, v147
	s_mov_b32 s4, 0x3db504f3
	v_pk_add_f32 v[152:153], v[152:153], 1.0 op_sel_hi:[1,0]
	s_nop 0
	v_rcp_f32_e32 v154, v153
	s_nop 0
	v_mul_f32_e32 v147, v103, v154
	v_mov_b32_e32 v153, v147
	v_rcp_f32_e32 v154, v152
	s_nop 0
	v_mul_f32_e32 v147, v102, v154
	v_mov_b32_e32 v152, v147
	v_mul_f32_e32 v147, 0xbfb8aa3b, v104
	v_exp_f32_e32 v154, v147
	v_mul_f32_e32 v147, 0xbfb8aa3b, v105
	v_exp_f32_e32 v155, v147
	v_pk_mul_f32 v[152:153], v[152:153], s[4:5] op_sel_hi:[1,0]
	v_pk_add_f32 v[154:155], v[154:155], 1.0 op_sel_hi:[1,0]
	s_nop 0
	v_rcp_f32_e32 v156, v155
	s_nop 0
	v_mul_f32_e32 v147, v105, v156
	v_mov_b32_e32 v155, v147
	v_rcp_f32_e32 v156, v154
	s_nop 0
	v_mul_f32_e32 v147, v104, v156
	v_mov_b32_e32 v154, v147
	v_pk_mul_f32 v[154:155], v[154:155], s[4:5] op_sel_hi:[1,0]
	v_mov_b32_e32 v157, v153
	v_cvt_pk_bf16_f32 v153, v154, v155
	v_cvt_pk_bf16_f32 v152, v152, v157
	v_lshl_add_u64 v[154:155], v[148:149], 0, v[0:1]
	global_store_dwordx2 v[154:155], v[152:153], off offset:64
.LBB0_739:
	s_and_b64 vcc, exec, s[40:41]
	s_mov_b64 s[2:3], -1
	s_cbranch_vccnz .LBB0_749
	s_cmp_lt_i32 s34, 3
	s_cbranch_scc1 .LBB0_746
	s_cmp_eq_u32 s34, 3
	s_cbranch_scc1 .LBB0_743
	v_mul_f32_e32 v147, 0xbfb8aa3b, v98
	v_exp_f32_e32 v152, v147
	v_mul_f32_e32 v147, 0xbfb8aa3b, v99
	v_exp_f32_e32 v153, v147
	v_readlane_b32 s48, v253, 4
	v_readlane_b32 s49, v253, 5
	v_readlane_b32 s50, v253, 6
	v_pk_add_f32 v[152:153], v[152:153], 1.0 op_sel_hi:[1,0]
	v_readlane_b32 s51, v253, 7
	v_rcp_f32_e32 v154, v152
	s_nop 0
	v_mul_f32_e32 v147, v98, v154
	v_rcp_f32_e32 v154, v153
	s_nop 0
	v_mul_f32_e32 v152, v99, v154
	v_mov_b32_e32 v154, v152
	v_mul_f32_e32 v152, 0xbfb8aa3b, v100
	v_mul_f32_e32 v153, 0xbfb8aa3b, v101
	v_exp_f32_e32 v152, v152
	v_exp_f32_e32 v153, v153
	s_nop 0
	v_pk_add_f32 v[152:153], v[152:153], 1.0 op_sel_hi:[1,0]
	s_nop 0
	v_rcp_f32_e32 v156, v152
	s_nop 0
	v_mul_f32_e32 v155, v100, v156
	v_mov_b32_e32 v152, v155
	v_rcp_f32_e32 v156, v153
	s_mov_b64 s[2:3], 0
	v_mul_f32_e32 v155, v101, v156
	v_mov_b32_e32 v153, v155
	v_cvt_pk_bf16_f32 v153, v152, v153
	v_cvt_pk_bf16_f32 v152, v147, v154
	v_lshl_add_u64 v[154:155], s[48:49], 0, v[150:151]
	v_lshl_add_u64 v[154:155], v[154:155], 0, v[0:1]
	global_store_dwordx2 v[154:155], v[152:153], off offset:96
.LBB0_743:
	s_andn2_b64 vcc, exec, s[2:3]
	s_cbranch_vccnz .LBB0_745
	v_readlane_b32 s48, v252, 16
	v_readlane_b32 s62, v252, 30
	v_readlane_b32 s63, v252, 31
	v_cvt_pk_bf16_f32 v153, v100, v101
	v_cvt_pk_bf16_f32 v152, v98, v99
	v_lshl_add_u64 v[154:155], s[62:63], 0, v[150:151]
	v_lshl_add_u64 v[154:155], v[154:155], 0, v[0:1]
	v_readlane_b32 s49, v252, 17
	v_readlane_b32 s50, v252, 18
	v_readlane_b32 s51, v252, 19
	v_readlane_b32 s52, v252, 20
	v_readlane_b32 s53, v252, 21
	v_readlane_b32 s54, v252, 22
	v_readlane_b32 s55, v252, 23
	v_readlane_b32 s56, v252, 24
	v_readlane_b32 s57, v252, 25
	v_readlane_b32 s58, v252, 26
	v_readlane_b32 s59, v252, 27
	v_readlane_b32 s60, v252, 28
	v_readlane_b32 s61, v252, 29
	global_store_dwordx2 v[154:155], v[152:153], off offset:96

.LBB0_749:
	s_andn2_b64 vcc, exec, s[2:3]
	s_cbranch_vccnz .LBB0_751
	v_mul_f32_e32 v147, 0xbfb8aa3b, v98
	v_exp_f32_e32 v150, v147
	v_mul_f32_e32 v147, 0xbfb8aa3b, v99
	v_exp_f32_e32 v151, v147
	s_mov_b32 s4, 0x3db504f3
	v_lshl_add_u64 v[148:149], v[148:149], 0, v[0:1]
	v_pk_add_f32 v[150:151], v[150:151], 1.0 op_sel_hi:[1,0]
	s_nop 0
	v_rcp_f32_e32 v152, v151
	s_nop 0
	v_mul_f32_e32 v147, v99, v152
	v_mov_b32_e32 v151, v147
	v_rcp_f32_e32 v152, v150
	s_nop 0
	v_mul_f32_e32 v147, v98, v152
	v_mov_b32_e32 v150, v147
	v_mul_f32_e32 v147, 0xbfb8aa3b, v100
	v_exp_f32_e32 v152, v147
	v_mul_f32_e32 v147, 0xbfb8aa3b, v101
	v_exp_f32_e32 v153, v147
	v_pk_mul_f32 v[150:151], v[150:151], s[4:5] op_sel_hi:[1,0]
	v_pk_add_f32 v[152:153], v[152:153], 1.0 op_sel_hi:[1,0]
	s_nop 0
	v_rcp_f32_e32 v154, v153
	s_nop 0
	v_mul_f32_e32 v147, v101, v154
	v_mov_b32_e32 v153, v147
	v_rcp_f32_e32 v154, v152
	s_nop 0
	v_mul_f32_e32 v147, v100, v154
	v_mov_b32_e32 v152, v147
	v_pk_mul_f32 v[152:153], v[152:153], s[4:5] op_sel_hi:[1,0]
	v_mov_b32_e32 v155, v151
	v_cvt_pk_bf16_f32 v151, v152, v153
	v_cvt_pk_bf16_f32 v150, v150, v155
	global_store_dwordx2 v[148:149], v[150:151], off offset:96
.LBB0_751:
	v_or_b32_e32 v148, 32, v146
	v_ashrrev_i32_e32 v149, 31, v148
	s_and_b64 vcc, exec, s[40:41]
	s_mov_b64 s[2:3], -1
	s_cbranch_vccnz .LBB0_761
	s_cmp_lt_i32 s34, 3
	s_cbranch_scc1 .LBB0_758
	s_cmp_eq_u32 s34, 3
	s_cbranch_scc1 .LBB0_755
	v_mul_f32_e32 v147, 0xbfb8aa3b, v94
	v_exp_f32_e32 v150, v147
	v_mul_f32_e32 v147, 0xbfb8aa3b, v95
	v_exp_f32_e32 v151, v147
	v_readlane_b32 s48, v253, 4
	v_readlane_b32 s49, v253, 5
	v_readlane_b32 s50, v253, 6
	v_pk_add_f32 v[150:151], v[150:151], 1.0 op_sel_hi:[1,0]
	v_readlane_b32 s51, v253, 7
	v_rcp_f32_e32 v152, v150
	s_nop 0
	v_mul_f32_e32 v147, v94, v152
	v_rcp_f32_e32 v152, v151
	s_nop 0
	v_mul_f32_e32 v150, v95, v152
	v_mov_b32_e32 v152, v150
	v_mul_f32_e32 v150, 0xbfb8aa3b, v96
	v_mul_f32_e32 v151, 0xbfb8aa3b, v97
	v_exp_f32_e32 v150, v150
	v_exp_f32_e32 v151, v151
	s_nop 0
	v_pk_add_f32 v[150:151], v[150:151], 1.0 op_sel_hi:[1,0]
	s_nop 0
	v_rcp_f32_e32 v154, v150
	s_nop 0
	v_mul_f32_e32 v153, v96, v154
	v_mov_b32_e32 v150, v153
	v_rcp_f32_e32 v154, v151
	s_mov_b64 s[2:3], 0
	v_mul_f32_e32 v153, v97, v154
	v_mov_b32_e32 v151, v153
	v_cvt_pk_bf16_f32 v151, v150, v151
	v_cvt_pk_bf16_f32 v150, v147, v152
	v_lshlrev_b64 v[152:153], 11, v[148:149]
	v_lshl_add_u64 v[152:153], s[48:49], 0, v[152:153]
	v_lshl_add_u64 v[152:153], v[152:153], 0, v[0:1]
	global_store_dwordx2 v[152:153], v[150:151], off
.LBB0_755:
	s_andn2_b64 vcc, exec, s[2:3]
	s_cbranch_vccnz .LBB0_757
	v_readlane_b32 s48, v252, 16
	v_cvt_pk_bf16_f32 v151, v96, v97
	v_cvt_pk_bf16_f32 v150, v94, v95
	v_lshlrev_b64 v[152:153], 11, v[148:149]
	v_readlane_b32 s62, v252, 30
	v_readlane_b32 s63, v252, 31
	v_readlane_b32 s49, v252, 17
	v_readlane_b32 s50, v252, 18
	v_lshl_add_u64 v[152:153], s[62:63], 0, v[152:153]
	v_lshl_add_u64 v[152:153], v[152:153], 0, v[0:1]
	v_readlane_b32 s51, v252, 19
	v_readlane_b32 s52, v252, 20
	v_readlane_b32 s53, v252, 21
	v_readlane_b32 s54, v252, 22
	v_readlane_b32 s55, v252, 23
	v_readlane_b32 s56, v252, 24
	v_readlane_b32 s57, v252, 25
	v_readlane_b32 s58, v252, 26
	v_readlane_b32 s59, v252, 27
	v_readlane_b32 s60, v252, 28
	v_readlane_b32 s61, v252, 29
	global_store_dwordx2 v[152:153], v[150:151], off

.LBB0_761:
	v_readlane_b32 s48, v252, 16
	v_lshlrev_b64 v[150:151], 11, v[148:149]
	v_readlane_b32 s58, v252, 26
	v_readlane_b32 s59, v252, 27
	s_andn2_b64 vcc, exec, s[2:3]
	v_readlane_b32 s49, v252, 17
	v_lshl_add_u64 v[148:149], s[58:59], 0, v[150:151]
	v_readlane_b32 s50, v252, 18
	v_readlane_b32 s51, v252, 19
	v_readlane_b32 s52, v252, 20
	v_readlane_b32 s53, v252, 21
	v_readlane_b32 s54, v252, 22
	v_readlane_b32 s55, v252, 23
	v_readlane_b32 s56, v252, 24
	v_readlane_b32 s57, v252, 25
	v_readlane_b32 s60, v252, 28
	v_readlane_b32 s61, v252, 29
	v_readlane_b32 s62, v252, 30
	v_readlane_b32 s63, v252, 31
	s_cbranch_vccnz .LBB0_763
	v_mul_f32_e32 v147, 0xbfb8aa3b, v94
	v_exp_f32_e32 v152, v147
	v_mul_f32_e32 v147, 0xbfb8aa3b, v95
	v_exp_f32_e32 v153, v147
	s_mov_b32 s4, 0x3db504f3
	v_pk_add_f32 v[152:153], v[152:153], 1.0 op_sel_hi:[1,0]
	s_nop 0
	v_rcp_f32_e32 v154, v153
	s_nop 0
	v_mul_f32_e32 v147, v95, v154
	v_mov_b32_e32 v153, v147
	v_rcp_f32_e32 v154, v152
	s_nop 0
	v_mul_f32_e32 v147, v94, v154
	v_mov_b32_e32 v152, v147
	v_mul_f32_e32 v147, 0xbfb8aa3b, v96
	v_exp_f32_e32 v154, v147
	v_mul_f32_e32 v147, 0xbfb8aa3b, v97
	v_exp_f32_e32 v155, v147
	v_pk_mul_f32 v[152:153], v[152:153], s[4:5] op_sel_hi:[1,0]
	v_pk_add_f32 v[154:155], v[154:155], 1.0 op_sel_hi:[1,0]
	s_nop 0
	v_rcp_f32_e32 v156, v155
	s_nop 0
	v_mul_f32_e32 v147, v97, v156
	v_mov_b32_e32 v155, v147
	v_rcp_f32_e32 v156, v154
	s_nop 0
	v_mul_f32_e32 v147, v96, v156
	v_mov_b32_e32 v154, v147
	v_pk_mul_f32 v[154:155], v[154:155], s[4:5] op_sel_hi:[1,0]
	v_mov_b32_e32 v157, v153
	v_cvt_pk_bf16_f32 v153, v154, v155
	v_cvt_pk_bf16_f32 v152, v152, v157
	v_lshl_add_u64 v[154:155], v[148:149], 0, v[0:1]
	global_store_dwordx2 v[154:155], v[152:153], off
.LBB0_763:
	s_and_b64 vcc, exec, s[40:41]
	s_mov_b64 s[2:3], -1
	s_cbranch_vccnz .LBB0_773
	s_cmp_lt_i32 s34, 3
	s_cbranch_scc1 .LBB0_770
	s_cmp_eq_u32 s34, 3
	s_cbranch_scc1 .LBB0_767
	v_mul_f32_e32 v147, 0xbfb8aa3b, v90
	v_exp_f32_e32 v152, v147
	v_mul_f32_e32 v147, 0xbfb8aa3b, v91
	v_exp_f32_e32 v153, v147
	v_readlane_b32 s48, v253, 4
	v_readlane_b32 s49, v253, 5
	v_readlane_b32 s50, v253, 6
	v_pk_add_f32 v[152:153], v[152:153], 1.0 op_sel_hi:[1,0]
	v_readlane_b32 s51, v253, 7
	v_rcp_f32_e32 v154, v152
	s_nop 0
	v_mul_f32_e32 v147, v90, v154
	v_rcp_f32_e32 v154, v153
	s_nop 0
	v_mul_f32_e32 v152, v91, v154
	v_mov_b32_e32 v154, v152
	v_mul_f32_e32 v152, 0xbfb8aa3b, v92
	v_mul_f32_e32 v153, 0xbfb8aa3b, v93
	v_exp_f32_e32 v152, v152
	v_exp_f32_e32 v153, v153
	s_nop 0
	v_pk_add_f32 v[152:153], v[152:153], 1.0 op_sel_hi:[1,0]
	s_nop 0
	v_rcp_f32_e32 v156, v152
	s_nop 0
	v_mul_f32_e32 v155, v92, v156
	v_mov_b32_e32 v152, v155
	v_rcp_f32_e32 v156, v153
	s_mov_b64 s[2:3], 0
	v_mul_f32_e32 v155, v93, v156
	v_mov_b32_e32 v153, v155
	v_cvt_pk_bf16_f32 v153, v152, v153
	v_cvt_pk_bf16_f32 v152, v147, v154
	v_lshl_add_u64 v[154:155], s[48:49], 0, v[150:151]
	v_lshl_add_u64 v[154:155], v[154:155], 0, v[0:1]
	global_store_dwordx2 v[154:155], v[152:153], off offset:32
.LBB0_767:
	s_andn2_b64 vcc, exec, s[2:3]
	s_cbranch_vccnz .LBB0_769
	v_readlane_b32 s48, v252, 16
	v_readlane_b32 s62, v252, 30
	v_readlane_b32 s63, v252, 31
	v_cvt_pk_bf16_f32 v153, v92, v93
	v_cvt_pk_bf16_f32 v152, v90, v91
	v_lshl_add_u64 v[154:155], s[62:63], 0, v[150:151]
	v_lshl_add_u64 v[154:155], v[154:155], 0, v[0:1]
	v_readlane_b32 s49, v252, 17
	v_readlane_b32 s50, v252, 18
	v_readlane_b32 s51, v252, 19
	v_readlane_b32 s52, v252, 20
	v_readlane_b32 s53, v252, 21
	v_readlane_b32 s54, v252, 22
	v_readlane_b32 s55, v252, 23
	v_readlane_b32 s56, v252, 24
	v_readlane_b32 s57, v252, 25
	v_readlane_b32 s58, v252, 26
	v_readlane_b32 s59, v252, 27
	v_readlane_b32 s60, v252, 28
	v_readlane_b32 s61, v252, 29
	global_store_dwordx2 v[154:155], v[152:153], off offset:32

.LBB0_773:
	s_andn2_b64 vcc, exec, s[2:3]
	s_cbranch_vccnz .LBB0_775
	v_mul_f32_e32 v147, 0xbfb8aa3b, v90
	v_exp_f32_e32 v152, v147
	v_mul_f32_e32 v147, 0xbfb8aa3b, v91
	v_exp_f32_e32 v153, v147
	s_mov_b32 s4, 0x3db504f3
	v_pk_add_f32 v[152:153], v[152:153], 1.0 op_sel_hi:[1,0]
	s_nop 0
	v_rcp_f32_e32 v154, v153
	s_nop 0
	v_mul_f32_e32 v147, v91, v154
	v_mov_b32_e32 v153, v147
	v_rcp_f32_e32 v154, v152
	s_nop 0
	v_mul_f32_e32 v147, v90, v154
	v_mov_b32_e32 v152, v147
	v_mul_f32_e32 v147, 0xbfb8aa3b, v92
	v_exp_f32_e32 v154, v147
	v_mul_f32_e32 v147, 0xbfb8aa3b, v93
	v_exp_f32_e32 v155, v147
	v_pk_mul_f32 v[152:153], v[152:153], s[4:5] op_sel_hi:[1,0]
	v_pk_add_f32 v[154:155], v[154:155], 1.0 op_sel_hi:[1,0]
	s_nop 0
	v_rcp_f32_e32 v156, v155
	s_nop 0
	v_mul_f32_e32 v147, v93, v156
	v_mov_b32_e32 v155, v147
	v_rcp_f32_e32 v156, v154
	s_nop 0
	v_mul_f32_e32 v147, v92, v156
	v_mov_b32_e32 v154, v147
	v_pk_mul_f32 v[154:155], v[154:155], s[4:5] op_sel_hi:[1,0]
	v_mov_b32_e32 v157, v153
	v_cvt_pk_bf16_f32 v153, v154, v155
	v_cvt_pk_bf16_f32 v152, v152, v157
	v_lshl_add_u64 v[154:155], v[148:149], 0, v[0:1]
	global_store_dwordx2 v[154:155], v[152:153], off offset:32
.LBB0_775:
	s_and_b64 vcc, exec, s[40:41]
	s_mov_b64 s[2:3], -1
	s_cbranch_vccnz .LBB0_785
	s_cmp_lt_i32 s34, 3
	s_cbranch_scc1 .LBB0_782
	s_cmp_eq_u32 s34, 3
	s_cbranch_scc1 .LBB0_779
	v_mul_f32_e32 v147, 0xbfb8aa3b, v86
	v_exp_f32_e32 v152, v147
	v_mul_f32_e32 v147, 0xbfb8aa3b, v87
	v_exp_f32_e32 v153, v147
	v_readlane_b32 s48, v253, 4
	v_readlane_b32 s49, v253, 5
	v_readlane_b32 s50, v253, 6
	v_pk_add_f32 v[152:153], v[152:153], 1.0 op_sel_hi:[1,0]
	v_readlane_b32 s51, v253, 7
	v_rcp_f32_e32 v154, v152
	s_nop 0
	v_mul_f32_e32 v147, v86, v154
	v_rcp_f32_e32 v154, v153
	s_nop 0
	v_mul_f32_e32 v152, v87, v154
	v_mov_b32_e32 v154, v152
	v_mul_f32_e32 v152, 0xbfb8aa3b, v88
	v_mul_f32_e32 v153, 0xbfb8aa3b, v89
	v_exp_f32_e32 v152, v152
	v_exp_f32_e32 v153, v153
	s_nop 0
	v_pk_add_f32 v[152:153], v[152:153], 1.0 op_sel_hi:[1,0]
	s_nop 0
	v_rcp_f32_e32 v156, v152
	s_nop 0
	v_mul_f32_e32 v155, v88, v156
	v_mov_b32_e32 v152, v155
	v_rcp_f32_e32 v156, v153
	s_mov_b64 s[2:3], 0
	v_mul_f32_e32 v155, v89, v156
	v_mov_b32_e32 v153, v155
	v_cvt_pk_bf16_f32 v153, v152, v153
	v_cvt_pk_bf16_f32 v152, v147, v154
	v_lshl_add_u64 v[154:155], s[48:49], 0, v[150:151]
	v_lshl_add_u64 v[154:155], v[154:155], 0, v[0:1]
	global_store_dwordx2 v[154:155], v[152:153], off offset:64
.LBB0_779:
	s_andn2_b64 vcc, exec, s[2:3]
	s_cbranch_vccnz .LBB0_781
	v_readlane_b32 s48, v252, 16
	v_readlane_b32 s62, v252, 30
	v_readlane_b32 s63, v252, 31
	v_cvt_pk_bf16_f32 v153, v88, v89
	v_cvt_pk_bf16_f32 v152, v86, v87
	v_lshl_add_u64 v[154:155], s[62:63], 0, v[150:151]
	v_lshl_add_u64 v[154:155], v[154:155], 0, v[0:1]
	v_readlane_b32 s49, v252, 17
	v_readlane_b32 s50, v252, 18
	v_readlane_b32 s51, v252, 19
	v_readlane_b32 s52, v252, 20
	v_readlane_b32 s53, v252, 21
	v_readlane_b32 s54, v252, 22
	v_readlane_b32 s55, v252, 23
	v_readlane_b32 s56, v252, 24
	v_readlane_b32 s57, v252, 25
	v_readlane_b32 s58, v252, 26
	v_readlane_b32 s59, v252, 27
	v_readlane_b32 s60, v252, 28
	v_readlane_b32 s61, v252, 29
	global_store_dwordx2 v[154:155], v[152:153], off offset:64

.LBB0_785:
	s_andn2_b64 vcc, exec, s[2:3]
	s_cbranch_vccnz .LBB0_787
	v_mul_f32_e32 v147, 0xbfb8aa3b, v86
	v_exp_f32_e32 v152, v147
	v_mul_f32_e32 v147, 0xbfb8aa3b, v87
	v_exp_f32_e32 v153, v147
	s_mov_b32 s4, 0x3db504f3
	v_pk_add_f32 v[152:153], v[152:153], 1.0 op_sel_hi:[1,0]
	s_nop 0
	v_rcp_f32_e32 v154, v153
	s_nop 0
	v_mul_f32_e32 v147, v87, v154
	v_mov_b32_e32 v153, v147
	v_rcp_f32_e32 v154, v152
	s_nop 0
	v_mul_f32_e32 v147, v86, v154
	v_mov_b32_e32 v152, v147
	v_mul_f32_e32 v147, 0xbfb8aa3b, v88
	v_exp_f32_e32 v154, v147
	v_mul_f32_e32 v147, 0xbfb8aa3b, v89
	v_exp_f32_e32 v155, v147
	v_pk_mul_f32 v[152:153], v[152:153], s[4:5] op_sel_hi:[1,0]
	v_pk_add_f32 v[154:155], v[154:155], 1.0 op_sel_hi:[1,0]
	s_nop 0
	v_rcp_f32_e32 v156, v155
	s_nop 0
	v_mul_f32_e32 v147, v89, v156
	v_mov_b32_e32 v155, v147
	v_rcp_f32_e32 v156, v154
	s_nop 0
	v_mul_f32_e32 v147, v88, v156
	v_mov_b32_e32 v154, v147
	v_pk_mul_f32 v[154:155], v[154:155], s[4:5] op_sel_hi:[1,0]
	v_mov_b32_e32 v157, v153
	v_cvt_pk_bf16_f32 v153, v154, v155
	v_cvt_pk_bf16_f32 v152, v152, v157
	v_lshl_add_u64 v[154:155], v[148:149], 0, v[0:1]
	global_store_dwordx2 v[154:155], v[152:153], off offset:64
.LBB0_787:
	s_and_b64 vcc, exec, s[40:41]
	s_mov_b64 s[2:3], -1
	s_cbranch_vccnz .LBB0_797
	s_cmp_lt_i32 s34, 3
	s_cbranch_scc1 .LBB0_794
	s_cmp_eq_u32 s34, 3
	s_cbranch_scc1 .LBB0_791
	v_mul_f32_e32 v147, 0xbfb8aa3b, v82
	v_exp_f32_e32 v152, v147
	v_mul_f32_e32 v147, 0xbfb8aa3b, v83
	v_exp_f32_e32 v153, v147
	v_readlane_b32 s48, v253, 4
	v_readlane_b32 s49, v253, 5
	v_readlane_b32 s50, v253, 6
	v_pk_add_f32 v[152:153], v[152:153], 1.0 op_sel_hi:[1,0]
	v_readlane_b32 s51, v253, 7
	v_rcp_f32_e32 v154, v152
	s_nop 0
	v_mul_f32_e32 v147, v82, v154
	v_rcp_f32_e32 v154, v153
	s_nop 0
	v_mul_f32_e32 v152, v83, v154
	v_mov_b32_e32 v154, v152
	v_mul_f32_e32 v152, 0xbfb8aa3b, v84
	v_mul_f32_e32 v153, 0xbfb8aa3b, v85
	v_exp_f32_e32 v152, v152
	v_exp_f32_e32 v153, v153
	s_nop 0
	v_pk_add_f32 v[152:153], v[152:153], 1.0 op_sel_hi:[1,0]
	s_nop 0
	v_rcp_f32_e32 v156, v152
	s_nop 0
	v_mul_f32_e32 v155, v84, v156
	v_mov_b32_e32 v152, v155
	v_rcp_f32_e32 v156, v153
	s_mov_b64 s[2:3], 0
	v_mul_f32_e32 v155, v85, v156
	v_mov_b32_e32 v153, v155
	v_cvt_pk_bf16_f32 v153, v152, v153
	v_cvt_pk_bf16_f32 v152, v147, v154
	v_lshl_add_u64 v[154:155], s[48:49], 0, v[150:151]
	v_lshl_add_u64 v[154:155], v[154:155], 0, v[0:1]
	global_store_dwordx2 v[154:155], v[152:153], off offset:96
.LBB0_791:
	s_andn2_b64 vcc, exec, s[2:3]
	s_cbranch_vccnz .LBB0_793
	v_readlane_b32 s48, v252, 16
	v_readlane_b32 s62, v252, 30
	v_readlane_b32 s63, v252, 31
	v_cvt_pk_bf16_f32 v153, v84, v85
	v_cvt_pk_bf16_f32 v152, v82, v83
	v_lshl_add_u64 v[154:155], s[62:63], 0, v[150:151]
	v_lshl_add_u64 v[154:155], v[154:155], 0, v[0:1]
	v_readlane_b32 s49, v252, 17
	v_readlane_b32 s50, v252, 18
	v_readlane_b32 s51, v252, 19
	v_readlane_b32 s52, v252, 20
	v_readlane_b32 s53, v252, 21
	v_readlane_b32 s54, v252, 22
	v_readlane_b32 s55, v252, 23
	v_readlane_b32 s56, v252, 24
	v_readlane_b32 s57, v252, 25
	v_readlane_b32 s58, v252, 26
	v_readlane_b32 s59, v252, 27
	v_readlane_b32 s60, v252, 28
	v_readlane_b32 s61, v252, 29
	global_store_dwordx2 v[154:155], v[152:153], off offset:96

.LBB0_797:
	s_andn2_b64 vcc, exec, s[2:3]
	s_cbranch_vccnz .LBB0_799
	v_mul_f32_e32 v147, 0xbfb8aa3b, v82
	v_exp_f32_e32 v150, v147
	v_mul_f32_e32 v147, 0xbfb8aa3b, v83
	v_exp_f32_e32 v151, v147
	s_mov_b32 s4, 0x3db504f3
	v_lshl_add_u64 v[148:149], v[148:149], 0, v[0:1]
	v_pk_add_f32 v[150:151], v[150:151], 1.0 op_sel_hi:[1,0]
	s_nop 0
	v_rcp_f32_e32 v152, v151
	s_nop 0
	v_mul_f32_e32 v147, v83, v152
	v_mov_b32_e32 v151, v147
	v_rcp_f32_e32 v152, v150
	s_nop 0
	v_mul_f32_e32 v147, v82, v152
	v_mov_b32_e32 v150, v147
	v_mul_f32_e32 v147, 0xbfb8aa3b, v84
	v_exp_f32_e32 v152, v147
	v_mul_f32_e32 v147, 0xbfb8aa3b, v85
	v_exp_f32_e32 v153, v147
	v_pk_mul_f32 v[150:151], v[150:151], s[4:5] op_sel_hi:[1,0]
	v_pk_add_f32 v[152:153], v[152:153], 1.0 op_sel_hi:[1,0]
	s_nop 0
	v_rcp_f32_e32 v154, v153
	s_nop 0
	v_mul_f32_e32 v147, v85, v154
	v_mov_b32_e32 v153, v147
	v_rcp_f32_e32 v154, v152
	s_nop 0
	v_mul_f32_e32 v147, v84, v154
	v_mov_b32_e32 v152, v147
	v_pk_mul_f32 v[152:153], v[152:153], s[4:5] op_sel_hi:[1,0]
	v_mov_b32_e32 v155, v151
	v_cvt_pk_bf16_f32 v151, v152, v153
	v_cvt_pk_bf16_f32 v150, v150, v155
	global_store_dwordx2 v[148:149], v[150:151], off offset:96
.LBB0_799:
	v_or_b32_e32 v148, 48, v146
	v_ashrrev_i32_e32 v149, 31, v148
	s_and_b64 vcc, exec, s[40:41]
	s_mov_b64 s[2:3], -1
	s_cbranch_vccnz .LBB0_809
	s_cmp_lt_i32 s34, 3
	s_cbranch_scc1 .LBB0_806
	s_cmp_eq_u32 s34, 3
	s_cbranch_scc1 .LBB0_803
	v_mul_f32_e32 v147, 0xbfb8aa3b, v78
	v_exp_f32_e32 v150, v147
	v_mul_f32_e32 v147, 0xbfb8aa3b, v79
	v_exp_f32_e32 v151, v147
	v_readlane_b32 s48, v253, 4
	v_readlane_b32 s49, v253, 5
	v_readlane_b32 s50, v253, 6
	v_pk_add_f32 v[150:151], v[150:151], 1.0 op_sel_hi:[1,0]
	v_readlane_b32 s51, v253, 7
	v_rcp_f32_e32 v152, v150
	s_nop 0
	v_mul_f32_e32 v147, v78, v152
	v_rcp_f32_e32 v152, v151
	s_nop 0
	v_mul_f32_e32 v150, v79, v152
	v_mov_b32_e32 v152, v150
	v_mul_f32_e32 v150, 0xbfb8aa3b, v80
	v_mul_f32_e32 v151, 0xbfb8aa3b, v81
	v_exp_f32_e32 v150, v150
	v_exp_f32_e32 v151, v151
	s_nop 0
	v_pk_add_f32 v[150:151], v[150:151], 1.0 op_sel_hi:[1,0]
	s_nop 0
	v_rcp_f32_e32 v154, v150
	s_nop 0
	v_mul_f32_e32 v153, v80, v154
	v_mov_b32_e32 v150, v153
	v_rcp_f32_e32 v154, v151
	s_mov_b64 s[2:3], 0
	v_mul_f32_e32 v153, v81, v154
	v_mov_b32_e32 v151, v153
	v_cvt_pk_bf16_f32 v151, v150, v151
	v_cvt_pk_bf16_f32 v150, v147, v152
	v_lshlrev_b64 v[152:153], 11, v[148:149]
	v_lshl_add_u64 v[152:153], s[48:49], 0, v[152:153]
	v_lshl_add_u64 v[152:153], v[152:153], 0, v[0:1]
	global_store_dwordx2 v[152:153], v[150:151], off
.LBB0_803:
	s_andn2_b64 vcc, exec, s[2:3]
	s_cbranch_vccnz .LBB0_805
	v_readlane_b32 s48, v252, 16
	v_cvt_pk_bf16_f32 v151, v80, v81
	v_cvt_pk_bf16_f32 v150, v78, v79
	v_lshlrev_b64 v[152:153], 11, v[148:149]
	v_readlane_b32 s62, v252, 30
	v_readlane_b32 s63, v252, 31
	v_readlane_b32 s49, v252, 17
	v_readlane_b32 s50, v252, 18
	v_lshl_add_u64 v[152:153], s[62:63], 0, v[152:153]
	v_lshl_add_u64 v[152:153], v[152:153], 0, v[0:1]
	v_readlane_b32 s51, v252, 19
	v_readlane_b32 s52, v252, 20
	v_readlane_b32 s53, v252, 21
	v_readlane_b32 s54, v252, 22
	v_readlane_b32 s55, v252, 23
	v_readlane_b32 s56, v252, 24
	v_readlane_b32 s57, v252, 25
	v_readlane_b32 s58, v252, 26
	v_readlane_b32 s59, v252, 27
	v_readlane_b32 s60, v252, 28
	v_readlane_b32 s61, v252, 29
	global_store_dwordx2 v[152:153], v[150:151], off

.LBB0_809:
	v_readlane_b32 s48, v252, 16
	v_lshlrev_b64 v[150:151], 11, v[148:149]
	v_readlane_b32 s58, v252, 26
	v_readlane_b32 s59, v252, 27
	s_andn2_b64 vcc, exec, s[2:3]
	v_readlane_b32 s49, v252, 17
	v_lshl_add_u64 v[148:149], s[58:59], 0, v[150:151]
	v_readlane_b32 s50, v252, 18
	v_readlane_b32 s51, v252, 19
	v_readlane_b32 s52, v252, 20
	v_readlane_b32 s53, v252, 21
	v_readlane_b32 s54, v252, 22
	v_readlane_b32 s55, v252, 23
	v_readlane_b32 s56, v252, 24
	v_readlane_b32 s57, v252, 25
	v_readlane_b32 s60, v252, 28
	v_readlane_b32 s61, v252, 29
	v_readlane_b32 s62, v252, 30
	v_readlane_b32 s63, v252, 31
	s_cbranch_vccnz .LBB0_811
	v_mul_f32_e32 v147, 0xbfb8aa3b, v78
	v_exp_f32_e32 v152, v147
	v_mul_f32_e32 v147, 0xbfb8aa3b, v79
	v_exp_f32_e32 v153, v147
	s_mov_b32 s4, 0x3db504f3
	v_pk_add_f32 v[152:153], v[152:153], 1.0 op_sel_hi:[1,0]
	s_nop 0
	v_rcp_f32_e32 v154, v153
	s_nop 0
	v_mul_f32_e32 v147, v79, v154
	v_mov_b32_e32 v153, v147
	v_rcp_f32_e32 v154, v152
	s_nop 0
	v_mul_f32_e32 v147, v78, v154
	v_mov_b32_e32 v152, v147
	v_mul_f32_e32 v147, 0xbfb8aa3b, v80
	v_exp_f32_e32 v154, v147
	v_mul_f32_e32 v147, 0xbfb8aa3b, v81
	v_exp_f32_e32 v155, v147
	v_pk_mul_f32 v[152:153], v[152:153], s[4:5] op_sel_hi:[1,0]
	v_pk_add_f32 v[154:155], v[154:155], 1.0 op_sel_hi:[1,0]
	s_nop 0
	v_rcp_f32_e32 v156, v155
	s_nop 0
	v_mul_f32_e32 v147, v81, v156
	v_mov_b32_e32 v155, v147
	v_rcp_f32_e32 v156, v154
	s_nop 0
	v_mul_f32_e32 v147, v80, v156
	v_mov_b32_e32 v154, v147
	v_pk_mul_f32 v[154:155], v[154:155], s[4:5] op_sel_hi:[1,0]
	v_mov_b32_e32 v157, v153
	v_cvt_pk_bf16_f32 v153, v154, v155
	v_cvt_pk_bf16_f32 v152, v152, v157
	v_lshl_add_u64 v[154:155], v[148:149], 0, v[0:1]
	global_store_dwordx2 v[154:155], v[152:153], off
.LBB0_811:
	s_and_b64 vcc, exec, s[40:41]
	s_mov_b64 s[2:3], -1
	s_cbranch_vccnz .LBB0_821
	s_cmp_lt_i32 s34, 3
	s_cbranch_scc1 .LBB0_818
	s_cmp_eq_u32 s34, 3
	s_cbranch_scc1 .LBB0_815
	v_mul_f32_e32 v147, 0xbfb8aa3b, v74
	v_exp_f32_e32 v152, v147
	v_mul_f32_e32 v147, 0xbfb8aa3b, v75
	v_exp_f32_e32 v153, v147
	v_readlane_b32 s48, v253, 4
	v_readlane_b32 s49, v253, 5
	v_readlane_b32 s50, v253, 6
	v_pk_add_f32 v[152:153], v[152:153], 1.0 op_sel_hi:[1,0]
	v_readlane_b32 s51, v253, 7
	v_rcp_f32_e32 v154, v152
	s_nop 0
	v_mul_f32_e32 v147, v74, v154
	v_rcp_f32_e32 v154, v153
	s_nop 0
	v_mul_f32_e32 v152, v75, v154
	v_mov_b32_e32 v154, v152
	v_mul_f32_e32 v152, 0xbfb8aa3b, v76
	v_mul_f32_e32 v153, 0xbfb8aa3b, v77
	v_exp_f32_e32 v152, v152
	v_exp_f32_e32 v153, v153
	s_nop 0
	v_pk_add_f32 v[152:153], v[152:153], 1.0 op_sel_hi:[1,0]
	s_nop 0
	v_rcp_f32_e32 v156, v152
	s_nop 0
	v_mul_f32_e32 v155, v76, v156
	v_mov_b32_e32 v152, v155
	v_rcp_f32_e32 v156, v153
	s_mov_b64 s[2:3], 0
	v_mul_f32_e32 v155, v77, v156
	v_mov_b32_e32 v153, v155
	v_cvt_pk_bf16_f32 v153, v152, v153
	v_cvt_pk_bf16_f32 v152, v147, v154
	v_lshl_add_u64 v[154:155], s[48:49], 0, v[150:151]
	v_lshl_add_u64 v[154:155], v[154:155], 0, v[0:1]
	global_store_dwordx2 v[154:155], v[152:153], off offset:32
.LBB0_815:
	s_andn2_b64 vcc, exec, s[2:3]
	s_cbranch_vccnz .LBB0_817
	v_readlane_b32 s48, v252, 16
	v_readlane_b32 s62, v252, 30
	v_readlane_b32 s63, v252, 31
	v_cvt_pk_bf16_f32 v153, v76, v77
	v_cvt_pk_bf16_f32 v152, v74, v75
	v_lshl_add_u64 v[154:155], s[62:63], 0, v[150:151]
	v_lshl_add_u64 v[154:155], v[154:155], 0, v[0:1]
	v_readlane_b32 s49, v252, 17
	v_readlane_b32 s50, v252, 18
	v_readlane_b32 s51, v252, 19
	v_readlane_b32 s52, v252, 20
	v_readlane_b32 s53, v252, 21
	v_readlane_b32 s54, v252, 22
	v_readlane_b32 s55, v252, 23
	v_readlane_b32 s56, v252, 24
	v_readlane_b32 s57, v252, 25
	v_readlane_b32 s58, v252, 26
	v_readlane_b32 s59, v252, 27
	v_readlane_b32 s60, v252, 28
	v_readlane_b32 s61, v252, 29
	global_store_dwordx2 v[154:155], v[152:153], off offset:32

.LBB0_821:
	s_andn2_b64 vcc, exec, s[2:3]
	s_cbranch_vccnz .LBB0_823
	v_mul_f32_e32 v147, 0xbfb8aa3b, v74
	v_exp_f32_e32 v152, v147
	v_mul_f32_e32 v147, 0xbfb8aa3b, v75
	v_exp_f32_e32 v153, v147
	s_mov_b32 s4, 0x3db504f3
	v_pk_add_f32 v[152:153], v[152:153], 1.0 op_sel_hi:[1,0]
	s_nop 0
	v_rcp_f32_e32 v154, v153
	s_nop 0
	v_mul_f32_e32 v147, v75, v154
	v_mov_b32_e32 v153, v147
	v_rcp_f32_e32 v154, v152
	s_nop 0
	v_mul_f32_e32 v147, v74, v154
	v_mov_b32_e32 v152, v147
	v_mul_f32_e32 v147, 0xbfb8aa3b, v76
	v_exp_f32_e32 v154, v147
	v_mul_f32_e32 v147, 0xbfb8aa3b, v77
	v_exp_f32_e32 v155, v147
	v_pk_mul_f32 v[152:153], v[152:153], s[4:5] op_sel_hi:[1,0]
	v_pk_add_f32 v[154:155], v[154:155], 1.0 op_sel_hi:[1,0]
	s_nop 0
	v_rcp_f32_e32 v156, v155
	s_nop 0
	v_mul_f32_e32 v147, v77, v156
	v_mov_b32_e32 v155, v147
	v_rcp_f32_e32 v156, v154
	s_nop 0
	v_mul_f32_e32 v147, v76, v156
	v_mov_b32_e32 v154, v147
	v_pk_mul_f32 v[154:155], v[154:155], s[4:5] op_sel_hi:[1,0]
	v_mov_b32_e32 v157, v153
	v_cvt_pk_bf16_f32 v153, v154, v155
	v_cvt_pk_bf16_f32 v152, v152, v157
	v_lshl_add_u64 v[154:155], v[148:149], 0, v[0:1]
	global_store_dwordx2 v[154:155], v[152:153], off offset:32
.LBB0_823:
	s_and_b64 vcc, exec, s[40:41]
	s_mov_b64 s[2:3], -1
	s_cbranch_vccnz .LBB0_833
	s_cmp_lt_i32 s34, 3
	s_cbranch_scc1 .LBB0_830
	s_cmp_eq_u32 s34, 3
	s_cbranch_scc1 .LBB0_827
	v_mul_f32_e32 v147, 0xbfb8aa3b, v70
	v_exp_f32_e32 v152, v147
	v_mul_f32_e32 v147, 0xbfb8aa3b, v71
	v_exp_f32_e32 v153, v147
	v_readlane_b32 s48, v253, 4
	v_readlane_b32 s49, v253, 5
	v_readlane_b32 s50, v253, 6
	v_pk_add_f32 v[152:153], v[152:153], 1.0 op_sel_hi:[1,0]
	v_readlane_b32 s51, v253, 7
	v_rcp_f32_e32 v154, v152
	s_nop 0
	v_mul_f32_e32 v147, v70, v154
	v_rcp_f32_e32 v154, v153
	s_nop 0
	v_mul_f32_e32 v152, v71, v154
	v_mov_b32_e32 v154, v152
	v_mul_f32_e32 v152, 0xbfb8aa3b, v72
	v_mul_f32_e32 v153, 0xbfb8aa3b, v73
	v_exp_f32_e32 v152, v152
	v_exp_f32_e32 v153, v153
	s_nop 0
	v_pk_add_f32 v[152:153], v[152:153], 1.0 op_sel_hi:[1,0]
	s_nop 0
	v_rcp_f32_e32 v156, v152
	s_nop 0
	v_mul_f32_e32 v155, v72, v156
	v_mov_b32_e32 v152, v155
	v_rcp_f32_e32 v156, v153
	s_mov_b64 s[2:3], 0
	v_mul_f32_e32 v155, v73, v156
	v_mov_b32_e32 v153, v155
	v_cvt_pk_bf16_f32 v153, v152, v153
	v_cvt_pk_bf16_f32 v152, v147, v154
	v_lshl_add_u64 v[154:155], s[48:49], 0, v[150:151]
	v_lshl_add_u64 v[154:155], v[154:155], 0, v[0:1]
	global_store_dwordx2 v[154:155], v[152:153], off offset:64
.LBB0_827:
	s_andn2_b64 vcc, exec, s[2:3]
	s_cbranch_vccnz .LBB0_829
	v_readlane_b32 s48, v252, 16
	v_readlane_b32 s62, v252, 30
	v_readlane_b32 s63, v252, 31
	v_cvt_pk_bf16_f32 v153, v72, v73
	v_cvt_pk_bf16_f32 v152, v70, v71
	v_lshl_add_u64 v[154:155], s[62:63], 0, v[150:151]
	v_lshl_add_u64 v[154:155], v[154:155], 0, v[0:1]
	v_readlane_b32 s49, v252, 17
	v_readlane_b32 s50, v252, 18
	v_readlane_b32 s51, v252, 19
	v_readlane_b32 s52, v252, 20
	v_readlane_b32 s53, v252, 21
	v_readlane_b32 s54, v252, 22
	v_readlane_b32 s55, v252, 23
	v_readlane_b32 s56, v252, 24
	v_readlane_b32 s57, v252, 25
	v_readlane_b32 s58, v252, 26
	v_readlane_b32 s59, v252, 27
	v_readlane_b32 s60, v252, 28
	v_readlane_b32 s61, v252, 29
	global_store_dwordx2 v[154:155], v[152:153], off offset:64

.LBB0_833:
	s_andn2_b64 vcc, exec, s[2:3]
	s_cbranch_vccnz .LBB0_835
	v_mul_f32_e32 v147, 0xbfb8aa3b, v70
	v_exp_f32_e32 v152, v147
	v_mul_f32_e32 v147, 0xbfb8aa3b, v71
	v_exp_f32_e32 v153, v147
	s_mov_b32 s4, 0x3db504f3
	v_pk_add_f32 v[152:153], v[152:153], 1.0 op_sel_hi:[1,0]
	s_nop 0
	v_rcp_f32_e32 v154, v153
	s_nop 0
	v_mul_f32_e32 v147, v71, v154
	v_mov_b32_e32 v153, v147
	v_rcp_f32_e32 v154, v152
	s_nop 0
	v_mul_f32_e32 v147, v70, v154
	v_mov_b32_e32 v152, v147
	v_mul_f32_e32 v147, 0xbfb8aa3b, v72
	v_exp_f32_e32 v154, v147
	v_mul_f32_e32 v147, 0xbfb8aa3b, v73
	v_exp_f32_e32 v155, v147
	v_pk_mul_f32 v[152:153], v[152:153], s[4:5] op_sel_hi:[1,0]
	v_pk_add_f32 v[154:155], v[154:155], 1.0 op_sel_hi:[1,0]
	s_nop 0
	v_rcp_f32_e32 v156, v155
	s_nop 0
	v_mul_f32_e32 v147, v73, v156
	v_mov_b32_e32 v155, v147
	v_rcp_f32_e32 v156, v154
	s_nop 0
	v_mul_f32_e32 v147, v72, v156
	v_mov_b32_e32 v154, v147
	v_pk_mul_f32 v[154:155], v[154:155], s[4:5] op_sel_hi:[1,0]
	v_mov_b32_e32 v157, v153
	v_cvt_pk_bf16_f32 v153, v154, v155
	v_cvt_pk_bf16_f32 v152, v152, v157
	v_lshl_add_u64 v[154:155], v[148:149], 0, v[0:1]
	global_store_dwordx2 v[154:155], v[152:153], off offset:64
.LBB0_835:
	s_and_b64 vcc, exec, s[40:41]
	s_mov_b64 s[2:3], -1
	s_cbranch_vccnz .LBB0_845
	s_cmp_lt_i32 s34, 3
	s_cbranch_scc1 .LBB0_842
	s_cmp_eq_u32 s34, 3
	s_cbranch_scc1 .LBB0_839
	v_mul_f32_e32 v147, 0xbfb8aa3b, v66
	v_exp_f32_e32 v152, v147
	v_mul_f32_e32 v147, 0xbfb8aa3b, v67
	v_exp_f32_e32 v153, v147
	v_readlane_b32 s48, v253, 4
	v_readlane_b32 s49, v253, 5
	v_readlane_b32 s50, v253, 6
	v_pk_add_f32 v[152:153], v[152:153], 1.0 op_sel_hi:[1,0]
	v_readlane_b32 s51, v253, 7
	v_rcp_f32_e32 v154, v152
	s_nop 0
	v_mul_f32_e32 v147, v66, v154
	v_rcp_f32_e32 v154, v153
	s_nop 0
	v_mul_f32_e32 v152, v67, v154
	v_mov_b32_e32 v154, v152
	v_mul_f32_e32 v152, 0xbfb8aa3b, v68
	v_mul_f32_e32 v153, 0xbfb8aa3b, v69
	v_exp_f32_e32 v152, v152
	v_exp_f32_e32 v153, v153
	s_nop 0
	v_pk_add_f32 v[152:153], v[152:153], 1.0 op_sel_hi:[1,0]
	s_nop 0
	v_rcp_f32_e32 v156, v152
	s_nop 0
	v_mul_f32_e32 v155, v68, v156
	v_mov_b32_e32 v152, v155
	v_rcp_f32_e32 v156, v153
	s_mov_b64 s[2:3], 0
	v_mul_f32_e32 v155, v69, v156
	v_mov_b32_e32 v153, v155
	v_cvt_pk_bf16_f32 v153, v152, v153
	v_cvt_pk_bf16_f32 v152, v147, v154
	v_lshl_add_u64 v[154:155], s[48:49], 0, v[150:151]
	v_lshl_add_u64 v[154:155], v[154:155], 0, v[0:1]
	global_store_dwordx2 v[154:155], v[152:153], off offset:96
.LBB0_839:
	s_andn2_b64 vcc, exec, s[2:3]
	s_cbranch_vccnz .LBB0_841
	v_readlane_b32 s48, v252, 16
	v_readlane_b32 s62, v252, 30
	v_readlane_b32 s63, v252, 31
	v_cvt_pk_bf16_f32 v153, v68, v69
	v_cvt_pk_bf16_f32 v152, v66, v67
	v_lshl_add_u64 v[154:155], s[62:63], 0, v[150:151]
	v_lshl_add_u64 v[154:155], v[154:155], 0, v[0:1]
	v_readlane_b32 s49, v252, 17
	v_readlane_b32 s50, v252, 18
	v_readlane_b32 s51, v252, 19
	v_readlane_b32 s52, v252, 20
	v_readlane_b32 s53, v252, 21
	v_readlane_b32 s54, v252, 22
	v_readlane_b32 s55, v252, 23
	v_readlane_b32 s56, v252, 24
	v_readlane_b32 s57, v252, 25
	v_readlane_b32 s58, v252, 26
	v_readlane_b32 s59, v252, 27
	v_readlane_b32 s60, v252, 28
	v_readlane_b32 s61, v252, 29
	global_store_dwordx2 v[154:155], v[152:153], off offset:96

.LBB0_845:
	s_andn2_b64 vcc, exec, s[2:3]
	s_cbranch_vccnz .LBB0_847
	v_mul_f32_e32 v147, 0xbfb8aa3b, v66
	v_exp_f32_e32 v150, v147
	v_mul_f32_e32 v147, 0xbfb8aa3b, v67
	v_exp_f32_e32 v151, v147
	s_mov_b32 s4, 0x3db504f3
	v_lshl_add_u64 v[148:149], v[148:149], 0, v[0:1]
	v_pk_add_f32 v[150:151], v[150:151], 1.0 op_sel_hi:[1,0]
	s_nop 0
	v_rcp_f32_e32 v152, v151
	s_nop 0
	v_mul_f32_e32 v147, v67, v152
	v_mov_b32_e32 v151, v147
	v_rcp_f32_e32 v152, v150
	s_nop 0
	v_mul_f32_e32 v147, v66, v152
	v_mov_b32_e32 v150, v147
	v_mul_f32_e32 v147, 0xbfb8aa3b, v68
	v_exp_f32_e32 v152, v147
	v_mul_f32_e32 v147, 0xbfb8aa3b, v69
	v_exp_f32_e32 v153, v147
	v_pk_mul_f32 v[150:151], v[150:151], s[4:5] op_sel_hi:[1,0]
	v_pk_add_f32 v[152:153], v[152:153], 1.0 op_sel_hi:[1,0]
	s_nop 0
	v_rcp_f32_e32 v154, v153
	s_nop 0
	v_mul_f32_e32 v147, v69, v154
	v_mov_b32_e32 v153, v147
	v_rcp_f32_e32 v154, v152
	s_nop 0
	v_mul_f32_e32 v147, v68, v154
	v_mov_b32_e32 v152, v147
	v_pk_mul_f32 v[152:153], v[152:153], s[4:5] op_sel_hi:[1,0]
	v_mov_b32_e32 v155, v151
	v_cvt_pk_bf16_f32 v151, v152, v153
	v_cvt_pk_bf16_f32 v150, v150, v155
	global_store_dwordx2 v[148:149], v[150:151], off offset:96
.LBB0_847:
	v_or_b32_e32 v148, 64, v146
	v_ashrrev_i32_e32 v149, 31, v148
	s_and_b64 vcc, exec, s[40:41]
	s_mov_b64 s[2:3], -1
	s_cbranch_vccnz .LBB0_857
	s_cmp_lt_i32 s34, 3
	s_cbranch_scc1 .LBB0_854
	s_cmp_eq_u32 s34, 3
	s_cbranch_scc1 .LBB0_851
	v_mul_f32_e32 v147, 0xbfb8aa3b, v62
	v_exp_f32_e32 v150, v147
	v_mul_f32_e32 v147, 0xbfb8aa3b, v63
	v_exp_f32_e32 v151, v147
	v_readlane_b32 s48, v253, 4
	v_readlane_b32 s49, v253, 5
	v_readlane_b32 s50, v253, 6
	v_pk_add_f32 v[150:151], v[150:151], 1.0 op_sel_hi:[1,0]
	v_readlane_b32 s51, v253, 7
	v_rcp_f32_e32 v152, v150
	s_nop 0
	v_mul_f32_e32 v147, v62, v152
	v_rcp_f32_e32 v152, v151
	s_nop 0
	v_mul_f32_e32 v150, v63, v152
	v_mov_b32_e32 v152, v150
	v_mul_f32_e32 v150, 0xbfb8aa3b, v64
	v_mul_f32_e32 v151, 0xbfb8aa3b, v65
	v_exp_f32_e32 v150, v150
	v_exp_f32_e32 v151, v151
	s_nop 0
	v_pk_add_f32 v[150:151], v[150:151], 1.0 op_sel_hi:[1,0]
	s_nop 0
	v_rcp_f32_e32 v154, v150
	s_nop 0
	v_mul_f32_e32 v153, v64, v154
	v_mov_b32_e32 v150, v153
	v_rcp_f32_e32 v154, v151
	s_mov_b64 s[2:3], 0
	v_mul_f32_e32 v153, v65, v154
	v_mov_b32_e32 v151, v153
	v_cvt_pk_bf16_f32 v151, v150, v151
	v_cvt_pk_bf16_f32 v150, v147, v152
	v_lshlrev_b64 v[152:153], 11, v[148:149]
	v_lshl_add_u64 v[152:153], s[48:49], 0, v[152:153]
	v_lshl_add_u64 v[152:153], v[152:153], 0, v[0:1]
	global_store_dwordx2 v[152:153], v[150:151], off
.LBB0_851:
	s_andn2_b64 vcc, exec, s[2:3]
	s_cbranch_vccnz .LBB0_853
	v_readlane_b32 s48, v252, 16
	v_cvt_pk_bf16_f32 v151, v64, v65
	v_cvt_pk_bf16_f32 v150, v62, v63
	v_lshlrev_b64 v[152:153], 11, v[148:149]
	v_readlane_b32 s62, v252, 30
	v_readlane_b32 s63, v252, 31
	v_readlane_b32 s49, v252, 17
	v_readlane_b32 s50, v252, 18
	v_lshl_add_u64 v[152:153], s[62:63], 0, v[152:153]
	v_lshl_add_u64 v[152:153], v[152:153], 0, v[0:1]
	v_readlane_b32 s51, v252, 19
	v_readlane_b32 s52, v252, 20
	v_readlane_b32 s53, v252, 21
	v_readlane_b32 s54, v252, 22
	v_readlane_b32 s55, v252, 23
	v_readlane_b32 s56, v252, 24
	v_readlane_b32 s57, v252, 25
	v_readlane_b32 s58, v252, 26
	v_readlane_b32 s59, v252, 27
	v_readlane_b32 s60, v252, 28
	v_readlane_b32 s61, v252, 29
	global_store_dwordx2 v[152:153], v[150:151], off

.LBB0_857:
	v_readlane_b32 s48, v252, 16
	v_lshlrev_b64 v[150:151], 11, v[148:149]
	v_readlane_b32 s58, v252, 26
	v_readlane_b32 s59, v252, 27
	s_andn2_b64 vcc, exec, s[2:3]
	v_readlane_b32 s49, v252, 17
	v_lshl_add_u64 v[148:149], s[58:59], 0, v[150:151]
	v_readlane_b32 s50, v252, 18
	v_readlane_b32 s51, v252, 19
	v_readlane_b32 s52, v252, 20
	v_readlane_b32 s53, v252, 21
	v_readlane_b32 s54, v252, 22
	v_readlane_b32 s55, v252, 23
	v_readlane_b32 s56, v252, 24
	v_readlane_b32 s57, v252, 25
	v_readlane_b32 s60, v252, 28
	v_readlane_b32 s61, v252, 29
	v_readlane_b32 s62, v252, 30
	v_readlane_b32 s63, v252, 31
	s_cbranch_vccnz .LBB0_859
	v_mul_f32_e32 v147, 0xbfb8aa3b, v62
	v_exp_f32_e32 v152, v147
	v_mul_f32_e32 v147, 0xbfb8aa3b, v63
	v_exp_f32_e32 v153, v147
	s_mov_b32 s4, 0x3db504f3
	v_pk_add_f32 v[152:153], v[152:153], 1.0 op_sel_hi:[1,0]
	s_nop 0
	v_rcp_f32_e32 v154, v153
	s_nop 0
	v_mul_f32_e32 v147, v63, v154
	v_mov_b32_e32 v153, v147
	v_rcp_f32_e32 v154, v152
	s_nop 0
	v_mul_f32_e32 v147, v62, v154
	v_mov_b32_e32 v152, v147
	v_mul_f32_e32 v147, 0xbfb8aa3b, v64
	v_exp_f32_e32 v154, v147
	v_mul_f32_e32 v147, 0xbfb8aa3b, v65
	v_exp_f32_e32 v155, v147
	v_pk_mul_f32 v[152:153], v[152:153], s[4:5] op_sel_hi:[1,0]
	v_pk_add_f32 v[154:155], v[154:155], 1.0 op_sel_hi:[1,0]
	s_nop 0
	v_rcp_f32_e32 v156, v155
	s_nop 0
	v_mul_f32_e32 v147, v65, v156
	v_mov_b32_e32 v155, v147
	v_rcp_f32_e32 v156, v154
	s_nop 0
	v_mul_f32_e32 v147, v64, v156
	v_mov_b32_e32 v154, v147
	v_pk_mul_f32 v[154:155], v[154:155], s[4:5] op_sel_hi:[1,0]
	v_mov_b32_e32 v157, v153
	v_cvt_pk_bf16_f32 v153, v154, v155
	v_cvt_pk_bf16_f32 v152, v152, v157
	v_lshl_add_u64 v[154:155], v[148:149], 0, v[0:1]
	global_store_dwordx2 v[154:155], v[152:153], off
.LBB0_859:
	s_and_b64 vcc, exec, s[40:41]
	s_mov_b64 s[2:3], -1
	s_cbranch_vccnz .LBB0_869
	s_cmp_lt_i32 s34, 3
	s_cbranch_scc1 .LBB0_866
	s_cmp_eq_u32 s34, 3
	s_cbranch_scc1 .LBB0_863
	v_mul_f32_e32 v147, 0xbfb8aa3b, v58
	v_exp_f32_e32 v152, v147
	v_mul_f32_e32 v147, 0xbfb8aa3b, v59
	v_exp_f32_e32 v153, v147
	v_readlane_b32 s48, v253, 4
	v_readlane_b32 s49, v253, 5
	v_readlane_b32 s50, v253, 6
	v_pk_add_f32 v[152:153], v[152:153], 1.0 op_sel_hi:[1,0]
	v_readlane_b32 s51, v253, 7
	v_rcp_f32_e32 v154, v152
	s_nop 0
	v_mul_f32_e32 v147, v58, v154
	v_rcp_f32_e32 v154, v153
	s_nop 0
	v_mul_f32_e32 v152, v59, v154
	v_mov_b32_e32 v154, v152
	v_mul_f32_e32 v152, 0xbfb8aa3b, v60
	v_mul_f32_e32 v153, 0xbfb8aa3b, v61
	v_exp_f32_e32 v152, v152
	v_exp_f32_e32 v153, v153
	s_nop 0
	v_pk_add_f32 v[152:153], v[152:153], 1.0 op_sel_hi:[1,0]
	s_nop 0
	v_rcp_f32_e32 v156, v152
	s_nop 0
	v_mul_f32_e32 v155, v60, v156
	v_mov_b32_e32 v152, v155
	v_rcp_f32_e32 v156, v153
	s_mov_b64 s[2:3], 0
	v_mul_f32_e32 v155, v61, v156
	v_mov_b32_e32 v153, v155
	v_cvt_pk_bf16_f32 v153, v152, v153
	v_cvt_pk_bf16_f32 v152, v147, v154
	v_lshl_add_u64 v[154:155], s[48:49], 0, v[150:151]
	v_lshl_add_u64 v[154:155], v[154:155], 0, v[0:1]
	global_store_dwordx2 v[154:155], v[152:153], off offset:32
.LBB0_863:
	s_andn2_b64 vcc, exec, s[2:3]
	s_cbranch_vccnz .LBB0_865
	v_readlane_b32 s48, v252, 16
	v_readlane_b32 s62, v252, 30
	v_readlane_b32 s63, v252, 31
	v_cvt_pk_bf16_f32 v153, v60, v61
	v_cvt_pk_bf16_f32 v152, v58, v59
	v_lshl_add_u64 v[154:155], s[62:63], 0, v[150:151]
	v_lshl_add_u64 v[154:155], v[154:155], 0, v[0:1]
	v_readlane_b32 s49, v252, 17
	v_readlane_b32 s50, v252, 18
	v_readlane_b32 s51, v252, 19
	v_readlane_b32 s52, v252, 20
	v_readlane_b32 s53, v252, 21
	v_readlane_b32 s54, v252, 22
	v_readlane_b32 s55, v252, 23
	v_readlane_b32 s56, v252, 24
	v_readlane_b32 s57, v252, 25
	v_readlane_b32 s58, v252, 26
	v_readlane_b32 s59, v252, 27
	v_readlane_b32 s60, v252, 28
	v_readlane_b32 s61, v252, 29
	global_store_dwordx2 v[154:155], v[152:153], off offset:32

.LBB0_869:
	s_andn2_b64 vcc, exec, s[2:3]
	s_cbranch_vccnz .LBB0_871
	v_mul_f32_e32 v147, 0xbfb8aa3b, v58
	v_exp_f32_e32 v152, v147
	v_mul_f32_e32 v147, 0xbfb8aa3b, v59
	v_exp_f32_e32 v153, v147
	s_mov_b32 s4, 0x3db504f3
	v_pk_add_f32 v[152:153], v[152:153], 1.0 op_sel_hi:[1,0]
	s_nop 0
	v_rcp_f32_e32 v154, v153
	s_nop 0
	v_mul_f32_e32 v147, v59, v154
	v_mov_b32_e32 v153, v147
	v_rcp_f32_e32 v154, v152
	s_nop 0
	v_mul_f32_e32 v147, v58, v154
	v_mov_b32_e32 v152, v147
	v_mul_f32_e32 v147, 0xbfb8aa3b, v60
	v_exp_f32_e32 v154, v147
	v_mul_f32_e32 v147, 0xbfb8aa3b, v61
	v_exp_f32_e32 v155, v147
	v_pk_mul_f32 v[152:153], v[152:153], s[4:5] op_sel_hi:[1,0]
	v_pk_add_f32 v[154:155], v[154:155], 1.0 op_sel_hi:[1,0]
	s_nop 0
	v_rcp_f32_e32 v156, v155
	s_nop 0
	v_mul_f32_e32 v147, v61, v156
	v_mov_b32_e32 v155, v147
	v_rcp_f32_e32 v156, v154
	s_nop 0
	v_mul_f32_e32 v147, v60, v156
	v_mov_b32_e32 v154, v147
	v_pk_mul_f32 v[154:155], v[154:155], s[4:5] op_sel_hi:[1,0]
	v_mov_b32_e32 v157, v153
	v_cvt_pk_bf16_f32 v153, v154, v155
	v_cvt_pk_bf16_f32 v152, v152, v157
	v_lshl_add_u64 v[154:155], v[148:149], 0, v[0:1]
	global_store_dwordx2 v[154:155], v[152:153], off offset:32
.LBB0_871:
	s_and_b64 vcc, exec, s[40:41]
	s_mov_b64 s[2:3], -1
	s_cbranch_vccnz .LBB0_881
	s_cmp_lt_i32 s34, 3
	s_cbranch_scc1 .LBB0_878
	s_cmp_eq_u32 s34, 3
	s_cbranch_scc1 .LBB0_875
	v_mul_f32_e32 v147, 0xbfb8aa3b, v54
	v_exp_f32_e32 v152, v147
	v_mul_f32_e32 v147, 0xbfb8aa3b, v55
	v_exp_f32_e32 v153, v147
	v_readlane_b32 s48, v253, 4
	v_readlane_b32 s49, v253, 5
	v_readlane_b32 s50, v253, 6
	v_pk_add_f32 v[152:153], v[152:153], 1.0 op_sel_hi:[1,0]
	v_readlane_b32 s51, v253, 7
	v_rcp_f32_e32 v154, v152
	s_nop 0
	v_mul_f32_e32 v147, v54, v154
	v_rcp_f32_e32 v154, v153
	s_nop 0
	v_mul_f32_e32 v152, v55, v154
	v_mov_b32_e32 v154, v152
	v_mul_f32_e32 v152, 0xbfb8aa3b, v56
	v_mul_f32_e32 v153, 0xbfb8aa3b, v57
	v_exp_f32_e32 v152, v152
	v_exp_f32_e32 v153, v153
	s_nop 0
	v_pk_add_f32 v[152:153], v[152:153], 1.0 op_sel_hi:[1,0]
	s_nop 0
	v_rcp_f32_e32 v156, v152
	s_nop 0
	v_mul_f32_e32 v155, v56, v156
	v_mov_b32_e32 v152, v155
	v_rcp_f32_e32 v156, v153
	s_mov_b64 s[2:3], 0
	v_mul_f32_e32 v155, v57, v156
	v_mov_b32_e32 v153, v155
	v_cvt_pk_bf16_f32 v153, v152, v153
	v_cvt_pk_bf16_f32 v152, v147, v154
	v_lshl_add_u64 v[154:155], s[48:49], 0, v[150:151]
	v_lshl_add_u64 v[154:155], v[154:155], 0, v[0:1]
	global_store_dwordx2 v[154:155], v[152:153], off offset:64
.LBB0_875:
	s_andn2_b64 vcc, exec, s[2:3]
	s_cbranch_vccnz .LBB0_877
	v_readlane_b32 s48, v252, 16
	v_readlane_b32 s62, v252, 30
	v_readlane_b32 s63, v252, 31
	v_cvt_pk_bf16_f32 v153, v56, v57
	v_cvt_pk_bf16_f32 v152, v54, v55
	v_lshl_add_u64 v[154:155], s[62:63], 0, v[150:151]
	v_lshl_add_u64 v[154:155], v[154:155], 0, v[0:1]
	v_readlane_b32 s49, v252, 17
	v_readlane_b32 s50, v252, 18
	v_readlane_b32 s51, v252, 19
	v_readlane_b32 s52, v252, 20
	v_readlane_b32 s53, v252, 21
	v_readlane_b32 s54, v252, 22
	v_readlane_b32 s55, v252, 23
	v_readlane_b32 s56, v252, 24
	v_readlane_b32 s57, v252, 25
	v_readlane_b32 s58, v252, 26
	v_readlane_b32 s59, v252, 27
	v_readlane_b32 s60, v252, 28
	v_readlane_b32 s61, v252, 29
	global_store_dwordx2 v[154:155], v[152:153], off offset:64

.LBB0_881:
	s_andn2_b64 vcc, exec, s[2:3]
	s_cbranch_vccnz .LBB0_883
	v_mul_f32_e32 v147, 0xbfb8aa3b, v54
	v_exp_f32_e32 v152, v147
	v_mul_f32_e32 v147, 0xbfb8aa3b, v55
	v_exp_f32_e32 v153, v147
	s_mov_b32 s4, 0x3db504f3
	v_pk_add_f32 v[152:153], v[152:153], 1.0 op_sel_hi:[1,0]
	s_nop 0
	v_rcp_f32_e32 v154, v153
	s_nop 0
	v_mul_f32_e32 v147, v55, v154
	v_mov_b32_e32 v153, v147
	v_rcp_f32_e32 v154, v152
	s_nop 0
	v_mul_f32_e32 v147, v54, v154
	v_mov_b32_e32 v152, v147
	v_mul_f32_e32 v147, 0xbfb8aa3b, v56
	v_exp_f32_e32 v154, v147
	v_mul_f32_e32 v147, 0xbfb8aa3b, v57
	v_exp_f32_e32 v155, v147
	v_pk_mul_f32 v[152:153], v[152:153], s[4:5] op_sel_hi:[1,0]
	v_pk_add_f32 v[154:155], v[154:155], 1.0 op_sel_hi:[1,0]
	s_nop 0
	v_rcp_f32_e32 v156, v155
	s_nop 0
	v_mul_f32_e32 v147, v57, v156
	v_mov_b32_e32 v155, v147
	v_rcp_f32_e32 v156, v154
	s_nop 0
	v_mul_f32_e32 v147, v56, v156
	v_mov_b32_e32 v154, v147
	v_pk_mul_f32 v[154:155], v[154:155], s[4:5] op_sel_hi:[1,0]
	v_mov_b32_e32 v157, v153
	v_cvt_pk_bf16_f32 v153, v154, v155
	v_cvt_pk_bf16_f32 v152, v152, v157
	v_lshl_add_u64 v[154:155], v[148:149], 0, v[0:1]
	global_store_dwordx2 v[154:155], v[152:153], off offset:64
.LBB0_883:
	s_and_b64 vcc, exec, s[40:41]
	s_mov_b64 s[2:3], -1
	s_cbranch_vccnz .LBB0_893
	s_cmp_lt_i32 s34, 3
	s_cbranch_scc1 .LBB0_890
	s_cmp_eq_u32 s34, 3
	s_cbranch_scc1 .LBB0_887
	v_mul_f32_e32 v147, 0xbfb8aa3b, v50
	v_exp_f32_e32 v152, v147
	v_mul_f32_e32 v147, 0xbfb8aa3b, v51
	v_exp_f32_e32 v153, v147
	v_readlane_b32 s48, v253, 4
	v_readlane_b32 s49, v253, 5
	v_readlane_b32 s50, v253, 6
	v_pk_add_f32 v[152:153], v[152:153], 1.0 op_sel_hi:[1,0]
	v_readlane_b32 s51, v253, 7
	v_rcp_f32_e32 v154, v152
	s_nop 0
	v_mul_f32_e32 v147, v50, v154
	v_rcp_f32_e32 v154, v153
	s_nop 0
	v_mul_f32_e32 v152, v51, v154
	v_mov_b32_e32 v154, v152
	v_mul_f32_e32 v152, 0xbfb8aa3b, v52
	v_mul_f32_e32 v153, 0xbfb8aa3b, v53
	v_exp_f32_e32 v152, v152
	v_exp_f32_e32 v153, v153
	s_nop 0
	v_pk_add_f32 v[152:153], v[152:153], 1.0 op_sel_hi:[1,0]
	s_nop 0
	v_rcp_f32_e32 v156, v152
	s_nop 0
	v_mul_f32_e32 v155, v52, v156
	v_mov_b32_e32 v152, v155
	v_rcp_f32_e32 v156, v153
	s_mov_b64 s[2:3], 0
	v_mul_f32_e32 v155, v53, v156
	v_mov_b32_e32 v153, v155
	v_cvt_pk_bf16_f32 v153, v152, v153
	v_cvt_pk_bf16_f32 v152, v147, v154
	v_lshl_add_u64 v[154:155], s[48:49], 0, v[150:151]
	v_lshl_add_u64 v[154:155], v[154:155], 0, v[0:1]
	global_store_dwordx2 v[154:155], v[152:153], off offset:96
.LBB0_887:
	s_andn2_b64 vcc, exec, s[2:3]
	s_cbranch_vccnz .LBB0_889
	v_readlane_b32 s48, v252, 16
	v_readlane_b32 s62, v252, 30
	v_readlane_b32 s63, v252, 31
	v_cvt_pk_bf16_f32 v153, v52, v53
	v_cvt_pk_bf16_f32 v152, v50, v51
	v_lshl_add_u64 v[154:155], s[62:63], 0, v[150:151]
	v_lshl_add_u64 v[154:155], v[154:155], 0, v[0:1]
	v_readlane_b32 s49, v252, 17
	v_readlane_b32 s50, v252, 18
	v_readlane_b32 s51, v252, 19
	v_readlane_b32 s52, v252, 20
	v_readlane_b32 s53, v252, 21
	v_readlane_b32 s54, v252, 22
	v_readlane_b32 s55, v252, 23
	v_readlane_b32 s56, v252, 24
	v_readlane_b32 s57, v252, 25
	v_readlane_b32 s58, v252, 26
	v_readlane_b32 s59, v252, 27
	v_readlane_b32 s60, v252, 28
	v_readlane_b32 s61, v252, 29
	global_store_dwordx2 v[154:155], v[152:153], off offset:96

.LBB0_893:
	s_andn2_b64 vcc, exec, s[2:3]
	s_cbranch_vccnz .LBB0_895
	v_mul_f32_e32 v147, 0xbfb8aa3b, v50
	v_exp_f32_e32 v150, v147
	v_mul_f32_e32 v147, 0xbfb8aa3b, v51
	v_exp_f32_e32 v151, v147
	s_mov_b32 s4, 0x3db504f3
	v_lshl_add_u64 v[148:149], v[148:149], 0, v[0:1]
	v_pk_add_f32 v[150:151], v[150:151], 1.0 op_sel_hi:[1,0]
	s_nop 0
	v_rcp_f32_e32 v152, v151
	s_nop 0
	v_mul_f32_e32 v147, v51, v152
	v_mov_b32_e32 v151, v147
	v_rcp_f32_e32 v152, v150
	s_nop 0
	v_mul_f32_e32 v147, v50, v152
	v_mov_b32_e32 v150, v147
	v_mul_f32_e32 v147, 0xbfb8aa3b, v52
	v_exp_f32_e32 v152, v147
	v_mul_f32_e32 v147, 0xbfb8aa3b, v53
	v_exp_f32_e32 v153, v147
	v_pk_mul_f32 v[150:151], v[150:151], s[4:5] op_sel_hi:[1,0]
	v_pk_add_f32 v[152:153], v[152:153], 1.0 op_sel_hi:[1,0]
	s_nop 0
	v_rcp_f32_e32 v154, v153
	s_nop 0
	v_mul_f32_e32 v147, v53, v154
	v_mov_b32_e32 v153, v147
	v_rcp_f32_e32 v154, v152
	s_nop 0
	v_mul_f32_e32 v147, v52, v154
	v_mov_b32_e32 v152, v147
	v_pk_mul_f32 v[152:153], v[152:153], s[4:5] op_sel_hi:[1,0]
	v_mov_b32_e32 v155, v151
	v_cvt_pk_bf16_f32 v151, v152, v153
	v_cvt_pk_bf16_f32 v150, v150, v155
	global_store_dwordx2 v[148:149], v[150:151], off offset:96
.LBB0_895:
	v_or_b32_e32 v148, 0x50, v146
	v_ashrrev_i32_e32 v149, 31, v148
	s_and_b64 vcc, exec, s[40:41]
	s_mov_b64 s[2:3], -1
	s_cbranch_vccnz .LBB0_905
	s_cmp_lt_i32 s34, 3
	s_cbranch_scc1 .LBB0_902
	s_cmp_eq_u32 s34, 3
	s_cbranch_scc1 .LBB0_899
	v_mul_f32_e32 v147, 0xbfb8aa3b, v46
	v_exp_f32_e32 v150, v147
	v_mul_f32_e32 v147, 0xbfb8aa3b, v47
	v_exp_f32_e32 v151, v147
	v_readlane_b32 s48, v253, 4
	v_readlane_b32 s49, v253, 5
	v_readlane_b32 s50, v253, 6
	v_pk_add_f32 v[150:151], v[150:151], 1.0 op_sel_hi:[1,0]
	v_readlane_b32 s51, v253, 7
	v_rcp_f32_e32 v152, v150
	s_nop 0
	v_mul_f32_e32 v147, v46, v152
	v_rcp_f32_e32 v152, v151
	s_nop 0
	v_mul_f32_e32 v150, v47, v152
	v_mov_b32_e32 v152, v150
	v_mul_f32_e32 v150, 0xbfb8aa3b, v48
	v_mul_f32_e32 v151, 0xbfb8aa3b, v49
	v_exp_f32_e32 v150, v150
	v_exp_f32_e32 v151, v151
	s_nop 0
	v_pk_add_f32 v[150:151], v[150:151], 1.0 op_sel_hi:[1,0]
	s_nop 0
	v_rcp_f32_e32 v154, v150
	s_nop 0
	v_mul_f32_e32 v153, v48, v154
	v_mov_b32_e32 v150, v153
	v_rcp_f32_e32 v154, v151
	s_mov_b64 s[2:3], 0
	v_mul_f32_e32 v153, v49, v154
	v_mov_b32_e32 v151, v153
	v_cvt_pk_bf16_f32 v151, v150, v151
	v_cvt_pk_bf16_f32 v150, v147, v152
	v_lshlrev_b64 v[152:153], 11, v[148:149]
	v_lshl_add_u64 v[152:153], s[48:49], 0, v[152:153]
	v_lshl_add_u64 v[152:153], v[152:153], 0, v[0:1]
	global_store_dwordx2 v[152:153], v[150:151], off
.LBB0_899:
	s_andn2_b64 vcc, exec, s[2:3]
	s_cbranch_vccnz .LBB0_901
	v_readlane_b32 s48, v252, 16
	v_cvt_pk_bf16_f32 v151, v48, v49
	v_cvt_pk_bf16_f32 v150, v46, v47
	v_lshlrev_b64 v[152:153], 11, v[148:149]
	v_readlane_b32 s62, v252, 30
	v_readlane_b32 s63, v252, 31
	v_readlane_b32 s49, v252, 17
	v_readlane_b32 s50, v252, 18
	v_lshl_add_u64 v[152:153], s[62:63], 0, v[152:153]
	v_lshl_add_u64 v[152:153], v[152:153], 0, v[0:1]
	v_readlane_b32 s51, v252, 19
	v_readlane_b32 s52, v252, 20
	v_readlane_b32 s53, v252, 21
	v_readlane_b32 s54, v252, 22
	v_readlane_b32 s55, v252, 23
	v_readlane_b32 s56, v252, 24
	v_readlane_b32 s57, v252, 25
	v_readlane_b32 s58, v252, 26
	v_readlane_b32 s59, v252, 27
	v_readlane_b32 s60, v252, 28
	v_readlane_b32 s61, v252, 29
	global_store_dwordx2 v[152:153], v[150:151], off

.LBB0_905:
	v_readlane_b32 s48, v252, 16
	v_lshlrev_b64 v[150:151], 11, v[148:149]
	v_readlane_b32 s58, v252, 26
	v_readlane_b32 s59, v252, 27
	s_andn2_b64 vcc, exec, s[2:3]
	v_readlane_b32 s49, v252, 17
	v_lshl_add_u64 v[148:149], s[58:59], 0, v[150:151]
	v_readlane_b32 s50, v252, 18
	v_readlane_b32 s51, v252, 19
	v_readlane_b32 s52, v252, 20
	v_readlane_b32 s53, v252, 21
	v_readlane_b32 s54, v252, 22
	v_readlane_b32 s55, v252, 23
	v_readlane_b32 s56, v252, 24
	v_readlane_b32 s57, v252, 25
	v_readlane_b32 s60, v252, 28
	v_readlane_b32 s61, v252, 29
	v_readlane_b32 s62, v252, 30
	v_readlane_b32 s63, v252, 31
	s_cbranch_vccnz .LBB0_907
	v_mul_f32_e32 v147, 0xbfb8aa3b, v46
	v_exp_f32_e32 v152, v147
	v_mul_f32_e32 v147, 0xbfb8aa3b, v47
	v_exp_f32_e32 v153, v147
	s_mov_b32 s4, 0x3db504f3
	v_pk_add_f32 v[152:153], v[152:153], 1.0 op_sel_hi:[1,0]
	s_nop 0
	v_rcp_f32_e32 v154, v153
	s_nop 0
	v_mul_f32_e32 v147, v47, v154
	v_mov_b32_e32 v153, v147
	v_rcp_f32_e32 v154, v152
	s_nop 0
	v_mul_f32_e32 v147, v46, v154
	v_mov_b32_e32 v152, v147
	v_mul_f32_e32 v147, 0xbfb8aa3b, v48
	v_exp_f32_e32 v154, v147
	v_mul_f32_e32 v147, 0xbfb8aa3b, v49
	v_exp_f32_e32 v155, v147
	v_pk_mul_f32 v[152:153], v[152:153], s[4:5] op_sel_hi:[1,0]
	v_pk_add_f32 v[154:155], v[154:155], 1.0 op_sel_hi:[1,0]
	s_nop 0
	v_rcp_f32_e32 v156, v155
	s_nop 0
	v_mul_f32_e32 v147, v49, v156
	v_mov_b32_e32 v155, v147
	v_rcp_f32_e32 v156, v154
	s_nop 0
	v_mul_f32_e32 v147, v48, v156
	v_mov_b32_e32 v154, v147
	v_pk_mul_f32 v[154:155], v[154:155], s[4:5] op_sel_hi:[1,0]
	v_mov_b32_e32 v157, v153
	v_cvt_pk_bf16_f32 v153, v154, v155
	v_cvt_pk_bf16_f32 v152, v152, v157
	v_lshl_add_u64 v[154:155], v[148:149], 0, v[0:1]
	global_store_dwordx2 v[154:155], v[152:153], off
.LBB0_907:
	s_and_b64 vcc, exec, s[40:41]
	s_mov_b64 s[2:3], -1
	s_cbranch_vccnz .LBB0_917
	s_cmp_lt_i32 s34, 3
	s_cbranch_scc1 .LBB0_914
	s_cmp_eq_u32 s34, 3
	s_cbranch_scc1 .LBB0_911
	v_mul_f32_e32 v147, 0xbfb8aa3b, v42
	v_exp_f32_e32 v152, v147
	v_mul_f32_e32 v147, 0xbfb8aa3b, v43
	v_exp_f32_e32 v153, v147
	v_readlane_b32 s48, v253, 4
	v_readlane_b32 s49, v253, 5
	v_readlane_b32 s50, v253, 6
	v_pk_add_f32 v[152:153], v[152:153], 1.0 op_sel_hi:[1,0]
	v_readlane_b32 s51, v253, 7
	v_rcp_f32_e32 v154, v152
	s_nop 0
	v_mul_f32_e32 v147, v42, v154
	v_rcp_f32_e32 v154, v153
	s_nop 0
	v_mul_f32_e32 v152, v43, v154
	v_mov_b32_e32 v154, v152
	v_mul_f32_e32 v152, 0xbfb8aa3b, v44
	v_mul_f32_e32 v153, 0xbfb8aa3b, v45
	v_exp_f32_e32 v152, v152
	v_exp_f32_e32 v153, v153
	s_nop 0
	v_pk_add_f32 v[152:153], v[152:153], 1.0 op_sel_hi:[1,0]
	s_nop 0
	v_rcp_f32_e32 v156, v152
	s_nop 0
	v_mul_f32_e32 v155, v44, v156
	v_mov_b32_e32 v152, v155
	v_rcp_f32_e32 v156, v153
	s_mov_b64 s[2:3], 0
	v_mul_f32_e32 v155, v45, v156
	v_mov_b32_e32 v153, v155
	v_cvt_pk_bf16_f32 v153, v152, v153
	v_cvt_pk_bf16_f32 v152, v147, v154
	v_lshl_add_u64 v[154:155], s[48:49], 0, v[150:151]
	v_lshl_add_u64 v[154:155], v[154:155], 0, v[0:1]
	global_store_dwordx2 v[154:155], v[152:153], off offset:32
.LBB0_911:
	s_andn2_b64 vcc, exec, s[2:3]
	s_cbranch_vccnz .LBB0_913
	v_readlane_b32 s48, v252, 16
	v_readlane_b32 s62, v252, 30
	v_readlane_b32 s63, v252, 31
	v_cvt_pk_bf16_f32 v153, v44, v45
	v_cvt_pk_bf16_f32 v152, v42, v43
	v_lshl_add_u64 v[154:155], s[62:63], 0, v[150:151]
	v_lshl_add_u64 v[154:155], v[154:155], 0, v[0:1]
	v_readlane_b32 s49, v252, 17
	v_readlane_b32 s50, v252, 18
	v_readlane_b32 s51, v252, 19
	v_readlane_b32 s52, v252, 20
	v_readlane_b32 s53, v252, 21
	v_readlane_b32 s54, v252, 22
	v_readlane_b32 s55, v252, 23
	v_readlane_b32 s56, v252, 24
	v_readlane_b32 s57, v252, 25
	v_readlane_b32 s58, v252, 26
	v_readlane_b32 s59, v252, 27
	v_readlane_b32 s60, v252, 28
	v_readlane_b32 s61, v252, 29
	global_store_dwordx2 v[154:155], v[152:153], off offset:32

.LBB0_917:
	s_andn2_b64 vcc, exec, s[2:3]
	s_cbranch_vccnz .LBB0_919
	v_mul_f32_e32 v147, 0xbfb8aa3b, v42
	v_exp_f32_e32 v152, v147
	v_mul_f32_e32 v147, 0xbfb8aa3b, v43
	v_exp_f32_e32 v153, v147
	s_mov_b32 s4, 0x3db504f3
	v_pk_add_f32 v[152:153], v[152:153], 1.0 op_sel_hi:[1,0]
	s_nop 0
	v_rcp_f32_e32 v154, v153
	s_nop 0
	v_mul_f32_e32 v147, v43, v154
	v_mov_b32_e32 v153, v147
	v_rcp_f32_e32 v154, v152
	s_nop 0
	v_mul_f32_e32 v147, v42, v154
	v_mov_b32_e32 v152, v147
	v_mul_f32_e32 v147, 0xbfb8aa3b, v44
	v_exp_f32_e32 v154, v147
	v_mul_f32_e32 v147, 0xbfb8aa3b, v45
	v_exp_f32_e32 v155, v147
	v_pk_mul_f32 v[152:153], v[152:153], s[4:5] op_sel_hi:[1,0]
	v_pk_add_f32 v[154:155], v[154:155], 1.0 op_sel_hi:[1,0]
	s_nop 0
	v_rcp_f32_e32 v156, v155
	s_nop 0
	v_mul_f32_e32 v147, v45, v156
	v_mov_b32_e32 v155, v147
	v_rcp_f32_e32 v156, v154
	s_nop 0
	v_mul_f32_e32 v147, v44, v156
	v_mov_b32_e32 v154, v147
	v_pk_mul_f32 v[154:155], v[154:155], s[4:5] op_sel_hi:[1,0]
	v_mov_b32_e32 v157, v153
	v_cvt_pk_bf16_f32 v153, v154, v155
	v_cvt_pk_bf16_f32 v152, v152, v157
	v_lshl_add_u64 v[154:155], v[148:149], 0, v[0:1]
	global_store_dwordx2 v[154:155], v[152:153], off offset:32
.LBB0_919:
	s_and_b64 vcc, exec, s[40:41]
	s_mov_b64 s[2:3], -1
	s_cbranch_vccnz .LBB0_929
	s_cmp_lt_i32 s34, 3
	s_cbranch_scc1 .LBB0_926
	s_cmp_eq_u32 s34, 3
	s_cbranch_scc1 .LBB0_923
	v_mul_f32_e32 v147, 0xbfb8aa3b, v34
	v_exp_f32_e32 v152, v147
	v_mul_f32_e32 v147, 0xbfb8aa3b, v35
	v_exp_f32_e32 v153, v147
	v_readlane_b32 s48, v253, 4
	v_readlane_b32 s49, v253, 5
	v_readlane_b32 s50, v253, 6
	v_pk_add_f32 v[152:153], v[152:153], 1.0 op_sel_hi:[1,0]
	v_readlane_b32 s51, v253, 7
	v_rcp_f32_e32 v154, v152
	s_nop 0
	v_mul_f32_e32 v147, v34, v154
	v_rcp_f32_e32 v154, v153
	s_nop 0
	v_mul_f32_e32 v152, v35, v154
	v_mov_b32_e32 v154, v152
	v_mul_f32_e32 v152, 0xbfb8aa3b, v36
	v_mul_f32_e32 v153, 0xbfb8aa3b, v37
	v_exp_f32_e32 v152, v152
	v_exp_f32_e32 v153, v153
	s_nop 0
	v_pk_add_f32 v[152:153], v[152:153], 1.0 op_sel_hi:[1,0]
	s_nop 0
	v_rcp_f32_e32 v156, v152
	s_nop 0
	v_mul_f32_e32 v155, v36, v156
	v_mov_b32_e32 v152, v155
	v_rcp_f32_e32 v156, v153
	s_mov_b64 s[2:3], 0
	v_mul_f32_e32 v155, v37, v156
	v_mov_b32_e32 v153, v155
	v_cvt_pk_bf16_f32 v153, v152, v153
	v_cvt_pk_bf16_f32 v152, v147, v154
	v_lshl_add_u64 v[154:155], s[48:49], 0, v[150:151]
	v_lshl_add_u64 v[154:155], v[154:155], 0, v[0:1]
	global_store_dwordx2 v[154:155], v[152:153], off offset:64
.LBB0_923:
	s_andn2_b64 vcc, exec, s[2:3]
	s_cbranch_vccnz .LBB0_925
	v_readlane_b32 s48, v252, 16
	v_readlane_b32 s62, v252, 30
	v_readlane_b32 s63, v252, 31
	v_cvt_pk_bf16_f32 v153, v36, v37
	v_cvt_pk_bf16_f32 v152, v34, v35
	v_lshl_add_u64 v[154:155], s[62:63], 0, v[150:151]
	v_lshl_add_u64 v[154:155], v[154:155], 0, v[0:1]
	v_readlane_b32 s49, v252, 17
	v_readlane_b32 s50, v252, 18
	v_readlane_b32 s51, v252, 19
	v_readlane_b32 s52, v252, 20
	v_readlane_b32 s53, v252, 21
	v_readlane_b32 s54, v252, 22
	v_readlane_b32 s55, v252, 23
	v_readlane_b32 s56, v252, 24
	v_readlane_b32 s57, v252, 25
	v_readlane_b32 s58, v252, 26
	v_readlane_b32 s59, v252, 27
	v_readlane_b32 s60, v252, 28
	v_readlane_b32 s61, v252, 29
	global_store_dwordx2 v[154:155], v[152:153], off offset:64

.LBB0_929:
	s_andn2_b64 vcc, exec, s[2:3]
	s_cbranch_vccnz .LBB0_931
	v_mul_f32_e32 v147, 0xbfb8aa3b, v34
	v_exp_f32_e32 v152, v147
	v_mul_f32_e32 v147, 0xbfb8aa3b, v35
	v_exp_f32_e32 v153, v147
	s_mov_b32 s4, 0x3db504f3
	v_pk_add_f32 v[152:153], v[152:153], 1.0 op_sel_hi:[1,0]
	s_nop 0
	v_rcp_f32_e32 v154, v153
	s_nop 0
	v_mul_f32_e32 v147, v35, v154
	v_mov_b32_e32 v153, v147
	v_rcp_f32_e32 v154, v152
	s_nop 0
	v_mul_f32_e32 v147, v34, v154
	v_mov_b32_e32 v152, v147
	v_mul_f32_e32 v147, 0xbfb8aa3b, v36
	v_exp_f32_e32 v154, v147
	v_mul_f32_e32 v147, 0xbfb8aa3b, v37
	v_exp_f32_e32 v155, v147
	v_pk_mul_f32 v[152:153], v[152:153], s[4:5] op_sel_hi:[1,0]
	v_pk_add_f32 v[154:155], v[154:155], 1.0 op_sel_hi:[1,0]
	s_nop 0
	v_rcp_f32_e32 v156, v155
	s_nop 0
	v_mul_f32_e32 v147, v37, v156
	v_mov_b32_e32 v155, v147
	v_rcp_f32_e32 v156, v154
	s_nop 0
	v_mul_f32_e32 v147, v36, v156
	v_mov_b32_e32 v154, v147
	v_pk_mul_f32 v[154:155], v[154:155], s[4:5] op_sel_hi:[1,0]
	v_mov_b32_e32 v157, v153
	v_cvt_pk_bf16_f32 v153, v154, v155
	v_cvt_pk_bf16_f32 v152, v152, v157
	v_lshl_add_u64 v[154:155], v[148:149], 0, v[0:1]
	global_store_dwordx2 v[154:155], v[152:153], off offset:64
.LBB0_931:
	s_and_b64 vcc, exec, s[40:41]
	s_mov_b64 s[2:3], -1
	s_cbranch_vccnz .LBB0_941
	s_cmp_lt_i32 s34, 3
	s_cbranch_scc1 .LBB0_938
	s_cmp_eq_u32 s34, 3
	s_cbranch_scc1 .LBB0_935
	v_mul_f32_e32 v147, 0xbfb8aa3b, v30
	v_exp_f32_e32 v152, v147
	v_mul_f32_e32 v147, 0xbfb8aa3b, v31
	v_exp_f32_e32 v153, v147
	v_readlane_b32 s48, v253, 4
	v_readlane_b32 s49, v253, 5
	v_readlane_b32 s50, v253, 6
	v_pk_add_f32 v[152:153], v[152:153], 1.0 op_sel_hi:[1,0]
	v_readlane_b32 s51, v253, 7
	v_rcp_f32_e32 v154, v152
	s_nop 0
	v_mul_f32_e32 v147, v30, v154
	v_rcp_f32_e32 v154, v153
	s_nop 0
	v_mul_f32_e32 v152, v31, v154
	v_mov_b32_e32 v154, v152
	v_mul_f32_e32 v152, 0xbfb8aa3b, v32
	v_mul_f32_e32 v153, 0xbfb8aa3b, v33
	v_exp_f32_e32 v152, v152
	v_exp_f32_e32 v153, v153
	s_nop 0
	v_pk_add_f32 v[152:153], v[152:153], 1.0 op_sel_hi:[1,0]
	s_nop 0
	v_rcp_f32_e32 v156, v152
	s_nop 0
	v_mul_f32_e32 v155, v32, v156
	v_mov_b32_e32 v152, v155
	v_rcp_f32_e32 v156, v153
	s_mov_b64 s[2:3], 0
	v_mul_f32_e32 v155, v33, v156
	v_mov_b32_e32 v153, v155
	v_cvt_pk_bf16_f32 v153, v152, v153
	v_cvt_pk_bf16_f32 v152, v147, v154
	v_lshl_add_u64 v[154:155], s[48:49], 0, v[150:151]
	v_lshl_add_u64 v[154:155], v[154:155], 0, v[0:1]
	global_store_dwordx2 v[154:155], v[152:153], off offset:96
.LBB0_935:
	s_andn2_b64 vcc, exec, s[2:3]
	s_cbranch_vccnz .LBB0_937
	v_readlane_b32 s48, v252, 16
	v_readlane_b32 s62, v252, 30
	v_readlane_b32 s63, v252, 31
	v_cvt_pk_bf16_f32 v153, v32, v33
	v_cvt_pk_bf16_f32 v152, v30, v31
	v_lshl_add_u64 v[154:155], s[62:63], 0, v[150:151]
	v_lshl_add_u64 v[154:155], v[154:155], 0, v[0:1]
	v_readlane_b32 s49, v252, 17
	v_readlane_b32 s50, v252, 18
	v_readlane_b32 s51, v252, 19
	v_readlane_b32 s52, v252, 20
	v_readlane_b32 s53, v252, 21
	v_readlane_b32 s54, v252, 22
	v_readlane_b32 s55, v252, 23
	v_readlane_b32 s56, v252, 24
	v_readlane_b32 s57, v252, 25
	v_readlane_b32 s58, v252, 26
	v_readlane_b32 s59, v252, 27
	v_readlane_b32 s60, v252, 28
	v_readlane_b32 s61, v252, 29
	global_store_dwordx2 v[154:155], v[152:153], off offset:96

.LBB0_941:
	s_andn2_b64 vcc, exec, s[2:3]
	s_cbranch_vccnz .LBB0_943
	v_mul_f32_e32 v147, 0xbfb8aa3b, v30
	v_exp_f32_e32 v150, v147
	v_mul_f32_e32 v147, 0xbfb8aa3b, v31
	v_exp_f32_e32 v151, v147
	s_mov_b32 s4, 0x3db504f3
	v_lshl_add_u64 v[148:149], v[148:149], 0, v[0:1]
	v_pk_add_f32 v[150:151], v[150:151], 1.0 op_sel_hi:[1,0]
	s_nop 0
	v_rcp_f32_e32 v152, v151
	s_nop 0
	v_mul_f32_e32 v147, v31, v152
	v_mov_b32_e32 v151, v147
	v_rcp_f32_e32 v152, v150
	s_nop 0
	v_mul_f32_e32 v147, v30, v152
	v_mov_b32_e32 v150, v147
	v_mul_f32_e32 v147, 0xbfb8aa3b, v32
	v_exp_f32_e32 v152, v147
	v_mul_f32_e32 v147, 0xbfb8aa3b, v33
	v_exp_f32_e32 v153, v147
	v_pk_mul_f32 v[150:151], v[150:151], s[4:5] op_sel_hi:[1,0]
	v_pk_add_f32 v[152:153], v[152:153], 1.0 op_sel_hi:[1,0]
	s_nop 0
	v_rcp_f32_e32 v154, v153
	s_nop 0
	v_mul_f32_e32 v147, v33, v154
	v_mov_b32_e32 v153, v147
	v_rcp_f32_e32 v154, v152
	s_nop 0
	v_mul_f32_e32 v147, v32, v154
	v_mov_b32_e32 v152, v147
	v_pk_mul_f32 v[152:153], v[152:153], s[4:5] op_sel_hi:[1,0]
	v_mov_b32_e32 v155, v151
	v_cvt_pk_bf16_f32 v151, v152, v153
	v_cvt_pk_bf16_f32 v150, v150, v155
	global_store_dwordx2 v[148:149], v[150:151], off offset:96
.LBB0_943:
	v_or_b32_e32 v148, 0x60, v146
	v_ashrrev_i32_e32 v149, 31, v148
	s_and_b64 vcc, exec, s[40:41]
	s_mov_b64 s[2:3], -1
	s_cbranch_vccnz .LBB0_953
	s_cmp_lt_i32 s34, 3
	s_cbranch_scc1 .LBB0_950
	s_cmp_eq_u32 s34, 3
	s_cbranch_scc1 .LBB0_947
	v_mul_f32_e32 v147, 0xbfb8aa3b, v38
	v_exp_f32_e32 v150, v147
	v_mul_f32_e32 v147, 0xbfb8aa3b, v39
	v_exp_f32_e32 v151, v147
	v_readlane_b32 s48, v253, 4
	v_readlane_b32 s49, v253, 5
	v_readlane_b32 s50, v253, 6
	v_pk_add_f32 v[150:151], v[150:151], 1.0 op_sel_hi:[1,0]
	v_readlane_b32 s51, v253, 7
	v_rcp_f32_e32 v152, v150
	s_nop 0
	v_mul_f32_e32 v147, v38, v152
	v_rcp_f32_e32 v152, v151
	s_nop 0
	v_mul_f32_e32 v150, v39, v152
	v_mov_b32_e32 v152, v150
	v_mul_f32_e32 v150, 0xbfb8aa3b, v40
	v_mul_f32_e32 v151, 0xbfb8aa3b, v41
	v_exp_f32_e32 v150, v150
	v_exp_f32_e32 v151, v151
	s_nop 0
	v_pk_add_f32 v[150:151], v[150:151], 1.0 op_sel_hi:[1,0]
	s_nop 0
	v_rcp_f32_e32 v154, v150
	s_nop 0
	v_mul_f32_e32 v153, v40, v154
	v_mov_b32_e32 v150, v153
	v_rcp_f32_e32 v154, v151
	s_mov_b64 s[2:3], 0
	v_mul_f32_e32 v153, v41, v154
	v_mov_b32_e32 v151, v153
	v_cvt_pk_bf16_f32 v151, v150, v151
	v_cvt_pk_bf16_f32 v150, v147, v152
	v_lshlrev_b64 v[152:153], 11, v[148:149]
	v_lshl_add_u64 v[152:153], s[48:49], 0, v[152:153]
	v_lshl_add_u64 v[152:153], v[152:153], 0, v[0:1]
	global_store_dwordx2 v[152:153], v[150:151], off
.LBB0_947:
	s_andn2_b64 vcc, exec, s[2:3]
	s_cbranch_vccnz .LBB0_949
	v_readlane_b32 s48, v252, 16
	v_cvt_pk_bf16_f32 v151, v40, v41
	v_cvt_pk_bf16_f32 v150, v38, v39
	v_lshlrev_b64 v[152:153], 11, v[148:149]
	v_readlane_b32 s62, v252, 30
	v_readlane_b32 s63, v252, 31
	v_readlane_b32 s49, v252, 17
	v_readlane_b32 s50, v252, 18
	v_lshl_add_u64 v[152:153], s[62:63], 0, v[152:153]
	v_lshl_add_u64 v[152:153], v[152:153], 0, v[0:1]
	v_readlane_b32 s51, v252, 19
	v_readlane_b32 s52, v252, 20
	v_readlane_b32 s53, v252, 21
	v_readlane_b32 s54, v252, 22
	v_readlane_b32 s55, v252, 23
	v_readlane_b32 s56, v252, 24
	v_readlane_b32 s57, v252, 25
	v_readlane_b32 s58, v252, 26
	v_readlane_b32 s59, v252, 27
	v_readlane_b32 s60, v252, 28
	v_readlane_b32 s61, v252, 29
	global_store_dwordx2 v[152:153], v[150:151], off

.LBB0_953:
	v_readlane_b32 s48, v252, 16
	v_lshlrev_b64 v[150:151], 11, v[148:149]
	v_readlane_b32 s58, v252, 26
	v_readlane_b32 s59, v252, 27
	s_andn2_b64 vcc, exec, s[2:3]
	v_readlane_b32 s49, v252, 17
	v_lshl_add_u64 v[148:149], s[58:59], 0, v[150:151]
	v_readlane_b32 s50, v252, 18
	v_readlane_b32 s51, v252, 19
	v_readlane_b32 s52, v252, 20
	v_readlane_b32 s53, v252, 21
	v_readlane_b32 s54, v252, 22
	v_readlane_b32 s55, v252, 23
	v_readlane_b32 s56, v252, 24
	v_readlane_b32 s57, v252, 25
	v_readlane_b32 s60, v252, 28
	v_readlane_b32 s61, v252, 29
	v_readlane_b32 s62, v252, 30
	v_readlane_b32 s63, v252, 31
	s_cbranch_vccnz .LBB0_955
	v_mul_f32_e32 v147, 0xbfb8aa3b, v38
	v_exp_f32_e32 v152, v147
	v_mul_f32_e32 v147, 0xbfb8aa3b, v39
	v_exp_f32_e32 v153, v147
	s_mov_b32 s4, 0x3db504f3
	v_pk_add_f32 v[152:153], v[152:153], 1.0 op_sel_hi:[1,0]
	s_nop 0
	v_rcp_f32_e32 v154, v153
	s_nop 0
	v_mul_f32_e32 v147, v39, v154
	v_mov_b32_e32 v153, v147
	v_rcp_f32_e32 v154, v152
	s_nop 0
	v_mul_f32_e32 v147, v38, v154
	v_mov_b32_e32 v152, v147
	v_mul_f32_e32 v147, 0xbfb8aa3b, v40
	v_exp_f32_e32 v154, v147
	v_mul_f32_e32 v147, 0xbfb8aa3b, v41
	v_exp_f32_e32 v155, v147
	v_pk_mul_f32 v[152:153], v[152:153], s[4:5] op_sel_hi:[1,0]
	v_pk_add_f32 v[154:155], v[154:155], 1.0 op_sel_hi:[1,0]
	s_nop 0
	v_rcp_f32_e32 v156, v155
	s_nop 0
	v_mul_f32_e32 v147, v41, v156
	v_mov_b32_e32 v155, v147
	v_rcp_f32_e32 v156, v154
	s_nop 0
	v_mul_f32_e32 v147, v40, v156
	v_mov_b32_e32 v154, v147
	v_pk_mul_f32 v[154:155], v[154:155], s[4:5] op_sel_hi:[1,0]
	v_mov_b32_e32 v157, v153
	v_cvt_pk_bf16_f32 v153, v154, v155
	v_cvt_pk_bf16_f32 v152, v152, v157
	v_lshl_add_u64 v[154:155], v[148:149], 0, v[0:1]
	global_store_dwordx2 v[154:155], v[152:153], off
.LBB0_955:
	s_and_b64 vcc, exec, s[40:41]
	s_mov_b64 s[2:3], -1
	s_cbranch_vccnz .LBB0_965
	s_cmp_lt_i32 s34, 3
	s_cbranch_scc1 .LBB0_962
	s_cmp_eq_u32 s34, 3
	s_cbranch_scc1 .LBB0_959
	v_mul_f32_e32 v147, 0xbfb8aa3b, v26
	v_exp_f32_e32 v152, v147
	v_mul_f32_e32 v147, 0xbfb8aa3b, v27
	v_exp_f32_e32 v153, v147
	v_readlane_b32 s48, v253, 4
	v_readlane_b32 s49, v253, 5
	v_readlane_b32 s50, v253, 6
	v_pk_add_f32 v[152:153], v[152:153], 1.0 op_sel_hi:[1,0]
	v_readlane_b32 s51, v253, 7
	v_rcp_f32_e32 v154, v152
	s_nop 0
	v_mul_f32_e32 v147, v26, v154
	v_rcp_f32_e32 v154, v153
	s_nop 0
	v_mul_f32_e32 v152, v27, v154
	v_mov_b32_e32 v154, v152
	v_mul_f32_e32 v152, 0xbfb8aa3b, v28
	v_mul_f32_e32 v153, 0xbfb8aa3b, v29
	v_exp_f32_e32 v152, v152
	v_exp_f32_e32 v153, v153
	s_nop 0
	v_pk_add_f32 v[152:153], v[152:153], 1.0 op_sel_hi:[1,0]
	s_nop 0
	v_rcp_f32_e32 v156, v152
	s_nop 0
	v_mul_f32_e32 v155, v28, v156
	v_mov_b32_e32 v152, v155
	v_rcp_f32_e32 v156, v153
	s_mov_b64 s[2:3], 0
	v_mul_f32_e32 v155, v29, v156
	v_mov_b32_e32 v153, v155
	v_cvt_pk_bf16_f32 v153, v152, v153
	v_cvt_pk_bf16_f32 v152, v147, v154
	v_lshl_add_u64 v[154:155], s[48:49], 0, v[150:151]
	v_lshl_add_u64 v[154:155], v[154:155], 0, v[0:1]
	global_store_dwordx2 v[154:155], v[152:153], off offset:32
.LBB0_959:
	s_andn2_b64 vcc, exec, s[2:3]
	s_cbranch_vccnz .LBB0_961
	v_readlane_b32 s48, v252, 16
	v_readlane_b32 s62, v252, 30
	v_readlane_b32 s63, v252, 31
	v_cvt_pk_bf16_f32 v153, v28, v29
	v_cvt_pk_bf16_f32 v152, v26, v27
	v_lshl_add_u64 v[154:155], s[62:63], 0, v[150:151]
	v_lshl_add_u64 v[154:155], v[154:155], 0, v[0:1]
	v_readlane_b32 s49, v252, 17
	v_readlane_b32 s50, v252, 18
	v_readlane_b32 s51, v252, 19
	v_readlane_b32 s52, v252, 20
	v_readlane_b32 s53, v252, 21
	v_readlane_b32 s54, v252, 22
	v_readlane_b32 s55, v252, 23
	v_readlane_b32 s56, v252, 24
	v_readlane_b32 s57, v252, 25
	v_readlane_b32 s58, v252, 26
	v_readlane_b32 s59, v252, 27
	v_readlane_b32 s60, v252, 28
	v_readlane_b32 s61, v252, 29
	global_store_dwordx2 v[154:155], v[152:153], off offset:32

.LBB0_965:
	s_andn2_b64 vcc, exec, s[2:3]
	s_cbranch_vccnz .LBB0_967
	v_mul_f32_e32 v147, 0xbfb8aa3b, v26
	v_exp_f32_e32 v152, v147
	v_mul_f32_e32 v147, 0xbfb8aa3b, v27
	v_exp_f32_e32 v153, v147
	s_mov_b32 s4, 0x3db504f3
	v_pk_add_f32 v[152:153], v[152:153], 1.0 op_sel_hi:[1,0]
	s_nop 0
	v_rcp_f32_e32 v154, v153
	s_nop 0
	v_mul_f32_e32 v147, v27, v154
	v_mov_b32_e32 v153, v147
	v_rcp_f32_e32 v154, v152
	s_nop 0
	v_mul_f32_e32 v147, v26, v154
	v_mov_b32_e32 v152, v147
	v_mul_f32_e32 v147, 0xbfb8aa3b, v28
	v_exp_f32_e32 v154, v147
	v_mul_f32_e32 v147, 0xbfb8aa3b, v29
	v_exp_f32_e32 v155, v147
	v_pk_mul_f32 v[152:153], v[152:153], s[4:5] op_sel_hi:[1,0]
	v_pk_add_f32 v[154:155], v[154:155], 1.0 op_sel_hi:[1,0]
	s_nop 0
	v_rcp_f32_e32 v156, v155
	s_nop 0
	v_mul_f32_e32 v147, v29, v156
	v_mov_b32_e32 v155, v147
	v_rcp_f32_e32 v156, v154
	s_nop 0
	v_mul_f32_e32 v147, v28, v156
	v_mov_b32_e32 v154, v147
	v_pk_mul_f32 v[154:155], v[154:155], s[4:5] op_sel_hi:[1,0]
	v_mov_b32_e32 v157, v153
	v_cvt_pk_bf16_f32 v153, v154, v155
	v_cvt_pk_bf16_f32 v152, v152, v157
	v_lshl_add_u64 v[154:155], v[148:149], 0, v[0:1]
	global_store_dwordx2 v[154:155], v[152:153], off offset:32
.LBB0_967:
	s_and_b64 vcc, exec, s[40:41]
	s_mov_b64 s[2:3], -1
	s_cbranch_vccnz .LBB0_977
	s_cmp_lt_i32 s34, 3
	s_cbranch_scc1 .LBB0_974
	s_cmp_eq_u32 s34, 3
	s_cbranch_scc1 .LBB0_971
	v_mul_f32_e32 v147, 0xbfb8aa3b, v22
	v_exp_f32_e32 v152, v147
	v_mul_f32_e32 v147, 0xbfb8aa3b, v23
	v_exp_f32_e32 v153, v147
	v_readlane_b32 s48, v253, 4
	v_readlane_b32 s49, v253, 5
	v_readlane_b32 s50, v253, 6
	v_pk_add_f32 v[152:153], v[152:153], 1.0 op_sel_hi:[1,0]
	v_readlane_b32 s51, v253, 7
	v_rcp_f32_e32 v154, v152
	s_nop 0
	v_mul_f32_e32 v147, v22, v154
	v_rcp_f32_e32 v154, v153
	s_nop 0
	v_mul_f32_e32 v152, v23, v154
	v_mov_b32_e32 v154, v152
	v_mul_f32_e32 v152, 0xbfb8aa3b, v24
	v_mul_f32_e32 v153, 0xbfb8aa3b, v25
	v_exp_f32_e32 v152, v152
	v_exp_f32_e32 v153, v153
	s_nop 0
	v_pk_add_f32 v[152:153], v[152:153], 1.0 op_sel_hi:[1,0]
	s_nop 0
	v_rcp_f32_e32 v156, v152
	s_nop 0
	v_mul_f32_e32 v155, v24, v156
	v_mov_b32_e32 v152, v155
	v_rcp_f32_e32 v156, v153
	s_mov_b64 s[2:3], 0
	v_mul_f32_e32 v155, v25, v156
	v_mov_b32_e32 v153, v155
	v_cvt_pk_bf16_f32 v153, v152, v153
	v_cvt_pk_bf16_f32 v152, v147, v154
	v_lshl_add_u64 v[154:155], s[48:49], 0, v[150:151]
	v_lshl_add_u64 v[154:155], v[154:155], 0, v[0:1]
	global_store_dwordx2 v[154:155], v[152:153], off offset:64
.LBB0_971:
	s_andn2_b64 vcc, exec, s[2:3]
	s_cbranch_vccnz .LBB0_973
	v_readlane_b32 s48, v252, 16
	v_readlane_b32 s62, v252, 30
	v_readlane_b32 s63, v252, 31
	v_cvt_pk_bf16_f32 v153, v24, v25
	v_cvt_pk_bf16_f32 v152, v22, v23
	v_lshl_add_u64 v[154:155], s[62:63], 0, v[150:151]
	v_lshl_add_u64 v[154:155], v[154:155], 0, v[0:1]
	v_readlane_b32 s49, v252, 17
	v_readlane_b32 s50, v252, 18
	v_readlane_b32 s51, v252, 19
	v_readlane_b32 s52, v252, 20
	v_readlane_b32 s53, v252, 21
	v_readlane_b32 s54, v252, 22
	v_readlane_b32 s55, v252, 23
	v_readlane_b32 s56, v252, 24
	v_readlane_b32 s57, v252, 25
	v_readlane_b32 s58, v252, 26
	v_readlane_b32 s59, v252, 27
	v_readlane_b32 s60, v252, 28
	v_readlane_b32 s61, v252, 29
	global_store_dwordx2 v[154:155], v[152:153], off offset:64

.LBB0_977:
	s_andn2_b64 vcc, exec, s[2:3]
	s_cbranch_vccnz .LBB0_979
	v_mul_f32_e32 v147, 0xbfb8aa3b, v22
	v_exp_f32_e32 v152, v147
	v_mul_f32_e32 v147, 0xbfb8aa3b, v23
	v_exp_f32_e32 v153, v147
	s_mov_b32 s4, 0x3db504f3
	v_pk_add_f32 v[152:153], v[152:153], 1.0 op_sel_hi:[1,0]
	s_nop 0
	v_rcp_f32_e32 v154, v153
	s_nop 0
	v_mul_f32_e32 v147, v23, v154
	v_mov_b32_e32 v153, v147
	v_rcp_f32_e32 v154, v152
	s_nop 0
	v_mul_f32_e32 v147, v22, v154
	v_mov_b32_e32 v152, v147
	v_mul_f32_e32 v147, 0xbfb8aa3b, v24
	v_exp_f32_e32 v154, v147
	v_mul_f32_e32 v147, 0xbfb8aa3b, v25
	v_exp_f32_e32 v155, v147
	v_pk_mul_f32 v[152:153], v[152:153], s[4:5] op_sel_hi:[1,0]
	v_pk_add_f32 v[154:155], v[154:155], 1.0 op_sel_hi:[1,0]
	s_nop 0
	v_rcp_f32_e32 v156, v155
	s_nop 0
	v_mul_f32_e32 v147, v25, v156
	v_mov_b32_e32 v155, v147
	v_rcp_f32_e32 v156, v154
	s_nop 0
	v_mul_f32_e32 v147, v24, v156
	v_mov_b32_e32 v154, v147
	v_pk_mul_f32 v[154:155], v[154:155], s[4:5] op_sel_hi:[1,0]
	v_mov_b32_e32 v157, v153
	v_cvt_pk_bf16_f32 v153, v154, v155
	v_cvt_pk_bf16_f32 v152, v152, v157
	v_lshl_add_u64 v[154:155], v[148:149], 0, v[0:1]
	global_store_dwordx2 v[154:155], v[152:153], off offset:64
.LBB0_979:
	s_and_b64 vcc, exec, s[40:41]
	s_mov_b64 s[2:3], -1
	s_cbranch_vccnz .LBB0_989
	s_cmp_lt_i32 s34, 3
	s_cbranch_scc1 .LBB0_986
	s_cmp_eq_u32 s34, 3
	s_cbranch_scc1 .LBB0_983
	v_mul_f32_e32 v147, 0xbfb8aa3b, v18
	v_exp_f32_e32 v152, v147
	v_mul_f32_e32 v147, 0xbfb8aa3b, v19
	v_exp_f32_e32 v153, v147
	v_readlane_b32 s48, v253, 4
	v_readlane_b32 s49, v253, 5
	v_readlane_b32 s50, v253, 6
	v_pk_add_f32 v[152:153], v[152:153], 1.0 op_sel_hi:[1,0]
	v_readlane_b32 s51, v253, 7
	v_rcp_f32_e32 v154, v152
	s_nop 0
	v_mul_f32_e32 v147, v18, v154
	v_rcp_f32_e32 v154, v153
	s_nop 0
	v_mul_f32_e32 v152, v19, v154
	v_mov_b32_e32 v154, v152
	v_mul_f32_e32 v152, 0xbfb8aa3b, v20
	v_mul_f32_e32 v153, 0xbfb8aa3b, v21
	v_exp_f32_e32 v152, v152
	v_exp_f32_e32 v153, v153
	s_nop 0
	v_pk_add_f32 v[152:153], v[152:153], 1.0 op_sel_hi:[1,0]
	s_nop 0
	v_rcp_f32_e32 v156, v152
	s_nop 0
	v_mul_f32_e32 v155, v20, v156
	v_mov_b32_e32 v152, v155
	v_rcp_f32_e32 v156, v153
	s_mov_b64 s[2:3], 0
	v_mul_f32_e32 v155, v21, v156
	v_mov_b32_e32 v153, v155
	v_cvt_pk_bf16_f32 v153, v152, v153
	v_cvt_pk_bf16_f32 v152, v147, v154
	v_lshl_add_u64 v[154:155], s[48:49], 0, v[150:151]
	v_lshl_add_u64 v[154:155], v[154:155], 0, v[0:1]
	global_store_dwordx2 v[154:155], v[152:153], off offset:96
.LBB0_983:
	s_andn2_b64 vcc, exec, s[2:3]
	s_cbranch_vccnz .LBB0_985
	v_readlane_b32 s48, v252, 16
	v_readlane_b32 s62, v252, 30
	v_readlane_b32 s63, v252, 31
	v_cvt_pk_bf16_f32 v153, v20, v21
	v_cvt_pk_bf16_f32 v152, v18, v19
	v_lshl_add_u64 v[154:155], s[62:63], 0, v[150:151]
	v_lshl_add_u64 v[154:155], v[154:155], 0, v[0:1]
	v_readlane_b32 s49, v252, 17
	v_readlane_b32 s50, v252, 18
	v_readlane_b32 s51, v252, 19
	v_readlane_b32 s52, v252, 20
	v_readlane_b32 s53, v252, 21
	v_readlane_b32 s54, v252, 22
	v_readlane_b32 s55, v252, 23
	v_readlane_b32 s56, v252, 24
	v_readlane_b32 s57, v252, 25
	v_readlane_b32 s58, v252, 26
	v_readlane_b32 s59, v252, 27
	v_readlane_b32 s60, v252, 28
	v_readlane_b32 s61, v252, 29
	global_store_dwordx2 v[154:155], v[152:153], off offset:96

.LBB0_989:
	s_andn2_b64 vcc, exec, s[2:3]
	s_cbranch_vccnz .LBB0_991
	v_mul_f32_e32 v147, 0xbfb8aa3b, v18
	v_exp_f32_e32 v150, v147
	v_mul_f32_e32 v147, 0xbfb8aa3b, v19
	v_exp_f32_e32 v151, v147
	s_mov_b32 s4, 0x3db504f3
	v_lshl_add_u64 v[148:149], v[148:149], 0, v[0:1]
	v_pk_add_f32 v[150:151], v[150:151], 1.0 op_sel_hi:[1,0]
	s_nop 0
	v_rcp_f32_e32 v152, v151
	s_nop 0
	v_mul_f32_e32 v147, v19, v152
	v_mov_b32_e32 v151, v147
	v_rcp_f32_e32 v152, v150
	s_nop 0
	v_mul_f32_e32 v147, v18, v152
	v_mov_b32_e32 v150, v147
	v_mul_f32_e32 v147, 0xbfb8aa3b, v20
	v_exp_f32_e32 v152, v147
	v_mul_f32_e32 v147, 0xbfb8aa3b, v21
	v_exp_f32_e32 v153, v147
	v_pk_mul_f32 v[150:151], v[150:151], s[4:5] op_sel_hi:[1,0]
	v_pk_add_f32 v[152:153], v[152:153], 1.0 op_sel_hi:[1,0]
	s_nop 0
	v_rcp_f32_e32 v154, v153
	s_nop 0
	v_mul_f32_e32 v147, v21, v154
	v_mov_b32_e32 v153, v147
	v_rcp_f32_e32 v154, v152
	s_nop 0
	v_mul_f32_e32 v147, v20, v154
	v_mov_b32_e32 v152, v147
	v_pk_mul_f32 v[152:153], v[152:153], s[4:5] op_sel_hi:[1,0]
	v_mov_b32_e32 v155, v151
	v_cvt_pk_bf16_f32 v151, v152, v153
	v_cvt_pk_bf16_f32 v150, v150, v155
	global_store_dwordx2 v[148:149], v[150:151], off offset:96
.LBB0_991:
	v_or_b32_e32 v146, 0x70, v146
	v_ashrrev_i32_e32 v147, 31, v146
	s_and_b64 vcc, exec, s[40:41]
	s_mov_b64 s[2:3], -1
	s_cbranch_vccnz .LBB0_1001
	s_cmp_lt_i32 s34, 3
	s_cbranch_scc1 .LBB0_998
	s_cmp_eq_u32 s34, 3
	s_cbranch_scc1 .LBB0_995
	v_mul_f32_e32 v148, 0xbfb8aa3b, v14
	v_mul_f32_e32 v149, 0xbfb8aa3b, v15
	v_exp_f32_e32 v148, v148
	v_exp_f32_e32 v149, v149
	v_readlane_b32 s48, v253, 4
	v_readlane_b32 s49, v253, 5
	v_readlane_b32 s50, v253, 6
	v_pk_add_f32 v[148:149], v[148:149], 1.0 op_sel_hi:[1,0]
	v_readlane_b32 s51, v253, 7
	v_rcp_f32_e32 v151, v148
	s_nop 0
	v_mul_f32_e32 v150, v14, v151
	v_rcp_f32_e32 v151, v149
	s_nop 0
	v_mul_f32_e32 v148, v15, v151
	v_mov_b32_e32 v151, v148
	v_mul_f32_e32 v148, 0xbfb8aa3b, v16
	v_mul_f32_e32 v149, 0xbfb8aa3b, v17
	v_exp_f32_e32 v148, v148
	v_exp_f32_e32 v149, v149
	s_nop 0
	v_pk_add_f32 v[148:149], v[148:149], 1.0 op_sel_hi:[1,0]
	s_nop 0
	v_rcp_f32_e32 v153, v148
	s_nop 0
	v_mul_f32_e32 v152, v16, v153
	v_mov_b32_e32 v148, v152
	v_rcp_f32_e32 v153, v149
	s_mov_b64 s[2:3], 0
	v_mul_f32_e32 v152, v17, v153
	v_mov_b32_e32 v149, v152
	v_cvt_pk_bf16_f32 v149, v148, v149
	v_cvt_pk_bf16_f32 v148, v150, v151
	v_lshlrev_b64 v[150:151], 11, v[146:147]
	v_lshl_add_u64 v[150:151], s[48:49], 0, v[150:151]
	v_lshl_add_u64 v[150:151], v[150:151], 0, v[0:1]
	global_store_dwordx2 v[150:151], v[148:149], off
.LBB0_995:
	s_andn2_b64 vcc, exec, s[2:3]
	s_cbranch_vccnz .LBB0_997
	v_readlane_b32 s48, v252, 16
	v_cvt_pk_bf16_f32 v149, v16, v17
	v_cvt_pk_bf16_f32 v148, v14, v15
	v_lshlrev_b64 v[150:151], 11, v[146:147]
	v_readlane_b32 s62, v252, 30
	v_readlane_b32 s63, v252, 31
	v_readlane_b32 s49, v252, 17
	v_readlane_b32 s50, v252, 18
	v_lshl_add_u64 v[150:151], s[62:63], 0, v[150:151]
	v_lshl_add_u64 v[150:151], v[150:151], 0, v[0:1]
	v_readlane_b32 s51, v252, 19
	v_readlane_b32 s52, v252, 20
	v_readlane_b32 s53, v252, 21
	v_readlane_b32 s54, v252, 22
	v_readlane_b32 s55, v252, 23
	v_readlane_b32 s56, v252, 24
	v_readlane_b32 s57, v252, 25
	v_readlane_b32 s58, v252, 26
	v_readlane_b32 s59, v252, 27
	v_readlane_b32 s60, v252, 28
	v_readlane_b32 s61, v252, 29
	global_store_dwordx2 v[150:151], v[148:149], off

.LBB0_1001:
	v_readlane_b32 s48, v252, 16
	s_waitcnt vmcnt(3)
	v_lshlrev_b64 v[144:145], 11, v[146:147]
	v_readlane_b32 s58, v252, 26
	v_readlane_b32 s59, v252, 27
	s_andn2_b64 vcc, exec, s[2:3]
	v_readlane_b32 s49, v252, 17
	v_lshl_add_u64 v[142:143], s[58:59], 0, v[144:145]
	v_readlane_b32 s50, v252, 18
	v_readlane_b32 s51, v252, 19
	v_readlane_b32 s52, v252, 20
	v_readlane_b32 s53, v252, 21
	v_readlane_b32 s54, v252, 22
	v_readlane_b32 s55, v252, 23
	v_readlane_b32 s56, v252, 24
	v_readlane_b32 s57, v252, 25
	v_readlane_b32 s60, v252, 28
	v_readlane_b32 s61, v252, 29
	v_readlane_b32 s62, v252, 30
	v_readlane_b32 s63, v252, 31
	s_cbranch_vccnz .LBB0_1003
	v_mul_f32_e32 v146, 0xbfb8aa3b, v14
	v_mul_f32_e32 v147, 0xbfb8aa3b, v15
	v_exp_f32_e32 v146, v146
	v_exp_f32_e32 v147, v147
	s_mov_b32 s4, 0x3db504f3
	v_pk_add_f32 v[146:147], v[146:147], 1.0 op_sel_hi:[1,0]
	s_nop 0
	v_rcp_f32_e32 v149, v147
	s_nop 0
	v_mul_f32_e32 v148, v15, v149
	v_mov_b32_e32 v147, v148
	v_rcp_f32_e32 v149, v146
	s_nop 0
	v_mul_f32_e32 v148, v14, v149
	v_mov_b32_e32 v146, v148
	v_mul_f32_e32 v148, 0xbfb8aa3b, v16
	v_mul_f32_e32 v149, 0xbfb8aa3b, v17
	v_exp_f32_e32 v148, v148
	v_exp_f32_e32 v149, v149
	v_pk_mul_f32 v[146:147], v[146:147], s[4:5] op_sel_hi:[1,0]
	v_pk_add_f32 v[148:149], v[148:149], 1.0 op_sel_hi:[1,0]
	s_nop 0
	v_rcp_f32_e32 v151, v149
	s_nop 0
	v_mul_f32_e32 v150, v17, v151
	v_mov_b32_e32 v149, v150
	v_rcp_f32_e32 v151, v148
	s_nop 0
	v_mul_f32_e32 v150, v16, v151
	v_mov_b32_e32 v148, v150
	v_pk_mul_f32 v[148:149], v[148:149], s[4:5] op_sel_hi:[1,0]
	v_mov_b32_e32 v152, v147
	v_mov_b32_e32 v147, v148
	v_cvt_pk_bf16_f32 v147, v147, v149
	v_cvt_pk_bf16_f32 v146, v146, v152
	v_lshl_add_u64 v[148:149], v[142:143], 0, v[0:1]
	global_store_dwordx2 v[148:149], v[146:147], off
.LBB0_1003:
	s_and_b64 vcc, exec, s[40:41]
	s_mov_b64 s[2:3], -1
	s_cbranch_vccnz .LBB0_1013
	s_cmp_lt_i32 s34, 3
	s_cbranch_scc1 .LBB0_1010
	s_cmp_eq_u32 s34, 3
	s_cbranch_scc1 .LBB0_1007
	v_mul_f32_e32 v146, 0xbfb8aa3b, v10
	v_mul_f32_e32 v147, 0xbfb8aa3b, v11
	v_exp_f32_e32 v146, v146
	v_exp_f32_e32 v147, v147
	v_readlane_b32 s48, v253, 4
	v_readlane_b32 s49, v253, 5
	v_readlane_b32 s50, v253, 6
	v_pk_add_f32 v[146:147], v[146:147], 1.0 op_sel_hi:[1,0]
	v_readlane_b32 s51, v253, 7
	v_rcp_f32_e32 v149, v146
	s_nop 0
	v_mul_f32_e32 v148, v10, v149
	v_rcp_f32_e32 v149, v147
	s_nop 0
	v_mul_f32_e32 v146, v11, v149
	v_mov_b32_e32 v149, v146
	v_mul_f32_e32 v146, 0xbfb8aa3b, v12
	v_mul_f32_e32 v147, 0xbfb8aa3b, v13
	v_exp_f32_e32 v146, v146
	v_exp_f32_e32 v147, v147
	s_nop 0
	v_pk_add_f32 v[146:147], v[146:147], 1.0 op_sel_hi:[1,0]
	s_nop 0
	v_rcp_f32_e32 v151, v146
	s_nop 0
	v_mul_f32_e32 v150, v12, v151
	v_mov_b32_e32 v146, v150
	v_rcp_f32_e32 v151, v147
	s_mov_b64 s[2:3], 0
	v_mul_f32_e32 v150, v13, v151
	v_mov_b32_e32 v147, v150
	v_cvt_pk_bf16_f32 v147, v146, v147
	v_cvt_pk_bf16_f32 v146, v148, v149
	v_lshl_add_u64 v[148:149], s[48:49], 0, v[144:145]
	v_lshl_add_u64 v[148:149], v[148:149], 0, v[0:1]
	global_store_dwordx2 v[148:149], v[146:147], off offset:32
.LBB0_1007:
	s_andn2_b64 vcc, exec, s[2:3]
	s_cbranch_vccnz .LBB0_1009
	v_readlane_b32 s48, v252, 16
	v_readlane_b32 s62, v252, 30
	v_readlane_b32 s63, v252, 31
	v_cvt_pk_bf16_f32 v147, v12, v13
	v_cvt_pk_bf16_f32 v146, v10, v11
	v_lshl_add_u64 v[148:149], s[62:63], 0, v[144:145]
	v_lshl_add_u64 v[148:149], v[148:149], 0, v[0:1]
	v_readlane_b32 s49, v252, 17
	v_readlane_b32 s50, v252, 18
	v_readlane_b32 s51, v252, 19
	v_readlane_b32 s52, v252, 20
	v_readlane_b32 s53, v252, 21
	v_readlane_b32 s54, v252, 22
	v_readlane_b32 s55, v252, 23
	v_readlane_b32 s56, v252, 24
	v_readlane_b32 s57, v252, 25
	v_readlane_b32 s58, v252, 26
	v_readlane_b32 s59, v252, 27
	v_readlane_b32 s60, v252, 28
	v_readlane_b32 s61, v252, 29
	global_store_dwordx2 v[148:149], v[146:147], off offset:32

.LBB0_1013:
	s_andn2_b64 vcc, exec, s[2:3]
	s_cbranch_vccnz .LBB0_1015
	s_waitcnt vmcnt(2)
	v_mul_f32_e32 v138, 0xbfb8aa3b, v10
	v_mul_f32_e32 v139, 0xbfb8aa3b, v11
	v_exp_f32_e32 v138, v138
	v_exp_f32_e32 v139, v139
	s_mov_b32 s4, 0x3db504f3
	v_pk_add_f32 v[138:139], v[138:139], 1.0 op_sel_hi:[1,0]
	s_nop 0
	v_rcp_f32_e32 v141, v139
	s_nop 0
	v_mul_f32_e32 v140, v11, v141
	v_mov_b32_e32 v139, v140
	v_rcp_f32_e32 v141, v138
	s_nop 0
	v_mul_f32_e32 v140, v10, v141
	v_mov_b32_e32 v138, v140
	v_mul_f32_e32 v140, 0xbfb8aa3b, v12
	v_mul_f32_e32 v141, 0xbfb8aa3b, v13
	v_exp_f32_e32 v140, v140
	v_exp_f32_e32 v141, v141
	v_pk_mul_f32 v[138:139], v[138:139], s[4:5] op_sel_hi:[1,0]
	v_pk_add_f32 v[140:141], v[140:141], 1.0 op_sel_hi:[1,0]
	s_nop 0
	v_rcp_f32_e32 v147, v141
	s_nop 0
	v_mul_f32_e32 v146, v13, v147
	v_mov_b32_e32 v141, v146
	v_rcp_f32_e32 v147, v140
	s_nop 0
	v_mul_f32_e32 v146, v12, v147
	v_mov_b32_e32 v140, v146
	v_pk_mul_f32 v[140:141], v[140:141], s[4:5] op_sel_hi:[1,0]
	v_mov_b32_e32 v148, v139
	v_mov_b32_e32 v139, v140
	v_cvt_pk_bf16_f32 v139, v139, v141
	v_cvt_pk_bf16_f32 v138, v138, v148
	v_lshl_add_u64 v[140:141], v[142:143], 0, v[0:1]
	global_store_dwordx2 v[140:141], v[138:139], off offset:32
.LBB0_1015:
	s_and_b64 vcc, exec, s[40:41]
	s_mov_b64 s[2:3], -1
	s_cbranch_vccnz .LBB0_1025
	s_cmp_lt_i32 s34, 3
	s_cbranch_scc1 .LBB0_1022
	s_cmp_eq_u32 s34, 3
	s_cbranch_scc1 .LBB0_1019
	s_waitcnt vmcnt(2)
	v_mul_f32_e32 v138, 0xbfb8aa3b, v6
	v_mul_f32_e32 v139, 0xbfb8aa3b, v7
	v_exp_f32_e32 v138, v138
	v_exp_f32_e32 v139, v139
	v_readlane_b32 s48, v253, 4
	v_readlane_b32 s49, v253, 5
	v_readlane_b32 s50, v253, 6
	v_pk_add_f32 v[138:139], v[138:139], 1.0 op_sel_hi:[1,0]
	v_readlane_b32 s51, v253, 7
	v_rcp_f32_e32 v141, v138
	s_nop 0
	v_mul_f32_e32 v140, v6, v141
	v_rcp_f32_e32 v141, v139
	s_nop 0
	v_mul_f32_e32 v138, v7, v141
	v_mov_b32_e32 v141, v138
	v_mul_f32_e32 v138, 0xbfb8aa3b, v8
	v_mul_f32_e32 v139, 0xbfb8aa3b, v9
	v_exp_f32_e32 v138, v138
	v_exp_f32_e32 v139, v139
	s_nop 0
	v_pk_add_f32 v[138:139], v[138:139], 1.0 op_sel_hi:[1,0]
	s_nop 0
	v_rcp_f32_e32 v147, v138
	s_nop 0
	v_mul_f32_e32 v146, v8, v147
	v_mov_b32_e32 v138, v146
	v_rcp_f32_e32 v147, v139
	s_mov_b64 s[2:3], 0
	v_mul_f32_e32 v146, v9, v147
	v_mov_b32_e32 v139, v146
	v_cvt_pk_bf16_f32 v139, v138, v139
	v_cvt_pk_bf16_f32 v138, v140, v141
	v_lshl_add_u64 v[140:141], s[48:49], 0, v[144:145]
	v_lshl_add_u64 v[140:141], v[140:141], 0, v[0:1]
	global_store_dwordx2 v[140:141], v[138:139], off offset:64
.LBB0_1019:
	s_andn2_b64 vcc, exec, s[2:3]
	s_cbranch_vccnz .LBB0_1021
	s_waitcnt vmcnt(2)
	v_readlane_b32 s48, v252, 16
	v_readlane_b32 s62, v252, 30
	v_readlane_b32 s63, v252, 31
	v_cvt_pk_bf16_f32 v139, v8, v9
	v_cvt_pk_bf16_f32 v138, v6, v7
	v_lshl_add_u64 v[140:141], s[62:63], 0, v[144:145]
	v_lshl_add_u64 v[140:141], v[140:141], 0, v[0:1]
	v_readlane_b32 s49, v252, 17
	v_readlane_b32 s50, v252, 18
	v_readlane_b32 s51, v252, 19
	v_readlane_b32 s52, v252, 20
	v_readlane_b32 s53, v252, 21
	v_readlane_b32 s54, v252, 22
	v_readlane_b32 s55, v252, 23
	v_readlane_b32 s56, v252, 24
	v_readlane_b32 s57, v252, 25
	v_readlane_b32 s58, v252, 26
	v_readlane_b32 s59, v252, 27
	v_readlane_b32 s60, v252, 28
	v_readlane_b32 s61, v252, 29
	global_store_dwordx2 v[140:141], v[138:139], off offset:64

.LBB0_1025:
	s_andn2_b64 vcc, exec, s[2:3]
	s_cbranch_vccnz .LBB0_1027
	s_waitcnt vmcnt(1)
	v_mul_f32_e32 v134, 0xbfb8aa3b, v6
	v_mul_f32_e32 v135, 0xbfb8aa3b, v7
	v_exp_f32_e32 v134, v134
	v_exp_f32_e32 v135, v135
	s_mov_b32 s4, 0x3db504f3
	v_pk_add_f32 v[134:135], v[134:135], 1.0 op_sel_hi:[1,0]
	s_nop 0
	v_rcp_f32_e32 v137, v135
	s_nop 0
	v_mul_f32_e32 v136, v7, v137
	v_mov_b32_e32 v135, v136
	v_rcp_f32_e32 v137, v134
	s_nop 0
	v_mul_f32_e32 v136, v6, v137
	v_mov_b32_e32 v134, v136
	v_mul_f32_e32 v136, 0xbfb8aa3b, v8
	v_mul_f32_e32 v137, 0xbfb8aa3b, v9
	v_exp_f32_e32 v136, v136
	v_exp_f32_e32 v137, v137
	v_pk_mul_f32 v[134:135], v[134:135], s[4:5] op_sel_hi:[1,0]
	v_pk_add_f32 v[136:137], v[136:137], 1.0 op_sel_hi:[1,0]
	s_nop 0
	v_rcp_f32_e32 v139, v137
	s_nop 0
	v_mul_f32_e32 v138, v9, v139
	v_mov_b32_e32 v137, v138
	v_rcp_f32_e32 v139, v136
	s_nop 0
	v_mul_f32_e32 v138, v8, v139
	v_mov_b32_e32 v136, v138
	v_pk_mul_f32 v[136:137], v[136:137], s[4:5] op_sel_hi:[1,0]
	v_mov_b32_e32 v140, v135
	v_mov_b32_e32 v135, v136
	v_cvt_pk_bf16_f32 v135, v135, v137
	v_cvt_pk_bf16_f32 v134, v134, v140
	v_lshl_add_u64 v[136:137], v[142:143], 0, v[0:1]
	global_store_dwordx2 v[136:137], v[134:135], off offset:64
.LBB0_1027:
	s_and_b64 vcc, exec, s[40:41]
	s_mov_b64 s[2:3], -1
	s_cbranch_vccnz .LBB0_1037
	s_cmp_lt_i32 s34, 3
	s_cbranch_scc1 .LBB0_1034
	s_cmp_eq_u32 s34, 3
	s_cbranch_scc1 .LBB0_1031
	s_waitcnt vmcnt(1)
	v_mul_f32_e32 v134, 0xbfb8aa3b, v2
	v_mul_f32_e32 v135, 0xbfb8aa3b, v3
	v_exp_f32_e32 v134, v134
	v_exp_f32_e32 v135, v135
	v_readlane_b32 s48, v253, 4
	v_readlane_b32 s49, v253, 5
	v_readlane_b32 s50, v253, 6
	v_pk_add_f32 v[134:135], v[134:135], 1.0 op_sel_hi:[1,0]
	v_readlane_b32 s51, v253, 7
	v_rcp_f32_e32 v137, v134
	s_nop 0
	v_mul_f32_e32 v136, v2, v137
	v_rcp_f32_e32 v137, v135
	s_nop 0
	v_mul_f32_e32 v134, v3, v137
	v_mov_b32_e32 v137, v134
	v_mul_f32_e32 v134, 0xbfb8aa3b, v4
	v_mul_f32_e32 v135, 0xbfb8aa3b, v5
	v_exp_f32_e32 v134, v134
	v_exp_f32_e32 v135, v135
	s_nop 0
	v_pk_add_f32 v[134:135], v[134:135], 1.0 op_sel_hi:[1,0]
	s_nop 0
	v_rcp_f32_e32 v139, v134
	s_nop 0
	v_mul_f32_e32 v138, v4, v139
	v_mov_b32_e32 v134, v138
	v_rcp_f32_e32 v139, v135
	s_mov_b64 s[2:3], 0
	v_mul_f32_e32 v138, v5, v139
	v_mov_b32_e32 v135, v138
	v_cvt_pk_bf16_f32 v135, v134, v135
	v_cvt_pk_bf16_f32 v134, v136, v137
	v_lshl_add_u64 v[136:137], s[48:49], 0, v[144:145]
	v_lshl_add_u64 v[136:137], v[136:137], 0, v[0:1]
	global_store_dwordx2 v[136:137], v[134:135], off offset:96
.LBB0_1031:
	s_andn2_b64 vcc, exec, s[2:3]
	s_cbranch_vccnz .LBB0_1033
	s_waitcnt vmcnt(1)
	v_readlane_b32 s48, v252, 16
	v_readlane_b32 s62, v252, 30
	v_readlane_b32 s63, v252, 31
	v_cvt_pk_bf16_f32 v135, v4, v5
	v_cvt_pk_bf16_f32 v134, v2, v3
	v_lshl_add_u64 v[136:137], s[62:63], 0, v[144:145]
	v_lshl_add_u64 v[136:137], v[136:137], 0, v[0:1]
	v_readlane_b32 s49, v252, 17
	v_readlane_b32 s50, v252, 18
	v_readlane_b32 s51, v252, 19
	v_readlane_b32 s52, v252, 20
	v_readlane_b32 s53, v252, 21
	v_readlane_b32 s54, v252, 22
	v_readlane_b32 s55, v252, 23
	v_readlane_b32 s56, v252, 24
	v_readlane_b32 s57, v252, 25
	v_readlane_b32 s58, v252, 26
	v_readlane_b32 s59, v252, 27
	v_readlane_b32 s60, v252, 28
	v_readlane_b32 s61, v252, 29
	global_store_dwordx2 v[136:137], v[134:135], off offset:96

.LBB0_1037:
	s_andn2_b64 vcc, exec, s[2:3]
	s_cbranch_vccnz .LBB0_1039
	s_waitcnt vmcnt(0)
	v_mul_f32_e32 v130, 0xbfb8aa3b, v2
	v_mul_f32_e32 v131, 0xbfb8aa3b, v3
	v_exp_f32_e32 v130, v130
	v_exp_f32_e32 v131, v131
	s_mov_b32 s4, 0x3db504f3
	v_pk_add_f32 v[130:131], v[130:131], 1.0 op_sel_hi:[1,0]
	s_nop 0
	v_rcp_f32_e32 v133, v131
	s_nop 0
	v_mul_f32_e32 v132, v3, v133
	v_mov_b32_e32 v131, v132
	v_rcp_f32_e32 v133, v130
	s_nop 0
	v_mul_f32_e32 v132, v2, v133
	v_mov_b32_e32 v130, v132
	v_mul_f32_e32 v132, 0xbfb8aa3b, v4
	v_mul_f32_e32 v133, 0xbfb8aa3b, v5
	v_exp_f32_e32 v132, v132
	v_exp_f32_e32 v133, v133
	v_pk_mul_f32 v[130:131], v[130:131], s[4:5] op_sel_hi:[1,0]
	v_pk_add_f32 v[132:133], v[132:133], 1.0 op_sel_hi:[1,0]
	s_nop 0
	v_rcp_f32_e32 v135, v133
	s_nop 0
	v_mul_f32_e32 v134, v5, v135
	v_mov_b32_e32 v133, v134
	v_rcp_f32_e32 v135, v132
	s_nop 0
	v_mul_f32_e32 v134, v4, v135
	v_mov_b32_e32 v132, v134
	v_pk_mul_f32 v[132:133], v[132:133], s[4:5] op_sel_hi:[1,0]
	v_mov_b32_e32 v136, v131
	v_mov_b32_e32 v131, v132
	v_cvt_pk_bf16_f32 v131, v131, v133
	v_cvt_pk_bf16_f32 v130, v130, v136
	v_lshl_add_u64 v[132:133], v[142:143], 0, v[0:1]
	global_store_dwordx2 v[132:133], v[130:131], off offset:96

.LBB0_1086:
	s_and_b64 vcc, exec, s[2:3]
	s_cbranch_vccz .LBB0_1216
	s_and_b64 s[2:3], s[8:9], exec
	v_readlane_b32 s2, v255, 28
	s_waitcnt vmcnt(0)
	v_add_u32_e32 v132, s45, v225
	v_or_b32_e32 v130, s6, v224
	v_readlane_b32 s3, v255, 29
	v_ashrrev_i32_e32 v133, 31, v132
	v_ashrrev_i32_e32 v130, 1, v130
	s_cselect_b32 s3, 0, s3
	s_cselect_b32 s2, 0, s2
	v_lshlrev_b32_e32 v0, 2, v223
	v_lshlrev_b64 v[136:137], 11, v[132:133]
	v_and_b32_e32 v131, 64, v224
	v_and_b32_e32 v130, 0xffffffc0, v130
	v_and_or_b32 v0, v224, 64, v0
	v_cmp_ne_u32_e32 vcc, 0, v131
	v_ashrrev_i32_e32 v131, 31, v130
	v_lshl_add_u64 v[134:135], s[2:3], 0, v[136:137]
	v_lshl_add_u64 v[134:135], v[130:131], 1, v[134:135]
	v_lshlrev_b32_e32 v0, 1, v0
	s_and_saveexec_b64 s[4:5], vcc
	s_xor_b64 s[4:5], exec, s[4:5]
	s_movk_i32 s8, 0xff80
	v_lshl_add_u64 v[138:139], v[134:135], 0, v[0:1]
	s_mov_b32 s9, -1
	v_lshl_add_u64 v[138:139], v[138:139], 0, s[8:9]
	s_or_saveexec_b64 s[4:5], s[4:5]
	v_lshl_add_u64 v[136:137], s[42:43], 0, v[136:137]
	v_lshl_add_u64 v[136:137], v[130:131], 1, v[136:137]
	s_xor_b64 exec, exec, s[4:5]
	v_lshl_add_u64 v[138:139], v[136:137], 0, v[0:1]
	s_or_b64 exec, exec, s[4:5]
	v_cvt_pk_bf16_f32 v141, v128, v129
	v_cvt_pk_bf16_f32 v140, v126, v127
	global_store_dwordx2 v[138:139], v[140:141], off
	s_and_saveexec_b64 s[4:5], vcc
	s_xor_b64 s[4:5], exec, s[4:5]
	s_movk_i32 s8, 0xffa0
	v_lshl_add_u64 v[138:139], v[134:135], 0, v[0:1]
	s_mov_b32 s9, -1
	v_lshl_add_u64 v[138:139], v[138:139], 0, s[8:9]
	s_andn2_saveexec_b64 s[4:5], s[4:5]
	v_lshl_add_u64 v[138:139], v[136:137], 0, v[0:1]
	v_lshl_add_u64 v[138:139], v[138:139], 0, 32
	s_or_b64 exec, exec, s[4:5]
	v_cvt_pk_bf16_f32 v141, v124, v125
	v_cvt_pk_bf16_f32 v140, v122, v123
	global_store_dwordx2 v[138:139], v[140:141], off
	s_and_saveexec_b64 s[4:5], vcc
	s_xor_b64 s[4:5], exec, s[4:5]
	s_movk_i32 s8, 0xffc0
	v_lshl_add_u64 v[138:139], v[134:135], 0, v[0:1]
	s_mov_b32 s9, -1
	v_lshl_add_u64 v[138:139], v[138:139], 0, s[8:9]
	s_andn2_saveexec_b64 s[4:5], s[4:5]
	v_lshl_add_u64 v[138:139], v[136:137], 0, v[0:1]
	v_lshl_add_u64 v[138:139], v[138:139], 0, 64
	s_or_b64 exec, exec, s[4:5]
	v_cvt_pk_bf16_f32 v141, v120, v121
	v_cvt_pk_bf16_f32 v140, v118, v119
	global_store_dwordx2 v[138:139], v[140:141], off
	s_and_saveexec_b64 s[4:5], vcc
	s_xor_b64 s[4:5], exec, s[4:5]
	s_movk_i32 s8, 0xffe0
	v_lshl_add_u64 v[134:135], v[134:135], 0, v[0:1]
	s_mov_b32 s9, -1
	v_lshl_add_u64 v[138:139], v[134:135], 0, s[8:9]
	s_andn2_saveexec_b64 s[4:5], s[4:5]
	v_lshl_add_u64 v[134:135], v[136:137], 0, v[0:1]
	s_mov_b64 s[8:9], 0x60
	v_lshl_add_u64 v[138:139], v[134:135], 0, s[8:9]
	s_or_b64 exec, exec, s[4:5]
	v_cvt_pk_bf16_f32 v135, v116, v117
	v_cvt_pk_bf16_f32 v134, v114, v115
	global_store_dwordx2 v[138:139], v[134:135], off
	v_or_b32_e32 v134, 16, v132
	v_ashrrev_i32_e32 v135, 31, v134
	v_lshlrev_b64 v[136:137], 11, v[134:135]
	v_lshl_add_u64 v[134:135], s[2:3], 0, v[136:137]
	v_lshl_add_u64 v[134:135], v[130:131], 1, v[134:135]
	s_and_saveexec_b64 s[4:5], vcc
	s_xor_b64 s[4:5], exec, s[4:5]
	s_movk_i32 s8, 0xff80
	v_lshl_add_u64 v[138:139], v[134:135], 0, v[0:1]
	s_mov_b32 s9, -1
	v_lshl_add_u64 v[138:139], v[138:139], 0, s[8:9]
	s_or_saveexec_b64 s[4:5], s[4:5]
	v_lshl_add_u64 v[136:137], s[42:43], 0, v[136:137]
	v_lshl_add_u64 v[136:137], v[130:131], 1, v[136:137]
	s_xor_b64 exec, exec, s[4:5]
	v_lshl_add_u64 v[138:139], v[136:137], 0, v[0:1]
	s_or_b64 exec, exec, s[4:5]
	v_cvt_pk_bf16_f32 v141, v112, v113
	v_cvt_pk_bf16_f32 v140, v110, v111
	global_store_dwordx2 v[138:139], v[140:141], off
	s_and_saveexec_b64 s[4:5], vcc
	s_xor_b64 s[4:5], exec, s[4:5]
	s_movk_i32 s8, 0xffa0
	v_lshl_add_u64 v[138:139], v[134:135], 0, v[0:1]
	s_mov_b32 s9, -1
	v_lshl_add_u64 v[138:139], v[138:139], 0, s[8:9]
	s_andn2_saveexec_b64 s[4:5], s[4:5]
	v_lshl_add_u64 v[138:139], v[136:137], 0, v[0:1]
	v_lshl_add_u64 v[138:139], v[138:139], 0, 32
	s_or_b64 exec, exec, s[4:5]
	v_cvt_pk_bf16_f32 v141, v108, v109
	v_cvt_pk_bf16_f32 v140, v106, v107
	global_store_dwordx2 v[138:139], v[140:141], off
	s_and_saveexec_b64 s[4:5], vcc
	s_xor_b64 s[4:5], exec, s[4:5]
	s_movk_i32 s8, 0xffc0
	v_lshl_add_u64 v[138:139], v[134:135], 0, v[0:1]
	s_mov_b32 s9, -1
	v_lshl_add_u64 v[138:139], v[138:139], 0, s[8:9]
	s_andn2_saveexec_b64 s[4:5], s[4:5]
	v_lshl_add_u64 v[138:139], v[136:137], 0, v[0:1]
	v_lshl_add_u64 v[138:139], v[138:139], 0, 64
	s_or_b64 exec, exec, s[4:5]
	v_cvt_pk_bf16_f32 v141, v104, v105
	v_cvt_pk_bf16_f32 v140, v102, v103
	global_store_dwordx2 v[138:139], v[140:141], off
	s_and_saveexec_b64 s[4:5], vcc
	s_xor_b64 s[4:5], exec, s[4:5]
	s_movk_i32 s8, 0xffe0
	v_lshl_add_u64 v[134:135], v[134:135], 0, v[0:1]
	s_mov_b32 s9, -1
	v_lshl_add_u64 v[138:139], v[134:135], 0, s[8:9]
	s_andn2_saveexec_b64 s[4:5], s[4:5]
	v_lshl_add_u64 v[134:135], v[136:137], 0, v[0:1]
	s_mov_b64 s[8:9], 0x60
	v_lshl_add_u64 v[138:139], v[134:135], 0, s[8:9]
	s_or_b64 exec, exec, s[4:5]
	v_cvt_pk_bf16_f32 v135, v100, v101
	v_cvt_pk_bf16_f32 v134, v98, v99
	global_store_dwordx2 v[138:139], v[134:135], off
	v_or_b32_e32 v134, 32, v132
	v_ashrrev_i32_e32 v135, 31, v134
	v_lshlrev_b64 v[136:137], 11, v[134:135]
	v_lshl_add_u64 v[134:135], s[2:3], 0, v[136:137]
	v_lshl_add_u64 v[134:135], v[130:131], 1, v[134:135]
	s_and_saveexec_b64 s[4:5], vcc
	s_xor_b64 s[4:5], exec, s[4:5]
	s_movk_i32 s8, 0xff80
	v_lshl_add_u64 v[138:139], v[134:135], 0, v[0:1]
	s_mov_b32 s9, -1
	v_lshl_add_u64 v[138:139], v[138:139], 0, s[8:9]
	s_or_saveexec_b64 s[4:5], s[4:5]
	v_lshl_add_u64 v[136:137], s[42:43], 0, v[136:137]
	v_lshl_add_u64 v[136:137], v[130:131], 1, v[136:137]
	s_xor_b64 exec, exec, s[4:5]
	v_lshl_add_u64 v[138:139], v[136:137], 0, v[0:1]
	s_or_b64 exec, exec, s[4:5]
	v_cvt_pk_bf16_f32 v141, v96, v97
	v_cvt_pk_bf16_f32 v140, v94, v95
	global_store_dwordx2 v[138:139], v[140:141], off
	s_and_saveexec_b64 s[4:5], vcc
	s_xor_b64 s[4:5], exec, s[4:5]
	s_movk_i32 s8, 0xffa0
	v_lshl_add_u64 v[138:139], v[134:135], 0, v[0:1]
	s_mov_b32 s9, -1
	v_lshl_add_u64 v[138:139], v[138:139], 0, s[8:9]
	s_andn2_saveexec_b64 s[4:5], s[4:5]
	v_lshl_add_u64 v[138:139], v[136:137], 0, v[0:1]
	v_lshl_add_u64 v[138:139], v[138:139], 0, 32
	s_or_b64 exec, exec, s[4:5]
	v_cvt_pk_bf16_f32 v141, v92, v93
	v_cvt_pk_bf16_f32 v140, v90, v91
	global_store_dwordx2 v[138:139], v[140:141], off
	s_and_saveexec_b64 s[4:5], vcc
	s_xor_b64 s[4:5], exec, s[4:5]
	s_movk_i32 s8, 0xffc0
	v_lshl_add_u64 v[138:139], v[134:135], 0, v[0:1]
	s_mov_b32 s9, -1
	v_lshl_add_u64 v[138:139], v[138:139], 0, s[8:9]
	s_andn2_saveexec_b64 s[4:5], s[4:5]
	v_lshl_add_u64 v[138:139], v[136:137], 0, v[0:1]
	v_lshl_add_u64 v[138:139], v[138:139], 0, 64
	s_or_b64 exec, exec, s[4:5]
	v_cvt_pk_bf16_f32 v141, v88, v89
	v_cvt_pk_bf16_f32 v140, v86, v87
	global_store_dwordx2 v[138:139], v[140:141], off
	s_and_saveexec_b64 s[4:5], vcc
	s_xor_b64 s[4:5], exec, s[4:5]
	s_movk_i32 s8, 0xffe0
	v_lshl_add_u64 v[134:135], v[134:135], 0, v[0:1]
	s_mov_b32 s9, -1
	v_lshl_add_u64 v[138:139], v[134:135], 0, s[8:9]
	s_andn2_saveexec_b64 s[4:5], s[4:5]
	v_lshl_add_u64 v[134:135], v[136:137], 0, v[0:1]
	s_mov_b64 s[8:9], 0x60
	v_lshl_add_u64 v[138:139], v[134:135], 0, s[8:9]
	s_or_b64 exec, exec, s[4:5]
	v_cvt_pk_bf16_f32 v135, v84, v85
	v_cvt_pk_bf16_f32 v134, v82, v83
	global_store_dwordx2 v[138:139], v[134:135], off
	v_or_b32_e32 v134, 48, v132
	v_ashrrev_i32_e32 v135, 31, v134
	v_lshlrev_b64 v[136:137], 11, v[134:135]
	v_lshl_add_u64 v[134:135], s[2:3], 0, v[136:137]
	v_lshl_add_u64 v[134:135], v[130:131], 1, v[134:135]
	s_and_saveexec_b64 s[4:5], vcc
	s_xor_b64 s[4:5], exec, s[4:5]
	s_movk_i32 s8, 0xff80
	v_lshl_add_u64 v[138:139], v[134:135], 0, v[0:1]
	s_mov_b32 s9, -1
	v_lshl_add_u64 v[138:139], v[138:139], 0, s[8:9]
	s_or_saveexec_b64 s[4:5], s[4:5]
	v_lshl_add_u64 v[136:137], s[42:43], 0, v[136:137]
	v_lshl_add_u64 v[136:137], v[130:131], 1, v[136:137]
	s_xor_b64 exec, exec, s[4:5]
	v_lshl_add_u64 v[138:139], v[136:137], 0, v[0:1]
	s_or_b64 exec, exec, s[4:5]
	v_cvt_pk_bf16_f32 v141, v80, v81
	v_cvt_pk_bf16_f32 v140, v78, v79
	global_store_dwordx2 v[138:139], v[140:141], off
	s_and_saveexec_b64 s[4:5], vcc
	s_xor_b64 s[4:5], exec, s[4:5]
	s_movk_i32 s8, 0xffa0
	v_lshl_add_u64 v[138:139], v[134:135], 0, v[0:1]
	s_mov_b32 s9, -1
	v_lshl_add_u64 v[138:139], v[138:139], 0, s[8:9]
	s_andn2_saveexec_b64 s[4:5], s[4:5]
	v_lshl_add_u64 v[138:139], v[136:137], 0, v[0:1]
	v_lshl_add_u64 v[138:139], v[138:139], 0, 32
	s_or_b64 exec, exec, s[4:5]
	v_cvt_pk_bf16_f32 v141, v76, v77
	v_cvt_pk_bf16_f32 v140, v74, v75
	global_store_dwordx2 v[138:139], v[140:141], off
	s_and_saveexec_b64 s[4:5], vcc
	s_xor_b64 s[4:5], exec, s[4:5]
	s_movk_i32 s8, 0xffc0
	v_lshl_add_u64 v[138:139], v[134:135], 0, v[0:1]
	s_mov_b32 s9, -1
	v_lshl_add_u64 v[138:139], v[138:139], 0, s[8:9]
	s_andn2_saveexec_b64 s[4:5], s[4:5]
	v_lshl_add_u64 v[138:139], v[136:137], 0, v[0:1]
	v_lshl_add_u64 v[138:139], v[138:139], 0, 64
	s_or_b64 exec, exec, s[4:5]
	v_cvt_pk_bf16_f32 v141, v72, v73
	v_cvt_pk_bf16_f32 v140, v70, v71
	global_store_dwordx2 v[138:139], v[140:141], off
	s_and_saveexec_b64 s[4:5], vcc
	s_xor_b64 s[4:5], exec, s[4:5]
	s_movk_i32 s8, 0xffe0
	v_lshl_add_u64 v[134:135], v[134:135], 0, v[0:1]
	s_mov_b32 s9, -1
	v_lshl_add_u64 v[138:139], v[134:135], 0, s[8:9]
	s_andn2_saveexec_b64 s[4:5], s[4:5]
	v_lshl_add_u64 v[134:135], v[136:137], 0, v[0:1]
	s_mov_b64 s[8:9], 0x60
	v_lshl_add_u64 v[138:139], v[134:135], 0, s[8:9]
	s_or_b64 exec, exec, s[4:5]
	v_cvt_pk_bf16_f32 v135, v68, v69
	v_cvt_pk_bf16_f32 v134, v66, v67
	global_store_dwordx2 v[138:139], v[134:135], off
	v_or_b32_e32 v134, 64, v132
	v_ashrrev_i32_e32 v135, 31, v134
	v_lshlrev_b64 v[136:137], 11, v[134:135]
	v_lshl_add_u64 v[134:135], s[2:3], 0, v[136:137]
	v_lshl_add_u64 v[134:135], v[130:131], 1, v[134:135]
	s_and_saveexec_b64 s[4:5], vcc
	s_xor_b64 s[4:5], exec, s[4:5]
	s_movk_i32 s8, 0xff80
	v_lshl_add_u64 v[138:139], v[134:135], 0, v[0:1]
	s_mov_b32 s9, -1
	v_lshl_add_u64 v[138:139], v[138:139], 0, s[8:9]
	s_or_saveexec_b64 s[4:5], s[4:5]
	v_lshl_add_u64 v[136:137], s[42:43], 0, v[136:137]
	v_lshl_add_u64 v[136:137], v[130:131], 1, v[136:137]
	s_xor_b64 exec, exec, s[4:5]
	v_lshl_add_u64 v[138:139], v[136:137], 0, v[0:1]
	s_or_b64 exec, exec, s[4:5]
	v_cvt_pk_bf16_f32 v141, v64, v65
	v_cvt_pk_bf16_f32 v140, v62, v63
	global_store_dwordx2 v[138:139], v[140:141], off
	s_and_saveexec_b64 s[4:5], vcc
	s_xor_b64 s[4:5], exec, s[4:5]
	s_movk_i32 s8, 0xffa0
	v_lshl_add_u64 v[138:139], v[134:135], 0, v[0:1]
	s_mov_b32 s9, -1
	v_lshl_add_u64 v[138:139], v[138:139], 0, s[8:9]
	s_andn2_saveexec_b64 s[4:5], s[4:5]
	v_lshl_add_u64 v[138:139], v[136:137], 0, v[0:1]
	v_lshl_add_u64 v[138:139], v[138:139], 0, 32
	s_or_b64 exec, exec, s[4:5]
	v_cvt_pk_bf16_f32 v141, v60, v61
	v_cvt_pk_bf16_f32 v140, v58, v59
	global_store_dwordx2 v[138:139], v[140:141], off
	s_and_saveexec_b64 s[4:5], vcc
	s_xor_b64 s[4:5], exec, s[4:5]
	s_movk_i32 s8, 0xffc0
	v_lshl_add_u64 v[138:139], v[134:135], 0, v[0:1]
	s_mov_b32 s9, -1
	v_lshl_add_u64 v[138:139], v[138:139], 0, s[8:9]
	s_andn2_saveexec_b64 s[4:5], s[4:5]
	v_lshl_add_u64 v[138:139], v[136:137], 0, v[0:1]
	v_lshl_add_u64 v[138:139], v[138:139], 0, 64
	s_or_b64 exec, exec, s[4:5]
	v_cvt_pk_bf16_f32 v141, v56, v57
	v_cvt_pk_bf16_f32 v140, v54, v55
	global_store_dwordx2 v[138:139], v[140:141], off
	s_and_saveexec_b64 s[4:5], vcc
	s_xor_b64 s[4:5], exec, s[4:5]
	s_movk_i32 s8, 0xffe0
	v_lshl_add_u64 v[134:135], v[134:135], 0, v[0:1]
	s_mov_b32 s9, -1
	v_lshl_add_u64 v[138:139], v[134:135], 0, s[8:9]
	s_andn2_saveexec_b64 s[4:5], s[4:5]
	v_lshl_add_u64 v[134:135], v[136:137], 0, v[0:1]
	s_mov_b64 s[8:9], 0x60
	v_lshl_add_u64 v[138:139], v[134:135], 0, s[8:9]
	s_or_b64 exec, exec, s[4:5]
	v_cvt_pk_bf16_f32 v135, v52, v53
	v_cvt_pk_bf16_f32 v134, v50, v51
	global_store_dwordx2 v[138:139], v[134:135], off
	v_or_b32_e32 v134, 0x50, v132
	v_ashrrev_i32_e32 v135, 31, v134
	v_lshlrev_b64 v[136:137], 11, v[134:135]
	v_lshl_add_u64 v[134:135], s[2:3], 0, v[136:137]
	v_lshl_add_u64 v[134:135], v[130:131], 1, v[134:135]
	s_and_saveexec_b64 s[4:5], vcc
	s_xor_b64 s[4:5], exec, s[4:5]
	s_movk_i32 s8, 0xff80
	v_lshl_add_u64 v[138:139], v[134:135], 0, v[0:1]
	s_mov_b32 s9, -1
	v_lshl_add_u64 v[138:139], v[138:139], 0, s[8:9]
	s_or_saveexec_b64 s[4:5], s[4:5]
	v_lshl_add_u64 v[136:137], s[42:43], 0, v[136:137]
	v_lshl_add_u64 v[136:137], v[130:131], 1, v[136:137]
	s_xor_b64 exec, exec, s[4:5]
	v_lshl_add_u64 v[138:139], v[136:137], 0, v[0:1]
	s_or_b64 exec, exec, s[4:5]
	v_cvt_pk_bf16_f32 v141, v48, v49
	v_cvt_pk_bf16_f32 v140, v46, v47
	global_store_dwordx2 v[138:139], v[140:141], off
	s_and_saveexec_b64 s[4:5], vcc
	s_xor_b64 s[4:5], exec, s[4:5]
	s_movk_i32 s8, 0xffa0
	v_lshl_add_u64 v[138:139], v[134:135], 0, v[0:1]
	s_mov_b32 s9, -1
	v_lshl_add_u64 v[138:139], v[138:139], 0, s[8:9]
	s_andn2_saveexec_b64 s[4:5], s[4:5]
	v_lshl_add_u64 v[138:139], v[136:137], 0, v[0:1]
	v_lshl_add_u64 v[138:139], v[138:139], 0, 32
	s_or_b64 exec, exec, s[4:5]
	v_cvt_pk_bf16_f32 v141, v44, v45
	v_cvt_pk_bf16_f32 v140, v42, v43
	global_store_dwordx2 v[138:139], v[140:141], off
	s_and_saveexec_b64 s[4:5], vcc
	s_xor_b64 s[4:5], exec, s[4:5]
	s_movk_i32 s8, 0xffc0
	v_lshl_add_u64 v[138:139], v[134:135], 0, v[0:1]
	s_mov_b32 s9, -1
	v_lshl_add_u64 v[138:139], v[138:139], 0, s[8:9]
	s_andn2_saveexec_b64 s[4:5], s[4:5]
	v_lshl_add_u64 v[138:139], v[136:137], 0, v[0:1]
	v_lshl_add_u64 v[138:139], v[138:139], 0, 64
	s_or_b64 exec, exec, s[4:5]
	v_cvt_pk_bf16_f32 v141, v36, v37
	v_cvt_pk_bf16_f32 v140, v34, v35
	global_store_dwordx2 v[138:139], v[140:141], off
	s_and_saveexec_b64 s[4:5], vcc
	s_xor_b64 s[4:5], exec, s[4:5]
	s_movk_i32 s8, 0xffe0
	v_lshl_add_u64 v[134:135], v[134:135], 0, v[0:1]
	s_mov_b32 s9, -1
	v_lshl_add_u64 v[138:139], v[134:135], 0, s[8:9]
	s_andn2_saveexec_b64 s[4:5], s[4:5]
	v_lshl_add_u64 v[134:135], v[136:137], 0, v[0:1]
	s_mov_b64 s[8:9], 0x60
	v_lshl_add_u64 v[138:139], v[134:135], 0, s[8:9]
	s_or_b64 exec, exec, s[4:5]
	v_cvt_pk_bf16_f32 v135, v32, v33
	v_cvt_pk_bf16_f32 v134, v30, v31
	global_store_dwordx2 v[138:139], v[134:135], off
	v_or_b32_e32 v134, 0x60, v132
	v_ashrrev_i32_e32 v135, 31, v134
	v_lshlrev_b64 v[136:137], 11, v[134:135]
	v_lshl_add_u64 v[134:135], s[2:3], 0, v[136:137]
	v_lshl_add_u64 v[134:135], v[130:131], 1, v[134:135]
	s_and_saveexec_b64 s[4:5], vcc
	s_xor_b64 s[4:5], exec, s[4:5]
	s_movk_i32 s8, 0xff80
	v_lshl_add_u64 v[138:139], v[134:135], 0, v[0:1]
	s_mov_b32 s9, -1
	v_lshl_add_u64 v[138:139], v[138:139], 0, s[8:9]
	s_or_saveexec_b64 s[4:5], s[4:5]
	v_lshl_add_u64 v[136:137], s[42:43], 0, v[136:137]
	v_lshl_add_u64 v[136:137], v[130:131], 1, v[136:137]
	s_xor_b64 exec, exec, s[4:5]
	v_lshl_add_u64 v[138:139], v[136:137], 0, v[0:1]
	s_or_b64 exec, exec, s[4:5]
	v_cvt_pk_bf16_f32 v141, v40, v41
	v_cvt_pk_bf16_f32 v140, v38, v39
	global_store_dwordx2 v[138:139], v[140:141], off
	s_and_saveexec_b64 s[4:5], vcc
	s_xor_b64 s[4:5], exec, s[4:5]
	s_movk_i32 s8, 0xffa0
	v_lshl_add_u64 v[138:139], v[134:135], 0, v[0:1]
	s_mov_b32 s9, -1
	v_lshl_add_u64 v[138:139], v[138:139], 0, s[8:9]
	s_andn2_saveexec_b64 s[4:5], s[4:5]
	v_lshl_add_u64 v[138:139], v[136:137], 0, v[0:1]
	v_lshl_add_u64 v[138:139], v[138:139], 0, 32
	s_or_b64 exec, exec, s[4:5]
	v_cvt_pk_bf16_f32 v141, v28, v29
	v_cvt_pk_bf16_f32 v140, v26, v27
	global_store_dwordx2 v[138:139], v[140:141], off
	s_and_saveexec_b64 s[4:5], vcc
	s_xor_b64 s[4:5], exec, s[4:5]
	s_movk_i32 s8, 0xffc0
	v_lshl_add_u64 v[138:139], v[134:135], 0, v[0:1]
	s_mov_b32 s9, -1
	v_lshl_add_u64 v[138:139], v[138:139], 0, s[8:9]
	s_andn2_saveexec_b64 s[4:5], s[4:5]
	v_lshl_add_u64 v[138:139], v[136:137], 0, v[0:1]
	v_lshl_add_u64 v[138:139], v[138:139], 0, 64
	s_or_b64 exec, exec, s[4:5]
	v_cvt_pk_bf16_f32 v141, v24, v25
	v_cvt_pk_bf16_f32 v140, v22, v23
	global_store_dwordx2 v[138:139], v[140:141], off
	s_and_saveexec_b64 s[4:5], vcc
	s_xor_b64 s[4:5], exec, s[4:5]
	s_movk_i32 s8, 0xffe0
	v_lshl_add_u64 v[134:135], v[134:135], 0, v[0:1]
	s_mov_b32 s9, -1
	v_lshl_add_u64 v[138:139], v[134:135], 0, s[8:9]
	s_andn2_saveexec_b64 s[4:5], s[4:5]
	v_lshl_add_u64 v[134:135], v[136:137], 0, v[0:1]
	s_mov_b64 s[8:9], 0x60
	v_lshl_add_u64 v[138:139], v[134:135], 0, s[8:9]
	s_or_b64 exec, exec, s[4:5]
	v_cvt_pk_bf16_f32 v135, v20, v21
	v_cvt_pk_bf16_f32 v134, v18, v19
	v_or_b32_e32 v132, 0x70, v132
	global_store_dwordx2 v[138:139], v[134:135], off
	v_ashrrev_i32_e32 v133, 31, v132
	v_lshlrev_b64 v[136:137], 11, v[132:133]
	v_lshl_add_u64 v[132:133], s[2:3], 0, v[136:137]
	v_lshl_add_u64 v[132:133], v[130:131], 1, v[132:133]
	s_and_saveexec_b64 s[2:3], vcc
	s_xor_b64 s[2:3], exec, s[2:3]
	s_movk_i32 s4, 0xff80
	v_lshl_add_u64 v[134:135], v[132:133], 0, v[0:1]
	s_mov_b32 s5, -1
	v_lshl_add_u64 v[134:135], v[134:135], 0, s[4:5]
	s_or_saveexec_b64 s[2:3], s[2:3]
	v_lshl_add_u64 v[136:137], s[42:43], 0, v[136:137]
	v_lshl_add_u64 v[130:131], v[130:131], 1, v[136:137]
	s_xor_b64 exec, exec, s[2:3]
	v_lshl_add_u64 v[134:135], v[130:131], 0, v[0:1]
	s_or_b64 exec, exec, s[2:3]
	v_cvt_pk_bf16_f32 v137, v16, v17
	v_cvt_pk_bf16_f32 v136, v14, v15
	global_store_dwordx2 v[134:135], v[136:137], off
	s_and_saveexec_b64 s[2:3], vcc
	s_xor_b64 s[2:3], exec, s[2:3]
	s_movk_i32 s4, 0xffa0
	v_lshl_add_u64 v[134:135], v[132:133], 0, v[0:1]
	s_mov_b32 s5, -1
	v_lshl_add_u64 v[134:135], v[134:135], 0, s[4:5]
	s_andn2_saveexec_b64 s[2:3], s[2:3]
	v_lshl_add_u64 v[134:135], v[130:131], 0, v[0:1]
	v_lshl_add_u64 v[134:135], v[134:135], 0, 32
	s_or_b64 exec, exec, s[2:3]
	v_cvt_pk_bf16_f32 v137, v12, v13
	v_cvt_pk_bf16_f32 v136, v10, v11
	global_store_dwordx2 v[134:135], v[136:137], off
	s_and_saveexec_b64 s[2:3], vcc
	s_xor_b64 s[2:3], exec, s[2:3]
	s_movk_i32 s4, 0xffc0
	v_lshl_add_u64 v[134:135], v[132:133], 0, v[0:1]
	s_mov_b32 s5, -1
	v_lshl_add_u64 v[134:135], v[134:135], 0, s[4:5]
	s_andn2_saveexec_b64 s[2:3], s[2:3]
	v_lshl_add_u64 v[134:135], v[130:131], 0, v[0:1]
	v_lshl_add_u64 v[134:135], v[134:135], 0, 64
	s_or_b64 exec, exec, s[2:3]
	v_cvt_pk_bf16_f32 v137, v8, v9
	v_cvt_pk_bf16_f32 v136, v6, v7
	global_store_dwordx2 v[134:135], v[136:137], off
	s_and_saveexec_b64 s[2:3], vcc
	s_xor_b64 s[2:3], exec, s[2:3]
	s_movk_i32 s4, 0xffe0
	v_lshl_add_u64 v[130:131], v[132:133], 0, v[0:1]
	s_mov_b32 s5, -1
	v_lshl_add_u64 v[134:135], v[130:131], 0, s[4:5]
	s_andn2_saveexec_b64 s[2:3], s[2:3]
	v_lshl_add_u64 v[130:131], v[130:131], 0, v[0:1]
	s_mov_b64 s[4:5], 0x60
	v_lshl_add_u64 v[134:135], v[130:131], 0, s[4:5]
	s_or_b64 exec, exec, s[2:3]
	v_cvt_pk_bf16_f32 v131, v4, v5
	v_cvt_pk_bf16_f32 v130, v2, v3
	global_store_dwordx2 v[134:135], v[130:131], off

.LBB0_1284:
	s_and_b64 vcc, exec, s[2:3]
	s_cbranch_vccz .LBB0_632
	v_subrev_u32_e32 v0, s39, v0
	v_cvt_pk_bf16_f32 v129, v128, v129
	v_cvt_pk_bf16_f32 v128, v126, v127
	v_ashrrev_i32_e32 v126, 31, v0
	v_mul_lo_u32 v134, v126, s46
	v_mad_u64_u32 v[126:127], s[2:3], v0, s46, 0
	v_add_u32_e32 v127, v127, v134
	v_ashrrev_i32_e32 v131, 31, v130
	v_lshl_add_u64 v[132:133], v[126:127], 1, s[42:43]
	v_lshlrev_b64 v[126:127], 1, v[130:131]
	v_lshl_add_u64 v[130:131], v[132:133], 0, v[126:127]
	global_store_dwordx2 v[130:131], v[128:129], off
	v_mov_b32_e32 v132, v123
	v_mov_b32_e32 v123, v124
	v_cvt_pk_bf16_f32 v123, v123, v125
	v_cvt_pk_bf16_f32 v122, v122, v132
	global_store_dwordx2 v[130:131], v[122:123], off offset:32
	v_mov_b32_e32 v124, v119
	v_mov_b32_e32 v119, v120
	v_cvt_pk_bf16_f32 v119, v119, v121
	v_cvt_pk_bf16_f32 v118, v118, v124
	global_store_dwordx2 v[130:131], v[118:119], off offset:64
	v_mov_b32_e32 v120, v115
	v_mov_b32_e32 v115, v116
	v_cvt_pk_bf16_f32 v115, v115, v117
	v_cvt_pk_bf16_f32 v114, v114, v120
	global_store_dwordx2 v[130:131], v[114:115], off offset:96
	v_mov_b32_e32 v116, v111
	v_mov_b32_e32 v111, v112
	v_cvt_pk_bf16_f32 v111, v111, v113
	v_or_b32_e32 v112, 16, v0
	v_mad_u64_u32 v[112:113], s[2:3], v112, s46, 0
	v_add_u32_e32 v113, v113, v134
	v_lshl_add_u64 v[112:113], v[112:113], 1, s[42:43]
	v_cvt_pk_bf16_f32 v110, v110, v116
	v_lshl_add_u64 v[112:113], v[112:113], 0, v[126:127]
	global_store_dwordx2 v[112:113], v[110:111], off
	v_mov_b32_e32 v114, v107
	v_mov_b32_e32 v107, v108
	v_cvt_pk_bf16_f32 v107, v107, v109
	v_cvt_pk_bf16_f32 v106, v106, v114
	global_store_dwordx2 v[112:113], v[106:107], off offset:32
	v_mov_b32_e32 v108, v103
	v_mov_b32_e32 v103, v104
	v_cvt_pk_bf16_f32 v103, v103, v105
	v_cvt_pk_bf16_f32 v102, v102, v108
	global_store_dwordx2 v[112:113], v[102:103], off offset:64
	v_mov_b32_e32 v104, v99
	v_mov_b32_e32 v99, v100
	v_cvt_pk_bf16_f32 v99, v99, v101
	v_cvt_pk_bf16_f32 v98, v98, v104
	global_store_dwordx2 v[112:113], v[98:99], off offset:96
	v_mov_b32_e32 v100, v95
	v_mov_b32_e32 v95, v96
	v_cvt_pk_bf16_f32 v95, v95, v97
	v_or_b32_e32 v96, 32, v0
	v_mad_u64_u32 v[96:97], s[2:3], v96, s46, 0
	v_add_u32_e32 v97, v97, v134
	v_lshl_add_u64 v[96:97], v[96:97], 1, s[42:43]
	v_cvt_pk_bf16_f32 v94, v94, v100
	v_lshl_add_u64 v[96:97], v[96:97], 0, v[126:127]
	global_store_dwordx2 v[96:97], v[94:95], off
	v_mov_b32_e32 v98, v91
	v_mov_b32_e32 v91, v92
	v_cvt_pk_bf16_f32 v91, v91, v93
	v_cvt_pk_bf16_f32 v90, v90, v98
	global_store_dwordx2 v[96:97], v[90:91], off offset:32
	v_mov_b32_e32 v92, v87
	v_mov_b32_e32 v87, v88
	v_cvt_pk_bf16_f32 v87, v87, v89
	v_cvt_pk_bf16_f32 v86, v86, v92
	global_store_dwordx2 v[96:97], v[86:87], off offset:64
	v_mov_b32_e32 v88, v83
	v_mov_b32_e32 v83, v84
	v_cvt_pk_bf16_f32 v83, v83, v85
	v_cvt_pk_bf16_f32 v82, v82, v88
	global_store_dwordx2 v[96:97], v[82:83], off offset:96
	v_mov_b32_e32 v84, v79
	v_mov_b32_e32 v79, v80
	v_cvt_pk_bf16_f32 v79, v79, v81
	v_or_b32_e32 v80, 48, v0
	v_mad_u64_u32 v[80:81], s[2:3], v80, s46, 0
	v_add_u32_e32 v81, v81, v134
	v_lshl_add_u64 v[80:81], v[80:81], 1, s[42:43]
	v_cvt_pk_bf16_f32 v78, v78, v84
	v_lshl_add_u64 v[80:81], v[80:81], 0, v[126:127]
	global_store_dwordx2 v[80:81], v[78:79], off
	v_mov_b32_e32 v82, v75
	v_mov_b32_e32 v75, v76
	v_cvt_pk_bf16_f32 v75, v75, v77
	v_cvt_pk_bf16_f32 v74, v74, v82
	global_store_dwordx2 v[80:81], v[74:75], off offset:32
	v_mov_b32_e32 v76, v71
	v_mov_b32_e32 v71, v72
	v_cvt_pk_bf16_f32 v71, v71, v73
	v_cvt_pk_bf16_f32 v70, v70, v76
	global_store_dwordx2 v[80:81], v[70:71], off offset:64
	v_mov_b32_e32 v72, v67
	v_mov_b32_e32 v67, v68
	v_cvt_pk_bf16_f32 v67, v67, v69
	v_cvt_pk_bf16_f32 v66, v66, v72
	global_store_dwordx2 v[80:81], v[66:67], off offset:96
	v_mov_b32_e32 v68, v63
	v_mov_b32_e32 v63, v64
	v_cvt_pk_bf16_f32 v63, v63, v65
	v_or_b32_e32 v64, 64, v0
	v_mad_u64_u32 v[64:65], s[2:3], v64, s46, 0
	v_add_u32_e32 v65, v65, v134
	v_lshl_add_u64 v[64:65], v[64:65], 1, s[42:43]
	v_cvt_pk_bf16_f32 v62, v62, v68
	v_lshl_add_u64 v[64:65], v[64:65], 0, v[126:127]
	global_store_dwordx2 v[64:65], v[62:63], off
	v_mov_b32_e32 v66, v59
	v_mov_b32_e32 v59, v60
	v_cvt_pk_bf16_f32 v59, v59, v61
	v_cvt_pk_bf16_f32 v58, v58, v66
	global_store_dwordx2 v[64:65], v[58:59], off offset:32
	v_mov_b32_e32 v60, v55
	v_mov_b32_e32 v55, v56
	v_cvt_pk_bf16_f32 v55, v55, v57
	v_cvt_pk_bf16_f32 v54, v54, v60
	global_store_dwordx2 v[64:65], v[54:55], off offset:64
	v_mov_b32_e32 v56, v51
	v_mov_b32_e32 v51, v52
	v_cvt_pk_bf16_f32 v51, v51, v53
	v_cvt_pk_bf16_f32 v50, v50, v56
	global_store_dwordx2 v[64:65], v[50:51], off offset:96
	v_mov_b32_e32 v52, v47
	v_mov_b32_e32 v47, v48
	v_cvt_pk_bf16_f32 v47, v47, v49
	v_or_b32_e32 v48, 0x50, v0
	v_mad_u64_u32 v[48:49], s[2:3], v48, s46, 0
	v_add_u32_e32 v49, v49, v134
	v_lshl_add_u64 v[48:49], v[48:49], 1, s[42:43]
	v_cvt_pk_bf16_f32 v46, v46, v52
	v_lshl_add_u64 v[48:49], v[48:49], 0, v[126:127]
	global_store_dwordx2 v[48:49], v[46:47], off
	v_mov_b32_e32 v50, v43
	v_mov_b32_e32 v43, v44
	v_cvt_pk_bf16_f32 v43, v43, v45
	v_cvt_pk_bf16_f32 v42, v42, v50
	global_store_dwordx2 v[48:49], v[42:43], off offset:32
	v_mov_b32_e32 v44, v35
	v_mov_b32_e32 v35, v36
	v_cvt_pk_bf16_f32 v35, v35, v37
	v_cvt_pk_bf16_f32 v34, v34, v44
	global_store_dwordx2 v[48:49], v[34:35], off offset:64
	v_mov_b32_e32 v36, v31
	v_mov_b32_e32 v31, v32
	v_cvt_pk_bf16_f32 v31, v31, v33
	v_cvt_pk_bf16_f32 v30, v30, v36
	global_store_dwordx2 v[48:49], v[30:31], off offset:96
	v_cvt_pk_bf16_f32 v31, v40, v41
	v_cvt_pk_bf16_f32 v30, v38, v39
	v_or_b32_e32 v32, 0x60, v0
	v_mad_u64_u32 v[32:33], s[2:3], v32, s46, 0
	v_add_u32_e32 v33, v33, v134
	v_lshl_add_u64 v[32:33], v[32:33], 1, s[42:43]
	v_lshl_add_u64 v[32:33], v[32:33], 0, v[126:127]
	global_store_dwordx2 v[32:33], v[30:31], off
	v_mov_b32_e32 v34, v27
	v_mov_b32_e32 v27, v28
	v_cvt_pk_bf16_f32 v27, v27, v29
	v_cvt_pk_bf16_f32 v26, v26, v34
	global_store_dwordx2 v[32:33], v[26:27], off offset:32
	v_mov_b32_e32 v28, v23
	v_mov_b32_e32 v23, v24
	v_cvt_pk_bf16_f32 v23, v23, v25
	v_cvt_pk_bf16_f32 v22, v22, v28
	global_store_dwordx2 v[32:33], v[22:23], off offset:64
	v_mov_b32_e32 v24, v19
	v_mov_b32_e32 v19, v20
	v_cvt_pk_bf16_f32 v19, v19, v21
	v_cvt_pk_bf16_f32 v18, v18, v24
	global_store_dwordx2 v[32:33], v[18:19], off offset:96
	v_mov_b32_e32 v20, v15
	v_mov_b32_e32 v15, v16
	v_or_b32_e32 v0, 0x70, v0
	v_cvt_pk_bf16_f32 v15, v15, v17
	v_mad_u64_u32 v[16:17], s[2:3], v0, s46, 0
	v_add_u32_e32 v17, v17, v134
	v_lshl_add_u64 v[16:17], v[16:17], 1, s[42:43]
	v_cvt_pk_bf16_f32 v14, v14, v20
	v_lshl_add_u64 v[16:17], v[16:17], 0, v[126:127]
	global_store_dwordx2 v[16:17], v[14:15], off
	v_mov_b32_e32 v15, v11
	v_cvt_pk_bf16_f32 v11, v12, v13
	v_cvt_pk_bf16_f32 v10, v10, v15
	global_store_dwordx2 v[16:17], v[10:11], off offset:32
	v_mov_b32_e32 v11, v7
	v_cvt_pk_bf16_f32 v7, v8, v9
	v_cvt_pk_bf16_f32 v6, v6, v11
	global_store_dwordx2 v[16:17], v[6:7], off offset:64
	v_mov_b32_e32 v7, v3
	v_cvt_pk_bf16_f32 v3, v4, v5
	v_cvt_pk_bf16_f32 v2, v2, v7
	global_store_dwordx2 v[16:17], v[2:3], off offset:96
	s_branch .LBB0_632

.LBB0_1287:
	s_or_b64 exec, exec, s[4:5]
	s_waitcnt vmcnt(14)
	v_mov_b32_e32 v66, v14
	v_mov_b32_e32 v67, v34
	v_pk_mul_f32 v[66:67], v[66:67], v[66:67]
	v_mov_b32_e32 v68, v15
	v_mov_b32_e32 v69, v35
	v_pk_fma_f32 v[66:67], v[68:69], v[68:69], v[66:67]
	v_mov_b32_e32 v68, v16
	v_mov_b32_e32 v69, v36
	v_pk_fma_f32 v[66:67], v[68:69], v[68:69], v[66:67]
	v_mov_b32_e32 v68, v17
	v_mov_b32_e32 v69, v37
	v_pk_fma_f32 v[66:67], v[68:69], v[68:69], v[66:67]
	s_waitcnt vmcnt(12)
	v_mov_b32_e32 v68, v2
	v_mov_b32_e32 v69, v6
	v_pk_mul_f32 v[68:69], v[68:69], v[68:69]
	v_mov_b32_e32 v104, v3
	v_mov_b32_e32 v105, v7
	v_pk_fma_f32 v[68:69], v[104:105], v[104:105], v[68:69]
	v_mov_b32_e32 v104, v4
	v_mov_b32_e32 v105, v8
	v_pk_fma_f32 v[68:69], v[104:105], v[104:105], v[68:69]
	v_mov_b32_e32 v104, v5
	v_mov_b32_e32 v105, v9
	v_pk_fma_f32 v[68:69], v[104:105], v[104:105], v[68:69]
	s_waitcnt vmcnt(10)
	v_mov_b32_e32 v104, v26
	v_mov_b32_e32 v105, v46
	v_pk_mul_f32 v[104:105], v[104:105], v[104:105]
	v_mov_b32_e32 v106, v27
	v_mov_b32_e32 v107, v47
	v_pk_fma_f32 v[104:105], v[106:107], v[106:107], v[104:105]
	v_mov_b32_e32 v106, v28
	v_mov_b32_e32 v107, v48
	v_pk_fma_f32 v[104:105], v[106:107], v[106:107], v[104:105]
	v_mov_b32_e32 v106, v29
	v_mov_b32_e32 v107, v49
	v_pk_fma_f32 v[104:105], v[106:107], v[106:107], v[104:105]
	s_waitcnt vmcnt(8)
	v_mov_b32_e32 v106, v10
	v_mov_b32_e32 v107, v18
	v_pk_mul_f32 v[106:107], v[106:107], v[106:107]
	v_mov_b32_e32 v108, v11
	v_mov_b32_e32 v109, v19
	v_pk_fma_f32 v[106:107], v[108:109], v[108:109], v[106:107]
	v_mov_b32_e32 v108, v12
	v_mov_b32_e32 v109, v20
	v_pk_fma_f32 v[106:107], v[108:109], v[108:109], v[106:107]
	v_mov_b32_e32 v108, v13
	v_mov_b32_e32 v109, v21
	v_pk_fma_f32 v[106:107], v[108:109], v[108:109], v[106:107]
	v_mov_b32_e32 v108, v104
	v_mov_b32_e32 v109, v66
	v_mov_b32_e32 v66, v105
	v_pk_add_f32 v[66:67], v[108:109], v[66:67]
	v_mov_b32_e32 v104, v107
	v_mov_b32_e32 v105, v69
	v_pk_add_f32 v[66:67], v[104:105], v[66:67]
	v_mov_b32_e32 v107, v68
	v_pk_add_f32 v[66:67], v[106:107], v[66:67]
	ds_bpermute_b32 v69, v71, v67
	ds_bpermute_b32 v68, v71, v66
	s_mov_b32 s4, 0x358637bd
	s_mov_b32 s24, 0x3a800000
	s_mov_b32 s14, 0x800000
	s_waitcnt vmcnt(6)
	v_mov_b32_e32 v108, v39
	s_waitcnt lgkmcnt(0)
	v_pk_add_f32 v[66:67], v[66:67], v[68:69]
	ds_bpermute_b32 v69, v178, v67
	ds_bpermute_b32 v68, v178, v66
	v_mov_b32_e32 v109, v55
	s_waitcnt vmcnt(4)
	v_mov_b32_e32 v110, v23
	v_mov_b32_e32 v111, v31
	s_waitcnt vmcnt(2)
	v_mov_b32_e32 v112, v59
	s_waitcnt lgkmcnt(0)
	v_pk_add_f32 v[66:67], v[66:67], v[68:69]
	ds_bpermute_b32 v69, v179, v67
	ds_bpermute_b32 v68, v179, v66
	v_mov_b32_e32 v113, v63
	s_waitcnt vmcnt(1)
	v_mov_b32_e32 v114, v50
	s_waitcnt vmcnt(0)
	v_mov_b32_e32 v115, v43
	v_pk_mul_f32 v[114:115], v[114:115], v[114:115]
	s_waitcnt lgkmcnt(0)
	v_pk_add_f32 v[66:67], v[66:67], v[68:69]
	ds_bpermute_b32 v69, v180, v67
	ds_bpermute_b32 v68, v180, v66
	v_mov_b32_e32 v95, v1
	s_waitcnt lgkmcnt(0)
	v_pk_add_f32 v[66:67], v[66:67], v[68:69]
	ds_bpermute_b32 v69, v181, v67
	ds_bpermute_b32 v68, v181, v66
	s_waitcnt lgkmcnt(0)
	v_pk_add_f32 v[66:67], v[66:67], v[68:69]
	ds_bpermute_b32 v69, v182, v67
	ds_bpermute_b32 v68, v182, v66
	s_waitcnt lgkmcnt(0)
	v_pk_add_f32 v[66:67], v[66:67], v[68:69]
	v_mov_b64_e32 v[68:69], s[4:5]
	v_pk_fma_f32 v[66:67], v[66:67], s[24:25], v[68:69] op_sel_hi:[1,0,0]
	s_nop 0
	v_mul_f32_e32 v89, 0x4b800000, v67
	v_cmp_gt_f32_e64 s[4:5], s14, v67
	v_cmp_gt_f32_e32 vcc, s14, v66
	s_nop 0
	v_cndmask_b32_e64 v67, v67, v89, s[4:5]
	v_rsq_f32_e32 v67, v67
	s_nop 0
	v_mul_f32_e32 v89, 0x45800000, v67
	v_cndmask_b32_e64 v106, v67, v89, s[4:5]
	v_mul_f32_e32 v67, 0x4b800000, v66
	v_cndmask_b32_e32 v66, v66, v67, vcc
	v_rsq_f32_e32 v66, v66
	v_pk_mul_f32 v[34:35], v[34:35], v[106:107] op_sel_hi:[1,0]
	v_pk_mul_f32 v[36:37], v[36:37], v[106:107] op_sel_hi:[1,0]
	v_pk_mul_f32 v[14:15], v[14:15], v[106:107] op_sel_hi:[1,0]
	v_mul_f32_e32 v67, 0x45800000, v66
	v_cndmask_b32_e32 v104, v66, v67, vcc
	v_mov_b32_e32 v66, v38
	v_mov_b32_e32 v67, v54
	v_pk_mul_f32 v[66:67], v[66:67], v[66:67]
	v_pk_mul_f32 v[16:17], v[16:17], v[106:107] op_sel_hi:[1,0]
	v_pk_fma_f32 v[66:67], v[108:109], v[108:109], v[66:67]
	v_mov_b32_e32 v108, v40
	v_mov_b32_e32 v109, v56
	v_pk_fma_f32 v[66:67], v[108:109], v[108:109], v[66:67]
	v_mov_b32_e32 v108, v41
	v_mov_b32_e32 v109, v57
	v_pk_fma_f32 v[66:67], v[108:109], v[108:109], v[66:67]
	v_mov_b32_e32 v108, v22
	v_mov_b32_e32 v109, v30
	v_pk_mul_f32 v[108:109], v[108:109], v[108:109]
	v_pk_mul_f32 v[6:7], v[6:7], v[106:107] op_sel_hi:[1,0]
	v_pk_fma_f32 v[108:109], v[110:111], v[110:111], v[108:109]
	v_mov_b32_e32 v110, v24
	v_mov_b32_e32 v111, v32
	v_pk_fma_f32 v[108:109], v[110:111], v[110:111], v[108:109]
	v_mov_b32_e32 v110, v25
	v_mov_b32_e32 v111, v33
	v_pk_fma_f32 v[108:109], v[110:111], v[110:111], v[108:109]
	v_mov_b32_e32 v110, v58
	v_mov_b32_e32 v111, v62
	v_pk_mul_f32 v[110:111], v[110:111], v[110:111]
	v_pk_mul_f32 v[8:9], v[8:9], v[106:107] op_sel_hi:[1,0]
	v_pk_fma_f32 v[110:111], v[112:113], v[112:113], v[110:111]
	v_mov_b32_e32 v112, v60
	v_mov_b32_e32 v113, v64
	v_pk_fma_f32 v[110:111], v[112:113], v[112:113], v[110:111]
	v_mov_b32_e32 v112, v61
	v_mov_b32_e32 v113, v65
	v_pk_fma_f32 v[110:111], v[112:113], v[112:113], v[110:111]
	v_pk_mov_b32 v[112:113], v[50:51], v[42:43] op_sel:[1,0]
	v_pk_mul_f32 v[2:3], v[2:3], v[106:107] op_sel_hi:[1,0]
	v_pk_fma_f32 v[112:113], v[112:113], v[112:113], v[114:115]
	v_mov_b32_e32 v114, v52
	v_mov_b32_e32 v115, v44
	v_pk_fma_f32 v[112:113], v[114:115], v[114:115], v[112:113]
	v_mov_b32_e32 v114, v53
	v_mov_b32_e32 v115, v45
	v_pk_fma_f32 v[112:113], v[114:115], v[114:115], v[112:113]
	v_mov_b32_e32 v114, v110
	v_mov_b32_e32 v115, v66
	v_mov_b32_e32 v66, v111
	v_pk_add_f32 v[66:67], v[114:115], v[66:67]
	v_mov_b32_e32 v110, v112
	v_mov_b32_e32 v111, v109
	v_pk_add_f32 v[66:67], v[110:111], v[66:67]
	v_pk_mov_b32 v[108:109], v[112:113], v[108:109] op_sel:[1,0]
	v_pk_mul_f32 v[4:5], v[4:5], v[106:107] op_sel_hi:[1,0]
	v_pk_add_f32 v[66:67], v[66:67], v[108:109]
	ds_bpermute_b32 v109, v71, v67
	ds_bpermute_b32 v108, v71, v66
	s_waitcnt lgkmcnt(0)
	v_pk_add_f32 v[66:67], v[66:67], v[108:109]
	ds_bpermute_b32 v109, v178, v67
	ds_bpermute_b32 v108, v178, v66
	s_waitcnt lgkmcnt(0)
	v_pk_add_f32 v[66:67], v[66:67], v[108:109]
	ds_bpermute_b32 v109, v179, v67
	ds_bpermute_b32 v108, v179, v66
	s_waitcnt lgkmcnt(0)
	v_pk_add_f32 v[66:67], v[66:67], v[108:109]
	ds_bpermute_b32 v109, v180, v67
	ds_bpermute_b32 v108, v180, v66
	s_waitcnt lgkmcnt(0)
	v_pk_add_f32 v[66:67], v[66:67], v[108:109]
	ds_bpermute_b32 v109, v181, v67
	ds_bpermute_b32 v108, v181, v66
	s_waitcnt lgkmcnt(0)
	v_pk_add_f32 v[66:67], v[66:67], v[108:109]
	ds_bpermute_b32 v109, v182, v67
	ds_bpermute_b32 v108, v182, v66
	s_waitcnt lgkmcnt(0)
	v_pk_add_f32 v[66:67], v[66:67], v[108:109]
	s_nop 0
	v_pk_fma_f32 v[66:67], v[66:67], s[24:25], v[68:69] op_sel_hi:[1,0,0]
	s_nop 0
	v_mul_f32_e32 v68, 0x4b800000, v67
	v_cmp_gt_f32_e64 s[4:5], s14, v67
	v_cmp_gt_f32_e32 vcc, s14, v66
	s_nop 0
	v_cndmask_b32_e64 v67, v67, v68, s[4:5]
	v_rsq_f32_e32 v67, v67
	s_nop 0
	v_mul_f32_e32 v68, 0x45800000, v67
	v_cndmask_b32_e64 v110, v67, v68, s[4:5]
	v_mul_f32_e32 v67, 0x4b800000, v66
	v_cndmask_b32_e32 v66, v66, v67, vcc
	v_rsq_f32_e32 v66, v66
	s_mov_b32 s4, 0x8000
	v_mul_f32_e32 v67, 0x45800000, v66
	v_cndmask_b32_e32 v108, v66, v67, vcc
	v_add_u32_e32 v66, v93, v91
	v_mul_i32_i24_e32 v67, 0xffffef00, v66
	v_add3_u32 v67, v67, v88, s4
	v_cmp_lt_i32_e32 vcc, s33, v67
	s_movk_i32 s4, 0x6000
	s_nop 0
	v_cndmask_b32_e32 v66, 8, v66, vcc
	v_add_u32_e32 v68, s30, v66
	v_mov_b64_e32 v[66:67], s[10:11]
	v_mad_i64_i32 v[66:67], s[4:5], v68, s4, v[66:67]
	s_mov_b64 s[4:5], 0x1000
	s_nop 0
	v_lshl_add_u64 v[114:115], v[66:67], 0, s[4:5]
	v_lshl_add_u64 v[68:69], v[114:115], 0, v[0:1]
	v_lshl_add_u64 v[112:113], v[66:67], 0, v[0:1]
	global_load_dwordx4 v[116:119], v[72:73], off
	global_load_dwordx4 v[120:123], v[68:69], off
	s_nop 0
	global_load_dwordx4 v[66:69], v[112:113], off
	v_readlane_b32 s4, v254, 10
	s_waitcnt vmcnt(1)
	v_pk_add_f32 v[120:121], v[120:121], 1.0 op_sel_hi:[1,0]
	s_nop 0
	v_pk_mul_f32 v[116:117], v[116:117], v[120:121]
	v_pk_add_f32 v[120:121], v[122:123], 1.0 op_sel_hi:[1,0]
	s_waitcnt vmcnt(0)
	v_pk_fma_f32 v[34:35], v[34:35], v[116:117], v[66:67]
	v_pk_mul_f32 v[118:119], v[118:119], v[120:121]
	v_pk_fma_f32 v[36:37], v[36:37], v[118:119], v[68:69]
	v_cvt_pk_bf16_f32 v37, v36, v37
	v_cvt_pk_bf16_f32 v36, v34, v35
	v_lshlrev_b64 v[34:35], 11, v[96:97]
	v_lshl_add_u64 v[34:35], v[76:77], 0, v[34:35]
	global_store_dwordx2 v[34:35], v[36:37], off
	v_pk_mul_f32 v[36:37], v[46:47], v[104:105] op_sel_hi:[1,0]
	v_pk_mul_f32 v[46:47], v[48:49], v[104:105] op_sel_hi:[1,0]
	v_pk_fma_f32 v[36:37], v[36:37], v[116:117], v[66:67]
	v_pk_fma_f32 v[46:47], v[46:47], v[118:119], v[68:69]
	v_cvt_pk_bf16_f32 v47, v46, v47
	v_cvt_pk_bf16_f32 v46, v36, v37
	v_lshlrev_b64 v[36:37], 11, v[98:99]
	v_lshl_add_u64 v[36:37], v[76:77], 0, v[36:37]
	global_store_dwordx2 v[36:37], v[46:47], off
	v_pk_mul_f32 v[46:47], v[54:55], v[110:111] op_sel_hi:[1,0]
	v_pk_mul_f32 v[48:49], v[56:57], v[110:111] op_sel_hi:[1,0]
	v_pk_fma_f32 v[46:47], v[46:47], v[116:117], v[66:67]
	v_pk_fma_f32 v[48:49], v[48:49], v[118:119], v[68:69]
	v_cvt_pk_bf16_f32 v49, v48, v49
	v_cvt_pk_bf16_f32 v48, v46, v47
	v_lshlrev_b64 v[46:47], 11, v[100:101]
	v_lshl_add_u64 v[46:47], v[76:77], 0, v[46:47]
	global_store_dwordx2 v[46:47], v[48:49], off
	v_pk_mul_f32 v[48:49], v[62:63], v[108:109] op_sel_hi:[1,0]
	v_pk_mul_f32 v[54:55], v[64:65], v[108:109] op_sel_hi:[1,0]
	v_pk_fma_f32 v[48:49], v[116:117], v[48:49], v[66:67]
	v_pk_fma_f32 v[54:55], v[118:119], v[54:55], v[68:69]
	v_cvt_pk_bf16_f32 v55, v54, v55
	v_cvt_pk_bf16_f32 v54, v48, v49
	v_lshlrev_b64 v[48:49], 11, v[102:103]
	v_lshl_add_u64 v[48:49], v[76:77], 0, v[48:49]
	v_mov_b32_e32 v91, v1
	global_store_dwordx2 v[48:49], v[54:55], off
	v_lshl_add_u64 v[62:63], v[114:115], 0, v[90:91]
	global_load_dwordx4 v[54:57], v[72:73], off offset:1024
	s_nop 0
	global_load_dwordx4 v[62:65], v[62:63], off
	s_nop 0
	global_load_dwordx4 v[66:69], v[112:113], off offset:1024
	v_mov_b32_e32 v93, v1
	v_add_u32_e32 v88, s4, v88
	s_mov_b32 s4, 0x87ff
	s_waitcnt vmcnt(1)
	v_pk_add_f32 v[62:63], v[62:63], 1.0 op_sel_hi:[1,0]
	s_nop 0
	v_pk_mul_f32 v[54:55], v[54:55], v[62:63]
	v_pk_add_f32 v[62:63], v[64:65], 1.0 op_sel_hi:[1,0]
	s_waitcnt vmcnt(0)
	v_pk_fma_f32 v[14:15], v[14:15], v[54:55], v[66:67]
	v_pk_mul_f32 v[56:57], v[56:57], v[62:63]
	v_pk_fma_f32 v[16:17], v[16:17], v[56:57], v[68:69]
	v_cvt_pk_bf16_f32 v14, v14, v15
	v_cvt_pk_bf16_f32 v15, v16, v17
	global_store_dwordx2 v[34:35], v[14:15], off offset:512
	v_pk_mul_f32 v[14:15], v[26:27], v[104:105] op_sel_hi:[1,0]
	v_pk_mul_f32 v[16:17], v[28:29], v[104:105] op_sel_hi:[1,0]
	v_pk_fma_f32 v[14:15], v[14:15], v[54:55], v[66:67]
	v_pk_fma_f32 v[16:17], v[16:17], v[56:57], v[68:69]
	v_cvt_pk_bf16_f32 v14, v14, v15
	v_cvt_pk_bf16_f32 v15, v16, v17
	global_store_dwordx2 v[36:37], v[14:15], off offset:512
	v_pk_mul_f32 v[14:15], v[38:39], v[110:111] op_sel_hi:[1,0]
	v_pk_mul_f32 v[16:17], v[40:41], v[110:111] op_sel_hi:[1,0]
	v_pk_fma_f32 v[14:15], v[14:15], v[54:55], v[66:67]
	v_pk_fma_f32 v[16:17], v[16:17], v[56:57], v[68:69]
	v_cvt_pk_bf16_f32 v14, v14, v15
	v_cvt_pk_bf16_f32 v15, v16, v17
	global_store_dwordx2 v[46:47], v[14:15], off offset:512
	v_pk_mul_f32 v[14:15], v[58:59], v[108:109] op_sel_hi:[1,0]
	v_pk_mul_f32 v[16:17], v[60:61], v[108:109] op_sel_hi:[1,0]
	v_pk_fma_f32 v[14:15], v[14:15], v[54:55], v[66:67]
	v_pk_fma_f32 v[16:17], v[16:17], v[56:57], v[68:69]
	v_cvt_pk_bf16_f32 v14, v14, v15
	v_cvt_pk_bf16_f32 v15, v16, v17
	global_store_dwordx2 v[48:49], v[14:15], off offset:512
	v_lshl_add_u64 v[26:27], v[114:115], 0, v[92:93]
	global_load_dwordx4 v[14:17], v[72:73], off offset:2048
	s_nop 0
	global_load_dwordx4 v[26:29], v[26:27], off
	s_nop 0
	global_load_dwordx4 v[38:41], v[112:113], off offset:2048
	s_waitcnt vmcnt(1)
	v_pk_add_f32 v[26:27], v[26:27], 1.0 op_sel_hi:[1,0]
	s_nop 0
	v_pk_mul_f32 v[14:15], v[14:15], v[26:27]
	v_pk_add_f32 v[26:27], v[28:29], 1.0 op_sel_hi:[1,0]
	s_waitcnt vmcnt(0)
	v_pk_fma_f32 v[6:7], v[6:7], v[14:15], v[38:39]
	v_pk_mul_f32 v[16:17], v[16:17], v[26:27]
	v_pk_fma_f32 v[8:9], v[8:9], v[16:17], v[40:41]
	v_cvt_pk_bf16_f32 v6, v6, v7
	v_cvt_pk_bf16_f32 v7, v8, v9
	global_store_dwordx2 v[34:35], v[6:7], off offset:1024
	v_pk_mul_f32 v[6:7], v[18:19], v[104:105] op_sel_hi:[1,0]
	v_pk_mul_f32 v[8:9], v[20:21], v[104:105] op_sel_hi:[1,0]
	v_pk_fma_f32 v[6:7], v[6:7], v[14:15], v[38:39]
	v_pk_fma_f32 v[8:9], v[8:9], v[16:17], v[40:41]
	v_cvt_pk_bf16_f32 v6, v6, v7
	v_cvt_pk_bf16_f32 v7, v8, v9
	global_store_dwordx2 v[36:37], v[6:7], off offset:1024
	v_pk_mul_f32 v[6:7], v[30:31], v[110:111] op_sel_hi:[1,0]
	v_pk_mul_f32 v[8:9], v[32:33], v[110:111] op_sel_hi:[1,0]
	v_pk_fma_f32 v[6:7], v[6:7], v[14:15], v[38:39]
	v_pk_fma_f32 v[8:9], v[8:9], v[16:17], v[40:41]
	v_cvt_pk_bf16_f32 v6, v6, v7
	v_cvt_pk_bf16_f32 v7, v8, v9
	global_store_dwordx2 v[46:47], v[6:7], off offset:1024
	v_pk_mul_f32 v[6:7], v[50:51], v[108:109] op_sel_hi:[1,0]
	v_pk_mul_f32 v[8:9], v[52:53], v[108:109] op_sel_hi:[1,0]
	v_pk_fma_f32 v[6:7], v[6:7], v[14:15], v[38:39]
	v_pk_fma_f32 v[8:9], v[8:9], v[16:17], v[40:41]
	v_cvt_pk_bf16_f32 v6, v6, v7
	v_cvt_pk_bf16_f32 v7, v8, v9
	global_store_dwordx2 v[48:49], v[6:7], off offset:1024
	v_lshl_add_u64 v[14:15], v[114:115], 0, v[94:95]
	global_load_dwordx4 v[6:9], v[72:73], off offset:3072
	s_nop 0
	global_load_dwordx4 v[14:17], v[14:15], off
	s_nop 0
	global_load_dwordx4 v[18:21], v[112:113], off offset:3072
	s_waitcnt vmcnt(1)
	v_pk_add_f32 v[14:15], v[14:15], 1.0 op_sel_hi:[1,0]
	s_nop 0
	v_pk_mul_f32 v[6:7], v[6:7], v[14:15]
	v_pk_add_f32 v[14:15], v[16:17], 1.0 op_sel_hi:[1,0]
	s_waitcnt vmcnt(0)
	v_pk_fma_f32 v[2:3], v[2:3], v[6:7], v[18:19]
	v_pk_mul_f32 v[8:9], v[8:9], v[14:15]
	v_pk_fma_f32 v[4:5], v[4:5], v[8:9], v[20:21]
	v_cvt_pk_bf16_f32 v2, v2, v3
	v_cvt_pk_bf16_f32 v3, v4, v5
	global_store_dwordx2 v[34:35], v[2:3], off offset:1536
	v_pk_mul_f32 v[2:3], v[10:11], v[104:105] op_sel_hi:[1,0]
	v_pk_mul_f32 v[4:5], v[12:13], v[104:105] op_sel_hi:[1,0]
	v_pk_fma_f32 v[2:3], v[2:3], v[6:7], v[18:19]
	v_pk_fma_f32 v[4:5], v[4:5], v[8:9], v[20:21]
	v_cvt_pk_bf16_f32 v2, v2, v3
	v_cvt_pk_bf16_f32 v3, v4, v5
	global_store_dwordx2 v[36:37], v[2:3], off offset:1536
	v_pk_mul_f32 v[2:3], v[22:23], v[110:111] op_sel_hi:[1,0]
	v_pk_mul_f32 v[4:5], v[24:25], v[110:111] op_sel_hi:[1,0]
	v_pk_fma_f32 v[2:3], v[2:3], v[6:7], v[18:19]
	v_pk_fma_f32 v[4:5], v[4:5], v[8:9], v[20:21]
	v_cvt_pk_bf16_f32 v2, v2, v3
	v_cvt_pk_bf16_f32 v3, v4, v5
	global_store_dwordx2 v[46:47], v[2:3], off offset:1536
	v_pk_mul_f32 v[2:3], v[42:43], v[108:109] op_sel_hi:[1,0]
	v_pk_mul_f32 v[4:5], v[44:45], v[108:109] op_sel_hi:[1,0]
	v_pk_fma_f32 v[2:3], v[2:3], v[6:7], v[18:19]
	v_pk_fma_f32 v[4:5], v[4:5], v[8:9], v[20:21]
	v_cvt_pk_bf16_f32 v2, v2, v3
	v_add_u32_e32 v0, 0x8000, v88
	v_cmp_lt_i32_e32 vcc, s4, v0
	v_cvt_pk_bf16_f32 v3, v4, v5
	s_or_b64 s[38:39], vcc, s[38:39]
	global_store_dwordx2 v[48:49], v[2:3], off offset:1536
	s_andn2_b64 exec, exec, s[38:39]
	s_cbranch_execz .LBB0_1310

.LBB0_1315:
	s_or_b64 exec, exec, s[4:5]
	s_waitcnt vmcnt(0)
	ds_write_b32 v18, v2 offset:192
	ds_write2_b32 v19, v3, v4 offset0:113 offset1:178
	ds_write_b32 v19, v5 offset:972
	v_lshlrev_b32_sdwa v2, v215, v9 dst_sel:DWORD dst_unused:UNUSED_PAD src0_sel:DWORD src1_sel:BYTE_0
	v_lshrrev_b32_sdwa v13, v214, v9 dst_sel:DWORD dst_unused:UNUSED_PAD src0_sel:DWORD src1_sel:BYTE_0
	v_and_b32_e32 v20, 48, v2
	v_mul_u32_u24_e32 v2, 0x104, v13
	v_lshlrev_b32_e32 v3, 2, v20
	v_add3_u32 v21, v222, v2, v3
	s_waitcnt lgkmcnt(0)
	s_barrier
	ds_read2_b32 v[2:3], v21 offset1:1
	ds_read2_b32 v[6:7], v21 offset0:8 offset1:9
	ds_read2_b32 v[4:5], v21 offset0:2 offset1:3
	ds_read2_b32 v[8:9], v21 offset0:10 offset1:11
	ds_read2_b32 v[14:15], v21 offset0:4 offset1:5
	ds_read2_b32 v[16:17], v21 offset0:12 offset1:13
	ds_read2_b32 v[18:19], v21 offset0:6 offset1:7
	s_waitcnt lgkmcnt(4)
	s_waitcnt lgkmcnt(2)
	s_waitcnt lgkmcnt(0)
	v_mov_b32_e32 v28, v3
	v_mov_b32_e32 v3, v4
	v_mov_b32_e32 v26, v5
	v_mov_b32_e32 v4, v14
	v_cvt_pk_bf16_f32 v5, v18, v19
	v_cvt_pk_bf16_f32 v4, v4, v15
	ds_read2_b32 v[14:15], v21 offset0:14 offset1:15
	s_waitcnt lgkmcnt(0)
	v_mov_b32_e32 v25, v7
	v_mov_b32_e32 v7, v8
	v_mov_b32_e32 v23, v9
	v_mov_b32_e32 v8, v16
	v_mov_b32_e32 v9, v14
	v_cvt_pk_bf16_f32 v9, v9, v15
	v_cvt_pk_bf16_f32 v8, v8, v17
	global_load_dwordx3 v[14:16], v[10:11], off offset:672
	v_or_b32_e32 v0, v13, v0
	v_ashrrev_i32_e32 v13, 31, v12
	v_cvt_pk_bf16_f32 v3, v3, v26
	v_cvt_pk_bf16_f32 v2, v2, v28
	v_cvt_pk_bf16_f32 v7, v7, v23
	v_cvt_pk_bf16_f32 v6, v6, v25
	s_waitcnt vmcnt(0)
	v_mad_i64_i32 v[10:11], s[4:5], v16, v0, 0
	v_lshl_add_u64 v[10:11], v[10:11], 1, v[14:15]
	v_lshl_add_u64 v[10:11], v[12:13], 1, v[10:11]
	v_lshlrev_b32_e32 v0, 1, v20
	v_lshl_add_u64 v[10:11], v[10:11], 0, v[0:1]
	global_store_dwordx4 v[10:11], v[2:5], off
	global_store_dwordx4 v[10:11], v[6:9], off offset:16
	s_barrier
